# back-edge rotation (asm guide 7.11) in the 10 GEMM K-loops: loop-carried scalar pointer/counter updates moved from behind the closing barrier into the last MMA segment
# baseline (speedup 1.0000x reference)
; #define PG8_STAGE(bufoff, gbase, voff) do { _Pragma("unroll") for (int _i = 0; _i < 2; ++_i) \
;         __builtin_amdgcn_global_load_lds((const unsigned*)((const char*)(gbase) + (voff)[_i]), (LAS unsigned*)(lds + (bufoff) + ldsw + _i * 8192), 16, 0, 0); } while (0)
; #define PG8_LDA(dst, b, h) do { _Pragma("unroll") for (int m = 0; m < 4; ++m) _Pragma("unroll") for (int k = 0; k < 2; ++k) dst[m][k] = *(const LAS bf16x8*)(lds + PG8_SA(b, h) + aoff + m * 2048 + k * 1024); } while (0)
; #define PG8_LDB(dst, b, h) do { _Pragma("unroll") for (int n = 0; n < 2; ++n) _Pragma("unroll") for (int k = 0; k < 2; ++k) dst[n][k] = *(const LAS bf16x8*)(lds + PG8_SB(b, h) + boff + n * 2048 + k * 1024); } while (0)
; #define PG8_MMA(ai, bj, At, Bt) do { __builtin_amdgcn_s_setprio(1); _Pragma("unroll") for (int m = 0; m < 4; ++m) _Pragma("unroll") for (int n = 0; n < 2; ++n) _Pragma("unroll") for (int k = 0; k < 2; ++k) \
;         acc[ai][bj][m][n] = __builtin_amdgcn_mfma_f32_16x16x32_bf16(Bt[n][k], At[m][k], acc[ai][bj][m][n], 0, 0, 0); __builtin_amdgcn_s_setprio(0); } while (0)
; #define PG8_WAIT_V(n) asm volatile("s_waitcnt vmcnt(" #n ")" ::: "memory")
; #define PG8_WAIT_L(n) asm volatile("s_waitcnt lgkmcnt(" #n ")" ::: "memory")
; #define PG8_BAR __builtin_amdgcn_s_barrier()
; template <int GI>
; __device__ __forceinline__ void gemm_phase(LAS unsigned char* lds, unsigned char* ws, int G, int cblk) {
;     ...
;         const char* nA = has_next ? nxt.A : cA; const char* nB = has_next ? nxt.B : cB;
;         for (int t = 0; t < nt; t += 2) {
;             const bool last = (t == nt - 2);
;             const char* a1 = cA + (size_t)(t + 1) * kstep;
;             const char* a2 = last ? nA : cA + (size_t)(t + 2) * kstep; const char* b2 = last ? nB : cB + (size_t)(t + 2) * kstep;
;             const char* a3 = a2 + kstep; const char* b3 = b2 + kstep;
;             PG8_LDB(B0, 0, 0); PG8_LDB(B1, 0, 1); PG8_SCHED; PG8_LDA(At, 0, 0); PG8_STAGE(PG8_SA(1, 1), a1 + hstepA, voffA);
;             PG8_WAIT_V(8); PG8_WAIT_L(0); PG8_BAR; PG8_MMA(0, 0, At, B0); PG8_MMA(0, 1, At, B1); PG8_BAR; PG8_SCHED;
;             PG8_LDA(At, 0, 1); PG8_STAGE(PG8_SB(0, 0), b2, voffB); PG8_STAGE(PG8_SB(0, 1), b2 + hstepB, voffB); PG8_STAGE(PG8_SA(0, 0), a2, voffA);
;             PG8_WAIT_V(8); PG8_WAIT_L(0); PG8_BAR; PG8_MMA(1, 0, At, B0); PG8_MMA(1, 1, At, B1); PG8_BAR; PG8_SCHED;
.LBB0_97:
	s_add_u32 s4, s94, 0x80080
	s_addc_u32 s5, s95, 0
	s_add_u32 s15, s92, 0x100
	s_addc_u32 s58, s93, 0
	s_mov_b32 s94, -2
	ds_read_b128 v[164:167], v154
	ds_read_b128 v[168:171], v154 offset:1024
	ds_read_b128 v[172:175], v154 offset:2048
	ds_read_b128 v[176:179], v154 offset:3072
	ds_read_b128 v[180:183], v155
	ds_read_b128 v[184:187], v155 offset:1024
	ds_read_b128 v[192:195], v155 offset:2048
	ds_read_b128 v[196:199], v155 offset:3072
	s_add_u32 s6, s4, 0xfff80080
	s_addc_u32 s7, s5, -1
	s_cmp_eq_u32 s94, 28
	s_cselect_b32 s93, s81, s7
	s_cselect_b32 s92, s80, s6
	s_cselect_b32 s7, s85, s58
	s_cselect_b32 s6, s84, s15
	v_lshl_add_u64 v[158:159], s[4:5], 0, v[148:149]
	s_add_i32 m0, s19, 0xc000
	ds_read_b128 v[200:203], v156
	ds_read_b128 v[204:207], v156 offset:1024
	ds_read_b128 v[208:211], v156 offset:2048
	ds_read_b128 v[212:215], v156 offset:3072
	ds_read_b128 v[216:219], v156 offset:4096
	ds_read_b128 v[220:223], v156 offset:5120
	ds_read_b128 v[224:227], v156 offset:6144
	ds_read_b128 v[228:231], v156 offset:7168
	global_load_lds_dwordx4 v[158:159], off
	v_lshl_add_u64 v[158:159], s[4:5], 0, v[150:151]
	s_add_i32 m0, s19, 0xe000
	s_nop 0
	global_load_lds_dwordx4 v[158:159], off
	s_waitcnt vmcnt(8)
	s_waitcnt lgkmcnt(0)
	s_barrier
	s_setprio 1
	s_waitcnt lgkmcnt(0)
	v_mfma_f32_16x16x32_bf16 v[124:127], v[164:167], v[200:203], 0
	v_mfma_f32_16x16x32_bf16 v[120:123], v[172:175], v[200:203], 0
	v_mfma_f32_16x16x32_bf16 v[112:115], v[164:167], v[208:211], 0
	v_mfma_f32_16x16x32_bf16 v[104:107], v[172:175], v[208:211], 0
	v_mfma_f32_16x16x32_bf16 v[96:99], v[164:167], v[216:219], 0
	v_mfma_f32_16x16x32_bf16 v[88:91], v[172:175], v[216:219], 0
	v_mfma_f32_16x16x32_bf16 v[80:83], v[164:167], v[224:227], 0
	v_mfma_f32_16x16x32_bf16 v[72:75], v[172:175], v[224:227], 0
	v_mfma_f32_16x16x32_bf16 v[124:127], v[168:171], v[204:207], v[124:127]
	v_mfma_f32_16x16x32_bf16 v[120:123], v[176:179], v[204:207], v[120:123]
	v_mfma_f32_16x16x32_bf16 v[112:115], v[168:171], v[212:215], v[112:115]
	v_mfma_f32_16x16x32_bf16 v[104:107], v[176:179], v[212:215], v[104:107]
	v_mfma_f32_16x16x32_bf16 v[96:99], v[168:171], v[220:223], v[96:99]
	v_mfma_f32_16x16x32_bf16 v[88:91], v[176:179], v[220:223], v[88:91]
	v_mfma_f32_16x16x32_bf16 v[80:83], v[168:171], v[228:231], v[80:83]
	v_mfma_f32_16x16x32_bf16 v[72:75], v[176:179], v[228:231], v[72:75]
	s_setprio 0
	s_setprio 1
	v_mfma_f32_16x16x32_bf16 v[116:119], v[180:183], v[200:203], 0
	v_mfma_f32_16x16x32_bf16 v[108:111], v[192:195], v[200:203], 0
	v_mfma_f32_16x16x32_bf16 v[100:103], v[180:183], v[208:211], 0
	v_mfma_f32_16x16x32_bf16 v[92:95], v[192:195], v[208:211], 0
	v_mfma_f32_16x16x32_bf16 v[84:87], v[180:183], v[216:219], 0
	v_mfma_f32_16x16x32_bf16 v[76:79], v[192:195], v[216:219], 0
	v_mfma_f32_16x16x32_bf16 v[68:71], v[180:183], v[224:227], 0
	v_mfma_f32_16x16x32_bf16 v[64:67], v[192:195], v[224:227], 0
	v_mfma_f32_16x16x32_bf16 v[116:119], v[184:187], v[204:207], v[116:119]
	v_mfma_f32_16x16x32_bf16 v[108:111], v[196:199], v[204:207], v[108:111]
	v_mfma_f32_16x16x32_bf16 v[100:103], v[184:187], v[212:215], v[100:103]
	v_mfma_f32_16x16x32_bf16 v[92:95], v[196:199], v[212:215], v[92:95]
	v_mfma_f32_16x16x32_bf16 v[84:87], v[184:187], v[220:223], v[84:87]
	v_mfma_f32_16x16x32_bf16 v[76:79], v[196:199], v[220:223], v[76:79]
	v_mfma_f32_16x16x32_bf16 v[68:71], v[184:187], v[228:231], v[68:71]
	v_mfma_f32_16x16x32_bf16 v[64:67], v[196:199], v[228:231], v[64:67]
	s_setprio 0
	s_barrier
	s_add_i32 s34, s27, s18
	v_lshl_add_u64 v[158:159], s[6:7], 0, v[130:131]
	s_mov_b32 m0, s34
	ds_read_b128 v[200:203], v156 offset:16384
	ds_read_b128 v[204:207], v156 offset:17408
	ds_read_b128 v[208:211], v156 offset:18432
	ds_read_b128 v[212:215], v156 offset:19456
	ds_read_b128 v[216:219], v156 offset:20480
	ds_read_b128 v[220:223], v156 offset:21504
	ds_read_b128 v[224:227], v156 offset:22528
	ds_read_b128 v[228:231], v156 offset:23552
	global_load_lds_dwordx4 v[158:159], off
	s_add_i32 m0, s34, 0x2000
	s_add_u32 s96, s6, 0x80000
	v_lshl_add_u64 v[188:189], s[6:7], 0, v[134:135]
	s_addc_u32 s97, s7, 0
	s_add_i32 s34, s24, s18
	global_load_lds_dwordx4 v[188:189], off
	v_lshl_add_u64 v[232:233], s[96:97], 0, v[130:131]
	s_mov_b32 m0, s34
	v_lshl_add_u64 v[234:235], s[92:93], 0, v[132:133]
	global_load_lds_dwordx4 v[232:233], off
	v_lshl_add_u64 v[232:233], s[96:97], 0, v[134:135]
	s_add_i32 m0, s34, 0x2000
	s_nop 0
	global_load_lds_dwordx4 v[232:233], off
	v_lshl_add_u64 v[232:233], s[92:93], 0, v[128:129]
	s_mov_b32 m0, s19
	s_nop 0
	global_load_lds_dwordx4 v[232:233], off
	s_mov_b32 m0, s20
	s_nop 0
	global_load_lds_dwordx4 v[234:235], off
	s_waitcnt vmcnt(8)
	s_waitcnt lgkmcnt(0)
	s_barrier
; #define PG8_STAGE(bufoff, gbase, voff) do { _Pragma("unroll") for (int _i = 0; _i < 2; ++_i) \
;         __builtin_amdgcn_global_load_lds((const unsigned*)((const char*)(gbase) + (voff)[_i]), (LAS unsigned*)(lds + (bufoff) + ldsw + _i * 8192), 16, 0, 0); } while (0)
; #define PG8_LDA(dst, b, h) do { _Pragma("unroll") for (int m = 0; m < 4; ++m) _Pragma("unroll") for (int k = 0; k < 2; ++k) dst[m][k] = *(const LAS bf16x8*)(lds + PG8_SA(b, h) + aoff + m * 2048 + k * 1024); } while (0)
; #define PG8_LDB(dst, b, h) do { _Pragma("unroll") for (int n = 0; n < 2; ++n) _Pragma("unroll") for (int k = 0; k < 2; ++k) dst[n][k] = *(const LAS bf16x8*)(lds + PG8_SB(b, h) + boff + n * 2048 + k * 1024); } while (0)
; #define PG8_MMA(ai, bj, At, Bt) do { __builtin_amdgcn_s_setprio(1); _Pragma("unroll") for (int m = 0; m < 4; ++m) _Pragma("unroll") for (int n = 0; n < 2; ++n) _Pragma("unroll") for (int k = 0; k < 2; ++k) \
;         acc[ai][bj][m][n] = __builtin_amdgcn_mfma_f32_16x16x32_bf16(Bt[n][k], At[m][k], acc[ai][bj][m][n], 0, 0, 0); __builtin_amdgcn_s_setprio(0); } while (0)
; #define PG8_WAIT_V(n) asm volatile("s_waitcnt vmcnt(" #n ")" ::: "memory")
; #define PG8_WAIT_L(n) asm volatile("s_waitcnt lgkmcnt(" #n ")" ::: "memory")
; #define PG8_BAR __builtin_amdgcn_s_barrier()
; #define PG8_SCHED __builtin_amdgcn_sched_barrier(0)
; template <int GI>
; __device__ __forceinline__ void gemm_phase(LAS unsigned char* lds, unsigned char* ws, int G, int cblk) {
;     ...
;             PG8_WAIT_V(8); PG8_WAIT_L(0); PG8_BAR; PG8_MMA(1, 0, At, B0); PG8_MMA(1, 1, At, B1); PG8_BAR; PG8_SCHED;
;             PG8_LDB(B0, 1, 0); PG8_LDB(B1, 1, 1); PG8_SCHED; PG8_LDA(At, 1, 0); PG8_STAGE(PG8_SA(0, 1), a2 + hstepA, voffA);
;             PG8_WAIT_V(8); PG8_WAIT_L(0); PG8_BAR; PG8_MMA(0, 0, At, B0); PG8_MMA(0, 1, At, B1); PG8_BAR; PG8_SCHED;
	s_setprio 1
	s_waitcnt lgkmcnt(0)
	v_mfma_f32_16x16x32_bf16 v[60:63], v[164:167], v[200:203], 0
	v_mfma_f32_16x16x32_bf16 v[56:59], v[172:175], v[200:203], 0
	v_mfma_f32_16x16x32_bf16 v[52:55], v[164:167], v[208:211], 0
	v_mfma_f32_16x16x32_bf16 v[44:47], v[172:175], v[208:211], 0
	v_mfma_f32_16x16x32_bf16 v[36:39], v[164:167], v[216:219], 0
	v_mfma_f32_16x16x32_bf16 v[28:31], v[172:175], v[216:219], 0
	v_mfma_f32_16x16x32_bf16 v[20:23], v[164:167], v[224:227], 0
	v_mfma_f32_16x16x32_bf16 v[12:15], v[172:175], v[224:227], 0
	v_mfma_f32_16x16x32_bf16 v[60:63], v[168:171], v[204:207], v[60:63]
	v_mfma_f32_16x16x32_bf16 v[56:59], v[176:179], v[204:207], v[56:59]
	v_mfma_f32_16x16x32_bf16 v[52:55], v[168:171], v[212:215], v[52:55]
	v_mfma_f32_16x16x32_bf16 v[44:47], v[176:179], v[212:215], v[44:47]
	v_mfma_f32_16x16x32_bf16 v[36:39], v[168:171], v[220:223], v[36:39]
	v_mfma_f32_16x16x32_bf16 v[28:31], v[176:179], v[220:223], v[28:31]
	v_mfma_f32_16x16x32_bf16 v[20:23], v[168:171], v[228:231], v[20:23]
	v_mfma_f32_16x16x32_bf16 v[12:15], v[176:179], v[228:231], v[12:15]
	s_setprio 0
	s_setprio 1
	v_mfma_f32_16x16x32_bf16 v[48:51], v[180:183], v[200:203], 0
	v_mfma_f32_16x16x32_bf16 v[40:43], v[192:195], v[200:203], 0
	v_mfma_f32_16x16x32_bf16 v[32:35], v[180:183], v[208:211], 0
	v_mfma_f32_16x16x32_bf16 v[24:27], v[192:195], v[208:211], 0
	v_mfma_f32_16x16x32_bf16 v[16:19], v[180:183], v[216:219], 0
	v_mfma_f32_16x16x32_bf16 v[8:11], v[192:195], v[216:219], 0
	v_mfma_f32_16x16x32_bf16 v[4:7], v[180:183], v[224:227], 0
	v_mfma_f32_16x16x32_bf16 v[0:3], v[192:195], v[224:227], 0
	v_mfma_f32_16x16x32_bf16 v[48:51], v[184:187], v[204:207], v[48:51]
	v_mfma_f32_16x16x32_bf16 v[40:43], v[196:199], v[204:207], v[40:43]
	v_mfma_f32_16x16x32_bf16 v[32:35], v[184:187], v[212:215], v[32:35]
	v_mfma_f32_16x16x32_bf16 v[24:27], v[196:199], v[212:215], v[24:27]
	v_mfma_f32_16x16x32_bf16 v[16:19], v[184:187], v[220:223], v[16:19]
	v_mfma_f32_16x16x32_bf16 v[8:11], v[196:199], v[220:223], v[8:11]
	v_mfma_f32_16x16x32_bf16 v[4:7], v[184:187], v[228:231], v[4:7]
	v_mfma_f32_16x16x32_bf16 v[0:3], v[196:199], v[228:231], v[0:3]
	s_setprio 0
	s_barrier
	s_add_i32 s34, 0, 0x18000
	v_add_u32_e32 v161, s34, v153
	s_add_i32 s95, 0, 0x1c000
	ds_read_b128 v[164:167], v161
	ds_read_b128 v[168:171], v161 offset:1024
	ds_read_b128 v[172:175], v161 offset:2048
	ds_read_b128 v[176:179], v161 offset:3072
	v_add_u32_e32 v161, s95, v153
	ds_read_b128 v[180:183], v161
	ds_read_b128 v[184:187], v161 offset:1024
	ds_read_b128 v[192:195], v161 offset:2048
	ds_read_b128 v[196:199], v161 offset:3072
	s_add_u32 s92, s92, 0x80000
	s_addc_u32 s93, s93, 0
	s_mov_b32 m0, s21
	v_lshl_add_u64 v[236:237], s[92:93], 0, v[128:129]
	ds_read_b128 v[200:203], v156 offset:32768
	ds_read_b128 v[204:207], v156 offset:33792
	ds_read_b128 v[208:211], v156 offset:34816
	ds_read_b128 v[212:215], v156 offset:35840
	ds_read_b128 v[216:219], v156 offset:36864
	ds_read_b128 v[220:223], v156 offset:37888
	ds_read_b128 v[224:227], v156 offset:38912
	ds_read_b128 v[228:231], v156 offset:39936
	global_load_lds_dwordx4 v[236:237], off
	v_lshl_add_u64 v[236:237], s[92:93], 0, v[132:133]
	s_mov_b32 m0, s35
	s_nop 0
	global_load_lds_dwordx4 v[236:237], off
	s_waitcnt vmcnt(8)
	s_waitcnt lgkmcnt(0)
	s_barrier
	s_setprio 1
	s_waitcnt lgkmcnt(0)
	v_mfma_f32_16x16x32_bf16 v[124:127], v[164:167], v[200:203], v[124:127]
	v_mfma_f32_16x16x32_bf16 v[120:123], v[172:175], v[200:203], v[120:123]
	v_mfma_f32_16x16x32_bf16 v[112:115], v[164:167], v[208:211], v[112:115]
	v_mfma_f32_16x16x32_bf16 v[104:107], v[172:175], v[208:211], v[104:107]
	v_mfma_f32_16x16x32_bf16 v[96:99], v[164:167], v[216:219], v[96:99]
	v_mfma_f32_16x16x32_bf16 v[88:91], v[172:175], v[216:219], v[88:91]
	v_mfma_f32_16x16x32_bf16 v[80:83], v[164:167], v[224:227], v[80:83]
	v_mfma_f32_16x16x32_bf16 v[72:75], v[172:175], v[224:227], v[72:75]
	v_mfma_f32_16x16x32_bf16 v[124:127], v[168:171], v[204:207], v[124:127]
	v_mfma_f32_16x16x32_bf16 v[120:123], v[176:179], v[204:207], v[120:123]
	v_mfma_f32_16x16x32_bf16 v[112:115], v[168:171], v[212:215], v[112:115]
	v_mfma_f32_16x16x32_bf16 v[104:107], v[176:179], v[212:215], v[104:107]
	v_mfma_f32_16x16x32_bf16 v[96:99], v[168:171], v[220:223], v[96:99]
	v_mfma_f32_16x16x32_bf16 v[88:91], v[176:179], v[220:223], v[88:91]
	v_mfma_f32_16x16x32_bf16 v[80:83], v[168:171], v[228:231], v[80:83]
	v_mfma_f32_16x16x32_bf16 v[72:75], v[176:179], v[228:231], v[72:75]
	s_setprio 0
	s_setprio 1
	v_mfma_f32_16x16x32_bf16 v[116:119], v[180:183], v[200:203], v[116:119]
	v_mfma_f32_16x16x32_bf16 v[108:111], v[192:195], v[200:203], v[108:111]
	v_mfma_f32_16x16x32_bf16 v[100:103], v[180:183], v[208:211], v[100:103]
	v_mfma_f32_16x16x32_bf16 v[92:95], v[192:195], v[208:211], v[92:95]
	v_mfma_f32_16x16x32_bf16 v[84:87], v[180:183], v[216:219], v[84:87]
	v_mfma_f32_16x16x32_bf16 v[76:79], v[192:195], v[216:219], v[76:79]
	v_mfma_f32_16x16x32_bf16 v[68:71], v[180:183], v[224:227], v[68:71]
	v_mfma_f32_16x16x32_bf16 v[64:67], v[192:195], v[224:227], v[64:67]
	v_mfma_f32_16x16x32_bf16 v[116:119], v[184:187], v[204:207], v[116:119]
	v_mfma_f32_16x16x32_bf16 v[108:111], v[196:199], v[204:207], v[108:111]
	v_mfma_f32_16x16x32_bf16 v[100:103], v[184:187], v[212:215], v[100:103]
	v_mfma_f32_16x16x32_bf16 v[92:95], v[196:199], v[212:215], v[92:95]
	v_mfma_f32_16x16x32_bf16 v[84:87], v[184:187], v[220:223], v[84:87]
	v_mfma_f32_16x16x32_bf16 v[76:79], v[196:199], v[220:223], v[76:79]
	v_mfma_f32_16x16x32_bf16 v[68:71], v[184:187], v[228:231], v[68:71]
	v_mfma_f32_16x16x32_bf16 v[64:67], v[196:199], v[228:231], v[64:67]
	s_setprio 0
	s_barrier
; #define PG8_STAGE(bufoff, gbase, voff) do { _Pragma("unroll") for (int _i = 0; _i < 2; ++_i) \
;         __builtin_amdgcn_global_load_lds((const unsigned*)((const char*)(gbase) + (voff)[_i]), (LAS unsigned*)(lds + (bufoff) + ldsw + _i * 8192), 16, 0, 0); } while (0)
; #define PG8_LDA(dst, b, h) do { _Pragma("unroll") for (int m = 0; m < 4; ++m) _Pragma("unroll") for (int k = 0; k < 2; ++k) dst[m][k] = *(const LAS bf16x8*)(lds + PG8_SA(b, h) + aoff + m * 2048 + k * 1024); } while (0)
; #define PG8_LDB(dst, b, h) do { _Pragma("unroll") for (int n = 0; n < 2; ++n) _Pragma("unroll") for (int k = 0; k < 2; ++k) dst[n][k] = *(const LAS bf16x8*)(lds + PG8_SB(b, h) + boff + n * 2048 + k * 1024); } while (0)
; #define PG8_MMA(ai, bj, At, Bt) do { __builtin_amdgcn_s_setprio(1); _Pragma("unroll") for (int m = 0; m < 4; ++m) _Pragma("unroll") for (int n = 0; n < 2; ++n) _Pragma("unroll") for (int k = 0; k < 2; ++k) \
;         acc[ai][bj][m][n] = __builtin_amdgcn_mfma_f32_16x16x32_bf16(Bt[n][k], At[m][k], acc[ai][bj][m][n], 0, 0, 0); __builtin_amdgcn_s_setprio(0); } while (0)
; #define PG8_WAIT_V(n) asm volatile("s_waitcnt vmcnt(" #n ")" ::: "memory")
; #define PG8_BAR __builtin_amdgcn_s_barrier()
; template <int GI>
; __device__ __forceinline__ void gemm_phase(LAS unsigned char* lds, unsigned char* ws, int G, int cblk) {
;     ...
;             PG8_LDB(B0, 0, 0); PG8_LDB(B1, 0, 1); PG8_SCHED; PG8_LDA(At, 0, 0); PG8_STAGE(PG8_SA(1, 1), a1 + hstepA, voffA);
;             PG8_WAIT_V(8); PG8_WAIT_L(0); PG8_BAR; PG8_MMA(0, 0, At, B0); PG8_MMA(0, 1, At, B1); PG8_BAR; PG8_SCHED;
;             PG8_LDA(At, 0, 1); PG8_STAGE(PG8_SB(0, 0), b2, voffB); PG8_STAGE(PG8_SB(0, 1), b2 + hstepB, voffB); PG8_STAGE(PG8_SA(0, 0), a2, voffA);
;             PG8_WAIT_V(8); PG8_WAIT_L(0); PG8_BAR; PG8_MMA(1, 0, At, B0); PG8_MMA(1, 1, At, B1); PG8_BAR; PG8_SCHED;
;             PG8_LDB(B0, 1, 0); PG8_LDB(B1, 1, 1); PG8_SCHED; PG8_LDA(At, 1, 0); PG8_STAGE(PG8_SA(0, 1), a2 + hstepA, voffA);
;             PG8_WAIT_V(8); PG8_WAIT_L(0); PG8_BAR; PG8_MMA(0, 0, At, B0); PG8_MMA(0, 1, At, B1); PG8_BAR; PG8_SCHED;
;             PG8_LDA(At, 1, 1); PG8_STAGE(PG8_SB(1, 0), b3, voffB); PG8_STAGE(PG8_SB(1, 1), b3 + hstepB, voffB); PG8_STAGE(PG8_SA(1, 0), a3, voffA);
;             PG8_WAIT_V(8); PG8_WAIT_L(0); PG8_BAR; PG8_MMA(1, 0, At, B0); PG8_MMA(1, 1, At, B1); PG8_BAR; PG8_SCHED;
;         }
	s_add_i32 s34, s34, s18
	v_lshl_add_u64 v[158:159], v[158:159], 0, s[70:71]
	s_mov_b32 m0, s34
	ds_read_b128 v[200:203], v156 offset:49152
	ds_read_b128 v[204:207], v156 offset:50176
	ds_read_b128 v[208:211], v156 offset:51200
	ds_read_b128 v[212:215], v156 offset:52224
	ds_read_b128 v[216:219], v156 offset:53248
	ds_read_b128 v[220:223], v156 offset:54272
	ds_read_b128 v[224:227], v156 offset:55296
	ds_read_b128 v[228:231], v156 offset:56320
	global_load_lds_dwordx4 v[158:159], off
	s_add_i32 m0, s34, 0x2000
	s_add_u32 s6, s6, 0x80080
	v_lshl_add_u64 v[158:159], v[188:189], 0, s[70:71]
	s_addc_u32 s7, s7, 0
	s_add_i32 s34, s95, s18
	global_load_lds_dwordx4 v[158:159], off
	v_lshl_add_u64 v[158:159], s[6:7], 0, v[130:131]
	s_mov_b32 m0, s34
	s_nop 0
	global_load_lds_dwordx4 v[158:159], off
	v_lshl_add_u64 v[158:159], s[6:7], 0, v[134:135]
	s_add_i32 m0, s34, 0x2000
	s_nop 0
	global_load_lds_dwordx4 v[158:159], off
	v_lshl_add_u64 v[158:159], v[232:233], 0, s[70:71]
	s_mov_b32 m0, s0
	s_nop 0
	global_load_lds_dwordx4 v[158:159], off
	v_lshl_add_u64 v[158:159], v[234:235], 0, s[70:71]
	s_mov_b32 m0, s1
	s_nop 0
	global_load_lds_dwordx4 v[158:159], off
	s_waitcnt vmcnt(8)
	s_waitcnt lgkmcnt(0)
	s_barrier
	s_setprio 1
	s_waitcnt lgkmcnt(0)
	v_mfma_f32_16x16x32_bf16 v[60:63], v[164:167], v[200:203], v[60:63]
	v_mfma_f32_16x16x32_bf16 v[56:59], v[172:175], v[200:203], v[56:59]
	s_add_i32 s94, s94, 2
	s_add_u32 s4, s4, 0x100
	s_addc_u32 s5, s5, 0
	s_add_u32 s15, s15, 0x100
	s_addc_u32 s58, s58, 0
	v_mfma_f32_16x16x32_bf16 v[52:55], v[164:167], v[208:211], v[52:55]
	v_mfma_f32_16x16x32_bf16 v[44:47], v[172:175], v[208:211], v[44:47]
	v_mfma_f32_16x16x32_bf16 v[36:39], v[164:167], v[216:219], v[36:39]
	v_mfma_f32_16x16x32_bf16 v[28:31], v[172:175], v[216:219], v[28:31]
	v_mfma_f32_16x16x32_bf16 v[20:23], v[164:167], v[224:227], v[20:23]
	v_mfma_f32_16x16x32_bf16 v[12:15], v[172:175], v[224:227], v[12:15]
	v_mfma_f32_16x16x32_bf16 v[60:63], v[168:171], v[204:207], v[60:63]
	v_mfma_f32_16x16x32_bf16 v[56:59], v[176:179], v[204:207], v[56:59]
	v_mfma_f32_16x16x32_bf16 v[52:55], v[168:171], v[212:215], v[52:55]
	v_mfma_f32_16x16x32_bf16 v[44:47], v[176:179], v[212:215], v[44:47]
	v_mfma_f32_16x16x32_bf16 v[36:39], v[168:171], v[220:223], v[36:39]
	v_mfma_f32_16x16x32_bf16 v[28:31], v[176:179], v[220:223], v[28:31]
	v_mfma_f32_16x16x32_bf16 v[20:23], v[168:171], v[228:231], v[20:23]
	v_mfma_f32_16x16x32_bf16 v[12:15], v[176:179], v[228:231], v[12:15]
	s_setprio 0
	s_setprio 1
	v_mfma_f32_16x16x32_bf16 v[48:51], v[180:183], v[200:203], v[48:51]
	v_mfma_f32_16x16x32_bf16 v[40:43], v[192:195], v[200:203], v[40:43]
	v_mfma_f32_16x16x32_bf16 v[32:35], v[180:183], v[208:211], v[32:35]
	v_mfma_f32_16x16x32_bf16 v[24:27], v[192:195], v[208:211], v[24:27]
	v_mfma_f32_16x16x32_bf16 v[16:19], v[180:183], v[216:219], v[16:19]
	v_mfma_f32_16x16x32_bf16 v[8:11], v[192:195], v[216:219], v[8:11]
	v_mfma_f32_16x16x32_bf16 v[4:7], v[180:183], v[224:227], v[4:7]
	v_mfma_f32_16x16x32_bf16 v[0:3], v[192:195], v[224:227], v[0:3]
	v_mfma_f32_16x16x32_bf16 v[48:51], v[184:187], v[204:207], v[48:51]
	v_mfma_f32_16x16x32_bf16 v[40:43], v[196:199], v[204:207], v[40:43]
	v_mfma_f32_16x16x32_bf16 v[32:35], v[184:187], v[212:215], v[32:35]
	v_mfma_f32_16x16x32_bf16 v[24:27], v[196:199], v[212:215], v[24:27]
	v_mfma_f32_16x16x32_bf16 v[16:19], v[184:187], v[220:223], v[16:19]
	v_mfma_f32_16x16x32_bf16 v[8:11], v[196:199], v[220:223], v[8:11]
	v_mfma_f32_16x16x32_bf16 v[4:7], v[184:187], v[228:231], v[4:7]
	v_mfma_f32_16x16x32_bf16 v[0:3], v[196:199], v[228:231], v[0:3]
	s_setprio 0
	s_barrier
	s_cmp_gt_u32 s94, 29
	s_cbranch_scc0 .LBB0_98
	s_branch .Lpeel_exit_0
.LBB0_98:
	ds_read_b128 v[164:167], v154
	ds_read_b128 v[168:171], v154 offset:1024
	ds_read_b128 v[172:175], v154 offset:2048
	ds_read_b128 v[176:179], v154 offset:3072
	ds_read_b128 v[180:183], v155
	ds_read_b128 v[184:187], v155 offset:1024
	ds_read_b128 v[192:195], v155 offset:2048
	ds_read_b128 v[196:199], v155 offset:3072
	s_add_u32 s6, s4, 0xfff80080
	s_addc_u32 s7, s5, -1
	s_cmp_eq_u32 s94, 28
	s_cselect_b32 s93, s81, s7
	s_cselect_b32 s92, s80, s6
	s_cselect_b32 s7, s85, s58
	s_cselect_b32 s6, s84, s15
	v_lshl_add_u64 v[158:159], s[4:5], 0, v[148:149]
	s_add_i32 m0, s19, 0xc000
	ds_read_b128 v[200:203], v156
	ds_read_b128 v[204:207], v156 offset:1024
	ds_read_b128 v[208:211], v156 offset:2048
	ds_read_b128 v[212:215], v156 offset:3072
	ds_read_b128 v[216:219], v156 offset:4096
	ds_read_b128 v[220:223], v156 offset:5120
	ds_read_b128 v[224:227], v156 offset:6144
	ds_read_b128 v[228:231], v156 offset:7168
	global_load_lds_dwordx4 v[158:159], off
	v_lshl_add_u64 v[158:159], s[4:5], 0, v[150:151]
	s_add_i32 m0, s19, 0xe000
	s_nop 0
	global_load_lds_dwordx4 v[158:159], off
	s_waitcnt vmcnt(8)
	s_waitcnt lgkmcnt(0)
	s_barrier
; #define PG8_STAGE(bufoff, gbase, voff) do { _Pragma("unroll") for (int _i = 0; _i < 2; ++_i) \
;         __builtin_amdgcn_global_load_lds((const unsigned*)((const char*)(gbase) + (voff)[_i]), (LAS unsigned*)(lds + (bufoff) + ldsw + _i * 8192), 16, 0, 0); } while (0)
; #define PG8_LDA(dst, b, h) do { _Pragma("unroll") for (int m = 0; m < 4; ++m) _Pragma("unroll") for (int k = 0; k < 2; ++k) dst[m][k] = *(const LAS bf16x8*)(lds + PG8_SA(b, h) + aoff + m * 2048 + k * 1024); } while (0)
; #define PG8_MMA(ai, bj, At, Bt) do { __builtin_amdgcn_s_setprio(1); _Pragma("unroll") for (int m = 0; m < 4; ++m) _Pragma("unroll") for (int n = 0; n < 2; ++n) _Pragma("unroll") for (int k = 0; k < 2; ++k) \
;         acc[ai][bj][m][n] = __builtin_amdgcn_mfma_f32_16x16x32_bf16(Bt[n][k], At[m][k], acc[ai][bj][m][n], 0, 0, 0); __builtin_amdgcn_s_setprio(0); } while (0)
; #define PG8_WAIT_V(n) asm volatile("s_waitcnt vmcnt(" #n ")" ::: "memory")
; #define PG8_WAIT_L(n) asm volatile("s_waitcnt lgkmcnt(" #n ")" ::: "memory")
; #define PG8_BAR __builtin_amdgcn_s_barrier()
; #define PG8_SCHED __builtin_amdgcn_sched_barrier(0)
; template <int GI>
; __device__ __forceinline__ void gemm_phase(LAS unsigned char* lds, unsigned char* ws, int G, int cblk) {
;     ...
;             PG8_WAIT_V(8); PG8_WAIT_L(0); PG8_BAR; PG8_MMA(0, 0, At, B0); PG8_MMA(0, 1, At, B1); PG8_BAR; PG8_SCHED;
;             PG8_LDA(At, 0, 1); PG8_STAGE(PG8_SB(0, 0), b2, voffB); PG8_STAGE(PG8_SB(0, 1), b2 + hstepB, voffB); PG8_STAGE(PG8_SA(0, 0), a2, voffA);
;             PG8_WAIT_V(8); PG8_WAIT_L(0); PG8_BAR; PG8_MMA(1, 0, At, B0); PG8_MMA(1, 1, At, B1); PG8_BAR; PG8_SCHED;
	s_setprio 1
	s_waitcnt lgkmcnt(0)
	v_mfma_f32_16x16x32_bf16 v[124:127], v[164:167], v[200:203], v[124:127]
	v_mfma_f32_16x16x32_bf16 v[120:123], v[172:175], v[200:203], v[120:123]
	v_mfma_f32_16x16x32_bf16 v[112:115], v[164:167], v[208:211], v[112:115]
	v_mfma_f32_16x16x32_bf16 v[104:107], v[172:175], v[208:211], v[104:107]
	v_mfma_f32_16x16x32_bf16 v[96:99], v[164:167], v[216:219], v[96:99]
	v_mfma_f32_16x16x32_bf16 v[88:91], v[172:175], v[216:219], v[88:91]
	v_mfma_f32_16x16x32_bf16 v[80:83], v[164:167], v[224:227], v[80:83]
	v_mfma_f32_16x16x32_bf16 v[72:75], v[172:175], v[224:227], v[72:75]
	v_mfma_f32_16x16x32_bf16 v[124:127], v[168:171], v[204:207], v[124:127]
	v_mfma_f32_16x16x32_bf16 v[120:123], v[176:179], v[204:207], v[120:123]
	v_mfma_f32_16x16x32_bf16 v[112:115], v[168:171], v[212:215], v[112:115]
	v_mfma_f32_16x16x32_bf16 v[104:107], v[176:179], v[212:215], v[104:107]
	v_mfma_f32_16x16x32_bf16 v[96:99], v[168:171], v[220:223], v[96:99]
	v_mfma_f32_16x16x32_bf16 v[88:91], v[176:179], v[220:223], v[88:91]
	v_mfma_f32_16x16x32_bf16 v[80:83], v[168:171], v[228:231], v[80:83]
	v_mfma_f32_16x16x32_bf16 v[72:75], v[176:179], v[228:231], v[72:75]
	s_setprio 0
	s_setprio 1
	v_mfma_f32_16x16x32_bf16 v[116:119], v[180:183], v[200:203], v[116:119]
	v_mfma_f32_16x16x32_bf16 v[108:111], v[192:195], v[200:203], v[108:111]
	v_mfma_f32_16x16x32_bf16 v[100:103], v[180:183], v[208:211], v[100:103]
	v_mfma_f32_16x16x32_bf16 v[92:95], v[192:195], v[208:211], v[92:95]
	v_mfma_f32_16x16x32_bf16 v[84:87], v[180:183], v[216:219], v[84:87]
	v_mfma_f32_16x16x32_bf16 v[76:79], v[192:195], v[216:219], v[76:79]
	v_mfma_f32_16x16x32_bf16 v[68:71], v[180:183], v[224:227], v[68:71]
	v_mfma_f32_16x16x32_bf16 v[64:67], v[192:195], v[224:227], v[64:67]
	v_mfma_f32_16x16x32_bf16 v[116:119], v[184:187], v[204:207], v[116:119]
	v_mfma_f32_16x16x32_bf16 v[108:111], v[196:199], v[204:207], v[108:111]
	v_mfma_f32_16x16x32_bf16 v[100:103], v[184:187], v[212:215], v[100:103]
	v_mfma_f32_16x16x32_bf16 v[92:95], v[196:199], v[212:215], v[92:95]
	v_mfma_f32_16x16x32_bf16 v[84:87], v[184:187], v[220:223], v[84:87]
	v_mfma_f32_16x16x32_bf16 v[76:79], v[196:199], v[220:223], v[76:79]
	v_mfma_f32_16x16x32_bf16 v[68:71], v[184:187], v[228:231], v[68:71]
	v_mfma_f32_16x16x32_bf16 v[64:67], v[196:199], v[228:231], v[64:67]
	s_setprio 0
	s_barrier
	s_add_i32 s34, s27, s18
	v_lshl_add_u64 v[158:159], s[6:7], 0, v[130:131]
	s_mov_b32 m0, s34
	ds_read_b128 v[200:203], v156 offset:16384
	ds_read_b128 v[204:207], v156 offset:17408
	ds_read_b128 v[208:211], v156 offset:18432
	ds_read_b128 v[212:215], v156 offset:19456
	ds_read_b128 v[216:219], v156 offset:20480
	ds_read_b128 v[220:223], v156 offset:21504
	ds_read_b128 v[224:227], v156 offset:22528
	ds_read_b128 v[228:231], v156 offset:23552
	global_load_lds_dwordx4 v[158:159], off
	s_add_i32 m0, s34, 0x2000
	s_add_u32 s96, s6, 0x80000
	v_lshl_add_u64 v[188:189], s[6:7], 0, v[134:135]
	s_addc_u32 s97, s7, 0
	s_add_i32 s34, s24, s18
	global_load_lds_dwordx4 v[188:189], off
	v_lshl_add_u64 v[232:233], s[96:97], 0, v[130:131]
	s_mov_b32 m0, s34
	v_lshl_add_u64 v[234:235], s[92:93], 0, v[132:133]
	global_load_lds_dwordx4 v[232:233], off
	v_lshl_add_u64 v[232:233], s[96:97], 0, v[134:135]
	s_add_i32 m0, s34, 0x2000
	s_nop 0
	global_load_lds_dwordx4 v[232:233], off
	v_lshl_add_u64 v[232:233], s[92:93], 0, v[128:129]
	s_mov_b32 m0, s19
	s_nop 0
	global_load_lds_dwordx4 v[232:233], off
	s_mov_b32 m0, s20
	s_nop 0
	global_load_lds_dwordx4 v[234:235], off
	s_waitcnt vmcnt(8)
	s_waitcnt lgkmcnt(0)
	s_barrier
	s_setprio 1
	s_waitcnt lgkmcnt(0)
	v_mfma_f32_16x16x32_bf16 v[60:63], v[164:167], v[200:203], v[60:63]
	v_mfma_f32_16x16x32_bf16 v[56:59], v[172:175], v[200:203], v[56:59]
	v_mfma_f32_16x16x32_bf16 v[52:55], v[164:167], v[208:211], v[52:55]
	v_mfma_f32_16x16x32_bf16 v[44:47], v[172:175], v[208:211], v[44:47]
	v_mfma_f32_16x16x32_bf16 v[36:39], v[164:167], v[216:219], v[36:39]
	v_mfma_f32_16x16x32_bf16 v[28:31], v[172:175], v[216:219], v[28:31]
	v_mfma_f32_16x16x32_bf16 v[20:23], v[164:167], v[224:227], v[20:23]
	v_mfma_f32_16x16x32_bf16 v[12:15], v[172:175], v[224:227], v[12:15]
	v_mfma_f32_16x16x32_bf16 v[60:63], v[168:171], v[204:207], v[60:63]
	v_mfma_f32_16x16x32_bf16 v[56:59], v[176:179], v[204:207], v[56:59]
	v_mfma_f32_16x16x32_bf16 v[52:55], v[168:171], v[212:215], v[52:55]
	v_mfma_f32_16x16x32_bf16 v[44:47], v[176:179], v[212:215], v[44:47]
	v_mfma_f32_16x16x32_bf16 v[36:39], v[168:171], v[220:223], v[36:39]
	v_mfma_f32_16x16x32_bf16 v[28:31], v[176:179], v[220:223], v[28:31]
	v_mfma_f32_16x16x32_bf16 v[20:23], v[168:171], v[228:231], v[20:23]
	v_mfma_f32_16x16x32_bf16 v[12:15], v[176:179], v[228:231], v[12:15]
	s_setprio 0
	s_setprio 1
	v_mfma_f32_16x16x32_bf16 v[48:51], v[180:183], v[200:203], v[48:51]
	v_mfma_f32_16x16x32_bf16 v[40:43], v[192:195], v[200:203], v[40:43]
	v_mfma_f32_16x16x32_bf16 v[32:35], v[180:183], v[208:211], v[32:35]
	v_mfma_f32_16x16x32_bf16 v[24:27], v[192:195], v[208:211], v[24:27]
	v_mfma_f32_16x16x32_bf16 v[16:19], v[180:183], v[216:219], v[16:19]
	v_mfma_f32_16x16x32_bf16 v[8:11], v[192:195], v[216:219], v[8:11]
	v_mfma_f32_16x16x32_bf16 v[4:7], v[180:183], v[224:227], v[4:7]
	v_mfma_f32_16x16x32_bf16 v[0:3], v[192:195], v[224:227], v[0:3]
	v_mfma_f32_16x16x32_bf16 v[48:51], v[184:187], v[204:207], v[48:51]
	v_mfma_f32_16x16x32_bf16 v[40:43], v[196:199], v[204:207], v[40:43]
	v_mfma_f32_16x16x32_bf16 v[32:35], v[184:187], v[212:215], v[32:35]
	v_mfma_f32_16x16x32_bf16 v[24:27], v[196:199], v[212:215], v[24:27]
	v_mfma_f32_16x16x32_bf16 v[16:19], v[184:187], v[220:223], v[16:19]
	v_mfma_f32_16x16x32_bf16 v[8:11], v[196:199], v[220:223], v[8:11]
	v_mfma_f32_16x16x32_bf16 v[4:7], v[184:187], v[228:231], v[4:7]
	v_mfma_f32_16x16x32_bf16 v[0:3], v[196:199], v[228:231], v[0:3]
	s_setprio 0
	s_barrier
; #define PG8_STAGE(bufoff, gbase, voff) do { _Pragma("unroll") for (int _i = 0; _i < 2; ++_i) \
;         __builtin_amdgcn_global_load_lds((const unsigned*)((const char*)(gbase) + (voff)[_i]), (LAS unsigned*)(lds + (bufoff) + ldsw + _i * 8192), 16, 0, 0); } while (0)
; #define PG8_LDA(dst, b, h) do { _Pragma("unroll") for (int m = 0; m < 4; ++m) _Pragma("unroll") for (int k = 0; k < 2; ++k) dst[m][k] = *(const LAS bf16x8*)(lds + PG8_SA(b, h) + aoff + m * 2048 + k * 1024); } while (0)
; #define PG8_LDB(dst, b, h) do { _Pragma("unroll") for (int n = 0; n < 2; ++n) _Pragma("unroll") for (int k = 0; k < 2; ++k) dst[n][k] = *(const LAS bf16x8*)(lds + PG8_SB(b, h) + boff + n * 2048 + k * 1024); } while (0)
; #define PG8_MMA(ai, bj, At, Bt) do { __builtin_amdgcn_s_setprio(1); _Pragma("unroll") for (int m = 0; m < 4; ++m) _Pragma("unroll") for (int n = 0; n < 2; ++n) _Pragma("unroll") for (int k = 0; k < 2; ++k) \
;         acc[ai][bj][m][n] = __builtin_amdgcn_mfma_f32_16x16x32_bf16(Bt[n][k], At[m][k], acc[ai][bj][m][n], 0, 0, 0); __builtin_amdgcn_s_setprio(0); } while (0)
; #define PG8_WAIT_V(n) asm volatile("s_waitcnt vmcnt(" #n ")" ::: "memory")
; #define PG8_WAIT_L(n) asm volatile("s_waitcnt lgkmcnt(" #n ")" ::: "memory")
; #define PG8_BAR __builtin_amdgcn_s_barrier()
; #define PG8_SCHED __builtin_amdgcn_sched_barrier(0)
; template <int GI>
; __device__ __forceinline__ void gemm_phase(LAS unsigned char* lds, unsigned char* ws, int G, int cblk) {
;     ...
;             PG8_LDB(B0, 1, 0); PG8_LDB(B1, 1, 1); PG8_SCHED; PG8_LDA(At, 1, 0); PG8_STAGE(PG8_SA(0, 1), a2 + hstepA, voffA);
;             PG8_WAIT_V(8); PG8_WAIT_L(0); PG8_BAR; PG8_MMA(0, 0, At, B0); PG8_MMA(0, 1, At, B1); PG8_BAR; PG8_SCHED;
	s_add_i32 s34, 0, 0x18000
	v_add_u32_e32 v161, s34, v153
	s_add_i32 s95, 0, 0x1c000
	ds_read_b128 v[164:167], v161
	ds_read_b128 v[168:171], v161 offset:1024
	ds_read_b128 v[172:175], v161 offset:2048
	ds_read_b128 v[176:179], v161 offset:3072
	v_add_u32_e32 v161, s95, v153
	ds_read_b128 v[180:183], v161
	ds_read_b128 v[184:187], v161 offset:1024
	ds_read_b128 v[192:195], v161 offset:2048
	ds_read_b128 v[196:199], v161 offset:3072
	s_add_u32 s92, s92, 0x80000
	s_addc_u32 s93, s93, 0
	s_mov_b32 m0, s21
	v_lshl_add_u64 v[236:237], s[92:93], 0, v[128:129]
	ds_read_b128 v[200:203], v156 offset:32768
	ds_read_b128 v[204:207], v156 offset:33792
	ds_read_b128 v[208:211], v156 offset:34816
	ds_read_b128 v[212:215], v156 offset:35840
	ds_read_b128 v[216:219], v156 offset:36864
	ds_read_b128 v[220:223], v156 offset:37888
	ds_read_b128 v[224:227], v156 offset:38912
	ds_read_b128 v[228:231], v156 offset:39936
	global_load_lds_dwordx4 v[236:237], off
	v_lshl_add_u64 v[236:237], s[92:93], 0, v[132:133]
	s_mov_b32 m0, s35
	s_nop 0
	global_load_lds_dwordx4 v[236:237], off
	s_waitcnt vmcnt(8)
	s_waitcnt lgkmcnt(0)
	s_barrier
	s_setprio 1
	s_waitcnt lgkmcnt(0)
	v_mfma_f32_16x16x32_bf16 v[124:127], v[164:167], v[200:203], v[124:127]
	v_mfma_f32_16x16x32_bf16 v[120:123], v[172:175], v[200:203], v[120:123]
	v_mfma_f32_16x16x32_bf16 v[112:115], v[164:167], v[208:211], v[112:115]
	v_mfma_f32_16x16x32_bf16 v[104:107], v[172:175], v[208:211], v[104:107]
	v_mfma_f32_16x16x32_bf16 v[96:99], v[164:167], v[216:219], v[96:99]
	v_mfma_f32_16x16x32_bf16 v[88:91], v[172:175], v[216:219], v[88:91]
	v_mfma_f32_16x16x32_bf16 v[80:83], v[164:167], v[224:227], v[80:83]
	v_mfma_f32_16x16x32_bf16 v[72:75], v[172:175], v[224:227], v[72:75]
	v_mfma_f32_16x16x32_bf16 v[124:127], v[168:171], v[204:207], v[124:127]
	v_mfma_f32_16x16x32_bf16 v[120:123], v[176:179], v[204:207], v[120:123]
	v_mfma_f32_16x16x32_bf16 v[112:115], v[168:171], v[212:215], v[112:115]
	v_mfma_f32_16x16x32_bf16 v[104:107], v[176:179], v[212:215], v[104:107]
	v_mfma_f32_16x16x32_bf16 v[96:99], v[168:171], v[220:223], v[96:99]
	v_mfma_f32_16x16x32_bf16 v[88:91], v[176:179], v[220:223], v[88:91]
	v_mfma_f32_16x16x32_bf16 v[80:83], v[168:171], v[228:231], v[80:83]
	v_mfma_f32_16x16x32_bf16 v[72:75], v[176:179], v[228:231], v[72:75]
	s_setprio 0
	s_setprio 1
	v_mfma_f32_16x16x32_bf16 v[116:119], v[180:183], v[200:203], v[116:119]
	v_mfma_f32_16x16x32_bf16 v[108:111], v[192:195], v[200:203], v[108:111]
	v_mfma_f32_16x16x32_bf16 v[100:103], v[180:183], v[208:211], v[100:103]
	v_mfma_f32_16x16x32_bf16 v[92:95], v[192:195], v[208:211], v[92:95]
	v_mfma_f32_16x16x32_bf16 v[84:87], v[180:183], v[216:219], v[84:87]
	v_mfma_f32_16x16x32_bf16 v[76:79], v[192:195], v[216:219], v[76:79]
	v_mfma_f32_16x16x32_bf16 v[68:71], v[180:183], v[224:227], v[68:71]
	v_mfma_f32_16x16x32_bf16 v[64:67], v[192:195], v[224:227], v[64:67]
	v_mfma_f32_16x16x32_bf16 v[116:119], v[184:187], v[204:207], v[116:119]
	v_mfma_f32_16x16x32_bf16 v[108:111], v[196:199], v[204:207], v[108:111]
	v_mfma_f32_16x16x32_bf16 v[100:103], v[184:187], v[212:215], v[100:103]
	v_mfma_f32_16x16x32_bf16 v[92:95], v[196:199], v[212:215], v[92:95]
	v_mfma_f32_16x16x32_bf16 v[84:87], v[184:187], v[220:223], v[84:87]
	v_mfma_f32_16x16x32_bf16 v[76:79], v[196:199], v[220:223], v[76:79]
	v_mfma_f32_16x16x32_bf16 v[68:71], v[184:187], v[228:231], v[68:71]
	v_mfma_f32_16x16x32_bf16 v[64:67], v[196:199], v[228:231], v[64:67]
	s_setprio 0
	s_barrier
; #define PG8_STAGE(bufoff, gbase, voff) do { _Pragma("unroll") for (int _i = 0; _i < 2; ++_i) \
;         __builtin_amdgcn_global_load_lds((const unsigned*)((const char*)(gbase) + (voff)[_i]), (LAS unsigned*)(lds + (bufoff) + ldsw + _i * 8192), 16, 0, 0); } while (0)
; #define PG8_LDA(dst, b, h) do { _Pragma("unroll") for (int m = 0; m < 4; ++m) _Pragma("unroll") for (int k = 0; k < 2; ++k) dst[m][k] = *(const LAS bf16x8*)(lds + PG8_SA(b, h) + aoff + m * 2048 + k * 1024); } while (0)
; #define PG8_MMA(ai, bj, At, Bt) do { __builtin_amdgcn_s_setprio(1); _Pragma("unroll") for (int m = 0; m < 4; ++m) _Pragma("unroll") for (int n = 0; n < 2; ++n) _Pragma("unroll") for (int k = 0; k < 2; ++k) \
;         acc[ai][bj][m][n] = __builtin_amdgcn_mfma_f32_16x16x32_bf16(Bt[n][k], At[m][k], acc[ai][bj][m][n], 0, 0, 0); __builtin_amdgcn_s_setprio(0); } while (0)
; #define PG8_WAIT_V(n) asm volatile("s_waitcnt vmcnt(" #n ")" ::: "memory")
; #define PG8_WAIT_L(n) asm volatile("s_waitcnt lgkmcnt(" #n ")" ::: "memory")
; #define PG8_BAR __builtin_amdgcn_s_barrier()
; #define PG8_SCHED __builtin_amdgcn_sched_barrier(0)
; template <int GI>
; __device__ __forceinline__ void gemm_phase(LAS unsigned char* lds, unsigned char* ws, int G, int cblk) {
;     ...
;             PG8_LDA(At, 1, 1); PG8_STAGE(PG8_SB(1, 0), b3, voffB); PG8_STAGE(PG8_SB(1, 1), b3 + hstepB, voffB); PG8_STAGE(PG8_SA(1, 0), a3, voffA);
;             PG8_WAIT_V(8); PG8_WAIT_L(0); PG8_BAR; PG8_MMA(1, 0, At, B0); PG8_MMA(1, 1, At, B1); PG8_BAR; PG8_SCHED;
;         }
	s_add_i32 s34, s34, s18
	v_lshl_add_u64 v[158:159], v[158:159], 0, s[70:71]
	s_mov_b32 m0, s34
	ds_read_b128 v[200:203], v156 offset:49152
	ds_read_b128 v[204:207], v156 offset:50176
	ds_read_b128 v[208:211], v156 offset:51200
	ds_read_b128 v[212:215], v156 offset:52224
	ds_read_b128 v[216:219], v156 offset:53248
	ds_read_b128 v[220:223], v156 offset:54272
	ds_read_b128 v[224:227], v156 offset:55296
	ds_read_b128 v[228:231], v156 offset:56320
	global_load_lds_dwordx4 v[158:159], off
	s_add_i32 m0, s34, 0x2000
	s_add_u32 s6, s6, 0x80080
	v_lshl_add_u64 v[158:159], v[188:189], 0, s[70:71]
	s_addc_u32 s7, s7, 0
	s_add_i32 s34, s95, s18
	global_load_lds_dwordx4 v[158:159], off
	v_lshl_add_u64 v[158:159], s[6:7], 0, v[130:131]
	s_mov_b32 m0, s34
	s_nop 0
	global_load_lds_dwordx4 v[158:159], off
	v_lshl_add_u64 v[158:159], s[6:7], 0, v[134:135]
	s_add_i32 m0, s34, 0x2000
	s_nop 0
	global_load_lds_dwordx4 v[158:159], off
	v_lshl_add_u64 v[158:159], v[232:233], 0, s[70:71]
	s_mov_b32 m0, s0
	s_nop 0
	global_load_lds_dwordx4 v[158:159], off
	v_lshl_add_u64 v[158:159], v[234:235], 0, s[70:71]
	s_mov_b32 m0, s1
	s_nop 0
	global_load_lds_dwordx4 v[158:159], off
	s_waitcnt vmcnt(8)
	s_waitcnt lgkmcnt(0)
	s_barrier
	s_setprio 1
	s_waitcnt lgkmcnt(0)
	v_mfma_f32_16x16x32_bf16 v[60:63], v[164:167], v[200:203], v[60:63]
	v_mfma_f32_16x16x32_bf16 v[56:59], v[172:175], v[200:203], v[56:59]
	s_add_i32 s94, s94, 2
	s_add_u32 s4, s4, 0x100
	s_addc_u32 s5, s5, 0
	s_add_u32 s15, s15, 0x100
	s_addc_u32 s58, s58, 0
	v_mfma_f32_16x16x32_bf16 v[52:55], v[164:167], v[208:211], v[52:55]
	v_mfma_f32_16x16x32_bf16 v[44:47], v[172:175], v[208:211], v[44:47]
	v_mfma_f32_16x16x32_bf16 v[36:39], v[164:167], v[216:219], v[36:39]
	v_mfma_f32_16x16x32_bf16 v[28:31], v[172:175], v[216:219], v[28:31]
	v_mfma_f32_16x16x32_bf16 v[20:23], v[164:167], v[224:227], v[20:23]
	v_mfma_f32_16x16x32_bf16 v[12:15], v[172:175], v[224:227], v[12:15]
	v_mfma_f32_16x16x32_bf16 v[60:63], v[168:171], v[204:207], v[60:63]
	v_mfma_f32_16x16x32_bf16 v[56:59], v[176:179], v[204:207], v[56:59]
	v_mfma_f32_16x16x32_bf16 v[52:55], v[168:171], v[212:215], v[52:55]
	v_mfma_f32_16x16x32_bf16 v[44:47], v[176:179], v[212:215], v[44:47]
	v_mfma_f32_16x16x32_bf16 v[36:39], v[168:171], v[220:223], v[36:39]
	v_mfma_f32_16x16x32_bf16 v[28:31], v[176:179], v[220:223], v[28:31]
	v_mfma_f32_16x16x32_bf16 v[20:23], v[168:171], v[228:231], v[20:23]
	v_mfma_f32_16x16x32_bf16 v[12:15], v[176:179], v[228:231], v[12:15]
	s_setprio 0
	s_setprio 1
	v_mfma_f32_16x16x32_bf16 v[48:51], v[180:183], v[200:203], v[48:51]
	v_mfma_f32_16x16x32_bf16 v[40:43], v[192:195], v[200:203], v[40:43]
	v_mfma_f32_16x16x32_bf16 v[32:35], v[180:183], v[208:211], v[32:35]
	v_mfma_f32_16x16x32_bf16 v[24:27], v[192:195], v[208:211], v[24:27]
	v_mfma_f32_16x16x32_bf16 v[16:19], v[180:183], v[216:219], v[16:19]
	v_mfma_f32_16x16x32_bf16 v[8:11], v[192:195], v[216:219], v[8:11]
	v_mfma_f32_16x16x32_bf16 v[4:7], v[180:183], v[224:227], v[4:7]
	v_mfma_f32_16x16x32_bf16 v[0:3], v[192:195], v[224:227], v[0:3]
	v_mfma_f32_16x16x32_bf16 v[48:51], v[184:187], v[204:207], v[48:51]
	v_mfma_f32_16x16x32_bf16 v[40:43], v[196:199], v[204:207], v[40:43]
	v_mfma_f32_16x16x32_bf16 v[32:35], v[184:187], v[212:215], v[32:35]
	v_mfma_f32_16x16x32_bf16 v[24:27], v[196:199], v[212:215], v[24:27]
	v_mfma_f32_16x16x32_bf16 v[16:19], v[184:187], v[220:223], v[16:19]
	v_mfma_f32_16x16x32_bf16 v[8:11], v[196:199], v[220:223], v[8:11]
	v_mfma_f32_16x16x32_bf16 v[4:7], v[184:187], v[228:231], v[4:7]
	v_mfma_f32_16x16x32_bf16 v[0:3], v[196:199], v[228:231], v[0:3]
	s_setprio 0
	s_barrier
	s_cmp_gt_u32 s94, 29
	s_cbranch_scc0 .LBB0_98

; #define PG8_STAGE(bufoff, gbase, voff) do { _Pragma("unroll") for (int _i = 0; _i < 2; ++_i) \
;         __builtin_amdgcn_global_load_lds((const unsigned*)((const char*)(gbase) + (voff)[_i]), (LAS unsigned*)(lds + (bufoff) + ldsw + _i * 8192), 16, 0, 0); } while (0)
; #define PG8_LDA(dst, b, h) do { _Pragma("unroll") for (int m = 0; m < 4; ++m) _Pragma("unroll") for (int k = 0; k < 2; ++k) dst[m][k] = *(const LAS bf16x8*)(lds + PG8_SA(b, h) + aoff + m * 2048 + k * 1024); } while (0)
; #define PG8_LDB(dst, b, h) do { _Pragma("unroll") for (int n = 0; n < 2; ++n) _Pragma("unroll") for (int k = 0; k < 2; ++k) dst[n][k] = *(const LAS bf16x8*)(lds + PG8_SB(b, h) + boff + n * 2048 + k * 1024); } while (0)
; #define PG8_MMA(ai, bj, At, Bt) do { __builtin_amdgcn_s_setprio(1); _Pragma("unroll") for (int m = 0; m < 4; ++m) _Pragma("unroll") for (int n = 0; n < 2; ++n) _Pragma("unroll") for (int k = 0; k < 2; ++k) \
;         acc[ai][bj][m][n] = __builtin_amdgcn_mfma_f32_16x16x32_bf16(Bt[n][k], At[m][k], acc[ai][bj][m][n], 0, 0, 0); __builtin_amdgcn_s_setprio(0); } while (0)
; #define PG8_WAIT_V(n) asm volatile("s_waitcnt vmcnt(" #n ")" ::: "memory")
; #define PG8_WAIT_L(n) asm volatile("s_waitcnt lgkmcnt(" #n ")" ::: "memory")
; #define PG8_BAR __builtin_amdgcn_s_barrier()
; #define PG8_SCHED __builtin_amdgcn_sched_barrier(0)
; template <int GI>
; __device__ __forceinline__ void gemm_phase(LAS unsigned char* lds, unsigned char* ws, int G, int cblk) {
;     ...
;         for (int t = 0; t < nt; t += 2) {
;             const bool last = (t == nt - 2);
;             const char* a1 = cA + (size_t)(t + 1) * kstep;
;             const char* a2 = last ? nA : cA + (size_t)(t + 2) * kstep; const char* b2 = last ? nB : cB + (size_t)(t + 2) * kstep;
;             const char* a3 = a2 + kstep; const char* b3 = b2 + kstep;
;             PG8_LDB(B0, 0, 0); PG8_LDB(B1, 0, 1); PG8_SCHED; PG8_LDA(At, 0, 0); PG8_STAGE(PG8_SA(1, 1), a1 + hstepA, voffA);
;             PG8_WAIT_V(8); PG8_WAIT_L(0); PG8_BAR; PG8_MMA(0, 0, At, B0); PG8_MMA(0, 1, At, B1); PG8_BAR; PG8_SCHED;
;             PG8_LDA(At, 0, 1); PG8_STAGE(PG8_SB(0, 0), b2, voffB); PG8_STAGE(PG8_SB(0, 1), b2 + hstepB, voffB); PG8_STAGE(PG8_SA(0, 0), a2, voffA);
;             PG8_WAIT_V(8); PG8_WAIT_L(0); PG8_BAR; PG8_MMA(1, 0, At, B0); PG8_MMA(1, 1, At, B1); PG8_BAR; PG8_SCHED;
.LBB0_123:
	s_add_u32 s86, s86, 0x80080
	s_addc_u32 s87, s87, 0
	s_add_u32 s4, s88, 0x100
	s_addc_u32 s14, s89, 0
	s_mov_b32 s15, -2
	ds_read_b128 v[154:157], v151
	ds_read_b128 v[164:167], v151 offset:1024
	ds_read_b128 v[168:171], v151 offset:2048
	ds_read_b128 v[172:175], v151 offset:3072
	ds_read_b128 v[176:179], v152
	ds_read_b128 v[180:183], v152 offset:1024
	ds_read_b128 v[184:187], v152 offset:2048
	ds_read_b128 v[192:195], v152 offset:3072
	s_add_u32 s34, s86, 0xfff80080
	s_addc_u32 s63, s87, -1
	s_cmp_eq_u32 s15, 28
	s_cselect_b32 s91, s75, s63
	s_cselect_b32 s90, s74, s34
	s_cselect_b32 s89, s77, s14
	s_cselect_b32 s88, s76, s4
	v_lshl_add_u64 v[158:159], s[86:87], 0, v[146:147]
	s_add_i32 m0, s16, 0xc000
	ds_read_b128 v[196:199], v153
	ds_read_b128 v[200:203], v153 offset:1024
	ds_read_b128 v[204:207], v153 offset:2048
	ds_read_b128 v[208:211], v153 offset:3072
	ds_read_b128 v[212:215], v153 offset:4096
	ds_read_b128 v[216:219], v153 offset:5120
	ds_read_b128 v[220:223], v153 offset:6144
	ds_read_b128 v[224:227], v153 offset:7168
	global_load_lds_dwordx4 v[158:159], off
	v_lshl_add_u64 v[158:159], s[86:87], 0, v[148:149]
	s_add_i32 m0, s16, 0xe000
	s_nop 0
	global_load_lds_dwordx4 v[158:159], off
	s_waitcnt vmcnt(8)
	s_waitcnt lgkmcnt(0)
	s_barrier
	s_setprio 1
	s_waitcnt lgkmcnt(0)
	v_mfma_f32_16x16x32_bf16 v[124:127], v[154:157], v[196:199], 0
	v_mfma_f32_16x16x32_bf16 v[120:123], v[168:171], v[196:199], 0
	v_mfma_f32_16x16x32_bf16 v[116:119], v[154:157], v[204:207], 0
	v_mfma_f32_16x16x32_bf16 v[108:111], v[168:171], v[204:207], 0
	v_mfma_f32_16x16x32_bf16 v[100:103], v[154:157], v[212:215], 0
	v_mfma_f32_16x16x32_bf16 v[92:95], v[168:171], v[212:215], 0
	v_mfma_f32_16x16x32_bf16 v[84:87], v[154:157], v[220:223], 0
	v_mfma_f32_16x16x32_bf16 v[76:79], v[168:171], v[220:223], 0
	v_mfma_f32_16x16x32_bf16 v[124:127], v[164:167], v[200:203], v[124:127]
	v_mfma_f32_16x16x32_bf16 v[120:123], v[172:175], v[200:203], v[120:123]
	v_mfma_f32_16x16x32_bf16 v[116:119], v[164:167], v[208:211], v[116:119]
	v_mfma_f32_16x16x32_bf16 v[108:111], v[172:175], v[208:211], v[108:111]
	v_mfma_f32_16x16x32_bf16 v[100:103], v[164:167], v[216:219], v[100:103]
	v_mfma_f32_16x16x32_bf16 v[92:95], v[172:175], v[216:219], v[92:95]
	v_mfma_f32_16x16x32_bf16 v[84:87], v[164:167], v[224:227], v[84:87]
	v_mfma_f32_16x16x32_bf16 v[76:79], v[172:175], v[224:227], v[76:79]
	s_setprio 0
	s_setprio 1
	v_mfma_f32_16x16x32_bf16 v[112:115], v[176:179], v[196:199], 0
	v_mfma_f32_16x16x32_bf16 v[104:107], v[184:187], v[196:199], 0
	v_mfma_f32_16x16x32_bf16 v[96:99], v[176:179], v[204:207], 0
	v_mfma_f32_16x16x32_bf16 v[88:91], v[184:187], v[204:207], 0
	v_mfma_f32_16x16x32_bf16 v[80:83], v[176:179], v[212:215], 0
	v_mfma_f32_16x16x32_bf16 v[72:75], v[184:187], v[212:215], 0
	v_mfma_f32_16x16x32_bf16 v[68:71], v[176:179], v[220:223], 0
	v_mfma_f32_16x16x32_bf16 v[64:67], v[184:187], v[220:223], 0
	v_mfma_f32_16x16x32_bf16 v[112:115], v[180:183], v[200:203], v[112:115]
	v_mfma_f32_16x16x32_bf16 v[104:107], v[192:195], v[200:203], v[104:107]
	v_mfma_f32_16x16x32_bf16 v[96:99], v[180:183], v[208:211], v[96:99]
	v_mfma_f32_16x16x32_bf16 v[88:91], v[192:195], v[208:211], v[88:91]
	v_mfma_f32_16x16x32_bf16 v[80:83], v[180:183], v[216:219], v[80:83]
	v_mfma_f32_16x16x32_bf16 v[72:75], v[192:195], v[216:219], v[72:75]
	v_mfma_f32_16x16x32_bf16 v[68:71], v[180:183], v[224:227], v[68:71]
	v_mfma_f32_16x16x32_bf16 v[64:67], v[192:195], v[224:227], v[64:67]
	s_setprio 0
	s_barrier
	s_add_i32 s34, s25, s0
	v_lshl_add_u64 v[158:159], s[88:89], 0, v[130:131]
	s_mov_b32 m0, s34
	ds_read_b128 v[196:199], v153 offset:16384
	ds_read_b128 v[200:203], v153 offset:17408
	ds_read_b128 v[204:207], v153 offset:18432
	ds_read_b128 v[208:211], v153 offset:19456
	ds_read_b128 v[212:215], v153 offset:20480
	ds_read_b128 v[216:219], v153 offset:21504
	ds_read_b128 v[220:223], v153 offset:22528
	ds_read_b128 v[224:227], v153 offset:23552
	global_load_lds_dwordx4 v[158:159], off
	s_add_i32 m0, s34, 0x2000
	s_add_u32 s92, s88, 0x80000
	v_lshl_add_u64 v[188:189], s[88:89], 0, v[134:135]
	s_addc_u32 s93, s89, 0
	s_add_i32 s34, s26, s0
	global_load_lds_dwordx4 v[188:189], off
	v_lshl_add_u64 v[228:229], s[92:93], 0, v[130:131]
	s_mov_b32 m0, s34
	v_lshl_add_u64 v[230:231], s[90:91], 0, v[132:133]
	global_load_lds_dwordx4 v[228:229], off
	v_lshl_add_u64 v[228:229], s[92:93], 0, v[134:135]
	s_add_i32 m0, s34, 0x2000
	s_nop 0
	global_load_lds_dwordx4 v[228:229], off
	v_lshl_add_u64 v[228:229], s[90:91], 0, v[128:129]
	s_mov_b32 m0, s16
	s_nop 0
	global_load_lds_dwordx4 v[228:229], off
	s_mov_b32 m0, s17
	s_nop 0
	global_load_lds_dwordx4 v[230:231], off
	s_waitcnt vmcnt(8)
	s_waitcnt lgkmcnt(0)
	s_barrier
; #define PG8_STAGE(bufoff, gbase, voff) do { _Pragma("unroll") for (int _i = 0; _i < 2; ++_i) \
;         __builtin_amdgcn_global_load_lds((const unsigned*)((const char*)(gbase) + (voff)[_i]), (LAS unsigned*)(lds + (bufoff) + ldsw + _i * 8192), 16, 0, 0); } while (0)
; #define PG8_LDA(dst, b, h) do { _Pragma("unroll") for (int m = 0; m < 4; ++m) _Pragma("unroll") for (int k = 0; k < 2; ++k) dst[m][k] = *(const LAS bf16x8*)(lds + PG8_SA(b, h) + aoff + m * 2048 + k * 1024); } while (0)
; #define PG8_LDB(dst, b, h) do { _Pragma("unroll") for (int n = 0; n < 2; ++n) _Pragma("unroll") for (int k = 0; k < 2; ++k) dst[n][k] = *(const LAS bf16x8*)(lds + PG8_SB(b, h) + boff + n * 2048 + k * 1024); } while (0)
; #define PG8_MMA(ai, bj, At, Bt) do { __builtin_amdgcn_s_setprio(1); _Pragma("unroll") for (int m = 0; m < 4; ++m) _Pragma("unroll") for (int n = 0; n < 2; ++n) _Pragma("unroll") for (int k = 0; k < 2; ++k) \
;         acc[ai][bj][m][n] = __builtin_amdgcn_mfma_f32_16x16x32_bf16(Bt[n][k], At[m][k], acc[ai][bj][m][n], 0, 0, 0); __builtin_amdgcn_s_setprio(0); } while (0)
; #define PG8_WAIT_V(n) asm volatile("s_waitcnt vmcnt(" #n ")" ::: "memory")
; #define PG8_WAIT_L(n) asm volatile("s_waitcnt lgkmcnt(" #n ")" ::: "memory")
; #define PG8_BAR __builtin_amdgcn_s_barrier()
; #define PG8_SCHED __builtin_amdgcn_sched_barrier(0)
; template <int GI>
; __device__ __forceinline__ void gemm_phase(LAS unsigned char* lds, unsigned char* ws, int G, int cblk) {
;     ...
;             PG8_WAIT_V(8); PG8_WAIT_L(0); PG8_BAR; PG8_MMA(1, 0, At, B0); PG8_MMA(1, 1, At, B1); PG8_BAR; PG8_SCHED;
;             PG8_LDB(B0, 1, 0); PG8_LDB(B1, 1, 1); PG8_SCHED; PG8_LDA(At, 1, 0); PG8_STAGE(PG8_SA(0, 1), a2 + hstepA, voffA);
;             PG8_WAIT_V(8); PG8_WAIT_L(0); PG8_BAR; PG8_MMA(0, 0, At, B0); PG8_MMA(0, 1, At, B1); PG8_BAR; PG8_SCHED;
	s_setprio 1
	s_waitcnt lgkmcnt(0)
	v_mfma_f32_16x16x32_bf16 v[60:63], v[154:157], v[196:199], 0
	v_mfma_f32_16x16x32_bf16 v[56:59], v[168:171], v[196:199], 0
	v_mfma_f32_16x16x32_bf16 v[52:55], v[154:157], v[204:207], 0
	v_mfma_f32_16x16x32_bf16 v[48:51], v[168:171], v[204:207], 0
	v_mfma_f32_16x16x32_bf16 v[36:39], v[154:157], v[212:215], 0
	v_mfma_f32_16x16x32_bf16 v[32:35], v[168:171], v[212:215], 0
	v_mfma_f32_16x16x32_bf16 v[20:23], v[154:157], v[220:223], 0
	v_mfma_f32_16x16x32_bf16 v[16:19], v[168:171], v[220:223], 0
	v_mfma_f32_16x16x32_bf16 v[60:63], v[164:167], v[200:203], v[60:63]
	v_mfma_f32_16x16x32_bf16 v[56:59], v[172:175], v[200:203], v[56:59]
	v_mfma_f32_16x16x32_bf16 v[52:55], v[164:167], v[208:211], v[52:55]
	v_mfma_f32_16x16x32_bf16 v[48:51], v[172:175], v[208:211], v[48:51]
	v_mfma_f32_16x16x32_bf16 v[36:39], v[164:167], v[216:219], v[36:39]
	v_mfma_f32_16x16x32_bf16 v[32:35], v[172:175], v[216:219], v[32:35]
	v_mfma_f32_16x16x32_bf16 v[20:23], v[164:167], v[224:227], v[20:23]
	v_mfma_f32_16x16x32_bf16 v[16:19], v[172:175], v[224:227], v[16:19]
	s_setprio 0
	s_setprio 1
	v_mfma_f32_16x16x32_bf16 v[44:47], v[176:179], v[196:199], 0
	v_mfma_f32_16x16x32_bf16 v[40:43], v[184:187], v[196:199], 0
	v_mfma_f32_16x16x32_bf16 v[28:31], v[176:179], v[204:207], 0
	v_mfma_f32_16x16x32_bf16 v[24:27], v[184:187], v[204:207], 0
	v_mfma_f32_16x16x32_bf16 v[12:15], v[176:179], v[212:215], 0
	v_mfma_f32_16x16x32_bf16 v[8:11], v[184:187], v[212:215], 0
	v_mfma_f32_16x16x32_bf16 v[4:7], v[176:179], v[220:223], 0
	v_mfma_f32_16x16x32_bf16 v[0:3], v[184:187], v[220:223], 0
	v_mfma_f32_16x16x32_bf16 v[44:47], v[180:183], v[200:203], v[44:47]
	v_mfma_f32_16x16x32_bf16 v[40:43], v[192:195], v[200:203], v[40:43]
	v_mfma_f32_16x16x32_bf16 v[28:31], v[180:183], v[208:211], v[28:31]
	v_mfma_f32_16x16x32_bf16 v[24:27], v[192:195], v[208:211], v[24:27]
	v_mfma_f32_16x16x32_bf16 v[12:15], v[180:183], v[216:219], v[12:15]
	v_mfma_f32_16x16x32_bf16 v[8:11], v[192:195], v[216:219], v[8:11]
	v_mfma_f32_16x16x32_bf16 v[4:7], v[180:183], v[224:227], v[4:7]
	v_mfma_f32_16x16x32_bf16 v[0:3], v[192:195], v[224:227], v[0:3]
	s_setprio 0
	s_barrier
	s_add_i32 s34, 0, 0x18000
	v_add_u32_e32 v161, s34, v150
	s_add_i32 s63, 0, 0x1c000
	ds_read_b128 v[154:157], v161
	ds_read_b128 v[164:167], v161 offset:1024
	ds_read_b128 v[168:171], v161 offset:2048
	ds_read_b128 v[172:175], v161 offset:3072
	v_add_u32_e32 v161, s63, v150
	ds_read_b128 v[176:179], v161
	ds_read_b128 v[180:183], v161 offset:1024
	ds_read_b128 v[184:187], v161 offset:2048
	ds_read_b128 v[192:195], v161 offset:3072
	s_add_u32 s90, s90, 0x80000
	s_addc_u32 s91, s91, 0
	s_mov_b32 m0, s18
	v_lshl_add_u64 v[232:233], s[90:91], 0, v[128:129]
	ds_read_b128 v[196:199], v153 offset:32768
	ds_read_b128 v[200:203], v153 offset:33792
	ds_read_b128 v[204:207], v153 offset:34816
	ds_read_b128 v[208:211], v153 offset:35840
	ds_read_b128 v[212:215], v153 offset:36864
	ds_read_b128 v[216:219], v153 offset:37888
	ds_read_b128 v[220:223], v153 offset:38912
	ds_read_b128 v[224:227], v153 offset:39936
	global_load_lds_dwordx4 v[232:233], off
	v_lshl_add_u64 v[232:233], s[90:91], 0, v[132:133]
	s_mov_b32 m0, s19
	s_nop 0
	global_load_lds_dwordx4 v[232:233], off
	s_waitcnt vmcnt(8)
	s_waitcnt lgkmcnt(0)
	s_barrier
	s_setprio 1
	s_waitcnt lgkmcnt(0)
	v_mfma_f32_16x16x32_bf16 v[124:127], v[154:157], v[196:199], v[124:127]
	v_mfma_f32_16x16x32_bf16 v[120:123], v[168:171], v[196:199], v[120:123]
	v_mfma_f32_16x16x32_bf16 v[116:119], v[154:157], v[204:207], v[116:119]
	v_mfma_f32_16x16x32_bf16 v[108:111], v[168:171], v[204:207], v[108:111]
	v_mfma_f32_16x16x32_bf16 v[100:103], v[154:157], v[212:215], v[100:103]
	v_mfma_f32_16x16x32_bf16 v[92:95], v[168:171], v[212:215], v[92:95]
	v_mfma_f32_16x16x32_bf16 v[84:87], v[154:157], v[220:223], v[84:87]
	v_mfma_f32_16x16x32_bf16 v[76:79], v[168:171], v[220:223], v[76:79]
	v_mfma_f32_16x16x32_bf16 v[124:127], v[164:167], v[200:203], v[124:127]
	v_mfma_f32_16x16x32_bf16 v[120:123], v[172:175], v[200:203], v[120:123]
	v_mfma_f32_16x16x32_bf16 v[116:119], v[164:167], v[208:211], v[116:119]
	v_mfma_f32_16x16x32_bf16 v[108:111], v[172:175], v[208:211], v[108:111]
	v_mfma_f32_16x16x32_bf16 v[100:103], v[164:167], v[216:219], v[100:103]
	v_mfma_f32_16x16x32_bf16 v[92:95], v[172:175], v[216:219], v[92:95]
	v_mfma_f32_16x16x32_bf16 v[84:87], v[164:167], v[224:227], v[84:87]
	v_mfma_f32_16x16x32_bf16 v[76:79], v[172:175], v[224:227], v[76:79]
	s_setprio 0
	s_setprio 1
	v_mfma_f32_16x16x32_bf16 v[112:115], v[176:179], v[196:199], v[112:115]
	v_mfma_f32_16x16x32_bf16 v[104:107], v[184:187], v[196:199], v[104:107]
	v_mfma_f32_16x16x32_bf16 v[96:99], v[176:179], v[204:207], v[96:99]
	v_mfma_f32_16x16x32_bf16 v[88:91], v[184:187], v[204:207], v[88:91]
	v_mfma_f32_16x16x32_bf16 v[80:83], v[176:179], v[212:215], v[80:83]
	v_mfma_f32_16x16x32_bf16 v[72:75], v[184:187], v[212:215], v[72:75]
	v_mfma_f32_16x16x32_bf16 v[68:71], v[176:179], v[220:223], v[68:71]
	v_mfma_f32_16x16x32_bf16 v[64:67], v[184:187], v[220:223], v[64:67]
	v_mfma_f32_16x16x32_bf16 v[112:115], v[180:183], v[200:203], v[112:115]
	v_mfma_f32_16x16x32_bf16 v[104:107], v[192:195], v[200:203], v[104:107]
	v_mfma_f32_16x16x32_bf16 v[96:99], v[180:183], v[208:211], v[96:99]
	v_mfma_f32_16x16x32_bf16 v[88:91], v[192:195], v[208:211], v[88:91]
	v_mfma_f32_16x16x32_bf16 v[80:83], v[180:183], v[216:219], v[80:83]
	v_mfma_f32_16x16x32_bf16 v[72:75], v[192:195], v[216:219], v[72:75]
	v_mfma_f32_16x16x32_bf16 v[68:71], v[180:183], v[224:227], v[68:71]
	v_mfma_f32_16x16x32_bf16 v[64:67], v[192:195], v[224:227], v[64:67]
	s_setprio 0
	s_barrier
; #define PG8_STAGE(bufoff, gbase, voff) do { _Pragma("unroll") for (int _i = 0; _i < 2; ++_i) \
;         __builtin_amdgcn_global_load_lds((const unsigned*)((const char*)(gbase) + (voff)[_i]), (LAS unsigned*)(lds + (bufoff) + ldsw + _i * 8192), 16, 0, 0); } while (0)
; #define PG8_LDA(dst, b, h) do { _Pragma("unroll") for (int m = 0; m < 4; ++m) _Pragma("unroll") for (int k = 0; k < 2; ++k) dst[m][k] = *(const LAS bf16x8*)(lds + PG8_SA(b, h) + aoff + m * 2048 + k * 1024); } while (0)
; #define PG8_LDB(dst, b, h) do { _Pragma("unroll") for (int n = 0; n < 2; ++n) _Pragma("unroll") for (int k = 0; k < 2; ++k) dst[n][k] = *(const LAS bf16x8*)(lds + PG8_SB(b, h) + boff + n * 2048 + k * 1024); } while (0)
; #define PG8_MMA(ai, bj, At, Bt) do { __builtin_amdgcn_s_setprio(1); _Pragma("unroll") for (int m = 0; m < 4; ++m) _Pragma("unroll") for (int n = 0; n < 2; ++n) _Pragma("unroll") for (int k = 0; k < 2; ++k) \
;         acc[ai][bj][m][n] = __builtin_amdgcn_mfma_f32_16x16x32_bf16(Bt[n][k], At[m][k], acc[ai][bj][m][n], 0, 0, 0); __builtin_amdgcn_s_setprio(0); } while (0)
; #define PG8_WAIT_V(n) asm volatile("s_waitcnt vmcnt(" #n ")" ::: "memory")
; #define PG8_WAIT_L(n) asm volatile("s_waitcnt lgkmcnt(" #n ")" ::: "memory")
; #define PG8_BAR __builtin_amdgcn_s_barrier()
; #define PG8_SCHED __builtin_amdgcn_sched_barrier(0)
; template <int GI>
; __device__ __forceinline__ void gemm_phase(LAS unsigned char* lds, unsigned char* ws, int G, int cblk) {
;     ...
;         for (int t = 0; t < nt; t += 2) {
;             const bool last = (t == nt - 2);
;             const char* a1 = cA + (size_t)(t + 1) * kstep;
;             const char* a2 = last ? nA : cA + (size_t)(t + 2) * kstep; const char* b2 = last ? nB : cB + (size_t)(t + 2) * kstep;
;             const char* a3 = a2 + kstep; const char* b3 = b2 + kstep;
;             PG8_LDB(B0, 0, 0); PG8_LDB(B1, 0, 1); PG8_SCHED; PG8_LDA(At, 0, 0); PG8_STAGE(PG8_SA(1, 1), a1 + hstepA, voffA);
;             PG8_WAIT_V(8); PG8_WAIT_L(0); PG8_BAR; PG8_MMA(0, 0, At, B0); PG8_MMA(0, 1, At, B1); PG8_BAR; PG8_SCHED;
;     ...
;             PG8_LDA(At, 1, 1); PG8_STAGE(PG8_SB(1, 0), b3, voffB); PG8_STAGE(PG8_SB(1, 1), b3 + hstepB, voffB); PG8_STAGE(PG8_SA(1, 0), a3, voffA);
;             PG8_WAIT_V(8); PG8_WAIT_L(0); PG8_BAR; PG8_MMA(1, 0, At, B0); PG8_MMA(1, 1, At, B1); PG8_BAR; PG8_SCHED;
;         }
	s_add_i32 s34, s34, s0
	v_lshl_add_u64 v[158:159], v[158:159], 0, s[38:39]
	s_mov_b32 m0, s34
	ds_read_b128 v[196:199], v153 offset:49152
	ds_read_b128 v[200:203], v153 offset:50176
	ds_read_b128 v[204:207], v153 offset:51200
	ds_read_b128 v[208:211], v153 offset:52224
	ds_read_b128 v[212:215], v153 offset:53248
	ds_read_b128 v[216:219], v153 offset:54272
	ds_read_b128 v[220:223], v153 offset:55296
	ds_read_b128 v[224:227], v153 offset:56320
	global_load_lds_dwordx4 v[158:159], off
	s_add_i32 m0, s34, 0x2000
	s_add_u32 s88, s88, 0x80080
	v_lshl_add_u64 v[158:159], v[188:189], 0, s[38:39]
	s_addc_u32 s89, s89, 0
	s_add_i32 s34, s63, s0
	global_load_lds_dwordx4 v[158:159], off
	v_lshl_add_u64 v[158:159], s[88:89], 0, v[130:131]
	s_mov_b32 m0, s34
	s_nop 0
	global_load_lds_dwordx4 v[158:159], off
	v_lshl_add_u64 v[158:159], s[88:89], 0, v[134:135]
	s_add_i32 m0, s34, 0x2000
	s_nop 0
	global_load_lds_dwordx4 v[158:159], off
	v_lshl_add_u64 v[158:159], v[228:229], 0, s[38:39]
	s_mov_b32 m0, s22
	s_nop 0
	global_load_lds_dwordx4 v[158:159], off
	v_lshl_add_u64 v[158:159], v[230:231], 0, s[38:39]
	s_mov_b32 m0, s23
	s_nop 0
	global_load_lds_dwordx4 v[158:159], off
	s_waitcnt vmcnt(8)
	s_waitcnt lgkmcnt(0)
	s_barrier
	s_setprio 1
	s_waitcnt lgkmcnt(0)
	v_mfma_f32_16x16x32_bf16 v[60:63], v[154:157], v[196:199], v[60:63]
	v_mfma_f32_16x16x32_bf16 v[56:59], v[168:171], v[196:199], v[56:59]
	s_add_i32 s15, s15, 2
	s_add_u32 s86, s86, 0x100
	s_addc_u32 s87, s87, 0
	s_add_u32 s4, s4, 0x100
	s_addc_u32 s14, s14, 0
	v_mfma_f32_16x16x32_bf16 v[52:55], v[154:157], v[204:207], v[52:55]
	v_mfma_f32_16x16x32_bf16 v[48:51], v[168:171], v[204:207], v[48:51]
	v_mfma_f32_16x16x32_bf16 v[36:39], v[154:157], v[212:215], v[36:39]
	v_mfma_f32_16x16x32_bf16 v[32:35], v[168:171], v[212:215], v[32:35]
	v_mfma_f32_16x16x32_bf16 v[20:23], v[154:157], v[220:223], v[20:23]
	v_mfma_f32_16x16x32_bf16 v[16:19], v[168:171], v[220:223], v[16:19]
	v_mfma_f32_16x16x32_bf16 v[60:63], v[164:167], v[200:203], v[60:63]
	v_mfma_f32_16x16x32_bf16 v[56:59], v[172:175], v[200:203], v[56:59]
	v_mfma_f32_16x16x32_bf16 v[52:55], v[164:167], v[208:211], v[52:55]
	v_mfma_f32_16x16x32_bf16 v[48:51], v[172:175], v[208:211], v[48:51]
	v_mfma_f32_16x16x32_bf16 v[36:39], v[164:167], v[216:219], v[36:39]
	v_mfma_f32_16x16x32_bf16 v[32:35], v[172:175], v[216:219], v[32:35]
	v_mfma_f32_16x16x32_bf16 v[20:23], v[164:167], v[224:227], v[20:23]
	v_mfma_f32_16x16x32_bf16 v[16:19], v[172:175], v[224:227], v[16:19]
	s_setprio 0
	s_setprio 1
	v_mfma_f32_16x16x32_bf16 v[44:47], v[176:179], v[196:199], v[44:47]
	v_mfma_f32_16x16x32_bf16 v[40:43], v[184:187], v[196:199], v[40:43]
	v_mfma_f32_16x16x32_bf16 v[28:31], v[176:179], v[204:207], v[28:31]
	v_mfma_f32_16x16x32_bf16 v[24:27], v[184:187], v[204:207], v[24:27]
	v_mfma_f32_16x16x32_bf16 v[12:15], v[176:179], v[212:215], v[12:15]
	v_mfma_f32_16x16x32_bf16 v[8:11], v[184:187], v[212:215], v[8:11]
	v_mfma_f32_16x16x32_bf16 v[4:7], v[176:179], v[220:223], v[4:7]
	v_mfma_f32_16x16x32_bf16 v[0:3], v[184:187], v[220:223], v[0:3]
	v_mfma_f32_16x16x32_bf16 v[44:47], v[180:183], v[200:203], v[44:47]
	v_mfma_f32_16x16x32_bf16 v[40:43], v[192:195], v[200:203], v[40:43]
	v_mfma_f32_16x16x32_bf16 v[28:31], v[180:183], v[208:211], v[28:31]
	v_mfma_f32_16x16x32_bf16 v[24:27], v[192:195], v[208:211], v[24:27]
	v_mfma_f32_16x16x32_bf16 v[12:15], v[180:183], v[216:219], v[12:15]
	v_mfma_f32_16x16x32_bf16 v[8:11], v[192:195], v[216:219], v[8:11]
	v_mfma_f32_16x16x32_bf16 v[4:7], v[180:183], v[224:227], v[4:7]
	v_mfma_f32_16x16x32_bf16 v[0:3], v[192:195], v[224:227], v[0:3]
	s_setprio 0
	s_barrier
	s_cmp_gt_u32 s15, 29
	s_cbranch_scc0 .LBB0_124
	s_branch .Lpeel_exit_1
.LBB0_124:
	ds_read_b128 v[154:157], v151
	ds_read_b128 v[164:167], v151 offset:1024
	ds_read_b128 v[168:171], v151 offset:2048
	ds_read_b128 v[172:175], v151 offset:3072
	ds_read_b128 v[176:179], v152
	ds_read_b128 v[180:183], v152 offset:1024
	ds_read_b128 v[184:187], v152 offset:2048
	ds_read_b128 v[192:195], v152 offset:3072
	s_add_u32 s34, s86, 0xfff80080
	s_addc_u32 s63, s87, -1
	s_cmp_eq_u32 s15, 28
	s_cselect_b32 s91, s75, s63
	s_cselect_b32 s90, s74, s34
	s_cselect_b32 s89, s77, s14
	s_cselect_b32 s88, s76, s4
	v_lshl_add_u64 v[158:159], s[86:87], 0, v[146:147]
	s_add_i32 m0, s16, 0xc000
	ds_read_b128 v[196:199], v153
	ds_read_b128 v[200:203], v153 offset:1024
	ds_read_b128 v[204:207], v153 offset:2048
	ds_read_b128 v[208:211], v153 offset:3072
	ds_read_b128 v[212:215], v153 offset:4096
	ds_read_b128 v[216:219], v153 offset:5120
	ds_read_b128 v[220:223], v153 offset:6144
	ds_read_b128 v[224:227], v153 offset:7168
	global_load_lds_dwordx4 v[158:159], off
	v_lshl_add_u64 v[158:159], s[86:87], 0, v[148:149]
	s_add_i32 m0, s16, 0xe000
	s_nop 0
	global_load_lds_dwordx4 v[158:159], off
	s_waitcnt vmcnt(8)
	s_waitcnt lgkmcnt(0)
	s_barrier
; #define PG8_STAGE(bufoff, gbase, voff) do { _Pragma("unroll") for (int _i = 0; _i < 2; ++_i) \
;         __builtin_amdgcn_global_load_lds((const unsigned*)((const char*)(gbase) + (voff)[_i]), (LAS unsigned*)(lds + (bufoff) + ldsw + _i * 8192), 16, 0, 0); } while (0)
; #define PG8_LDA(dst, b, h) do { _Pragma("unroll") for (int m = 0; m < 4; ++m) _Pragma("unroll") for (int k = 0; k < 2; ++k) dst[m][k] = *(const LAS bf16x8*)(lds + PG8_SA(b, h) + aoff + m * 2048 + k * 1024); } while (0)
; #define PG8_MMA(ai, bj, At, Bt) do { __builtin_amdgcn_s_setprio(1); _Pragma("unroll") for (int m = 0; m < 4; ++m) _Pragma("unroll") for (int n = 0; n < 2; ++n) _Pragma("unroll") for (int k = 0; k < 2; ++k) \
;         acc[ai][bj][m][n] = __builtin_amdgcn_mfma_f32_16x16x32_bf16(Bt[n][k], At[m][k], acc[ai][bj][m][n], 0, 0, 0); __builtin_amdgcn_s_setprio(0); } while (0)
; #define PG8_WAIT_V(n) asm volatile("s_waitcnt vmcnt(" #n ")" ::: "memory")
; #define PG8_WAIT_L(n) asm volatile("s_waitcnt lgkmcnt(" #n ")" ::: "memory")
; #define PG8_BAR __builtin_amdgcn_s_barrier()
; #define PG8_SCHED __builtin_amdgcn_sched_barrier(0)
; template <int GI>
; __device__ __forceinline__ void gemm_phase(LAS unsigned char* lds, unsigned char* ws, int G, int cblk) {
;     ...
;             PG8_WAIT_V(8); PG8_WAIT_L(0); PG8_BAR; PG8_MMA(0, 0, At, B0); PG8_MMA(0, 1, At, B1); PG8_BAR; PG8_SCHED;
;             PG8_LDA(At, 0, 1); PG8_STAGE(PG8_SB(0, 0), b2, voffB); PG8_STAGE(PG8_SB(0, 1), b2 + hstepB, voffB); PG8_STAGE(PG8_SA(0, 0), a2, voffA);
;             PG8_WAIT_V(8); PG8_WAIT_L(0); PG8_BAR; PG8_MMA(1, 0, At, B0); PG8_MMA(1, 1, At, B1); PG8_BAR; PG8_SCHED;
	s_setprio 1
	s_waitcnt lgkmcnt(0)
	v_mfma_f32_16x16x32_bf16 v[124:127], v[154:157], v[196:199], v[124:127]
	v_mfma_f32_16x16x32_bf16 v[120:123], v[168:171], v[196:199], v[120:123]
	v_mfma_f32_16x16x32_bf16 v[116:119], v[154:157], v[204:207], v[116:119]
	v_mfma_f32_16x16x32_bf16 v[108:111], v[168:171], v[204:207], v[108:111]
	v_mfma_f32_16x16x32_bf16 v[100:103], v[154:157], v[212:215], v[100:103]
	v_mfma_f32_16x16x32_bf16 v[92:95], v[168:171], v[212:215], v[92:95]
	v_mfma_f32_16x16x32_bf16 v[84:87], v[154:157], v[220:223], v[84:87]
	v_mfma_f32_16x16x32_bf16 v[76:79], v[168:171], v[220:223], v[76:79]
	v_mfma_f32_16x16x32_bf16 v[124:127], v[164:167], v[200:203], v[124:127]
	v_mfma_f32_16x16x32_bf16 v[120:123], v[172:175], v[200:203], v[120:123]
	v_mfma_f32_16x16x32_bf16 v[116:119], v[164:167], v[208:211], v[116:119]
	v_mfma_f32_16x16x32_bf16 v[108:111], v[172:175], v[208:211], v[108:111]
	v_mfma_f32_16x16x32_bf16 v[100:103], v[164:167], v[216:219], v[100:103]
	v_mfma_f32_16x16x32_bf16 v[92:95], v[172:175], v[216:219], v[92:95]
	v_mfma_f32_16x16x32_bf16 v[84:87], v[164:167], v[224:227], v[84:87]
	v_mfma_f32_16x16x32_bf16 v[76:79], v[172:175], v[224:227], v[76:79]
	s_setprio 0
	s_setprio 1
	v_mfma_f32_16x16x32_bf16 v[112:115], v[176:179], v[196:199], v[112:115]
	v_mfma_f32_16x16x32_bf16 v[104:107], v[184:187], v[196:199], v[104:107]
	v_mfma_f32_16x16x32_bf16 v[96:99], v[176:179], v[204:207], v[96:99]
	v_mfma_f32_16x16x32_bf16 v[88:91], v[184:187], v[204:207], v[88:91]
	v_mfma_f32_16x16x32_bf16 v[80:83], v[176:179], v[212:215], v[80:83]
	v_mfma_f32_16x16x32_bf16 v[72:75], v[184:187], v[212:215], v[72:75]
	v_mfma_f32_16x16x32_bf16 v[68:71], v[176:179], v[220:223], v[68:71]
	v_mfma_f32_16x16x32_bf16 v[64:67], v[184:187], v[220:223], v[64:67]
	v_mfma_f32_16x16x32_bf16 v[112:115], v[180:183], v[200:203], v[112:115]
	v_mfma_f32_16x16x32_bf16 v[104:107], v[192:195], v[200:203], v[104:107]
	v_mfma_f32_16x16x32_bf16 v[96:99], v[180:183], v[208:211], v[96:99]
	v_mfma_f32_16x16x32_bf16 v[88:91], v[192:195], v[208:211], v[88:91]
	v_mfma_f32_16x16x32_bf16 v[80:83], v[180:183], v[216:219], v[80:83]
	v_mfma_f32_16x16x32_bf16 v[72:75], v[192:195], v[216:219], v[72:75]
	v_mfma_f32_16x16x32_bf16 v[68:71], v[180:183], v[224:227], v[68:71]
	v_mfma_f32_16x16x32_bf16 v[64:67], v[192:195], v[224:227], v[64:67]
	s_setprio 0
	s_barrier
	s_add_i32 s34, s25, s0
	v_lshl_add_u64 v[158:159], s[88:89], 0, v[130:131]
	s_mov_b32 m0, s34
	ds_read_b128 v[196:199], v153 offset:16384
	ds_read_b128 v[200:203], v153 offset:17408
	ds_read_b128 v[204:207], v153 offset:18432
	ds_read_b128 v[208:211], v153 offset:19456
	ds_read_b128 v[212:215], v153 offset:20480
	ds_read_b128 v[216:219], v153 offset:21504
	ds_read_b128 v[220:223], v153 offset:22528
	ds_read_b128 v[224:227], v153 offset:23552
	global_load_lds_dwordx4 v[158:159], off
	s_add_i32 m0, s34, 0x2000
	s_add_u32 s92, s88, 0x80000
	v_lshl_add_u64 v[188:189], s[88:89], 0, v[134:135]
	s_addc_u32 s93, s89, 0
	s_add_i32 s34, s26, s0
	global_load_lds_dwordx4 v[188:189], off
	v_lshl_add_u64 v[228:229], s[92:93], 0, v[130:131]
	s_mov_b32 m0, s34
	v_lshl_add_u64 v[230:231], s[90:91], 0, v[132:133]
	global_load_lds_dwordx4 v[228:229], off
	v_lshl_add_u64 v[228:229], s[92:93], 0, v[134:135]
	s_add_i32 m0, s34, 0x2000
	s_nop 0
	global_load_lds_dwordx4 v[228:229], off
	v_lshl_add_u64 v[228:229], s[90:91], 0, v[128:129]
	s_mov_b32 m0, s16
	s_nop 0
	global_load_lds_dwordx4 v[228:229], off
	s_mov_b32 m0, s17
	s_nop 0
	global_load_lds_dwordx4 v[230:231], off
	s_waitcnt vmcnt(8)
	s_waitcnt lgkmcnt(0)
	s_barrier
	s_setprio 1
	s_waitcnt lgkmcnt(0)
	v_mfma_f32_16x16x32_bf16 v[60:63], v[154:157], v[196:199], v[60:63]
	v_mfma_f32_16x16x32_bf16 v[56:59], v[168:171], v[196:199], v[56:59]
	v_mfma_f32_16x16x32_bf16 v[52:55], v[154:157], v[204:207], v[52:55]
	v_mfma_f32_16x16x32_bf16 v[48:51], v[168:171], v[204:207], v[48:51]
	v_mfma_f32_16x16x32_bf16 v[36:39], v[154:157], v[212:215], v[36:39]
	v_mfma_f32_16x16x32_bf16 v[32:35], v[168:171], v[212:215], v[32:35]
	v_mfma_f32_16x16x32_bf16 v[20:23], v[154:157], v[220:223], v[20:23]
	v_mfma_f32_16x16x32_bf16 v[16:19], v[168:171], v[220:223], v[16:19]
	v_mfma_f32_16x16x32_bf16 v[60:63], v[164:167], v[200:203], v[60:63]
	v_mfma_f32_16x16x32_bf16 v[56:59], v[172:175], v[200:203], v[56:59]
	v_mfma_f32_16x16x32_bf16 v[52:55], v[164:167], v[208:211], v[52:55]
	v_mfma_f32_16x16x32_bf16 v[48:51], v[172:175], v[208:211], v[48:51]
	v_mfma_f32_16x16x32_bf16 v[36:39], v[164:167], v[216:219], v[36:39]
	v_mfma_f32_16x16x32_bf16 v[32:35], v[172:175], v[216:219], v[32:35]
	v_mfma_f32_16x16x32_bf16 v[20:23], v[164:167], v[224:227], v[20:23]
	v_mfma_f32_16x16x32_bf16 v[16:19], v[172:175], v[224:227], v[16:19]
	s_setprio 0
	s_setprio 1
	v_mfma_f32_16x16x32_bf16 v[44:47], v[176:179], v[196:199], v[44:47]
	v_mfma_f32_16x16x32_bf16 v[40:43], v[184:187], v[196:199], v[40:43]
	v_mfma_f32_16x16x32_bf16 v[28:31], v[176:179], v[204:207], v[28:31]
	v_mfma_f32_16x16x32_bf16 v[24:27], v[184:187], v[204:207], v[24:27]
	v_mfma_f32_16x16x32_bf16 v[12:15], v[176:179], v[212:215], v[12:15]
	v_mfma_f32_16x16x32_bf16 v[8:11], v[184:187], v[212:215], v[8:11]
	v_mfma_f32_16x16x32_bf16 v[4:7], v[176:179], v[220:223], v[4:7]
	v_mfma_f32_16x16x32_bf16 v[0:3], v[184:187], v[220:223], v[0:3]
	v_mfma_f32_16x16x32_bf16 v[44:47], v[180:183], v[200:203], v[44:47]
	v_mfma_f32_16x16x32_bf16 v[40:43], v[192:195], v[200:203], v[40:43]
	v_mfma_f32_16x16x32_bf16 v[28:31], v[180:183], v[208:211], v[28:31]
	v_mfma_f32_16x16x32_bf16 v[24:27], v[192:195], v[208:211], v[24:27]
	v_mfma_f32_16x16x32_bf16 v[12:15], v[180:183], v[216:219], v[12:15]
	v_mfma_f32_16x16x32_bf16 v[8:11], v[192:195], v[216:219], v[8:11]
	v_mfma_f32_16x16x32_bf16 v[4:7], v[180:183], v[224:227], v[4:7]
	v_mfma_f32_16x16x32_bf16 v[0:3], v[192:195], v[224:227], v[0:3]
	s_setprio 0
	s_barrier
; #define PG8_STAGE(bufoff, gbase, voff) do { _Pragma("unroll") for (int _i = 0; _i < 2; ++_i) \
;         __builtin_amdgcn_global_load_lds((const unsigned*)((const char*)(gbase) + (voff)[_i]), (LAS unsigned*)(lds + (bufoff) + ldsw + _i * 8192), 16, 0, 0); } while (0)
; #define PG8_LDA(dst, b, h) do { _Pragma("unroll") for (int m = 0; m < 4; ++m) _Pragma("unroll") for (int k = 0; k < 2; ++k) dst[m][k] = *(const LAS bf16x8*)(lds + PG8_SA(b, h) + aoff + m * 2048 + k * 1024); } while (0)
; #define PG8_LDB(dst, b, h) do { _Pragma("unroll") for (int n = 0; n < 2; ++n) _Pragma("unroll") for (int k = 0; k < 2; ++k) dst[n][k] = *(const LAS bf16x8*)(lds + PG8_SB(b, h) + boff + n * 2048 + k * 1024); } while (0)
; #define PG8_MMA(ai, bj, At, Bt) do { __builtin_amdgcn_s_setprio(1); _Pragma("unroll") for (int m = 0; m < 4; ++m) _Pragma("unroll") for (int n = 0; n < 2; ++n) _Pragma("unroll") for (int k = 0; k < 2; ++k) \
;         acc[ai][bj][m][n] = __builtin_amdgcn_mfma_f32_16x16x32_bf16(Bt[n][k], At[m][k], acc[ai][bj][m][n], 0, 0, 0); __builtin_amdgcn_s_setprio(0); } while (0)
; #define PG8_WAIT_V(n) asm volatile("s_waitcnt vmcnt(" #n ")" ::: "memory")
; #define PG8_WAIT_L(n) asm volatile("s_waitcnt lgkmcnt(" #n ")" ::: "memory")
; #define PG8_BAR __builtin_amdgcn_s_barrier()
; #define PG8_SCHED __builtin_amdgcn_sched_barrier(0)
; template <int GI>
; __device__ __forceinline__ void gemm_phase(LAS unsigned char* lds, unsigned char* ws, int G, int cblk) {
;     ...
;             PG8_LDB(B0, 1, 0); PG8_LDB(B1, 1, 1); PG8_SCHED; PG8_LDA(At, 1, 0); PG8_STAGE(PG8_SA(0, 1), a2 + hstepA, voffA);
;             PG8_WAIT_V(8); PG8_WAIT_L(0); PG8_BAR; PG8_MMA(0, 0, At, B0); PG8_MMA(0, 1, At, B1); PG8_BAR; PG8_SCHED;
	s_add_i32 s34, 0, 0x18000
	v_add_u32_e32 v161, s34, v150
	s_add_i32 s63, 0, 0x1c000
	ds_read_b128 v[154:157], v161
	ds_read_b128 v[164:167], v161 offset:1024
	ds_read_b128 v[168:171], v161 offset:2048
	ds_read_b128 v[172:175], v161 offset:3072
	v_add_u32_e32 v161, s63, v150
	ds_read_b128 v[176:179], v161
	ds_read_b128 v[180:183], v161 offset:1024
	ds_read_b128 v[184:187], v161 offset:2048
	ds_read_b128 v[192:195], v161 offset:3072
	s_add_u32 s90, s90, 0x80000
	s_addc_u32 s91, s91, 0
	s_mov_b32 m0, s18
	v_lshl_add_u64 v[232:233], s[90:91], 0, v[128:129]
	ds_read_b128 v[196:199], v153 offset:32768
	ds_read_b128 v[200:203], v153 offset:33792
	ds_read_b128 v[204:207], v153 offset:34816
	ds_read_b128 v[208:211], v153 offset:35840
	ds_read_b128 v[212:215], v153 offset:36864
	ds_read_b128 v[216:219], v153 offset:37888
	ds_read_b128 v[220:223], v153 offset:38912
	ds_read_b128 v[224:227], v153 offset:39936
	global_load_lds_dwordx4 v[232:233], off
	v_lshl_add_u64 v[232:233], s[90:91], 0, v[132:133]
	s_mov_b32 m0, s19
	s_nop 0
	global_load_lds_dwordx4 v[232:233], off
	s_waitcnt vmcnt(8)
	s_waitcnt lgkmcnt(0)
	s_barrier
	s_setprio 1
	s_waitcnt lgkmcnt(0)
	v_mfma_f32_16x16x32_bf16 v[124:127], v[154:157], v[196:199], v[124:127]
	v_mfma_f32_16x16x32_bf16 v[120:123], v[168:171], v[196:199], v[120:123]
	v_mfma_f32_16x16x32_bf16 v[116:119], v[154:157], v[204:207], v[116:119]
	v_mfma_f32_16x16x32_bf16 v[108:111], v[168:171], v[204:207], v[108:111]
	v_mfma_f32_16x16x32_bf16 v[100:103], v[154:157], v[212:215], v[100:103]
	v_mfma_f32_16x16x32_bf16 v[92:95], v[168:171], v[212:215], v[92:95]
	v_mfma_f32_16x16x32_bf16 v[84:87], v[154:157], v[220:223], v[84:87]
	v_mfma_f32_16x16x32_bf16 v[76:79], v[168:171], v[220:223], v[76:79]
	v_mfma_f32_16x16x32_bf16 v[124:127], v[164:167], v[200:203], v[124:127]
	v_mfma_f32_16x16x32_bf16 v[120:123], v[172:175], v[200:203], v[120:123]
	v_mfma_f32_16x16x32_bf16 v[116:119], v[164:167], v[208:211], v[116:119]
	v_mfma_f32_16x16x32_bf16 v[108:111], v[172:175], v[208:211], v[108:111]
	v_mfma_f32_16x16x32_bf16 v[100:103], v[164:167], v[216:219], v[100:103]
	v_mfma_f32_16x16x32_bf16 v[92:95], v[172:175], v[216:219], v[92:95]
	v_mfma_f32_16x16x32_bf16 v[84:87], v[164:167], v[224:227], v[84:87]
	v_mfma_f32_16x16x32_bf16 v[76:79], v[172:175], v[224:227], v[76:79]
	s_setprio 0
	s_setprio 1
	v_mfma_f32_16x16x32_bf16 v[112:115], v[176:179], v[196:199], v[112:115]
	v_mfma_f32_16x16x32_bf16 v[104:107], v[184:187], v[196:199], v[104:107]
	v_mfma_f32_16x16x32_bf16 v[96:99], v[176:179], v[204:207], v[96:99]
	v_mfma_f32_16x16x32_bf16 v[88:91], v[184:187], v[204:207], v[88:91]
	v_mfma_f32_16x16x32_bf16 v[80:83], v[176:179], v[212:215], v[80:83]
	v_mfma_f32_16x16x32_bf16 v[72:75], v[184:187], v[212:215], v[72:75]
	v_mfma_f32_16x16x32_bf16 v[68:71], v[176:179], v[220:223], v[68:71]
	v_mfma_f32_16x16x32_bf16 v[64:67], v[184:187], v[220:223], v[64:67]
	v_mfma_f32_16x16x32_bf16 v[112:115], v[180:183], v[200:203], v[112:115]
	v_mfma_f32_16x16x32_bf16 v[104:107], v[192:195], v[200:203], v[104:107]
	v_mfma_f32_16x16x32_bf16 v[96:99], v[180:183], v[208:211], v[96:99]
	v_mfma_f32_16x16x32_bf16 v[88:91], v[192:195], v[208:211], v[88:91]
	v_mfma_f32_16x16x32_bf16 v[80:83], v[180:183], v[216:219], v[80:83]
	v_mfma_f32_16x16x32_bf16 v[72:75], v[192:195], v[216:219], v[72:75]
	v_mfma_f32_16x16x32_bf16 v[68:71], v[180:183], v[224:227], v[68:71]
	v_mfma_f32_16x16x32_bf16 v[64:67], v[192:195], v[224:227], v[64:67]
	s_setprio 0
	s_barrier
; #define PG8_STAGE(bufoff, gbase, voff) do { _Pragma("unroll") for (int _i = 0; _i < 2; ++_i) \
;         __builtin_amdgcn_global_load_lds((const unsigned*)((const char*)(gbase) + (voff)[_i]), (LAS unsigned*)(lds + (bufoff) + ldsw + _i * 8192), 16, 0, 0); } while (0)
; #define PG8_LDA(dst, b, h) do { _Pragma("unroll") for (int m = 0; m < 4; ++m) _Pragma("unroll") for (int k = 0; k < 2; ++k) dst[m][k] = *(const LAS bf16x8*)(lds + PG8_SA(b, h) + aoff + m * 2048 + k * 1024); } while (0)
; #define PG8_MMA(ai, bj, At, Bt) do { __builtin_amdgcn_s_setprio(1); _Pragma("unroll") for (int m = 0; m < 4; ++m) _Pragma("unroll") for (int n = 0; n < 2; ++n) _Pragma("unroll") for (int k = 0; k < 2; ++k) \
;         acc[ai][bj][m][n] = __builtin_amdgcn_mfma_f32_16x16x32_bf16(Bt[n][k], At[m][k], acc[ai][bj][m][n], 0, 0, 0); __builtin_amdgcn_s_setprio(0); } while (0)
; #define PG8_WAIT_V(n) asm volatile("s_waitcnt vmcnt(" #n ")" ::: "memory")
; #define PG8_WAIT_L(n) asm volatile("s_waitcnt lgkmcnt(" #n ")" ::: "memory")
; #define PG8_BAR __builtin_amdgcn_s_barrier()
; #define PG8_SCHED __builtin_amdgcn_sched_barrier(0)
; template <int GI>
; __device__ __forceinline__ void gemm_phase(LAS unsigned char* lds, unsigned char* ws, int G, int cblk) {
;     ...
;             PG8_LDA(At, 1, 1); PG8_STAGE(PG8_SB(1, 0), b3, voffB); PG8_STAGE(PG8_SB(1, 1), b3 + hstepB, voffB); PG8_STAGE(PG8_SA(1, 0), a3, voffA);
;             PG8_WAIT_V(8); PG8_WAIT_L(0); PG8_BAR; PG8_MMA(1, 0, At, B0); PG8_MMA(1, 1, At, B1); PG8_BAR; PG8_SCHED;
;         }
	s_add_i32 s34, s34, s0
	v_lshl_add_u64 v[158:159], v[158:159], 0, s[38:39]
	s_mov_b32 m0, s34
	ds_read_b128 v[196:199], v153 offset:49152
	ds_read_b128 v[200:203], v153 offset:50176
	ds_read_b128 v[204:207], v153 offset:51200
	ds_read_b128 v[208:211], v153 offset:52224
	ds_read_b128 v[212:215], v153 offset:53248
	ds_read_b128 v[216:219], v153 offset:54272
	ds_read_b128 v[220:223], v153 offset:55296
	ds_read_b128 v[224:227], v153 offset:56320
	global_load_lds_dwordx4 v[158:159], off
	s_add_i32 m0, s34, 0x2000
	s_add_u32 s88, s88, 0x80080
	v_lshl_add_u64 v[158:159], v[188:189], 0, s[38:39]
	s_addc_u32 s89, s89, 0
	s_add_i32 s34, s63, s0
	global_load_lds_dwordx4 v[158:159], off
	v_lshl_add_u64 v[158:159], s[88:89], 0, v[130:131]
	s_mov_b32 m0, s34
	s_nop 0
	global_load_lds_dwordx4 v[158:159], off
	v_lshl_add_u64 v[158:159], s[88:89], 0, v[134:135]
	s_add_i32 m0, s34, 0x2000
	s_nop 0
	global_load_lds_dwordx4 v[158:159], off
	v_lshl_add_u64 v[158:159], v[228:229], 0, s[38:39]
	s_mov_b32 m0, s22
	s_nop 0
	global_load_lds_dwordx4 v[158:159], off
	v_lshl_add_u64 v[158:159], v[230:231], 0, s[38:39]
	s_mov_b32 m0, s23
	s_nop 0
	global_load_lds_dwordx4 v[158:159], off
	s_waitcnt vmcnt(8)
	s_waitcnt lgkmcnt(0)
	s_barrier
	s_setprio 1
	s_waitcnt lgkmcnt(0)
	v_mfma_f32_16x16x32_bf16 v[60:63], v[154:157], v[196:199], v[60:63]
	v_mfma_f32_16x16x32_bf16 v[56:59], v[168:171], v[196:199], v[56:59]
	s_add_i32 s15, s15, 2
	s_add_u32 s86, s86, 0x100
	s_addc_u32 s87, s87, 0
	s_add_u32 s4, s4, 0x100
	s_addc_u32 s14, s14, 0
	v_mfma_f32_16x16x32_bf16 v[52:55], v[154:157], v[204:207], v[52:55]
	v_mfma_f32_16x16x32_bf16 v[48:51], v[168:171], v[204:207], v[48:51]
	v_mfma_f32_16x16x32_bf16 v[36:39], v[154:157], v[212:215], v[36:39]
	v_mfma_f32_16x16x32_bf16 v[32:35], v[168:171], v[212:215], v[32:35]
	v_mfma_f32_16x16x32_bf16 v[20:23], v[154:157], v[220:223], v[20:23]
	v_mfma_f32_16x16x32_bf16 v[16:19], v[168:171], v[220:223], v[16:19]
	v_mfma_f32_16x16x32_bf16 v[60:63], v[164:167], v[200:203], v[60:63]
	v_mfma_f32_16x16x32_bf16 v[56:59], v[172:175], v[200:203], v[56:59]
	v_mfma_f32_16x16x32_bf16 v[52:55], v[164:167], v[208:211], v[52:55]
	v_mfma_f32_16x16x32_bf16 v[48:51], v[172:175], v[208:211], v[48:51]
	v_mfma_f32_16x16x32_bf16 v[36:39], v[164:167], v[216:219], v[36:39]
	v_mfma_f32_16x16x32_bf16 v[32:35], v[172:175], v[216:219], v[32:35]
	v_mfma_f32_16x16x32_bf16 v[20:23], v[164:167], v[224:227], v[20:23]
	v_mfma_f32_16x16x32_bf16 v[16:19], v[172:175], v[224:227], v[16:19]
	s_setprio 0
	s_setprio 1
	v_mfma_f32_16x16x32_bf16 v[44:47], v[176:179], v[196:199], v[44:47]
	v_mfma_f32_16x16x32_bf16 v[40:43], v[184:187], v[196:199], v[40:43]
	v_mfma_f32_16x16x32_bf16 v[28:31], v[176:179], v[204:207], v[28:31]
	v_mfma_f32_16x16x32_bf16 v[24:27], v[184:187], v[204:207], v[24:27]
	v_mfma_f32_16x16x32_bf16 v[12:15], v[176:179], v[212:215], v[12:15]
	v_mfma_f32_16x16x32_bf16 v[8:11], v[184:187], v[212:215], v[8:11]
	v_mfma_f32_16x16x32_bf16 v[4:7], v[176:179], v[220:223], v[4:7]
	v_mfma_f32_16x16x32_bf16 v[0:3], v[184:187], v[220:223], v[0:3]
	v_mfma_f32_16x16x32_bf16 v[44:47], v[180:183], v[200:203], v[44:47]
	v_mfma_f32_16x16x32_bf16 v[40:43], v[192:195], v[200:203], v[40:43]
	v_mfma_f32_16x16x32_bf16 v[28:31], v[180:183], v[208:211], v[28:31]
	v_mfma_f32_16x16x32_bf16 v[24:27], v[192:195], v[208:211], v[24:27]
	v_mfma_f32_16x16x32_bf16 v[12:15], v[180:183], v[216:219], v[12:15]
	v_mfma_f32_16x16x32_bf16 v[8:11], v[192:195], v[216:219], v[8:11]
	v_mfma_f32_16x16x32_bf16 v[4:7], v[180:183], v[224:227], v[4:7]
	v_mfma_f32_16x16x32_bf16 v[0:3], v[192:195], v[224:227], v[0:3]
	s_setprio 0
	s_barrier
	s_cmp_gt_u32 s15, 29
	s_cbranch_scc0 .LBB0_124

; #define PG8_STAGE(bufoff, gbase, voff) do { _Pragma("unroll") for (int _i = 0; _i < 2; ++_i) \
;         __builtin_amdgcn_global_load_lds((const unsigned*)((const char*)(gbase) + (voff)[_i]), (LAS unsigned*)(lds + (bufoff) + ldsw + _i * 8192), 16, 0, 0); } while (0)
; #define PG8_LDA(dst, b, h) do { _Pragma("unroll") for (int m = 0; m < 4; ++m) _Pragma("unroll") for (int k = 0; k < 2; ++k) dst[m][k] = *(const LAS bf16x8*)(lds + PG8_SA(b, h) + aoff + m * 2048 + k * 1024); } while (0)
; #define PG8_LDB(dst, b, h) do { _Pragma("unroll") for (int n = 0; n < 2; ++n) _Pragma("unroll") for (int k = 0; k < 2; ++k) dst[n][k] = *(const LAS bf16x8*)(lds + PG8_SB(b, h) + boff + n * 2048 + k * 1024); } while (0)
; #define PG8_MMA(ai, bj, At, Bt) do { __builtin_amdgcn_s_setprio(1); _Pragma("unroll") for (int m = 0; m < 4; ++m) _Pragma("unroll") for (int n = 0; n < 2; ++n) _Pragma("unroll") for (int k = 0; k < 2; ++k) \
;         acc[ai][bj][m][n] = __builtin_amdgcn_mfma_f32_16x16x32_bf16(Bt[n][k], At[m][k], acc[ai][bj][m][n], 0, 0, 0); __builtin_amdgcn_s_setprio(0); } while (0)
; #define PG8_WAIT_V(n) asm volatile("s_waitcnt vmcnt(" #n ")" ::: "memory")
; #define PG8_WAIT_L(n) asm volatile("s_waitcnt lgkmcnt(" #n ")" ::: "memory")
; #define PG8_BAR __builtin_amdgcn_s_barrier()
; #define PG8_SCHED __builtin_amdgcn_sched_barrier(0)
; template <int GI>
; __device__ __forceinline__ void gemm_phase(LAS unsigned char* lds, unsigned char* ws, int G, int cblk) {
;     ...
;         for (int t = 0; t < nt; t += 2) {
;             const bool last = (t == nt - 2);
;             const char* a1 = cA + (size_t)(t + 1) * kstep;
;             const char* a2 = last ? nA : cA + (size_t)(t + 2) * kstep; const char* b2 = last ? nB : cB + (size_t)(t + 2) * kstep;
;             const char* a3 = a2 + kstep; const char* b3 = b2 + kstep;
;             PG8_LDB(B0, 0, 0); PG8_LDB(B1, 0, 1); PG8_SCHED; PG8_LDA(At, 0, 0); PG8_STAGE(PG8_SA(1, 1), a1 + hstepA, voffA);
;             PG8_WAIT_V(8); PG8_WAIT_L(0); PG8_BAR; PG8_MMA(0, 0, At, B0); PG8_MMA(0, 1, At, B1); PG8_BAR; PG8_SCHED;
;             PG8_LDA(At, 0, 1); PG8_STAGE(PG8_SB(0, 0), b2, voffB); PG8_STAGE(PG8_SB(0, 1), b2 + hstepB, voffB); PG8_STAGE(PG8_SA(0, 0), a2, voffA);
;             PG8_WAIT_V(8); PG8_WAIT_L(0); PG8_BAR; PG8_MMA(1, 0, At, B0); PG8_MMA(1, 1, At, B1); PG8_BAR; PG8_SCHED;
.LBB0_147:
	s_add_u32 s78, s78, 0x80080
	s_addc_u32 s79, s79, 0
	s_add_u32 s14, s80, 0x100
	s_addc_u32 s15, s81, 0
	s_mov_b32 s27, -2
	ds_read_b128 v[154:157], v151
	ds_read_b128 v[164:167], v151 offset:1024
	ds_read_b128 v[168:171], v151 offset:2048
	ds_read_b128 v[172:175], v151 offset:3072
	ds_read_b128 v[176:179], v152
	ds_read_b128 v[180:183], v152 offset:1024
	ds_read_b128 v[184:187], v152 offset:2048
	ds_read_b128 v[192:195], v152 offset:3072
	s_add_u32 s33, s78, 0xfff80080
	s_addc_u32 s34, s79, -1
	s_cmp_eq_u32 s27, 28
	s_cselect_b32 s83, s73, s34
	s_cselect_b32 s82, s72, s33
	s_cselect_b32 s81, s75, s15
	s_cselect_b32 s80, s74, s14
	v_lshl_add_u64 v[158:159], s[78:79], 0, v[138:139]
	s_add_i32 m0, s16, 0xc000
	ds_read_b128 v[196:199], v153
	ds_read_b128 v[200:203], v153 offset:1024
	ds_read_b128 v[204:207], v153 offset:2048
	ds_read_b128 v[208:211], v153 offset:3072
	ds_read_b128 v[212:215], v153 offset:4096
	ds_read_b128 v[216:219], v153 offset:5120
	ds_read_b128 v[220:223], v153 offset:6144
	ds_read_b128 v[224:227], v153 offset:7168
	global_load_lds_dwordx4 v[158:159], off
	v_lshl_add_u64 v[158:159], s[78:79], 0, v[140:141]
	s_add_i32 m0, s16, 0xe000
	s_nop 0
	global_load_lds_dwordx4 v[158:159], off
	s_waitcnt vmcnt(8)
	s_waitcnt lgkmcnt(0)
	s_barrier
	s_setprio 1
	s_waitcnt lgkmcnt(0)
	v_mfma_f32_16x16x32_bf16 v[124:127], v[154:157], v[196:199], 0
	v_mfma_f32_16x16x32_bf16 v[120:123], v[168:171], v[196:199], 0
	v_mfma_f32_16x16x32_bf16 v[116:119], v[154:157], v[204:207], 0
	v_mfma_f32_16x16x32_bf16 v[112:115], v[168:171], v[204:207], 0
	v_mfma_f32_16x16x32_bf16 v[100:103], v[154:157], v[212:215], 0
	v_mfma_f32_16x16x32_bf16 v[96:99], v[168:171], v[212:215], 0
	v_mfma_f32_16x16x32_bf16 v[84:87], v[154:157], v[220:223], 0
	v_mfma_f32_16x16x32_bf16 v[80:83], v[168:171], v[220:223], 0
	v_mfma_f32_16x16x32_bf16 v[124:127], v[164:167], v[200:203], v[124:127]
	v_mfma_f32_16x16x32_bf16 v[120:123], v[172:175], v[200:203], v[120:123]
	v_mfma_f32_16x16x32_bf16 v[116:119], v[164:167], v[208:211], v[116:119]
	v_mfma_f32_16x16x32_bf16 v[112:115], v[172:175], v[208:211], v[112:115]
	v_mfma_f32_16x16x32_bf16 v[100:103], v[164:167], v[216:219], v[100:103]
	v_mfma_f32_16x16x32_bf16 v[96:99], v[172:175], v[216:219], v[96:99]
	v_mfma_f32_16x16x32_bf16 v[84:87], v[164:167], v[224:227], v[84:87]
	v_mfma_f32_16x16x32_bf16 v[80:83], v[172:175], v[224:227], v[80:83]
	s_setprio 0
	s_setprio 1
	v_mfma_f32_16x16x32_bf16 v[108:111], v[176:179], v[196:199], 0
	v_mfma_f32_16x16x32_bf16 v[104:107], v[184:187], v[196:199], 0
	v_mfma_f32_16x16x32_bf16 v[92:95], v[176:179], v[204:207], 0
	v_mfma_f32_16x16x32_bf16 v[88:91], v[184:187], v[204:207], 0
	v_mfma_f32_16x16x32_bf16 v[76:79], v[176:179], v[212:215], 0
	v_mfma_f32_16x16x32_bf16 v[72:75], v[184:187], v[212:215], 0
	v_mfma_f32_16x16x32_bf16 v[68:71], v[176:179], v[220:223], 0
	v_mfma_f32_16x16x32_bf16 v[64:67], v[184:187], v[220:223], 0
	v_mfma_f32_16x16x32_bf16 v[108:111], v[180:183], v[200:203], v[108:111]
	v_mfma_f32_16x16x32_bf16 v[104:107], v[192:195], v[200:203], v[104:107]
	v_mfma_f32_16x16x32_bf16 v[92:95], v[180:183], v[208:211], v[92:95]
	v_mfma_f32_16x16x32_bf16 v[88:91], v[192:195], v[208:211], v[88:91]
	v_mfma_f32_16x16x32_bf16 v[76:79], v[180:183], v[216:219], v[76:79]
	v_mfma_f32_16x16x32_bf16 v[72:75], v[192:195], v[216:219], v[72:75]
	v_mfma_f32_16x16x32_bf16 v[68:71], v[180:183], v[224:227], v[68:71]
	v_mfma_f32_16x16x32_bf16 v[64:67], v[192:195], v[224:227], v[64:67]
	s_setprio 0
	s_barrier
	s_add_i32 s33, s24, s0
	v_lshl_add_u64 v[158:159], s[80:81], 0, v[130:131]
	s_mov_b32 m0, s33
	ds_read_b128 v[196:199], v153 offset:16384
	ds_read_b128 v[200:203], v153 offset:17408
	ds_read_b128 v[204:207], v153 offset:18432
	ds_read_b128 v[208:211], v153 offset:19456
	ds_read_b128 v[212:215], v153 offset:20480
	ds_read_b128 v[216:219], v153 offset:21504
	ds_read_b128 v[220:223], v153 offset:22528
	ds_read_b128 v[224:227], v153 offset:23552
	global_load_lds_dwordx4 v[158:159], off
	s_add_i32 m0, s33, 0x2000
	s_add_u32 s34, s80, 0x80000
	v_lshl_add_u64 v[188:189], s[80:81], 0, v[134:135]
	s_addc_u32 s35, s81, 0
	s_add_i32 s33, s25, s0
	global_load_lds_dwordx4 v[188:189], off
	v_lshl_add_u64 v[228:229], s[34:35], 0, v[130:131]
	s_mov_b32 m0, s33
	v_lshl_add_u64 v[230:231], s[82:83], 0, v[132:133]
	global_load_lds_dwordx4 v[228:229], off
	v_lshl_add_u64 v[228:229], s[34:35], 0, v[134:135]
	s_add_i32 m0, s33, 0x2000
	s_nop 0
	global_load_lds_dwordx4 v[228:229], off
	v_lshl_add_u64 v[228:229], s[82:83], 0, v[128:129]
	s_mov_b32 m0, s16
	s_nop 0
	global_load_lds_dwordx4 v[228:229], off
	s_mov_b32 m0, s17
	s_nop 0
	global_load_lds_dwordx4 v[230:231], off
	s_waitcnt vmcnt(8)
	s_waitcnt lgkmcnt(0)
	s_barrier
; #define PG8_STAGE(bufoff, gbase, voff) do { _Pragma("unroll") for (int _i = 0; _i < 2; ++_i) \
;         __builtin_amdgcn_global_load_lds((const unsigned*)((const char*)(gbase) + (voff)[_i]), (LAS unsigned*)(lds + (bufoff) + ldsw + _i * 8192), 16, 0, 0); } while (0)
; #define PG8_LDA(dst, b, h) do { _Pragma("unroll") for (int m = 0; m < 4; ++m) _Pragma("unroll") for (int k = 0; k < 2; ++k) dst[m][k] = *(const LAS bf16x8*)(lds + PG8_SA(b, h) + aoff + m * 2048 + k * 1024); } while (0)
; #define PG8_LDB(dst, b, h) do { _Pragma("unroll") for (int n = 0; n < 2; ++n) _Pragma("unroll") for (int k = 0; k < 2; ++k) dst[n][k] = *(const LAS bf16x8*)(lds + PG8_SB(b, h) + boff + n * 2048 + k * 1024); } while (0)
; #define PG8_MMA(ai, bj, At, Bt) do { __builtin_amdgcn_s_setprio(1); _Pragma("unroll") for (int m = 0; m < 4; ++m) _Pragma("unroll") for (int n = 0; n < 2; ++n) _Pragma("unroll") for (int k = 0; k < 2; ++k) \
;         acc[ai][bj][m][n] = __builtin_amdgcn_mfma_f32_16x16x32_bf16(Bt[n][k], At[m][k], acc[ai][bj][m][n], 0, 0, 0); __builtin_amdgcn_s_setprio(0); } while (0)
; #define PG8_WAIT_V(n) asm volatile("s_waitcnt vmcnt(" #n ")" ::: "memory")
; #define PG8_WAIT_L(n) asm volatile("s_waitcnt lgkmcnt(" #n ")" ::: "memory")
; #define PG8_BAR __builtin_amdgcn_s_barrier()
; #define PG8_SCHED __builtin_amdgcn_sched_barrier(0)
; template <int GI>
; __device__ __forceinline__ void gemm_phase(LAS unsigned char* lds, unsigned char* ws, int G, int cblk) {
;     ...
;             PG8_WAIT_V(8); PG8_WAIT_L(0); PG8_BAR; PG8_MMA(1, 0, At, B0); PG8_MMA(1, 1, At, B1); PG8_BAR; PG8_SCHED;
;             PG8_LDB(B0, 1, 0); PG8_LDB(B1, 1, 1); PG8_SCHED; PG8_LDA(At, 1, 0); PG8_STAGE(PG8_SA(0, 1), a2 + hstepA, voffA);
;             PG8_WAIT_V(8); PG8_WAIT_L(0); PG8_BAR; PG8_MMA(0, 0, At, B0); PG8_MMA(0, 1, At, B1); PG8_BAR; PG8_SCHED;
	s_setprio 1
	s_waitcnt lgkmcnt(0)
	v_mfma_f32_16x16x32_bf16 v[60:63], v[154:157], v[196:199], 0
	v_mfma_f32_16x16x32_bf16 v[56:59], v[168:171], v[196:199], 0
	v_mfma_f32_16x16x32_bf16 v[52:55], v[154:157], v[204:207], 0
	v_mfma_f32_16x16x32_bf16 v[48:51], v[168:171], v[204:207], 0
	v_mfma_f32_16x16x32_bf16 v[36:39], v[154:157], v[212:215], 0
	v_mfma_f32_16x16x32_bf16 v[32:35], v[168:171], v[212:215], 0
	v_mfma_f32_16x16x32_bf16 v[20:23], v[154:157], v[220:223], 0
	v_mfma_f32_16x16x32_bf16 v[16:19], v[168:171], v[220:223], 0
	v_mfma_f32_16x16x32_bf16 v[60:63], v[164:167], v[200:203], v[60:63]
	v_mfma_f32_16x16x32_bf16 v[56:59], v[172:175], v[200:203], v[56:59]
	v_mfma_f32_16x16x32_bf16 v[52:55], v[164:167], v[208:211], v[52:55]
	v_mfma_f32_16x16x32_bf16 v[48:51], v[172:175], v[208:211], v[48:51]
	v_mfma_f32_16x16x32_bf16 v[36:39], v[164:167], v[216:219], v[36:39]
	v_mfma_f32_16x16x32_bf16 v[32:35], v[172:175], v[216:219], v[32:35]
	v_mfma_f32_16x16x32_bf16 v[20:23], v[164:167], v[224:227], v[20:23]
	v_mfma_f32_16x16x32_bf16 v[16:19], v[172:175], v[224:227], v[16:19]
	s_setprio 0
	s_setprio 1
	v_mfma_f32_16x16x32_bf16 v[44:47], v[176:179], v[196:199], 0
	v_mfma_f32_16x16x32_bf16 v[40:43], v[184:187], v[196:199], 0
	v_mfma_f32_16x16x32_bf16 v[28:31], v[176:179], v[204:207], 0
	v_mfma_f32_16x16x32_bf16 v[24:27], v[184:187], v[204:207], 0
	v_mfma_f32_16x16x32_bf16 v[12:15], v[176:179], v[212:215], 0
	v_mfma_f32_16x16x32_bf16 v[8:11], v[184:187], v[212:215], 0
	v_mfma_f32_16x16x32_bf16 v[4:7], v[176:179], v[220:223], 0
	v_mfma_f32_16x16x32_bf16 v[0:3], v[184:187], v[220:223], 0
	v_mfma_f32_16x16x32_bf16 v[44:47], v[180:183], v[200:203], v[44:47]
	v_mfma_f32_16x16x32_bf16 v[40:43], v[192:195], v[200:203], v[40:43]
	v_mfma_f32_16x16x32_bf16 v[28:31], v[180:183], v[208:211], v[28:31]
	v_mfma_f32_16x16x32_bf16 v[24:27], v[192:195], v[208:211], v[24:27]
	v_mfma_f32_16x16x32_bf16 v[12:15], v[180:183], v[216:219], v[12:15]
	v_mfma_f32_16x16x32_bf16 v[8:11], v[192:195], v[216:219], v[8:11]
	v_mfma_f32_16x16x32_bf16 v[4:7], v[180:183], v[224:227], v[4:7]
	v_mfma_f32_16x16x32_bf16 v[0:3], v[192:195], v[224:227], v[0:3]
	s_setprio 0
	s_barrier
	s_add_i32 s33, 0, 0x18000
	v_add_u32_e32 v161, s33, v150
	s_add_i32 s63, 0, 0x1c000
	ds_read_b128 v[154:157], v161
	ds_read_b128 v[164:167], v161 offset:1024
	ds_read_b128 v[168:171], v161 offset:2048
	ds_read_b128 v[172:175], v161 offset:3072
	v_add_u32_e32 v161, s63, v150
	ds_read_b128 v[176:179], v161
	ds_read_b128 v[180:183], v161 offset:1024
	ds_read_b128 v[184:187], v161 offset:2048
	ds_read_b128 v[192:195], v161 offset:3072
	s_add_u32 s34, s82, 0x80000
	s_addc_u32 s35, s83, 0
	s_mov_b32 m0, s18
	v_lshl_add_u64 v[232:233], s[34:35], 0, v[128:129]
	ds_read_b128 v[196:199], v153 offset:32768
	ds_read_b128 v[200:203], v153 offset:33792
	ds_read_b128 v[204:207], v153 offset:34816
	ds_read_b128 v[208:211], v153 offset:35840
	ds_read_b128 v[212:215], v153 offset:36864
	ds_read_b128 v[216:219], v153 offset:37888
	ds_read_b128 v[220:223], v153 offset:38912
	ds_read_b128 v[224:227], v153 offset:39936
	global_load_lds_dwordx4 v[232:233], off
	v_lshl_add_u64 v[232:233], s[34:35], 0, v[132:133]
	s_mov_b32 m0, s19
	s_nop 0
	global_load_lds_dwordx4 v[232:233], off
	s_waitcnt vmcnt(8)
	s_waitcnt lgkmcnt(0)
	s_barrier
	s_setprio 1
	s_waitcnt lgkmcnt(0)
	v_mfma_f32_16x16x32_bf16 v[124:127], v[154:157], v[196:199], v[124:127]
	v_mfma_f32_16x16x32_bf16 v[120:123], v[168:171], v[196:199], v[120:123]
	v_mfma_f32_16x16x32_bf16 v[116:119], v[154:157], v[204:207], v[116:119]
	v_mfma_f32_16x16x32_bf16 v[112:115], v[168:171], v[204:207], v[112:115]
	v_mfma_f32_16x16x32_bf16 v[100:103], v[154:157], v[212:215], v[100:103]
	v_mfma_f32_16x16x32_bf16 v[96:99], v[168:171], v[212:215], v[96:99]
	v_mfma_f32_16x16x32_bf16 v[84:87], v[154:157], v[220:223], v[84:87]
	v_mfma_f32_16x16x32_bf16 v[80:83], v[168:171], v[220:223], v[80:83]
	v_mfma_f32_16x16x32_bf16 v[124:127], v[164:167], v[200:203], v[124:127]
	v_mfma_f32_16x16x32_bf16 v[120:123], v[172:175], v[200:203], v[120:123]
	v_mfma_f32_16x16x32_bf16 v[116:119], v[164:167], v[208:211], v[116:119]
	v_mfma_f32_16x16x32_bf16 v[112:115], v[172:175], v[208:211], v[112:115]
	v_mfma_f32_16x16x32_bf16 v[100:103], v[164:167], v[216:219], v[100:103]
	v_mfma_f32_16x16x32_bf16 v[96:99], v[172:175], v[216:219], v[96:99]
	v_mfma_f32_16x16x32_bf16 v[84:87], v[164:167], v[224:227], v[84:87]
	v_mfma_f32_16x16x32_bf16 v[80:83], v[172:175], v[224:227], v[80:83]
	s_setprio 0
	s_setprio 1
	v_mfma_f32_16x16x32_bf16 v[108:111], v[176:179], v[196:199], v[108:111]
	v_mfma_f32_16x16x32_bf16 v[104:107], v[184:187], v[196:199], v[104:107]
	v_mfma_f32_16x16x32_bf16 v[92:95], v[176:179], v[204:207], v[92:95]
	v_mfma_f32_16x16x32_bf16 v[88:91], v[184:187], v[204:207], v[88:91]
	v_mfma_f32_16x16x32_bf16 v[76:79], v[176:179], v[212:215], v[76:79]
	v_mfma_f32_16x16x32_bf16 v[72:75], v[184:187], v[212:215], v[72:75]
	v_mfma_f32_16x16x32_bf16 v[68:71], v[176:179], v[220:223], v[68:71]
	v_mfma_f32_16x16x32_bf16 v[64:67], v[184:187], v[220:223], v[64:67]
	v_mfma_f32_16x16x32_bf16 v[108:111], v[180:183], v[200:203], v[108:111]
	v_mfma_f32_16x16x32_bf16 v[104:107], v[192:195], v[200:203], v[104:107]
	v_mfma_f32_16x16x32_bf16 v[92:95], v[180:183], v[208:211], v[92:95]
	v_mfma_f32_16x16x32_bf16 v[88:91], v[192:195], v[208:211], v[88:91]
	v_mfma_f32_16x16x32_bf16 v[76:79], v[180:183], v[216:219], v[76:79]
	v_mfma_f32_16x16x32_bf16 v[72:75], v[192:195], v[216:219], v[72:75]
	v_mfma_f32_16x16x32_bf16 v[68:71], v[180:183], v[224:227], v[68:71]
	v_mfma_f32_16x16x32_bf16 v[64:67], v[192:195], v[224:227], v[64:67]
	s_setprio 0
	s_barrier
; #define PG8_STAGE(bufoff, gbase, voff) do { _Pragma("unroll") for (int _i = 0; _i < 2; ++_i) \
;         __builtin_amdgcn_global_load_lds((const unsigned*)((const char*)(gbase) + (voff)[_i]), (LAS unsigned*)(lds + (bufoff) + ldsw + _i * 8192), 16, 0, 0); } while (0)
; #define PG8_LDA(dst, b, h) do { _Pragma("unroll") for (int m = 0; m < 4; ++m) _Pragma("unroll") for (int k = 0; k < 2; ++k) dst[m][k] = *(const LAS bf16x8*)(lds + PG8_SA(b, h) + aoff + m * 2048 + k * 1024); } while (0)
; #define PG8_LDB(dst, b, h) do { _Pragma("unroll") for (int n = 0; n < 2; ++n) _Pragma("unroll") for (int k = 0; k < 2; ++k) dst[n][k] = *(const LAS bf16x8*)(lds + PG8_SB(b, h) + boff + n * 2048 + k * 1024); } while (0)
; #define PG8_MMA(ai, bj, At, Bt) do { __builtin_amdgcn_s_setprio(1); _Pragma("unroll") for (int m = 0; m < 4; ++m) _Pragma("unroll") for (int n = 0; n < 2; ++n) _Pragma("unroll") for (int k = 0; k < 2; ++k) \
;         acc[ai][bj][m][n] = __builtin_amdgcn_mfma_f32_16x16x32_bf16(Bt[n][k], At[m][k], acc[ai][bj][m][n], 0, 0, 0); __builtin_amdgcn_s_setprio(0); } while (0)
; #define PG8_WAIT_V(n) asm volatile("s_waitcnt vmcnt(" #n ")" ::: "memory")
; #define PG8_WAIT_L(n) asm volatile("s_waitcnt lgkmcnt(" #n ")" ::: "memory")
; #define PG8_BAR __builtin_amdgcn_s_barrier()
; #define PG8_SCHED __builtin_amdgcn_sched_barrier(0)
; template <int GI>
; __device__ __forceinline__ void gemm_phase(LAS unsigned char* lds, unsigned char* ws, int G, int cblk) {
;     ...
;         for (int t = 0; t < nt; t += 2) {
;             const bool last = (t == nt - 2);
;             const char* a1 = cA + (size_t)(t + 1) * kstep;
;             const char* a2 = last ? nA : cA + (size_t)(t + 2) * kstep; const char* b2 = last ? nB : cB + (size_t)(t + 2) * kstep;
;             const char* a3 = a2 + kstep; const char* b3 = b2 + kstep;
;             PG8_LDB(B0, 0, 0); PG8_LDB(B1, 0, 1); PG8_SCHED; PG8_LDA(At, 0, 0); PG8_STAGE(PG8_SA(1, 1), a1 + hstepA, voffA);
;             PG8_WAIT_V(8); PG8_WAIT_L(0); PG8_BAR; PG8_MMA(0, 0, At, B0); PG8_MMA(0, 1, At, B1); PG8_BAR; PG8_SCHED;
;     ...
;             PG8_LDA(At, 1, 1); PG8_STAGE(PG8_SB(1, 0), b3, voffB); PG8_STAGE(PG8_SB(1, 1), b3 + hstepB, voffB); PG8_STAGE(PG8_SA(1, 0), a3, voffA);
;             PG8_WAIT_V(8); PG8_WAIT_L(0); PG8_BAR; PG8_MMA(1, 0, At, B0); PG8_MMA(1, 1, At, B1); PG8_BAR; PG8_SCHED;
;         }
	s_add_i32 s33, s33, s0
	v_lshl_add_u64 v[158:159], v[158:159], 0, s[38:39]
	s_mov_b32 m0, s33
	ds_read_b128 v[196:199], v153 offset:49152
	ds_read_b128 v[200:203], v153 offset:50176
	ds_read_b128 v[204:207], v153 offset:51200
	ds_read_b128 v[208:211], v153 offset:52224
	ds_read_b128 v[212:215], v153 offset:53248
	ds_read_b128 v[216:219], v153 offset:54272
	ds_read_b128 v[220:223], v153 offset:55296
	ds_read_b128 v[224:227], v153 offset:56320
	global_load_lds_dwordx4 v[158:159], off
	s_add_i32 m0, s33, 0x2000
	s_add_u32 s34, s80, 0x80080
	v_lshl_add_u64 v[158:159], v[188:189], 0, s[38:39]
	s_addc_u32 s35, s81, 0
	s_add_i32 s33, s63, s0
	global_load_lds_dwordx4 v[158:159], off
	v_lshl_add_u64 v[158:159], s[34:35], 0, v[130:131]
	s_mov_b32 m0, s33
	s_nop 0
	global_load_lds_dwordx4 v[158:159], off
	v_lshl_add_u64 v[158:159], s[34:35], 0, v[134:135]
	s_add_i32 m0, s33, 0x2000
	s_nop 0
	global_load_lds_dwordx4 v[158:159], off
	v_lshl_add_u64 v[158:159], v[228:229], 0, s[38:39]
	s_mov_b32 m0, s22
	s_nop 0
	global_load_lds_dwordx4 v[158:159], off
	v_lshl_add_u64 v[158:159], v[230:231], 0, s[38:39]
	s_mov_b32 m0, s23
	s_nop 0
	global_load_lds_dwordx4 v[158:159], off
	s_waitcnt vmcnt(8)
	s_waitcnt lgkmcnt(0)
	s_barrier
	s_setprio 1
	s_waitcnt lgkmcnt(0)
	v_mfma_f32_16x16x32_bf16 v[60:63], v[154:157], v[196:199], v[60:63]
	v_mfma_f32_16x16x32_bf16 v[56:59], v[168:171], v[196:199], v[56:59]
	s_add_i32 s27, s27, 2
	s_add_u32 s78, s78, 0x100
	s_addc_u32 s79, s79, 0
	s_add_u32 s14, s14, 0x100
	s_addc_u32 s15, s15, 0
	v_mfma_f32_16x16x32_bf16 v[52:55], v[154:157], v[204:207], v[52:55]
	v_mfma_f32_16x16x32_bf16 v[48:51], v[168:171], v[204:207], v[48:51]
	v_mfma_f32_16x16x32_bf16 v[36:39], v[154:157], v[212:215], v[36:39]
	v_mfma_f32_16x16x32_bf16 v[32:35], v[168:171], v[212:215], v[32:35]
	v_mfma_f32_16x16x32_bf16 v[20:23], v[154:157], v[220:223], v[20:23]
	v_mfma_f32_16x16x32_bf16 v[16:19], v[168:171], v[220:223], v[16:19]
	v_mfma_f32_16x16x32_bf16 v[60:63], v[164:167], v[200:203], v[60:63]
	v_mfma_f32_16x16x32_bf16 v[56:59], v[172:175], v[200:203], v[56:59]
	v_mfma_f32_16x16x32_bf16 v[52:55], v[164:167], v[208:211], v[52:55]
	v_mfma_f32_16x16x32_bf16 v[48:51], v[172:175], v[208:211], v[48:51]
	v_mfma_f32_16x16x32_bf16 v[36:39], v[164:167], v[216:219], v[36:39]
	v_mfma_f32_16x16x32_bf16 v[32:35], v[172:175], v[216:219], v[32:35]
	v_mfma_f32_16x16x32_bf16 v[20:23], v[164:167], v[224:227], v[20:23]
	v_mfma_f32_16x16x32_bf16 v[16:19], v[172:175], v[224:227], v[16:19]
	s_setprio 0
	s_setprio 1
	v_mfma_f32_16x16x32_bf16 v[44:47], v[176:179], v[196:199], v[44:47]
	v_mfma_f32_16x16x32_bf16 v[40:43], v[184:187], v[196:199], v[40:43]
	v_mfma_f32_16x16x32_bf16 v[28:31], v[176:179], v[204:207], v[28:31]
	v_mfma_f32_16x16x32_bf16 v[24:27], v[184:187], v[204:207], v[24:27]
	v_mfma_f32_16x16x32_bf16 v[12:15], v[176:179], v[212:215], v[12:15]
	v_mfma_f32_16x16x32_bf16 v[8:11], v[184:187], v[212:215], v[8:11]
	v_mfma_f32_16x16x32_bf16 v[4:7], v[176:179], v[220:223], v[4:7]
	v_mfma_f32_16x16x32_bf16 v[0:3], v[184:187], v[220:223], v[0:3]
	v_mfma_f32_16x16x32_bf16 v[44:47], v[180:183], v[200:203], v[44:47]
	v_mfma_f32_16x16x32_bf16 v[40:43], v[192:195], v[200:203], v[40:43]
	v_mfma_f32_16x16x32_bf16 v[28:31], v[180:183], v[208:211], v[28:31]
	v_mfma_f32_16x16x32_bf16 v[24:27], v[192:195], v[208:211], v[24:27]
	v_mfma_f32_16x16x32_bf16 v[12:15], v[180:183], v[216:219], v[12:15]
	v_mfma_f32_16x16x32_bf16 v[8:11], v[192:195], v[216:219], v[8:11]
	v_mfma_f32_16x16x32_bf16 v[4:7], v[180:183], v[224:227], v[4:7]
	v_mfma_f32_16x16x32_bf16 v[0:3], v[192:195], v[224:227], v[0:3]
	s_setprio 0
	s_barrier
	s_cmp_gt_u32 s27, 29
	s_cbranch_scc0 .LBB0_148
	s_branch .Lpeel_exit_2
.LBB0_148:
	ds_read_b128 v[154:157], v151
	ds_read_b128 v[164:167], v151 offset:1024
	ds_read_b128 v[168:171], v151 offset:2048
	ds_read_b128 v[172:175], v151 offset:3072
	ds_read_b128 v[176:179], v152
	ds_read_b128 v[180:183], v152 offset:1024
	ds_read_b128 v[184:187], v152 offset:2048
	ds_read_b128 v[192:195], v152 offset:3072
	s_add_u32 s33, s78, 0xfff80080
	s_addc_u32 s34, s79, -1
	s_cmp_eq_u32 s27, 28
	s_cselect_b32 s83, s73, s34
	s_cselect_b32 s82, s72, s33
	s_cselect_b32 s81, s75, s15
	s_cselect_b32 s80, s74, s14
	v_lshl_add_u64 v[158:159], s[78:79], 0, v[138:139]
	s_add_i32 m0, s16, 0xc000
	ds_read_b128 v[196:199], v153
	ds_read_b128 v[200:203], v153 offset:1024
	ds_read_b128 v[204:207], v153 offset:2048
	ds_read_b128 v[208:211], v153 offset:3072
	ds_read_b128 v[212:215], v153 offset:4096
	ds_read_b128 v[216:219], v153 offset:5120
	ds_read_b128 v[220:223], v153 offset:6144
	ds_read_b128 v[224:227], v153 offset:7168
	global_load_lds_dwordx4 v[158:159], off
	v_lshl_add_u64 v[158:159], s[78:79], 0, v[140:141]
	s_add_i32 m0, s16, 0xe000
	s_nop 0
	global_load_lds_dwordx4 v[158:159], off
	s_waitcnt vmcnt(8)
	s_waitcnt lgkmcnt(0)
	s_barrier
; #define PG8_STAGE(bufoff, gbase, voff) do { _Pragma("unroll") for (int _i = 0; _i < 2; ++_i) \
;         __builtin_amdgcn_global_load_lds((const unsigned*)((const char*)(gbase) + (voff)[_i]), (LAS unsigned*)(lds + (bufoff) + ldsw + _i * 8192), 16, 0, 0); } while (0)
; #define PG8_LDA(dst, b, h) do { _Pragma("unroll") for (int m = 0; m < 4; ++m) _Pragma("unroll") for (int k = 0; k < 2; ++k) dst[m][k] = *(const LAS bf16x8*)(lds + PG8_SA(b, h) + aoff + m * 2048 + k * 1024); } while (0)
; #define PG8_MMA(ai, bj, At, Bt) do { __builtin_amdgcn_s_setprio(1); _Pragma("unroll") for (int m = 0; m < 4; ++m) _Pragma("unroll") for (int n = 0; n < 2; ++n) _Pragma("unroll") for (int k = 0; k < 2; ++k) \
;         acc[ai][bj][m][n] = __builtin_amdgcn_mfma_f32_16x16x32_bf16(Bt[n][k], At[m][k], acc[ai][bj][m][n], 0, 0, 0); __builtin_amdgcn_s_setprio(0); } while (0)
; #define PG8_WAIT_V(n) asm volatile("s_waitcnt vmcnt(" #n ")" ::: "memory")
; #define PG8_WAIT_L(n) asm volatile("s_waitcnt lgkmcnt(" #n ")" ::: "memory")
; #define PG8_BAR __builtin_amdgcn_s_barrier()
; #define PG8_SCHED __builtin_amdgcn_sched_barrier(0)
; template <int GI>
; __device__ __forceinline__ void gemm_phase(LAS unsigned char* lds, unsigned char* ws, int G, int cblk) {
;     ...
;             PG8_WAIT_V(8); PG8_WAIT_L(0); PG8_BAR; PG8_MMA(0, 0, At, B0); PG8_MMA(0, 1, At, B1); PG8_BAR; PG8_SCHED;
;             PG8_LDA(At, 0, 1); PG8_STAGE(PG8_SB(0, 0), b2, voffB); PG8_STAGE(PG8_SB(0, 1), b2 + hstepB, voffB); PG8_STAGE(PG8_SA(0, 0), a2, voffA);
;             PG8_WAIT_V(8); PG8_WAIT_L(0); PG8_BAR; PG8_MMA(1, 0, At, B0); PG8_MMA(1, 1, At, B1); PG8_BAR; PG8_SCHED;
	s_setprio 1
	s_waitcnt lgkmcnt(0)
	v_mfma_f32_16x16x32_bf16 v[124:127], v[154:157], v[196:199], v[124:127]
	v_mfma_f32_16x16x32_bf16 v[120:123], v[168:171], v[196:199], v[120:123]
	v_mfma_f32_16x16x32_bf16 v[116:119], v[154:157], v[204:207], v[116:119]
	v_mfma_f32_16x16x32_bf16 v[112:115], v[168:171], v[204:207], v[112:115]
	v_mfma_f32_16x16x32_bf16 v[100:103], v[154:157], v[212:215], v[100:103]
	v_mfma_f32_16x16x32_bf16 v[96:99], v[168:171], v[212:215], v[96:99]
	v_mfma_f32_16x16x32_bf16 v[84:87], v[154:157], v[220:223], v[84:87]
	v_mfma_f32_16x16x32_bf16 v[80:83], v[168:171], v[220:223], v[80:83]
	v_mfma_f32_16x16x32_bf16 v[124:127], v[164:167], v[200:203], v[124:127]
	v_mfma_f32_16x16x32_bf16 v[120:123], v[172:175], v[200:203], v[120:123]
	v_mfma_f32_16x16x32_bf16 v[116:119], v[164:167], v[208:211], v[116:119]
	v_mfma_f32_16x16x32_bf16 v[112:115], v[172:175], v[208:211], v[112:115]
	v_mfma_f32_16x16x32_bf16 v[100:103], v[164:167], v[216:219], v[100:103]
	v_mfma_f32_16x16x32_bf16 v[96:99], v[172:175], v[216:219], v[96:99]
	v_mfma_f32_16x16x32_bf16 v[84:87], v[164:167], v[224:227], v[84:87]
	v_mfma_f32_16x16x32_bf16 v[80:83], v[172:175], v[224:227], v[80:83]
	s_setprio 0
	s_setprio 1
	v_mfma_f32_16x16x32_bf16 v[108:111], v[176:179], v[196:199], v[108:111]
	v_mfma_f32_16x16x32_bf16 v[104:107], v[184:187], v[196:199], v[104:107]
	v_mfma_f32_16x16x32_bf16 v[92:95], v[176:179], v[204:207], v[92:95]
	v_mfma_f32_16x16x32_bf16 v[88:91], v[184:187], v[204:207], v[88:91]
	v_mfma_f32_16x16x32_bf16 v[76:79], v[176:179], v[212:215], v[76:79]
	v_mfma_f32_16x16x32_bf16 v[72:75], v[184:187], v[212:215], v[72:75]
	v_mfma_f32_16x16x32_bf16 v[68:71], v[176:179], v[220:223], v[68:71]
	v_mfma_f32_16x16x32_bf16 v[64:67], v[184:187], v[220:223], v[64:67]
	v_mfma_f32_16x16x32_bf16 v[108:111], v[180:183], v[200:203], v[108:111]
	v_mfma_f32_16x16x32_bf16 v[104:107], v[192:195], v[200:203], v[104:107]
	v_mfma_f32_16x16x32_bf16 v[92:95], v[180:183], v[208:211], v[92:95]
	v_mfma_f32_16x16x32_bf16 v[88:91], v[192:195], v[208:211], v[88:91]
	v_mfma_f32_16x16x32_bf16 v[76:79], v[180:183], v[216:219], v[76:79]
	v_mfma_f32_16x16x32_bf16 v[72:75], v[192:195], v[216:219], v[72:75]
	v_mfma_f32_16x16x32_bf16 v[68:71], v[180:183], v[224:227], v[68:71]
	v_mfma_f32_16x16x32_bf16 v[64:67], v[192:195], v[224:227], v[64:67]
	s_setprio 0
	s_barrier
	s_add_i32 s33, s24, s0
	v_lshl_add_u64 v[158:159], s[80:81], 0, v[130:131]
	s_mov_b32 m0, s33
	ds_read_b128 v[196:199], v153 offset:16384
	ds_read_b128 v[200:203], v153 offset:17408
	ds_read_b128 v[204:207], v153 offset:18432
	ds_read_b128 v[208:211], v153 offset:19456
	ds_read_b128 v[212:215], v153 offset:20480
	ds_read_b128 v[216:219], v153 offset:21504
	ds_read_b128 v[220:223], v153 offset:22528
	ds_read_b128 v[224:227], v153 offset:23552
	global_load_lds_dwordx4 v[158:159], off
	s_add_i32 m0, s33, 0x2000
	s_add_u32 s34, s80, 0x80000
	v_lshl_add_u64 v[188:189], s[80:81], 0, v[134:135]
	s_addc_u32 s35, s81, 0
	s_add_i32 s33, s25, s0
	global_load_lds_dwordx4 v[188:189], off
	v_lshl_add_u64 v[228:229], s[34:35], 0, v[130:131]
	s_mov_b32 m0, s33
	v_lshl_add_u64 v[230:231], s[82:83], 0, v[132:133]
	global_load_lds_dwordx4 v[228:229], off
	v_lshl_add_u64 v[228:229], s[34:35], 0, v[134:135]
	s_add_i32 m0, s33, 0x2000
	s_nop 0
	global_load_lds_dwordx4 v[228:229], off
	v_lshl_add_u64 v[228:229], s[82:83], 0, v[128:129]
	s_mov_b32 m0, s16
	s_nop 0
	global_load_lds_dwordx4 v[228:229], off
	s_mov_b32 m0, s17
	s_nop 0
	global_load_lds_dwordx4 v[230:231], off
	s_waitcnt vmcnt(8)
	s_waitcnt lgkmcnt(0)
	s_barrier
	s_setprio 1
	s_waitcnt lgkmcnt(0)
	v_mfma_f32_16x16x32_bf16 v[60:63], v[154:157], v[196:199], v[60:63]
	v_mfma_f32_16x16x32_bf16 v[56:59], v[168:171], v[196:199], v[56:59]
	v_mfma_f32_16x16x32_bf16 v[52:55], v[154:157], v[204:207], v[52:55]
	v_mfma_f32_16x16x32_bf16 v[48:51], v[168:171], v[204:207], v[48:51]
	v_mfma_f32_16x16x32_bf16 v[36:39], v[154:157], v[212:215], v[36:39]
	v_mfma_f32_16x16x32_bf16 v[32:35], v[168:171], v[212:215], v[32:35]
	v_mfma_f32_16x16x32_bf16 v[20:23], v[154:157], v[220:223], v[20:23]
	v_mfma_f32_16x16x32_bf16 v[16:19], v[168:171], v[220:223], v[16:19]
	v_mfma_f32_16x16x32_bf16 v[60:63], v[164:167], v[200:203], v[60:63]
	v_mfma_f32_16x16x32_bf16 v[56:59], v[172:175], v[200:203], v[56:59]
	v_mfma_f32_16x16x32_bf16 v[52:55], v[164:167], v[208:211], v[52:55]
	v_mfma_f32_16x16x32_bf16 v[48:51], v[172:175], v[208:211], v[48:51]
	v_mfma_f32_16x16x32_bf16 v[36:39], v[164:167], v[216:219], v[36:39]
	v_mfma_f32_16x16x32_bf16 v[32:35], v[172:175], v[216:219], v[32:35]
	v_mfma_f32_16x16x32_bf16 v[20:23], v[164:167], v[224:227], v[20:23]
	v_mfma_f32_16x16x32_bf16 v[16:19], v[172:175], v[224:227], v[16:19]
	s_setprio 0
	s_setprio 1
	v_mfma_f32_16x16x32_bf16 v[44:47], v[176:179], v[196:199], v[44:47]
	v_mfma_f32_16x16x32_bf16 v[40:43], v[184:187], v[196:199], v[40:43]
	v_mfma_f32_16x16x32_bf16 v[28:31], v[176:179], v[204:207], v[28:31]
	v_mfma_f32_16x16x32_bf16 v[24:27], v[184:187], v[204:207], v[24:27]
	v_mfma_f32_16x16x32_bf16 v[12:15], v[176:179], v[212:215], v[12:15]
	v_mfma_f32_16x16x32_bf16 v[8:11], v[184:187], v[212:215], v[8:11]
	v_mfma_f32_16x16x32_bf16 v[4:7], v[176:179], v[220:223], v[4:7]
	v_mfma_f32_16x16x32_bf16 v[0:3], v[184:187], v[220:223], v[0:3]
	v_mfma_f32_16x16x32_bf16 v[44:47], v[180:183], v[200:203], v[44:47]
	v_mfma_f32_16x16x32_bf16 v[40:43], v[192:195], v[200:203], v[40:43]
	v_mfma_f32_16x16x32_bf16 v[28:31], v[180:183], v[208:211], v[28:31]
	v_mfma_f32_16x16x32_bf16 v[24:27], v[192:195], v[208:211], v[24:27]
	v_mfma_f32_16x16x32_bf16 v[12:15], v[180:183], v[216:219], v[12:15]
	v_mfma_f32_16x16x32_bf16 v[8:11], v[192:195], v[216:219], v[8:11]
	v_mfma_f32_16x16x32_bf16 v[4:7], v[180:183], v[224:227], v[4:7]
	v_mfma_f32_16x16x32_bf16 v[0:3], v[192:195], v[224:227], v[0:3]
	s_setprio 0
	s_barrier
; #define PG8_STAGE(bufoff, gbase, voff) do { _Pragma("unroll") for (int _i = 0; _i < 2; ++_i) \
;         __builtin_amdgcn_global_load_lds((const unsigned*)((const char*)(gbase) + (voff)[_i]), (LAS unsigned*)(lds + (bufoff) + ldsw + _i * 8192), 16, 0, 0); } while (0)
; #define PG8_LDA(dst, b, h) do { _Pragma("unroll") for (int m = 0; m < 4; ++m) _Pragma("unroll") for (int k = 0; k < 2; ++k) dst[m][k] = *(const LAS bf16x8*)(lds + PG8_SA(b, h) + aoff + m * 2048 + k * 1024); } while (0)
; #define PG8_LDB(dst, b, h) do { _Pragma("unroll") for (int n = 0; n < 2; ++n) _Pragma("unroll") for (int k = 0; k < 2; ++k) dst[n][k] = *(const LAS bf16x8*)(lds + PG8_SB(b, h) + boff + n * 2048 + k * 1024); } while (0)
; #define PG8_MMA(ai, bj, At, Bt) do { __builtin_amdgcn_s_setprio(1); _Pragma("unroll") for (int m = 0; m < 4; ++m) _Pragma("unroll") for (int n = 0; n < 2; ++n) _Pragma("unroll") for (int k = 0; k < 2; ++k) \
;         acc[ai][bj][m][n] = __builtin_amdgcn_mfma_f32_16x16x32_bf16(Bt[n][k], At[m][k], acc[ai][bj][m][n], 0, 0, 0); __builtin_amdgcn_s_setprio(0); } while (0)
; #define PG8_WAIT_V(n) asm volatile("s_waitcnt vmcnt(" #n ")" ::: "memory")
; #define PG8_WAIT_L(n) asm volatile("s_waitcnt lgkmcnt(" #n ")" ::: "memory")
; #define PG8_BAR __builtin_amdgcn_s_barrier()
; #define PG8_SCHED __builtin_amdgcn_sched_barrier(0)
; template <int GI>
; __device__ __forceinline__ void gemm_phase(LAS unsigned char* lds, unsigned char* ws, int G, int cblk) {
;     ...
;             PG8_LDB(B0, 1, 0); PG8_LDB(B1, 1, 1); PG8_SCHED; PG8_LDA(At, 1, 0); PG8_STAGE(PG8_SA(0, 1), a2 + hstepA, voffA);
;             PG8_WAIT_V(8); PG8_WAIT_L(0); PG8_BAR; PG8_MMA(0, 0, At, B0); PG8_MMA(0, 1, At, B1); PG8_BAR; PG8_SCHED;
	s_add_i32 s33, 0, 0x18000
	v_add_u32_e32 v161, s33, v150
	s_add_i32 s63, 0, 0x1c000
	ds_read_b128 v[154:157], v161
	ds_read_b128 v[164:167], v161 offset:1024
	ds_read_b128 v[168:171], v161 offset:2048
	ds_read_b128 v[172:175], v161 offset:3072
	v_add_u32_e32 v161, s63, v150
	ds_read_b128 v[176:179], v161
	ds_read_b128 v[180:183], v161 offset:1024
	ds_read_b128 v[184:187], v161 offset:2048
	ds_read_b128 v[192:195], v161 offset:3072
	s_add_u32 s34, s82, 0x80000
	s_addc_u32 s35, s83, 0
	s_mov_b32 m0, s18
	v_lshl_add_u64 v[232:233], s[34:35], 0, v[128:129]
	ds_read_b128 v[196:199], v153 offset:32768
	ds_read_b128 v[200:203], v153 offset:33792
	ds_read_b128 v[204:207], v153 offset:34816
	ds_read_b128 v[208:211], v153 offset:35840
	ds_read_b128 v[212:215], v153 offset:36864
	ds_read_b128 v[216:219], v153 offset:37888
	ds_read_b128 v[220:223], v153 offset:38912
	ds_read_b128 v[224:227], v153 offset:39936
	global_load_lds_dwordx4 v[232:233], off
	v_lshl_add_u64 v[232:233], s[34:35], 0, v[132:133]
	s_mov_b32 m0, s19
	s_nop 0
	global_load_lds_dwordx4 v[232:233], off
	s_waitcnt vmcnt(8)
	s_waitcnt lgkmcnt(0)
	s_barrier
	s_setprio 1
	s_waitcnt lgkmcnt(0)
	v_mfma_f32_16x16x32_bf16 v[124:127], v[154:157], v[196:199], v[124:127]
	v_mfma_f32_16x16x32_bf16 v[120:123], v[168:171], v[196:199], v[120:123]
	v_mfma_f32_16x16x32_bf16 v[116:119], v[154:157], v[204:207], v[116:119]
	v_mfma_f32_16x16x32_bf16 v[112:115], v[168:171], v[204:207], v[112:115]
	v_mfma_f32_16x16x32_bf16 v[100:103], v[154:157], v[212:215], v[100:103]
	v_mfma_f32_16x16x32_bf16 v[96:99], v[168:171], v[212:215], v[96:99]
	v_mfma_f32_16x16x32_bf16 v[84:87], v[154:157], v[220:223], v[84:87]
	v_mfma_f32_16x16x32_bf16 v[80:83], v[168:171], v[220:223], v[80:83]
	v_mfma_f32_16x16x32_bf16 v[124:127], v[164:167], v[200:203], v[124:127]
	v_mfma_f32_16x16x32_bf16 v[120:123], v[172:175], v[200:203], v[120:123]
	v_mfma_f32_16x16x32_bf16 v[116:119], v[164:167], v[208:211], v[116:119]
	v_mfma_f32_16x16x32_bf16 v[112:115], v[172:175], v[208:211], v[112:115]
	v_mfma_f32_16x16x32_bf16 v[100:103], v[164:167], v[216:219], v[100:103]
	v_mfma_f32_16x16x32_bf16 v[96:99], v[172:175], v[216:219], v[96:99]
	v_mfma_f32_16x16x32_bf16 v[84:87], v[164:167], v[224:227], v[84:87]
	v_mfma_f32_16x16x32_bf16 v[80:83], v[172:175], v[224:227], v[80:83]
	s_setprio 0
	s_setprio 1
	v_mfma_f32_16x16x32_bf16 v[108:111], v[176:179], v[196:199], v[108:111]
	v_mfma_f32_16x16x32_bf16 v[104:107], v[184:187], v[196:199], v[104:107]
	v_mfma_f32_16x16x32_bf16 v[92:95], v[176:179], v[204:207], v[92:95]
	v_mfma_f32_16x16x32_bf16 v[88:91], v[184:187], v[204:207], v[88:91]
	v_mfma_f32_16x16x32_bf16 v[76:79], v[176:179], v[212:215], v[76:79]
	v_mfma_f32_16x16x32_bf16 v[72:75], v[184:187], v[212:215], v[72:75]
	v_mfma_f32_16x16x32_bf16 v[68:71], v[176:179], v[220:223], v[68:71]
	v_mfma_f32_16x16x32_bf16 v[64:67], v[184:187], v[220:223], v[64:67]
	v_mfma_f32_16x16x32_bf16 v[108:111], v[180:183], v[200:203], v[108:111]
	v_mfma_f32_16x16x32_bf16 v[104:107], v[192:195], v[200:203], v[104:107]
	v_mfma_f32_16x16x32_bf16 v[92:95], v[180:183], v[208:211], v[92:95]
	v_mfma_f32_16x16x32_bf16 v[88:91], v[192:195], v[208:211], v[88:91]
	v_mfma_f32_16x16x32_bf16 v[76:79], v[180:183], v[216:219], v[76:79]
	v_mfma_f32_16x16x32_bf16 v[72:75], v[192:195], v[216:219], v[72:75]
	v_mfma_f32_16x16x32_bf16 v[68:71], v[180:183], v[224:227], v[68:71]
	v_mfma_f32_16x16x32_bf16 v[64:67], v[192:195], v[224:227], v[64:67]
	s_setprio 0
	s_barrier
; #define PG8_STAGE(bufoff, gbase, voff) do { _Pragma("unroll") for (int _i = 0; _i < 2; ++_i) \
;         __builtin_amdgcn_global_load_lds((const unsigned*)((const char*)(gbase) + (voff)[_i]), (LAS unsigned*)(lds + (bufoff) + ldsw + _i * 8192), 16, 0, 0); } while (0)
; #define PG8_LDA(dst, b, h) do { _Pragma("unroll") for (int m = 0; m < 4; ++m) _Pragma("unroll") for (int k = 0; k < 2; ++k) dst[m][k] = *(const LAS bf16x8*)(lds + PG8_SA(b, h) + aoff + m * 2048 + k * 1024); } while (0)
; #define PG8_MMA(ai, bj, At, Bt) do { __builtin_amdgcn_s_setprio(1); _Pragma("unroll") for (int m = 0; m < 4; ++m) _Pragma("unroll") for (int n = 0; n < 2; ++n) _Pragma("unroll") for (int k = 0; k < 2; ++k) \
;         acc[ai][bj][m][n] = __builtin_amdgcn_mfma_f32_16x16x32_bf16(Bt[n][k], At[m][k], acc[ai][bj][m][n], 0, 0, 0); __builtin_amdgcn_s_setprio(0); } while (0)
; #define PG8_WAIT_V(n) asm volatile("s_waitcnt vmcnt(" #n ")" ::: "memory")
; #define PG8_WAIT_L(n) asm volatile("s_waitcnt lgkmcnt(" #n ")" ::: "memory")
; #define PG8_BAR __builtin_amdgcn_s_barrier()
; #define PG8_SCHED __builtin_amdgcn_sched_barrier(0)
; template <int GI>
; __device__ __forceinline__ void gemm_phase(LAS unsigned char* lds, unsigned char* ws, int G, int cblk) {
;     ...
;             PG8_LDA(At, 1, 1); PG8_STAGE(PG8_SB(1, 0), b3, voffB); PG8_STAGE(PG8_SB(1, 1), b3 + hstepB, voffB); PG8_STAGE(PG8_SA(1, 0), a3, voffA);
;             PG8_WAIT_V(8); PG8_WAIT_L(0); PG8_BAR; PG8_MMA(1, 0, At, B0); PG8_MMA(1, 1, At, B1); PG8_BAR; PG8_SCHED;
;         }
	s_add_i32 s33, s33, s0
	v_lshl_add_u64 v[158:159], v[158:159], 0, s[38:39]
	s_mov_b32 m0, s33
	ds_read_b128 v[196:199], v153 offset:49152
	ds_read_b128 v[200:203], v153 offset:50176
	ds_read_b128 v[204:207], v153 offset:51200
	ds_read_b128 v[208:211], v153 offset:52224
	ds_read_b128 v[212:215], v153 offset:53248
	ds_read_b128 v[216:219], v153 offset:54272
	ds_read_b128 v[220:223], v153 offset:55296
	ds_read_b128 v[224:227], v153 offset:56320
	global_load_lds_dwordx4 v[158:159], off
	s_add_i32 m0, s33, 0x2000
	s_add_u32 s34, s80, 0x80080
	v_lshl_add_u64 v[158:159], v[188:189], 0, s[38:39]
	s_addc_u32 s35, s81, 0
	s_add_i32 s33, s63, s0
	global_load_lds_dwordx4 v[158:159], off
	v_lshl_add_u64 v[158:159], s[34:35], 0, v[130:131]
	s_mov_b32 m0, s33
	s_nop 0
	global_load_lds_dwordx4 v[158:159], off
	v_lshl_add_u64 v[158:159], s[34:35], 0, v[134:135]
	s_add_i32 m0, s33, 0x2000
	s_nop 0
	global_load_lds_dwordx4 v[158:159], off
	v_lshl_add_u64 v[158:159], v[228:229], 0, s[38:39]
	s_mov_b32 m0, s22
	s_nop 0
	global_load_lds_dwordx4 v[158:159], off
	v_lshl_add_u64 v[158:159], v[230:231], 0, s[38:39]
	s_mov_b32 m0, s23
	s_nop 0
	global_load_lds_dwordx4 v[158:159], off
	s_waitcnt vmcnt(8)
	s_waitcnt lgkmcnt(0)
	s_barrier
	s_setprio 1
	s_waitcnt lgkmcnt(0)
	v_mfma_f32_16x16x32_bf16 v[60:63], v[154:157], v[196:199], v[60:63]
	v_mfma_f32_16x16x32_bf16 v[56:59], v[168:171], v[196:199], v[56:59]
	s_add_i32 s27, s27, 2
	s_add_u32 s78, s78, 0x100
	s_addc_u32 s79, s79, 0
	s_add_u32 s14, s14, 0x100
	s_addc_u32 s15, s15, 0
	v_mfma_f32_16x16x32_bf16 v[52:55], v[154:157], v[204:207], v[52:55]
	v_mfma_f32_16x16x32_bf16 v[48:51], v[168:171], v[204:207], v[48:51]
	v_mfma_f32_16x16x32_bf16 v[36:39], v[154:157], v[212:215], v[36:39]
	v_mfma_f32_16x16x32_bf16 v[32:35], v[168:171], v[212:215], v[32:35]
	v_mfma_f32_16x16x32_bf16 v[20:23], v[154:157], v[220:223], v[20:23]
	v_mfma_f32_16x16x32_bf16 v[16:19], v[168:171], v[220:223], v[16:19]
	v_mfma_f32_16x16x32_bf16 v[60:63], v[164:167], v[200:203], v[60:63]
	v_mfma_f32_16x16x32_bf16 v[56:59], v[172:175], v[200:203], v[56:59]
	v_mfma_f32_16x16x32_bf16 v[52:55], v[164:167], v[208:211], v[52:55]
	v_mfma_f32_16x16x32_bf16 v[48:51], v[172:175], v[208:211], v[48:51]
	v_mfma_f32_16x16x32_bf16 v[36:39], v[164:167], v[216:219], v[36:39]
	v_mfma_f32_16x16x32_bf16 v[32:35], v[172:175], v[216:219], v[32:35]
	v_mfma_f32_16x16x32_bf16 v[20:23], v[164:167], v[224:227], v[20:23]
	v_mfma_f32_16x16x32_bf16 v[16:19], v[172:175], v[224:227], v[16:19]
	s_setprio 0
	s_setprio 1
	v_mfma_f32_16x16x32_bf16 v[44:47], v[176:179], v[196:199], v[44:47]
	v_mfma_f32_16x16x32_bf16 v[40:43], v[184:187], v[196:199], v[40:43]
	v_mfma_f32_16x16x32_bf16 v[28:31], v[176:179], v[204:207], v[28:31]
	v_mfma_f32_16x16x32_bf16 v[24:27], v[184:187], v[204:207], v[24:27]
	v_mfma_f32_16x16x32_bf16 v[12:15], v[176:179], v[212:215], v[12:15]
	v_mfma_f32_16x16x32_bf16 v[8:11], v[184:187], v[212:215], v[8:11]
	v_mfma_f32_16x16x32_bf16 v[4:7], v[176:179], v[220:223], v[4:7]
	v_mfma_f32_16x16x32_bf16 v[0:3], v[184:187], v[220:223], v[0:3]
	v_mfma_f32_16x16x32_bf16 v[44:47], v[180:183], v[200:203], v[44:47]
	v_mfma_f32_16x16x32_bf16 v[40:43], v[192:195], v[200:203], v[40:43]
	v_mfma_f32_16x16x32_bf16 v[28:31], v[180:183], v[208:211], v[28:31]
	v_mfma_f32_16x16x32_bf16 v[24:27], v[192:195], v[208:211], v[24:27]
	v_mfma_f32_16x16x32_bf16 v[12:15], v[180:183], v[216:219], v[12:15]
	v_mfma_f32_16x16x32_bf16 v[8:11], v[192:195], v[216:219], v[8:11]
	v_mfma_f32_16x16x32_bf16 v[4:7], v[180:183], v[224:227], v[4:7]
	v_mfma_f32_16x16x32_bf16 v[0:3], v[192:195], v[224:227], v[0:3]
	s_setprio 0
	s_barrier
	s_cmp_gt_u32 s27, 29
	s_cbranch_scc0 .LBB0_148

; #define PG8_STAGE(bufoff, gbase, voff) do { _Pragma("unroll") for (int _i = 0; _i < 2; ++_i) \
;         __builtin_amdgcn_global_load_lds((const unsigned*)((const char*)(gbase) + (voff)[_i]), (LAS unsigned*)(lds + (bufoff) + ldsw + _i * 8192), 16, 0, 0); } while (0)
; #define PG8_LDA(dst, b, h) do { _Pragma("unroll") for (int m = 0; m < 4; ++m) _Pragma("unroll") for (int k = 0; k < 2; ++k) dst[m][k] = *(const LAS bf16x8*)(lds + PG8_SA(b, h) + aoff + m * 2048 + k * 1024); } while (0)
; #define PG8_LDB(dst, b, h) do { _Pragma("unroll") for (int n = 0; n < 2; ++n) _Pragma("unroll") for (int k = 0; k < 2; ++k) dst[n][k] = *(const LAS bf16x8*)(lds + PG8_SB(b, h) + boff + n * 2048 + k * 1024); } while (0)
; #define PG8_MMA(ai, bj, At, Bt) do { __builtin_amdgcn_s_setprio(1); _Pragma("unroll") for (int m = 0; m < 4; ++m) _Pragma("unroll") for (int n = 0; n < 2; ++n) _Pragma("unroll") for (int k = 0; k < 2; ++k) \
;         acc[ai][bj][m][n] = __builtin_amdgcn_mfma_f32_16x16x32_bf16(Bt[n][k], At[m][k], acc[ai][bj][m][n], 0, 0, 0); __builtin_amdgcn_s_setprio(0); } while (0)
; #define PG8_WAIT_V(n) asm volatile("s_waitcnt vmcnt(" #n ")" ::: "memory")
; #define PG8_WAIT_L(n) asm volatile("s_waitcnt lgkmcnt(" #n ")" ::: "memory")
; #define PG8_BAR __builtin_amdgcn_s_barrier()
; #define PG8_SCHED __builtin_amdgcn_sched_barrier(0)
; template <int GI>
; __device__ __forceinline__ void gemm_phase(LAS unsigned char* lds, unsigned char* ws, int G, int cblk) {
;     ...
;         for (int t = 0; t < nt; t += 2) {
;             const bool last = (t == nt - 2);
;             const char* a1 = cA + (size_t)(t + 1) * kstep;
;             const char* a2 = last ? nA : cA + (size_t)(t + 2) * kstep; const char* b2 = last ? nB : cB + (size_t)(t + 2) * kstep;
;             const char* a3 = a2 + kstep; const char* b3 = b2 + kstep;
;             PG8_LDB(B0, 0, 0); PG8_LDB(B1, 0, 1); PG8_SCHED; PG8_LDA(At, 0, 0); PG8_STAGE(PG8_SA(1, 1), a1 + hstepA, voffA);
;             PG8_WAIT_V(8); PG8_WAIT_L(0); PG8_BAR; PG8_MMA(0, 0, At, B0); PG8_MMA(0, 1, At, B1); PG8_BAR; PG8_SCHED;
;             PG8_LDA(At, 0, 1); PG8_STAGE(PG8_SB(0, 0), b2, voffB); PG8_STAGE(PG8_SB(0, 1), b2 + hstepB, voffB); PG8_STAGE(PG8_SA(0, 0), a2, voffA);
;             PG8_WAIT_V(8); PG8_WAIT_L(0); PG8_BAR; PG8_MMA(1, 0, At, B0); PG8_MMA(1, 1, At, B1); PG8_BAR; PG8_SCHED;
.LBB0_399:
	s_add_u32 s46, s46, 0x80080
	s_addc_u32 s47, s47, 0
	s_add_u32 s14, s48, 0x100
	s_addc_u32 s15, s49, 0
	s_mov_b32 s19, -2
	ds_read_b128 v[154:157], v151
	ds_read_b128 v[164:167], v151 offset:1024
	ds_read_b128 v[168:171], v151 offset:2048
	ds_read_b128 v[172:175], v151 offset:3072
	ds_read_b128 v[176:179], v152
	ds_read_b128 v[180:183], v152 offset:1024
	ds_read_b128 v[184:187], v152 offset:2048
	ds_read_b128 v[192:195], v152 offset:3072
	s_add_u32 s34, s46, 0xfff80080
	s_addc_u32 s48, s47, -1
	s_cmp_eq_u32 s19, 28
	s_cselect_b32 s51, s41, s48
	s_cselect_b32 s50, s40, s34
	s_cselect_b32 s49, s43, s15
	s_cselect_b32 s48, s42, s14
	v_lshl_add_u64 v[158:159], s[46:47], 0, v[138:139]
	s_add_i32 m0, s16, 0xc000
	ds_read_b128 v[196:199], v153
	ds_read_b128 v[200:203], v153 offset:1024
	ds_read_b128 v[204:207], v153 offset:2048
	ds_read_b128 v[208:211], v153 offset:3072
	ds_read_b128 v[212:215], v153 offset:4096
	ds_read_b128 v[216:219], v153 offset:5120
	ds_read_b128 v[220:223], v153 offset:6144
	ds_read_b128 v[224:227], v153 offset:7168
	global_load_lds_dwordx4 v[158:159], off
	v_lshl_add_u64 v[158:159], s[46:47], 0, v[140:141]
	s_add_i32 m0, s16, 0xe000
	s_nop 0
	global_load_lds_dwordx4 v[158:159], off
	s_waitcnt vmcnt(8)
	s_waitcnt lgkmcnt(0)
	s_barrier
	s_setprio 1
	s_waitcnt lgkmcnt(0)
	v_mfma_f32_16x16x32_bf16 v[124:127], v[154:157], v[196:199], 0
	v_mfma_f32_16x16x32_bf16 v[120:123], v[168:171], v[196:199], 0
	v_mfma_f32_16x16x32_bf16 v[116:119], v[154:157], v[204:207], 0
	v_mfma_f32_16x16x32_bf16 v[112:115], v[168:171], v[204:207], 0
	v_mfma_f32_16x16x32_bf16 v[100:103], v[154:157], v[212:215], 0
	v_mfma_f32_16x16x32_bf16 v[96:99], v[168:171], v[212:215], 0
	v_mfma_f32_16x16x32_bf16 v[84:87], v[154:157], v[220:223], 0
	v_mfma_f32_16x16x32_bf16 v[80:83], v[168:171], v[220:223], 0
	v_mfma_f32_16x16x32_bf16 v[124:127], v[164:167], v[200:203], v[124:127]
	v_mfma_f32_16x16x32_bf16 v[120:123], v[172:175], v[200:203], v[120:123]
	v_mfma_f32_16x16x32_bf16 v[116:119], v[164:167], v[208:211], v[116:119]
	v_mfma_f32_16x16x32_bf16 v[112:115], v[172:175], v[208:211], v[112:115]
	v_mfma_f32_16x16x32_bf16 v[100:103], v[164:167], v[216:219], v[100:103]
	v_mfma_f32_16x16x32_bf16 v[96:99], v[172:175], v[216:219], v[96:99]
	v_mfma_f32_16x16x32_bf16 v[84:87], v[164:167], v[224:227], v[84:87]
	v_mfma_f32_16x16x32_bf16 v[80:83], v[172:175], v[224:227], v[80:83]
	s_setprio 0
	s_setprio 1
	v_mfma_f32_16x16x32_bf16 v[108:111], v[176:179], v[196:199], 0
	v_mfma_f32_16x16x32_bf16 v[104:107], v[184:187], v[196:199], 0
	v_mfma_f32_16x16x32_bf16 v[92:95], v[176:179], v[204:207], 0
	v_mfma_f32_16x16x32_bf16 v[88:91], v[184:187], v[204:207], 0
	v_mfma_f32_16x16x32_bf16 v[76:79], v[176:179], v[212:215], 0
	v_mfma_f32_16x16x32_bf16 v[72:75], v[184:187], v[212:215], 0
	v_mfma_f32_16x16x32_bf16 v[68:71], v[176:179], v[220:223], 0
	v_mfma_f32_16x16x32_bf16 v[64:67], v[184:187], v[220:223], 0
	v_mfma_f32_16x16x32_bf16 v[108:111], v[180:183], v[200:203], v[108:111]
	v_mfma_f32_16x16x32_bf16 v[104:107], v[192:195], v[200:203], v[104:107]
	v_mfma_f32_16x16x32_bf16 v[92:95], v[180:183], v[208:211], v[92:95]
	v_mfma_f32_16x16x32_bf16 v[88:91], v[192:195], v[208:211], v[88:91]
	v_mfma_f32_16x16x32_bf16 v[76:79], v[180:183], v[216:219], v[76:79]
	v_mfma_f32_16x16x32_bf16 v[72:75], v[192:195], v[216:219], v[72:75]
	v_mfma_f32_16x16x32_bf16 v[68:71], v[180:183], v[224:227], v[68:71]
	v_mfma_f32_16x16x32_bf16 v[64:67], v[192:195], v[224:227], v[64:67]
	s_setprio 0
	s_barrier
	s_add_i32 s34, s33, s0
	v_lshl_add_u64 v[158:159], s[48:49], 0, v[130:131]
	s_mov_b32 m0, s34
	ds_read_b128 v[196:199], v153 offset:16384
	ds_read_b128 v[200:203], v153 offset:17408
	ds_read_b128 v[204:207], v153 offset:18432
	ds_read_b128 v[208:211], v153 offset:19456
	ds_read_b128 v[212:215], v153 offset:20480
	ds_read_b128 v[216:219], v153 offset:21504
	ds_read_b128 v[220:223], v153 offset:22528
	ds_read_b128 v[224:227], v153 offset:23552
	global_load_lds_dwordx4 v[158:159], off
	s_add_i32 m0, s34, 0x2000
	s_add_u32 s54, s48, 0x80000
	v_lshl_add_u64 v[188:189], s[48:49], 0, v[134:135]
	s_addc_u32 s55, s49, 0
	s_add_i32 s34, s35, s0
	global_load_lds_dwordx4 v[188:189], off
	v_lshl_add_u64 v[228:229], s[54:55], 0, v[130:131]
	s_mov_b32 m0, s34
	v_lshl_add_u64 v[230:231], s[50:51], 0, v[132:133]
	global_load_lds_dwordx4 v[228:229], off
	v_lshl_add_u64 v[228:229], s[54:55], 0, v[134:135]
	s_add_i32 m0, s34, 0x2000
	s_nop 0
	global_load_lds_dwordx4 v[228:229], off
	v_lshl_add_u64 v[228:229], s[50:51], 0, v[128:129]
	s_mov_b32 m0, s16
	s_nop 0
	global_load_lds_dwordx4 v[228:229], off
	s_mov_b32 m0, s17
	s_nop 0
	global_load_lds_dwordx4 v[230:231], off
	s_waitcnt vmcnt(8)
	s_waitcnt lgkmcnt(0)
	s_barrier
; #define PG8_STAGE(bufoff, gbase, voff) do { _Pragma("unroll") for (int _i = 0; _i < 2; ++_i) \
;         __builtin_amdgcn_global_load_lds((const unsigned*)((const char*)(gbase) + (voff)[_i]), (LAS unsigned*)(lds + (bufoff) + ldsw + _i * 8192), 16, 0, 0); } while (0)
; #define PG8_LDA(dst, b, h) do { _Pragma("unroll") for (int m = 0; m < 4; ++m) _Pragma("unroll") for (int k = 0; k < 2; ++k) dst[m][k] = *(const LAS bf16x8*)(lds + PG8_SA(b, h) + aoff + m * 2048 + k * 1024); } while (0)
; #define PG8_LDB(dst, b, h) do { _Pragma("unroll") for (int n = 0; n < 2; ++n) _Pragma("unroll") for (int k = 0; k < 2; ++k) dst[n][k] = *(const LAS bf16x8*)(lds + PG8_SB(b, h) + boff + n * 2048 + k * 1024); } while (0)
; #define PG8_MMA(ai, bj, At, Bt) do { __builtin_amdgcn_s_setprio(1); _Pragma("unroll") for (int m = 0; m < 4; ++m) _Pragma("unroll") for (int n = 0; n < 2; ++n) _Pragma("unroll") for (int k = 0; k < 2; ++k) \
;         acc[ai][bj][m][n] = __builtin_amdgcn_mfma_f32_16x16x32_bf16(Bt[n][k], At[m][k], acc[ai][bj][m][n], 0, 0, 0); __builtin_amdgcn_s_setprio(0); } while (0)
; #define PG8_WAIT_V(n) asm volatile("s_waitcnt vmcnt(" #n ")" ::: "memory")
; #define PG8_WAIT_L(n) asm volatile("s_waitcnt lgkmcnt(" #n ")" ::: "memory")
; #define PG8_BAR __builtin_amdgcn_s_barrier()
; #define PG8_SCHED __builtin_amdgcn_sched_barrier(0)
; template <int GI>
; __device__ __forceinline__ void gemm_phase(LAS unsigned char* lds, unsigned char* ws, int G, int cblk) {
;     ...
;             PG8_WAIT_V(8); PG8_WAIT_L(0); PG8_BAR; PG8_MMA(1, 0, At, B0); PG8_MMA(1, 1, At, B1); PG8_BAR; PG8_SCHED;
;             PG8_LDB(B0, 1, 0); PG8_LDB(B1, 1, 1); PG8_SCHED; PG8_LDA(At, 1, 0); PG8_STAGE(PG8_SA(0, 1), a2 + hstepA, voffA);
;             PG8_WAIT_V(8); PG8_WAIT_L(0); PG8_BAR; PG8_MMA(0, 0, At, B0); PG8_MMA(0, 1, At, B1); PG8_BAR; PG8_SCHED;
	s_setprio 1
	s_waitcnt lgkmcnt(0)
	v_mfma_f32_16x16x32_bf16 v[60:63], v[154:157], v[196:199], 0
	v_mfma_f32_16x16x32_bf16 v[56:59], v[168:171], v[196:199], 0
	v_mfma_f32_16x16x32_bf16 v[52:55], v[154:157], v[204:207], 0
	v_mfma_f32_16x16x32_bf16 v[48:51], v[168:171], v[204:207], 0
	v_mfma_f32_16x16x32_bf16 v[36:39], v[154:157], v[212:215], 0
	v_mfma_f32_16x16x32_bf16 v[32:35], v[168:171], v[212:215], 0
	v_mfma_f32_16x16x32_bf16 v[20:23], v[154:157], v[220:223], 0
	v_mfma_f32_16x16x32_bf16 v[16:19], v[168:171], v[220:223], 0
	v_mfma_f32_16x16x32_bf16 v[60:63], v[164:167], v[200:203], v[60:63]
	v_mfma_f32_16x16x32_bf16 v[56:59], v[172:175], v[200:203], v[56:59]
	v_mfma_f32_16x16x32_bf16 v[52:55], v[164:167], v[208:211], v[52:55]
	v_mfma_f32_16x16x32_bf16 v[48:51], v[172:175], v[208:211], v[48:51]
	v_mfma_f32_16x16x32_bf16 v[36:39], v[164:167], v[216:219], v[36:39]
	v_mfma_f32_16x16x32_bf16 v[32:35], v[172:175], v[216:219], v[32:35]
	v_mfma_f32_16x16x32_bf16 v[20:23], v[164:167], v[224:227], v[20:23]
	v_mfma_f32_16x16x32_bf16 v[16:19], v[172:175], v[224:227], v[16:19]
	s_setprio 0
	s_setprio 1
	v_mfma_f32_16x16x32_bf16 v[44:47], v[176:179], v[196:199], 0
	v_mfma_f32_16x16x32_bf16 v[40:43], v[184:187], v[196:199], 0
	v_mfma_f32_16x16x32_bf16 v[28:31], v[176:179], v[204:207], 0
	v_mfma_f32_16x16x32_bf16 v[24:27], v[184:187], v[204:207], 0
	v_mfma_f32_16x16x32_bf16 v[12:15], v[176:179], v[212:215], 0
	v_mfma_f32_16x16x32_bf16 v[8:11], v[184:187], v[212:215], 0
	v_mfma_f32_16x16x32_bf16 v[4:7], v[176:179], v[220:223], 0
	v_mfma_f32_16x16x32_bf16 v[0:3], v[184:187], v[220:223], 0
	v_mfma_f32_16x16x32_bf16 v[44:47], v[180:183], v[200:203], v[44:47]
	v_mfma_f32_16x16x32_bf16 v[40:43], v[192:195], v[200:203], v[40:43]
	v_mfma_f32_16x16x32_bf16 v[28:31], v[180:183], v[208:211], v[28:31]
	v_mfma_f32_16x16x32_bf16 v[24:27], v[192:195], v[208:211], v[24:27]
	v_mfma_f32_16x16x32_bf16 v[12:15], v[180:183], v[216:219], v[12:15]
	v_mfma_f32_16x16x32_bf16 v[8:11], v[192:195], v[216:219], v[8:11]
	v_mfma_f32_16x16x32_bf16 v[4:7], v[180:183], v[224:227], v[4:7]
	v_mfma_f32_16x16x32_bf16 v[0:3], v[192:195], v[224:227], v[0:3]
	s_setprio 0
	s_barrier
	s_add_i32 s34, 0, 0x18000
	v_add_u32_e32 v161, s34, v150
	s_add_i32 s53, 0, 0x1c000
	ds_read_b128 v[154:157], v161
	ds_read_b128 v[164:167], v161 offset:1024
	ds_read_b128 v[168:171], v161 offset:2048
	ds_read_b128 v[172:175], v161 offset:3072
	v_add_u32_e32 v161, s53, v150
	ds_read_b128 v[176:179], v161
	ds_read_b128 v[180:183], v161 offset:1024
	ds_read_b128 v[184:187], v161 offset:2048
	ds_read_b128 v[192:195], v161 offset:3072
	s_add_u32 s50, s50, 0x80000
	s_addc_u32 s51, s51, 0
	s_mov_b32 m0, s22
	v_lshl_add_u64 v[232:233], s[50:51], 0, v[128:129]
	ds_read_b128 v[196:199], v153 offset:32768
	ds_read_b128 v[200:203], v153 offset:33792
	ds_read_b128 v[204:207], v153 offset:34816
	ds_read_b128 v[208:211], v153 offset:35840
	ds_read_b128 v[212:215], v153 offset:36864
	ds_read_b128 v[216:219], v153 offset:37888
	ds_read_b128 v[220:223], v153 offset:38912
	ds_read_b128 v[224:227], v153 offset:39936
	global_load_lds_dwordx4 v[232:233], off
	v_lshl_add_u64 v[232:233], s[50:51], 0, v[132:133]
	s_mov_b32 m0, s23
	s_nop 0
	global_load_lds_dwordx4 v[232:233], off
	s_waitcnt vmcnt(8)
	s_waitcnt lgkmcnt(0)
	s_barrier
	s_setprio 1
	s_waitcnt lgkmcnt(0)
	v_mfma_f32_16x16x32_bf16 v[124:127], v[154:157], v[196:199], v[124:127]
	v_mfma_f32_16x16x32_bf16 v[120:123], v[168:171], v[196:199], v[120:123]
	v_mfma_f32_16x16x32_bf16 v[116:119], v[154:157], v[204:207], v[116:119]
	v_mfma_f32_16x16x32_bf16 v[112:115], v[168:171], v[204:207], v[112:115]
	v_mfma_f32_16x16x32_bf16 v[100:103], v[154:157], v[212:215], v[100:103]
	v_mfma_f32_16x16x32_bf16 v[96:99], v[168:171], v[212:215], v[96:99]
	v_mfma_f32_16x16x32_bf16 v[84:87], v[154:157], v[220:223], v[84:87]
	v_mfma_f32_16x16x32_bf16 v[80:83], v[168:171], v[220:223], v[80:83]
	v_mfma_f32_16x16x32_bf16 v[124:127], v[164:167], v[200:203], v[124:127]
	v_mfma_f32_16x16x32_bf16 v[120:123], v[172:175], v[200:203], v[120:123]
	v_mfma_f32_16x16x32_bf16 v[116:119], v[164:167], v[208:211], v[116:119]
	v_mfma_f32_16x16x32_bf16 v[112:115], v[172:175], v[208:211], v[112:115]
	v_mfma_f32_16x16x32_bf16 v[100:103], v[164:167], v[216:219], v[100:103]
	v_mfma_f32_16x16x32_bf16 v[96:99], v[172:175], v[216:219], v[96:99]
	v_mfma_f32_16x16x32_bf16 v[84:87], v[164:167], v[224:227], v[84:87]
	v_mfma_f32_16x16x32_bf16 v[80:83], v[172:175], v[224:227], v[80:83]
	s_setprio 0
	s_setprio 1
	v_mfma_f32_16x16x32_bf16 v[108:111], v[176:179], v[196:199], v[108:111]
	v_mfma_f32_16x16x32_bf16 v[104:107], v[184:187], v[196:199], v[104:107]
	v_mfma_f32_16x16x32_bf16 v[92:95], v[176:179], v[204:207], v[92:95]
	v_mfma_f32_16x16x32_bf16 v[88:91], v[184:187], v[204:207], v[88:91]
	v_mfma_f32_16x16x32_bf16 v[76:79], v[176:179], v[212:215], v[76:79]
	v_mfma_f32_16x16x32_bf16 v[72:75], v[184:187], v[212:215], v[72:75]
	v_mfma_f32_16x16x32_bf16 v[68:71], v[176:179], v[220:223], v[68:71]
	v_mfma_f32_16x16x32_bf16 v[64:67], v[184:187], v[220:223], v[64:67]
	v_mfma_f32_16x16x32_bf16 v[108:111], v[180:183], v[200:203], v[108:111]
	v_mfma_f32_16x16x32_bf16 v[104:107], v[192:195], v[200:203], v[104:107]
	v_mfma_f32_16x16x32_bf16 v[92:95], v[180:183], v[208:211], v[92:95]
	v_mfma_f32_16x16x32_bf16 v[88:91], v[192:195], v[208:211], v[88:91]
	v_mfma_f32_16x16x32_bf16 v[76:79], v[180:183], v[216:219], v[76:79]
	v_mfma_f32_16x16x32_bf16 v[72:75], v[192:195], v[216:219], v[72:75]
	v_mfma_f32_16x16x32_bf16 v[68:71], v[180:183], v[224:227], v[68:71]
	v_mfma_f32_16x16x32_bf16 v[64:67], v[192:195], v[224:227], v[64:67]
	s_setprio 0
	s_barrier
; #define PG8_STAGE(bufoff, gbase, voff) do { _Pragma("unroll") for (int _i = 0; _i < 2; ++_i) \
;         __builtin_amdgcn_global_load_lds((const unsigned*)((const char*)(gbase) + (voff)[_i]), (LAS unsigned*)(lds + (bufoff) + ldsw + _i * 8192), 16, 0, 0); } while (0)
; #define PG8_LDA(dst, b, h) do { _Pragma("unroll") for (int m = 0; m < 4; ++m) _Pragma("unroll") for (int k = 0; k < 2; ++k) dst[m][k] = *(const LAS bf16x8*)(lds + PG8_SA(b, h) + aoff + m * 2048 + k * 1024); } while (0)
; #define PG8_LDB(dst, b, h) do { _Pragma("unroll") for (int n = 0; n < 2; ++n) _Pragma("unroll") for (int k = 0; k < 2; ++k) dst[n][k] = *(const LAS bf16x8*)(lds + PG8_SB(b, h) + boff + n * 2048 + k * 1024); } while (0)
; #define PG8_MMA(ai, bj, At, Bt) do { __builtin_amdgcn_s_setprio(1); _Pragma("unroll") for (int m = 0; m < 4; ++m) _Pragma("unroll") for (int n = 0; n < 2; ++n) _Pragma("unroll") for (int k = 0; k < 2; ++k) \
;         acc[ai][bj][m][n] = __builtin_amdgcn_mfma_f32_16x16x32_bf16(Bt[n][k], At[m][k], acc[ai][bj][m][n], 0, 0, 0); __builtin_amdgcn_s_setprio(0); } while (0)
; #define PG8_WAIT_V(n) asm volatile("s_waitcnt vmcnt(" #n ")" ::: "memory")
; #define PG8_WAIT_L(n) asm volatile("s_waitcnt lgkmcnt(" #n ")" ::: "memory")
; #define PG8_BAR __builtin_amdgcn_s_barrier()
; #define PG8_SCHED __builtin_amdgcn_sched_barrier(0)
; template <int GI>
; __device__ __forceinline__ void gemm_phase(LAS unsigned char* lds, unsigned char* ws, int G, int cblk) {
;     ...
;         for (int t = 0; t < nt; t += 2) {
;             const bool last = (t == nt - 2);
;             const char* a1 = cA + (size_t)(t + 1) * kstep;
;             const char* a2 = last ? nA : cA + (size_t)(t + 2) * kstep; const char* b2 = last ? nB : cB + (size_t)(t + 2) * kstep;
;             const char* a3 = a2 + kstep; const char* b3 = b2 + kstep;
;             PG8_LDB(B0, 0, 0); PG8_LDB(B1, 0, 1); PG8_SCHED; PG8_LDA(At, 0, 0); PG8_STAGE(PG8_SA(1, 1), a1 + hstepA, voffA);
;             PG8_WAIT_V(8); PG8_WAIT_L(0); PG8_BAR; PG8_MMA(0, 0, At, B0); PG8_MMA(0, 1, At, B1); PG8_BAR; PG8_SCHED;
;     ...
;             PG8_LDA(At, 1, 1); PG8_STAGE(PG8_SB(1, 0), b3, voffB); PG8_STAGE(PG8_SB(1, 1), b3 + hstepB, voffB); PG8_STAGE(PG8_SA(1, 0), a3, voffA);
;             PG8_WAIT_V(8); PG8_WAIT_L(0); PG8_BAR; PG8_MMA(1, 0, At, B0); PG8_MMA(1, 1, At, B1); PG8_BAR; PG8_SCHED;
;         }
	s_add_i32 s34, s34, s0
	v_lshl_add_u64 v[158:159], v[158:159], 0, s[8:9]
	s_mov_b32 m0, s34
	ds_read_b128 v[196:199], v153 offset:49152
	ds_read_b128 v[200:203], v153 offset:50176
	ds_read_b128 v[204:207], v153 offset:51200
	ds_read_b128 v[208:211], v153 offset:52224
	ds_read_b128 v[212:215], v153 offset:53248
	ds_read_b128 v[216:219], v153 offset:54272
	ds_read_b128 v[220:223], v153 offset:55296
	ds_read_b128 v[224:227], v153 offset:56320
	global_load_lds_dwordx4 v[158:159], off
	s_add_i32 m0, s34, 0x2000
	s_add_u32 s48, s48, 0x80080
	v_lshl_add_u64 v[158:159], v[188:189], 0, s[8:9]
	s_addc_u32 s49, s49, 0
	s_add_i32 s34, s53, s0
	global_load_lds_dwordx4 v[158:159], off
	v_lshl_add_u64 v[158:159], s[48:49], 0, v[130:131]
	s_mov_b32 m0, s34
	s_nop 0
	global_load_lds_dwordx4 v[158:159], off
	v_lshl_add_u64 v[158:159], s[48:49], 0, v[134:135]
	s_add_i32 m0, s34, 0x2000
	s_nop 0
	global_load_lds_dwordx4 v[158:159], off
	v_lshl_add_u64 v[158:159], v[228:229], 0, s[8:9]
	s_mov_b32 m0, s26
	s_nop 0
	global_load_lds_dwordx4 v[158:159], off
	v_lshl_add_u64 v[158:159], v[230:231], 0, s[8:9]
	s_mov_b32 m0, s27
	s_nop 0
	global_load_lds_dwordx4 v[158:159], off
	s_waitcnt vmcnt(8)
	s_waitcnt lgkmcnt(0)
	s_barrier
	s_setprio 1
	s_waitcnt lgkmcnt(0)
	v_mfma_f32_16x16x32_bf16 v[60:63], v[154:157], v[196:199], v[60:63]
	v_mfma_f32_16x16x32_bf16 v[56:59], v[168:171], v[196:199], v[56:59]
	s_add_i32 s19, s19, 2
	s_add_u32 s46, s46, 0x100
	s_addc_u32 s47, s47, 0
	s_add_u32 s14, s14, 0x100
	s_addc_u32 s15, s15, 0
	v_mfma_f32_16x16x32_bf16 v[52:55], v[154:157], v[204:207], v[52:55]
	v_mfma_f32_16x16x32_bf16 v[48:51], v[168:171], v[204:207], v[48:51]
	v_mfma_f32_16x16x32_bf16 v[36:39], v[154:157], v[212:215], v[36:39]
	v_mfma_f32_16x16x32_bf16 v[32:35], v[168:171], v[212:215], v[32:35]
	v_mfma_f32_16x16x32_bf16 v[20:23], v[154:157], v[220:223], v[20:23]
	v_mfma_f32_16x16x32_bf16 v[16:19], v[168:171], v[220:223], v[16:19]
	v_mfma_f32_16x16x32_bf16 v[60:63], v[164:167], v[200:203], v[60:63]
	v_mfma_f32_16x16x32_bf16 v[56:59], v[172:175], v[200:203], v[56:59]
	v_mfma_f32_16x16x32_bf16 v[52:55], v[164:167], v[208:211], v[52:55]
	v_mfma_f32_16x16x32_bf16 v[48:51], v[172:175], v[208:211], v[48:51]
	v_mfma_f32_16x16x32_bf16 v[36:39], v[164:167], v[216:219], v[36:39]
	v_mfma_f32_16x16x32_bf16 v[32:35], v[172:175], v[216:219], v[32:35]
	v_mfma_f32_16x16x32_bf16 v[20:23], v[164:167], v[224:227], v[20:23]
	v_mfma_f32_16x16x32_bf16 v[16:19], v[172:175], v[224:227], v[16:19]
	s_setprio 0
	s_setprio 1
	v_mfma_f32_16x16x32_bf16 v[44:47], v[176:179], v[196:199], v[44:47]
	v_mfma_f32_16x16x32_bf16 v[40:43], v[184:187], v[196:199], v[40:43]
	v_mfma_f32_16x16x32_bf16 v[28:31], v[176:179], v[204:207], v[28:31]
	v_mfma_f32_16x16x32_bf16 v[24:27], v[184:187], v[204:207], v[24:27]
	v_mfma_f32_16x16x32_bf16 v[12:15], v[176:179], v[212:215], v[12:15]
	v_mfma_f32_16x16x32_bf16 v[8:11], v[184:187], v[212:215], v[8:11]
	v_mfma_f32_16x16x32_bf16 v[4:7], v[176:179], v[220:223], v[4:7]
	v_mfma_f32_16x16x32_bf16 v[0:3], v[184:187], v[220:223], v[0:3]
	v_mfma_f32_16x16x32_bf16 v[44:47], v[180:183], v[200:203], v[44:47]
	v_mfma_f32_16x16x32_bf16 v[40:43], v[192:195], v[200:203], v[40:43]
	v_mfma_f32_16x16x32_bf16 v[28:31], v[180:183], v[208:211], v[28:31]
	v_mfma_f32_16x16x32_bf16 v[24:27], v[192:195], v[208:211], v[24:27]
	v_mfma_f32_16x16x32_bf16 v[12:15], v[180:183], v[216:219], v[12:15]
	v_mfma_f32_16x16x32_bf16 v[8:11], v[192:195], v[216:219], v[8:11]
	v_mfma_f32_16x16x32_bf16 v[4:7], v[180:183], v[224:227], v[4:7]
	v_mfma_f32_16x16x32_bf16 v[0:3], v[192:195], v[224:227], v[0:3]
	s_setprio 0
	s_barrier
	s_cmp_gt_u32 s19, 29
	s_cbranch_scc0 .LBB0_400
	s_branch .Lpeel_exit_3
.LBB0_400:
	ds_read_b128 v[154:157], v151
	ds_read_b128 v[164:167], v151 offset:1024
	ds_read_b128 v[168:171], v151 offset:2048
	ds_read_b128 v[172:175], v151 offset:3072
	ds_read_b128 v[176:179], v152
	ds_read_b128 v[180:183], v152 offset:1024
	ds_read_b128 v[184:187], v152 offset:2048
	ds_read_b128 v[192:195], v152 offset:3072
	s_add_u32 s34, s46, 0xfff80080
	s_addc_u32 s48, s47, -1
	s_cmp_eq_u32 s19, 28
	s_cselect_b32 s51, s41, s48
	s_cselect_b32 s50, s40, s34
	s_cselect_b32 s49, s43, s15
	s_cselect_b32 s48, s42, s14
	v_lshl_add_u64 v[158:159], s[46:47], 0, v[138:139]
	s_add_i32 m0, s16, 0xc000
	ds_read_b128 v[196:199], v153
	ds_read_b128 v[200:203], v153 offset:1024
	ds_read_b128 v[204:207], v153 offset:2048
	ds_read_b128 v[208:211], v153 offset:3072
	ds_read_b128 v[212:215], v153 offset:4096
	ds_read_b128 v[216:219], v153 offset:5120
	ds_read_b128 v[220:223], v153 offset:6144
	ds_read_b128 v[224:227], v153 offset:7168
	global_load_lds_dwordx4 v[158:159], off
	v_lshl_add_u64 v[158:159], s[46:47], 0, v[140:141]
	s_add_i32 m0, s16, 0xe000
	s_nop 0
	global_load_lds_dwordx4 v[158:159], off
	s_waitcnt vmcnt(8)
	s_waitcnt lgkmcnt(0)
	s_barrier
; #define PG8_STAGE(bufoff, gbase, voff) do { _Pragma("unroll") for (int _i = 0; _i < 2; ++_i) \
;         __builtin_amdgcn_global_load_lds((const unsigned*)((const char*)(gbase) + (voff)[_i]), (LAS unsigned*)(lds + (bufoff) + ldsw + _i * 8192), 16, 0, 0); } while (0)
; #define PG8_LDA(dst, b, h) do { _Pragma("unroll") for (int m = 0; m < 4; ++m) _Pragma("unroll") for (int k = 0; k < 2; ++k) dst[m][k] = *(const LAS bf16x8*)(lds + PG8_SA(b, h) + aoff + m * 2048 + k * 1024); } while (0)
; #define PG8_MMA(ai, bj, At, Bt) do { __builtin_amdgcn_s_setprio(1); _Pragma("unroll") for (int m = 0; m < 4; ++m) _Pragma("unroll") for (int n = 0; n < 2; ++n) _Pragma("unroll") for (int k = 0; k < 2; ++k) \
;         acc[ai][bj][m][n] = __builtin_amdgcn_mfma_f32_16x16x32_bf16(Bt[n][k], At[m][k], acc[ai][bj][m][n], 0, 0, 0); __builtin_amdgcn_s_setprio(0); } while (0)
; #define PG8_WAIT_V(n) asm volatile("s_waitcnt vmcnt(" #n ")" ::: "memory")
; #define PG8_WAIT_L(n) asm volatile("s_waitcnt lgkmcnt(" #n ")" ::: "memory")
; #define PG8_BAR __builtin_amdgcn_s_barrier()
; #define PG8_SCHED __builtin_amdgcn_sched_barrier(0)
; template <int GI>
; __device__ __forceinline__ void gemm_phase(LAS unsigned char* lds, unsigned char* ws, int G, int cblk) {
;     ...
;             PG8_WAIT_V(8); PG8_WAIT_L(0); PG8_BAR; PG8_MMA(0, 0, At, B0); PG8_MMA(0, 1, At, B1); PG8_BAR; PG8_SCHED;
;             PG8_LDA(At, 0, 1); PG8_STAGE(PG8_SB(0, 0), b2, voffB); PG8_STAGE(PG8_SB(0, 1), b2 + hstepB, voffB); PG8_STAGE(PG8_SA(0, 0), a2, voffA);
;             PG8_WAIT_V(8); PG8_WAIT_L(0); PG8_BAR; PG8_MMA(1, 0, At, B0); PG8_MMA(1, 1, At, B1); PG8_BAR; PG8_SCHED;
	s_setprio 1
	s_waitcnt lgkmcnt(0)
	v_mfma_f32_16x16x32_bf16 v[124:127], v[154:157], v[196:199], v[124:127]
	v_mfma_f32_16x16x32_bf16 v[120:123], v[168:171], v[196:199], v[120:123]
	v_mfma_f32_16x16x32_bf16 v[116:119], v[154:157], v[204:207], v[116:119]
	v_mfma_f32_16x16x32_bf16 v[112:115], v[168:171], v[204:207], v[112:115]
	v_mfma_f32_16x16x32_bf16 v[100:103], v[154:157], v[212:215], v[100:103]
	v_mfma_f32_16x16x32_bf16 v[96:99], v[168:171], v[212:215], v[96:99]
	v_mfma_f32_16x16x32_bf16 v[84:87], v[154:157], v[220:223], v[84:87]
	v_mfma_f32_16x16x32_bf16 v[80:83], v[168:171], v[220:223], v[80:83]
	v_mfma_f32_16x16x32_bf16 v[124:127], v[164:167], v[200:203], v[124:127]
	v_mfma_f32_16x16x32_bf16 v[120:123], v[172:175], v[200:203], v[120:123]
	v_mfma_f32_16x16x32_bf16 v[116:119], v[164:167], v[208:211], v[116:119]
	v_mfma_f32_16x16x32_bf16 v[112:115], v[172:175], v[208:211], v[112:115]
	v_mfma_f32_16x16x32_bf16 v[100:103], v[164:167], v[216:219], v[100:103]
	v_mfma_f32_16x16x32_bf16 v[96:99], v[172:175], v[216:219], v[96:99]
	v_mfma_f32_16x16x32_bf16 v[84:87], v[164:167], v[224:227], v[84:87]
	v_mfma_f32_16x16x32_bf16 v[80:83], v[172:175], v[224:227], v[80:83]
	s_setprio 0
	s_setprio 1
	v_mfma_f32_16x16x32_bf16 v[108:111], v[176:179], v[196:199], v[108:111]
	v_mfma_f32_16x16x32_bf16 v[104:107], v[184:187], v[196:199], v[104:107]
	v_mfma_f32_16x16x32_bf16 v[92:95], v[176:179], v[204:207], v[92:95]
	v_mfma_f32_16x16x32_bf16 v[88:91], v[184:187], v[204:207], v[88:91]
	v_mfma_f32_16x16x32_bf16 v[76:79], v[176:179], v[212:215], v[76:79]
	v_mfma_f32_16x16x32_bf16 v[72:75], v[184:187], v[212:215], v[72:75]
	v_mfma_f32_16x16x32_bf16 v[68:71], v[176:179], v[220:223], v[68:71]
	v_mfma_f32_16x16x32_bf16 v[64:67], v[184:187], v[220:223], v[64:67]
	v_mfma_f32_16x16x32_bf16 v[108:111], v[180:183], v[200:203], v[108:111]
	v_mfma_f32_16x16x32_bf16 v[104:107], v[192:195], v[200:203], v[104:107]
	v_mfma_f32_16x16x32_bf16 v[92:95], v[180:183], v[208:211], v[92:95]
	v_mfma_f32_16x16x32_bf16 v[88:91], v[192:195], v[208:211], v[88:91]
	v_mfma_f32_16x16x32_bf16 v[76:79], v[180:183], v[216:219], v[76:79]
	v_mfma_f32_16x16x32_bf16 v[72:75], v[192:195], v[216:219], v[72:75]
	v_mfma_f32_16x16x32_bf16 v[68:71], v[180:183], v[224:227], v[68:71]
	v_mfma_f32_16x16x32_bf16 v[64:67], v[192:195], v[224:227], v[64:67]
	s_setprio 0
	s_barrier
	s_add_i32 s34, s33, s0
	v_lshl_add_u64 v[158:159], s[48:49], 0, v[130:131]
	s_mov_b32 m0, s34
	ds_read_b128 v[196:199], v153 offset:16384
	ds_read_b128 v[200:203], v153 offset:17408
	ds_read_b128 v[204:207], v153 offset:18432
	ds_read_b128 v[208:211], v153 offset:19456
	ds_read_b128 v[212:215], v153 offset:20480
	ds_read_b128 v[216:219], v153 offset:21504
	ds_read_b128 v[220:223], v153 offset:22528
	ds_read_b128 v[224:227], v153 offset:23552
	global_load_lds_dwordx4 v[158:159], off
	s_add_i32 m0, s34, 0x2000
	s_add_u32 s54, s48, 0x80000
	v_lshl_add_u64 v[188:189], s[48:49], 0, v[134:135]
	s_addc_u32 s55, s49, 0
	s_add_i32 s34, s35, s0
	global_load_lds_dwordx4 v[188:189], off
	v_lshl_add_u64 v[228:229], s[54:55], 0, v[130:131]
	s_mov_b32 m0, s34
	v_lshl_add_u64 v[230:231], s[50:51], 0, v[132:133]
	global_load_lds_dwordx4 v[228:229], off
	v_lshl_add_u64 v[228:229], s[54:55], 0, v[134:135]
	s_add_i32 m0, s34, 0x2000
	s_nop 0
	global_load_lds_dwordx4 v[228:229], off
	v_lshl_add_u64 v[228:229], s[50:51], 0, v[128:129]
	s_mov_b32 m0, s16
	s_nop 0
	global_load_lds_dwordx4 v[228:229], off
	s_mov_b32 m0, s17
	s_nop 0
	global_load_lds_dwordx4 v[230:231], off
	s_waitcnt vmcnt(8)
	s_waitcnt lgkmcnt(0)
	s_barrier
	s_setprio 1
	s_waitcnt lgkmcnt(0)
	v_mfma_f32_16x16x32_bf16 v[60:63], v[154:157], v[196:199], v[60:63]
	v_mfma_f32_16x16x32_bf16 v[56:59], v[168:171], v[196:199], v[56:59]
	v_mfma_f32_16x16x32_bf16 v[52:55], v[154:157], v[204:207], v[52:55]
	v_mfma_f32_16x16x32_bf16 v[48:51], v[168:171], v[204:207], v[48:51]
	v_mfma_f32_16x16x32_bf16 v[36:39], v[154:157], v[212:215], v[36:39]
	v_mfma_f32_16x16x32_bf16 v[32:35], v[168:171], v[212:215], v[32:35]
	v_mfma_f32_16x16x32_bf16 v[20:23], v[154:157], v[220:223], v[20:23]
	v_mfma_f32_16x16x32_bf16 v[16:19], v[168:171], v[220:223], v[16:19]
	v_mfma_f32_16x16x32_bf16 v[60:63], v[164:167], v[200:203], v[60:63]
	v_mfma_f32_16x16x32_bf16 v[56:59], v[172:175], v[200:203], v[56:59]
	v_mfma_f32_16x16x32_bf16 v[52:55], v[164:167], v[208:211], v[52:55]
	v_mfma_f32_16x16x32_bf16 v[48:51], v[172:175], v[208:211], v[48:51]
	v_mfma_f32_16x16x32_bf16 v[36:39], v[164:167], v[216:219], v[36:39]
	v_mfma_f32_16x16x32_bf16 v[32:35], v[172:175], v[216:219], v[32:35]
	v_mfma_f32_16x16x32_bf16 v[20:23], v[164:167], v[224:227], v[20:23]
	v_mfma_f32_16x16x32_bf16 v[16:19], v[172:175], v[224:227], v[16:19]
	s_setprio 0
	s_setprio 1
	v_mfma_f32_16x16x32_bf16 v[44:47], v[176:179], v[196:199], v[44:47]
	v_mfma_f32_16x16x32_bf16 v[40:43], v[184:187], v[196:199], v[40:43]
	v_mfma_f32_16x16x32_bf16 v[28:31], v[176:179], v[204:207], v[28:31]
	v_mfma_f32_16x16x32_bf16 v[24:27], v[184:187], v[204:207], v[24:27]
	v_mfma_f32_16x16x32_bf16 v[12:15], v[176:179], v[212:215], v[12:15]
	v_mfma_f32_16x16x32_bf16 v[8:11], v[184:187], v[212:215], v[8:11]
	v_mfma_f32_16x16x32_bf16 v[4:7], v[176:179], v[220:223], v[4:7]
	v_mfma_f32_16x16x32_bf16 v[0:3], v[184:187], v[220:223], v[0:3]
	v_mfma_f32_16x16x32_bf16 v[44:47], v[180:183], v[200:203], v[44:47]
	v_mfma_f32_16x16x32_bf16 v[40:43], v[192:195], v[200:203], v[40:43]
	v_mfma_f32_16x16x32_bf16 v[28:31], v[180:183], v[208:211], v[28:31]
	v_mfma_f32_16x16x32_bf16 v[24:27], v[192:195], v[208:211], v[24:27]
	v_mfma_f32_16x16x32_bf16 v[12:15], v[180:183], v[216:219], v[12:15]
	v_mfma_f32_16x16x32_bf16 v[8:11], v[192:195], v[216:219], v[8:11]
	v_mfma_f32_16x16x32_bf16 v[4:7], v[180:183], v[224:227], v[4:7]
	v_mfma_f32_16x16x32_bf16 v[0:3], v[192:195], v[224:227], v[0:3]
	s_setprio 0
	s_barrier
; #define PG8_STAGE(bufoff, gbase, voff) do { _Pragma("unroll") for (int _i = 0; _i < 2; ++_i) \
;         __builtin_amdgcn_global_load_lds((const unsigned*)((const char*)(gbase) + (voff)[_i]), (LAS unsigned*)(lds + (bufoff) + ldsw + _i * 8192), 16, 0, 0); } while (0)
; #define PG8_LDA(dst, b, h) do { _Pragma("unroll") for (int m = 0; m < 4; ++m) _Pragma("unroll") for (int k = 0; k < 2; ++k) dst[m][k] = *(const LAS bf16x8*)(lds + PG8_SA(b, h) + aoff + m * 2048 + k * 1024); } while (0)
; #define PG8_LDB(dst, b, h) do { _Pragma("unroll") for (int n = 0; n < 2; ++n) _Pragma("unroll") for (int k = 0; k < 2; ++k) dst[n][k] = *(const LAS bf16x8*)(lds + PG8_SB(b, h) + boff + n * 2048 + k * 1024); } while (0)
; #define PG8_MMA(ai, bj, At, Bt) do { __builtin_amdgcn_s_setprio(1); _Pragma("unroll") for (int m = 0; m < 4; ++m) _Pragma("unroll") for (int n = 0; n < 2; ++n) _Pragma("unroll") for (int k = 0; k < 2; ++k) \
;         acc[ai][bj][m][n] = __builtin_amdgcn_mfma_f32_16x16x32_bf16(Bt[n][k], At[m][k], acc[ai][bj][m][n], 0, 0, 0); __builtin_amdgcn_s_setprio(0); } while (0)
; #define PG8_WAIT_V(n) asm volatile("s_waitcnt vmcnt(" #n ")" ::: "memory")
; #define PG8_WAIT_L(n) asm volatile("s_waitcnt lgkmcnt(" #n ")" ::: "memory")
; #define PG8_BAR __builtin_amdgcn_s_barrier()
; #define PG8_SCHED __builtin_amdgcn_sched_barrier(0)
; template <int GI>
; __device__ __forceinline__ void gemm_phase(LAS unsigned char* lds, unsigned char* ws, int G, int cblk) {
;     ...
;             PG8_LDB(B0, 1, 0); PG8_LDB(B1, 1, 1); PG8_SCHED; PG8_LDA(At, 1, 0); PG8_STAGE(PG8_SA(0, 1), a2 + hstepA, voffA);
;             PG8_WAIT_V(8); PG8_WAIT_L(0); PG8_BAR; PG8_MMA(0, 0, At, B0); PG8_MMA(0, 1, At, B1); PG8_BAR; PG8_SCHED;
	s_add_i32 s34, 0, 0x18000
	v_add_u32_e32 v161, s34, v150
	s_add_i32 s53, 0, 0x1c000
	ds_read_b128 v[154:157], v161
	ds_read_b128 v[164:167], v161 offset:1024
	ds_read_b128 v[168:171], v161 offset:2048
	ds_read_b128 v[172:175], v161 offset:3072
	v_add_u32_e32 v161, s53, v150
	ds_read_b128 v[176:179], v161
	ds_read_b128 v[180:183], v161 offset:1024
	ds_read_b128 v[184:187], v161 offset:2048
	ds_read_b128 v[192:195], v161 offset:3072
	s_add_u32 s50, s50, 0x80000
	s_addc_u32 s51, s51, 0
	s_mov_b32 m0, s22
	v_lshl_add_u64 v[232:233], s[50:51], 0, v[128:129]
	ds_read_b128 v[196:199], v153 offset:32768
	ds_read_b128 v[200:203], v153 offset:33792
	ds_read_b128 v[204:207], v153 offset:34816
	ds_read_b128 v[208:211], v153 offset:35840
	ds_read_b128 v[212:215], v153 offset:36864
	ds_read_b128 v[216:219], v153 offset:37888
	ds_read_b128 v[220:223], v153 offset:38912
	ds_read_b128 v[224:227], v153 offset:39936
	global_load_lds_dwordx4 v[232:233], off
	v_lshl_add_u64 v[232:233], s[50:51], 0, v[132:133]
	s_mov_b32 m0, s23
	s_nop 0
	global_load_lds_dwordx4 v[232:233], off
	s_waitcnt vmcnt(8)
	s_waitcnt lgkmcnt(0)
	s_barrier
	s_setprio 1
	s_waitcnt lgkmcnt(0)
	v_mfma_f32_16x16x32_bf16 v[124:127], v[154:157], v[196:199], v[124:127]
	v_mfma_f32_16x16x32_bf16 v[120:123], v[168:171], v[196:199], v[120:123]
	v_mfma_f32_16x16x32_bf16 v[116:119], v[154:157], v[204:207], v[116:119]
	v_mfma_f32_16x16x32_bf16 v[112:115], v[168:171], v[204:207], v[112:115]
	v_mfma_f32_16x16x32_bf16 v[100:103], v[154:157], v[212:215], v[100:103]
	v_mfma_f32_16x16x32_bf16 v[96:99], v[168:171], v[212:215], v[96:99]
	v_mfma_f32_16x16x32_bf16 v[84:87], v[154:157], v[220:223], v[84:87]
	v_mfma_f32_16x16x32_bf16 v[80:83], v[168:171], v[220:223], v[80:83]
	v_mfma_f32_16x16x32_bf16 v[124:127], v[164:167], v[200:203], v[124:127]
	v_mfma_f32_16x16x32_bf16 v[120:123], v[172:175], v[200:203], v[120:123]
	v_mfma_f32_16x16x32_bf16 v[116:119], v[164:167], v[208:211], v[116:119]
	v_mfma_f32_16x16x32_bf16 v[112:115], v[172:175], v[208:211], v[112:115]
	v_mfma_f32_16x16x32_bf16 v[100:103], v[164:167], v[216:219], v[100:103]
	v_mfma_f32_16x16x32_bf16 v[96:99], v[172:175], v[216:219], v[96:99]
	v_mfma_f32_16x16x32_bf16 v[84:87], v[164:167], v[224:227], v[84:87]
	v_mfma_f32_16x16x32_bf16 v[80:83], v[172:175], v[224:227], v[80:83]
	s_setprio 0
	s_setprio 1
	v_mfma_f32_16x16x32_bf16 v[108:111], v[176:179], v[196:199], v[108:111]
	v_mfma_f32_16x16x32_bf16 v[104:107], v[184:187], v[196:199], v[104:107]
	v_mfma_f32_16x16x32_bf16 v[92:95], v[176:179], v[204:207], v[92:95]
	v_mfma_f32_16x16x32_bf16 v[88:91], v[184:187], v[204:207], v[88:91]
	v_mfma_f32_16x16x32_bf16 v[76:79], v[176:179], v[212:215], v[76:79]
	v_mfma_f32_16x16x32_bf16 v[72:75], v[184:187], v[212:215], v[72:75]
	v_mfma_f32_16x16x32_bf16 v[68:71], v[176:179], v[220:223], v[68:71]
	v_mfma_f32_16x16x32_bf16 v[64:67], v[184:187], v[220:223], v[64:67]
	v_mfma_f32_16x16x32_bf16 v[108:111], v[180:183], v[200:203], v[108:111]
	v_mfma_f32_16x16x32_bf16 v[104:107], v[192:195], v[200:203], v[104:107]
	v_mfma_f32_16x16x32_bf16 v[92:95], v[180:183], v[208:211], v[92:95]
	v_mfma_f32_16x16x32_bf16 v[88:91], v[192:195], v[208:211], v[88:91]
	v_mfma_f32_16x16x32_bf16 v[76:79], v[180:183], v[216:219], v[76:79]
	v_mfma_f32_16x16x32_bf16 v[72:75], v[192:195], v[216:219], v[72:75]
	v_mfma_f32_16x16x32_bf16 v[68:71], v[180:183], v[224:227], v[68:71]
	v_mfma_f32_16x16x32_bf16 v[64:67], v[192:195], v[224:227], v[64:67]
	s_setprio 0
	s_barrier
; #define PG8_STAGE(bufoff, gbase, voff) do { _Pragma("unroll") for (int _i = 0; _i < 2; ++_i) \
;         __builtin_amdgcn_global_load_lds((const unsigned*)((const char*)(gbase) + (voff)[_i]), (LAS unsigned*)(lds + (bufoff) + ldsw + _i * 8192), 16, 0, 0); } while (0)
; #define PG8_LDA(dst, b, h) do { _Pragma("unroll") for (int m = 0; m < 4; ++m) _Pragma("unroll") for (int k = 0; k < 2; ++k) dst[m][k] = *(const LAS bf16x8*)(lds + PG8_SA(b, h) + aoff + m * 2048 + k * 1024); } while (0)
; #define PG8_MMA(ai, bj, At, Bt) do { __builtin_amdgcn_s_setprio(1); _Pragma("unroll") for (int m = 0; m < 4; ++m) _Pragma("unroll") for (int n = 0; n < 2; ++n) _Pragma("unroll") for (int k = 0; k < 2; ++k) \
;         acc[ai][bj][m][n] = __builtin_amdgcn_mfma_f32_16x16x32_bf16(Bt[n][k], At[m][k], acc[ai][bj][m][n], 0, 0, 0); __builtin_amdgcn_s_setprio(0); } while (0)
; #define PG8_WAIT_V(n) asm volatile("s_waitcnt vmcnt(" #n ")" ::: "memory")
; #define PG8_WAIT_L(n) asm volatile("s_waitcnt lgkmcnt(" #n ")" ::: "memory")
; #define PG8_BAR __builtin_amdgcn_s_barrier()
; #define PG8_SCHED __builtin_amdgcn_sched_barrier(0)
; template <int GI>
; __device__ __forceinline__ void gemm_phase(LAS unsigned char* lds, unsigned char* ws, int G, int cblk) {
;     ...
;             PG8_LDA(At, 1, 1); PG8_STAGE(PG8_SB(1, 0), b3, voffB); PG8_STAGE(PG8_SB(1, 1), b3 + hstepB, voffB); PG8_STAGE(PG8_SA(1, 0), a3, voffA);
;             PG8_WAIT_V(8); PG8_WAIT_L(0); PG8_BAR; PG8_MMA(1, 0, At, B0); PG8_MMA(1, 1, At, B1); PG8_BAR; PG8_SCHED;
;         }
	s_add_i32 s34, s34, s0
	v_lshl_add_u64 v[158:159], v[158:159], 0, s[8:9]
	s_mov_b32 m0, s34
	ds_read_b128 v[196:199], v153 offset:49152
	ds_read_b128 v[200:203], v153 offset:50176
	ds_read_b128 v[204:207], v153 offset:51200
	ds_read_b128 v[208:211], v153 offset:52224
	ds_read_b128 v[212:215], v153 offset:53248
	ds_read_b128 v[216:219], v153 offset:54272
	ds_read_b128 v[220:223], v153 offset:55296
	ds_read_b128 v[224:227], v153 offset:56320
	global_load_lds_dwordx4 v[158:159], off
	s_add_i32 m0, s34, 0x2000
	s_add_u32 s48, s48, 0x80080
	v_lshl_add_u64 v[158:159], v[188:189], 0, s[8:9]
	s_addc_u32 s49, s49, 0
	s_add_i32 s34, s53, s0
	global_load_lds_dwordx4 v[158:159], off
	v_lshl_add_u64 v[158:159], s[48:49], 0, v[130:131]
	s_mov_b32 m0, s34
	s_nop 0
	global_load_lds_dwordx4 v[158:159], off
	v_lshl_add_u64 v[158:159], s[48:49], 0, v[134:135]
	s_add_i32 m0, s34, 0x2000
	s_nop 0
	global_load_lds_dwordx4 v[158:159], off
	v_lshl_add_u64 v[158:159], v[228:229], 0, s[8:9]
	s_mov_b32 m0, s26
	s_nop 0
	global_load_lds_dwordx4 v[158:159], off
	v_lshl_add_u64 v[158:159], v[230:231], 0, s[8:9]
	s_mov_b32 m0, s27
	s_nop 0
	global_load_lds_dwordx4 v[158:159], off
	s_waitcnt vmcnt(8)
	s_waitcnt lgkmcnt(0)
	s_barrier
	s_setprio 1
	s_waitcnt lgkmcnt(0)
	v_mfma_f32_16x16x32_bf16 v[60:63], v[154:157], v[196:199], v[60:63]
	v_mfma_f32_16x16x32_bf16 v[56:59], v[168:171], v[196:199], v[56:59]
	s_add_i32 s19, s19, 2
	s_add_u32 s46, s46, 0x100
	s_addc_u32 s47, s47, 0
	s_add_u32 s14, s14, 0x100
	s_addc_u32 s15, s15, 0
	v_mfma_f32_16x16x32_bf16 v[52:55], v[154:157], v[204:207], v[52:55]
	v_mfma_f32_16x16x32_bf16 v[48:51], v[168:171], v[204:207], v[48:51]
	v_mfma_f32_16x16x32_bf16 v[36:39], v[154:157], v[212:215], v[36:39]
	v_mfma_f32_16x16x32_bf16 v[32:35], v[168:171], v[212:215], v[32:35]
	v_mfma_f32_16x16x32_bf16 v[20:23], v[154:157], v[220:223], v[20:23]
	v_mfma_f32_16x16x32_bf16 v[16:19], v[168:171], v[220:223], v[16:19]
	v_mfma_f32_16x16x32_bf16 v[60:63], v[164:167], v[200:203], v[60:63]
	v_mfma_f32_16x16x32_bf16 v[56:59], v[172:175], v[200:203], v[56:59]
	v_mfma_f32_16x16x32_bf16 v[52:55], v[164:167], v[208:211], v[52:55]
	v_mfma_f32_16x16x32_bf16 v[48:51], v[172:175], v[208:211], v[48:51]
	v_mfma_f32_16x16x32_bf16 v[36:39], v[164:167], v[216:219], v[36:39]
	v_mfma_f32_16x16x32_bf16 v[32:35], v[172:175], v[216:219], v[32:35]
	v_mfma_f32_16x16x32_bf16 v[20:23], v[164:167], v[224:227], v[20:23]
	v_mfma_f32_16x16x32_bf16 v[16:19], v[172:175], v[224:227], v[16:19]
	s_setprio 0
	s_setprio 1
	v_mfma_f32_16x16x32_bf16 v[44:47], v[176:179], v[196:199], v[44:47]
	v_mfma_f32_16x16x32_bf16 v[40:43], v[184:187], v[196:199], v[40:43]
	v_mfma_f32_16x16x32_bf16 v[28:31], v[176:179], v[204:207], v[28:31]
	v_mfma_f32_16x16x32_bf16 v[24:27], v[184:187], v[204:207], v[24:27]
	v_mfma_f32_16x16x32_bf16 v[12:15], v[176:179], v[212:215], v[12:15]
	v_mfma_f32_16x16x32_bf16 v[8:11], v[184:187], v[212:215], v[8:11]
	v_mfma_f32_16x16x32_bf16 v[4:7], v[176:179], v[220:223], v[4:7]
	v_mfma_f32_16x16x32_bf16 v[0:3], v[184:187], v[220:223], v[0:3]
	v_mfma_f32_16x16x32_bf16 v[44:47], v[180:183], v[200:203], v[44:47]
	v_mfma_f32_16x16x32_bf16 v[40:43], v[192:195], v[200:203], v[40:43]
	v_mfma_f32_16x16x32_bf16 v[28:31], v[180:183], v[208:211], v[28:31]
	v_mfma_f32_16x16x32_bf16 v[24:27], v[192:195], v[208:211], v[24:27]
	v_mfma_f32_16x16x32_bf16 v[12:15], v[180:183], v[216:219], v[12:15]
	v_mfma_f32_16x16x32_bf16 v[8:11], v[192:195], v[216:219], v[8:11]
	v_mfma_f32_16x16x32_bf16 v[4:7], v[180:183], v[224:227], v[4:7]
	v_mfma_f32_16x16x32_bf16 v[0:3], v[192:195], v[224:227], v[0:3]
	s_setprio 0
	s_barrier
	s_cmp_gt_u32 s19, 29
	s_cbranch_scc0 .LBB0_400

; #define PG8_STAGE(bufoff, gbase, voff) do { _Pragma("unroll") for (int _i = 0; _i < 2; ++_i) \
;         __builtin_amdgcn_global_load_lds((const unsigned*)((const char*)(gbase) + (voff)[_i]), (LAS unsigned*)(lds + (bufoff) + ldsw + _i * 8192), 16, 0, 0); } while (0)
; #define PG8_LDA(dst, b, h) do { _Pragma("unroll") for (int m = 0; m < 4; ++m) _Pragma("unroll") for (int k = 0; k < 2; ++k) dst[m][k] = *(const LAS bf16x8*)(lds + PG8_SA(b, h) + aoff + m * 2048 + k * 1024); } while (0)
; #define PG8_LDB(dst, b, h) do { _Pragma("unroll") for (int n = 0; n < 2; ++n) _Pragma("unroll") for (int k = 0; k < 2; ++k) dst[n][k] = *(const LAS bf16x8*)(lds + PG8_SB(b, h) + boff + n * 2048 + k * 1024); } while (0)
; #define PG8_MMA(ai, bj, At, Bt) do { __builtin_amdgcn_s_setprio(1); _Pragma("unroll") for (int m = 0; m < 4; ++m) _Pragma("unroll") for (int n = 0; n < 2; ++n) _Pragma("unroll") for (int k = 0; k < 2; ++k) \
;         acc[ai][bj][m][n] = __builtin_amdgcn_mfma_f32_16x16x32_bf16(Bt[n][k], At[m][k], acc[ai][bj][m][n], 0, 0, 0); __builtin_amdgcn_s_setprio(0); } while (0)
; #define PG8_WAIT_V(n) asm volatile("s_waitcnt vmcnt(" #n ")" ::: "memory")
; #define PG8_WAIT_L(n) asm volatile("s_waitcnt lgkmcnt(" #n ")" ::: "memory")
; #define PG8_BAR __builtin_amdgcn_s_barrier()
; #define PG8_SCHED __builtin_amdgcn_sched_barrier(0)
; template <int GI>
; __device__ __forceinline__ void gemm_phase(LAS unsigned char* lds, unsigned char* ws, int G, int cblk) {
;     ...
;         for (int t = 0; t < nt; t += 2) {
;             const bool last = (t == nt - 2);
;             const char* a1 = cA + (size_t)(t + 1) * kstep;
;             const char* a2 = last ? nA : cA + (size_t)(t + 2) * kstep; const char* b2 = last ? nB : cB + (size_t)(t + 2) * kstep;
;             const char* a3 = a2 + kstep; const char* b3 = b2 + kstep;
;             PG8_LDB(B0, 0, 0); PG8_LDB(B1, 0, 1); PG8_SCHED; PG8_LDA(At, 0, 0); PG8_STAGE(PG8_SA(1, 1), a1 + hstepA, voffA);
;             PG8_WAIT_V(8); PG8_WAIT_L(0); PG8_BAR; PG8_MMA(0, 0, At, B0); PG8_MMA(0, 1, At, B1); PG8_BAR; PG8_SCHED;
;             PG8_LDA(At, 0, 1); PG8_STAGE(PG8_SB(0, 0), b2, voffB); PG8_STAGE(PG8_SB(0, 1), b2 + hstepB, voffB); PG8_STAGE(PG8_SA(0, 0), a2, voffA);
;             PG8_WAIT_V(8); PG8_WAIT_L(0); PG8_BAR; PG8_MMA(1, 0, At, B0); PG8_MMA(1, 1, At, B1); PG8_BAR; PG8_SCHED;
.LBB0_415:
	s_add_u32 s50, s50, 0x100080
	s_addc_u32 s51, s51, 0
	s_add_u32 s14, s52, 0x100
	s_addc_u32 s15, s53, 0
	s_mov_b32 s21, -2
	ds_read_b128 v[154:157], v151
	ds_read_b128 v[164:167], v151 offset:1024
	ds_read_b128 v[168:171], v151 offset:2048
	ds_read_b128 v[172:175], v151 offset:3072
	ds_read_b128 v[176:179], v152
	ds_read_b128 v[180:183], v152 offset:1024
	ds_read_b128 v[184:187], v152 offset:2048
	ds_read_b128 v[192:195], v152 offset:3072
	s_add_u32 s34, s50, 0xfff00080
	s_addc_u32 s52, s51, -1
	s_cmp_eq_u32 s21, 4
	s_cselect_b32 s55, s41, s52
	s_cselect_b32 s54, s40, s34
	s_cselect_b32 s53, s43, s15
	s_cselect_b32 s52, s42, s14
	v_lshl_add_u64 v[158:159], s[50:51], 0, v[138:139]
	s_add_i32 m0, s22, 0xc000
	ds_read_b128 v[196:199], v153
	ds_read_b128 v[200:203], v153 offset:1024
	ds_read_b128 v[204:207], v153 offset:2048
	ds_read_b128 v[208:211], v153 offset:3072
	ds_read_b128 v[212:215], v153 offset:4096
	ds_read_b128 v[216:219], v153 offset:5120
	ds_read_b128 v[220:223], v153 offset:6144
	ds_read_b128 v[224:227], v153 offset:7168
	global_load_lds_dwordx4 v[158:159], off
	v_lshl_add_u64 v[158:159], s[50:51], 0, v[140:141]
	s_add_i32 m0, s22, 0xe000
	s_nop 0
	global_load_lds_dwordx4 v[158:159], off
	s_waitcnt vmcnt(8)
	s_waitcnt lgkmcnt(0)
	s_barrier
	s_setprio 1
	s_waitcnt lgkmcnt(0)
	v_mfma_f32_16x16x32_bf16 v[124:127], v[154:157], v[196:199], 0
	v_mfma_f32_16x16x32_bf16 v[120:123], v[168:171], v[196:199], 0
	v_mfma_f32_16x16x32_bf16 v[116:119], v[154:157], v[204:207], 0
	v_mfma_f32_16x16x32_bf16 v[108:111], v[168:171], v[204:207], 0
	v_mfma_f32_16x16x32_bf16 v[100:103], v[154:157], v[212:215], 0
	v_mfma_f32_16x16x32_bf16 v[92:95], v[168:171], v[212:215], 0
	v_mfma_f32_16x16x32_bf16 v[84:87], v[154:157], v[220:223], 0
	v_mfma_f32_16x16x32_bf16 v[76:79], v[168:171], v[220:223], 0
	v_mfma_f32_16x16x32_bf16 v[124:127], v[164:167], v[200:203], v[124:127]
	v_mfma_f32_16x16x32_bf16 v[120:123], v[172:175], v[200:203], v[120:123]
	v_mfma_f32_16x16x32_bf16 v[116:119], v[164:167], v[208:211], v[116:119]
	v_mfma_f32_16x16x32_bf16 v[108:111], v[172:175], v[208:211], v[108:111]
	v_mfma_f32_16x16x32_bf16 v[100:103], v[164:167], v[216:219], v[100:103]
	v_mfma_f32_16x16x32_bf16 v[92:95], v[172:175], v[216:219], v[92:95]
	v_mfma_f32_16x16x32_bf16 v[84:87], v[164:167], v[224:227], v[84:87]
	v_mfma_f32_16x16x32_bf16 v[76:79], v[172:175], v[224:227], v[76:79]
	s_setprio 0
	s_setprio 1
	v_mfma_f32_16x16x32_bf16 v[112:115], v[176:179], v[196:199], 0
	v_mfma_f32_16x16x32_bf16 v[104:107], v[184:187], v[196:199], 0
	v_mfma_f32_16x16x32_bf16 v[96:99], v[176:179], v[204:207], 0
	v_mfma_f32_16x16x32_bf16 v[88:91], v[184:187], v[204:207], 0
	v_mfma_f32_16x16x32_bf16 v[80:83], v[176:179], v[212:215], 0
	v_mfma_f32_16x16x32_bf16 v[72:75], v[184:187], v[212:215], 0
	v_mfma_f32_16x16x32_bf16 v[68:71], v[176:179], v[220:223], 0
	v_mfma_f32_16x16x32_bf16 v[64:67], v[184:187], v[220:223], 0
	v_mfma_f32_16x16x32_bf16 v[112:115], v[180:183], v[200:203], v[112:115]
	v_mfma_f32_16x16x32_bf16 v[104:107], v[192:195], v[200:203], v[104:107]
	v_mfma_f32_16x16x32_bf16 v[96:99], v[180:183], v[208:211], v[96:99]
	v_mfma_f32_16x16x32_bf16 v[88:91], v[192:195], v[208:211], v[88:91]
	v_mfma_f32_16x16x32_bf16 v[80:83], v[180:183], v[216:219], v[80:83]
	v_mfma_f32_16x16x32_bf16 v[72:75], v[192:195], v[216:219], v[72:75]
	v_mfma_f32_16x16x32_bf16 v[68:71], v[180:183], v[224:227], v[68:71]
	v_mfma_f32_16x16x32_bf16 v[64:67], v[192:195], v[224:227], v[64:67]
	s_setprio 0
	s_barrier
	s_add_i32 s34, s39, s0
	v_lshl_add_u64 v[158:159], s[52:53], 0, v[132:133]
	s_mov_b32 m0, s34
	ds_read_b128 v[196:199], v153 offset:16384
	ds_read_b128 v[200:203], v153 offset:17408
	ds_read_b128 v[204:207], v153 offset:18432
	ds_read_b128 v[208:211], v153 offset:19456
	ds_read_b128 v[212:215], v153 offset:20480
	ds_read_b128 v[216:219], v153 offset:21504
	ds_read_b128 v[220:223], v153 offset:22528
	ds_read_b128 v[224:227], v153 offset:23552
	global_load_lds_dwordx4 v[158:159], off
	s_add_i32 m0, s34, 0x2000
	s_add_u32 s58, s52, 0x80000
	v_lshl_add_u64 v[188:189], s[52:53], 0, v[128:129]
	s_addc_u32 s59, s53, 0
	s_add_i32 s34, s56, s0
	global_load_lds_dwordx4 v[188:189], off
	v_lshl_add_u64 v[228:229], s[58:59], 0, v[132:133]
	s_mov_b32 m0, s34
	v_lshl_add_u64 v[230:231], s[54:55], 0, v[130:131]
	global_load_lds_dwordx4 v[228:229], off
	v_lshl_add_u64 v[228:229], s[58:59], 0, v[128:129]
	s_add_i32 m0, s34, 0x2000
	s_nop 0
	global_load_lds_dwordx4 v[228:229], off
	v_lshl_add_u64 v[228:229], s[54:55], 0, v[134:135]
	s_mov_b32 m0, s22
	s_nop 0
	global_load_lds_dwordx4 v[228:229], off
	s_mov_b32 m0, s23
	s_nop 0
	global_load_lds_dwordx4 v[230:231], off
	s_waitcnt vmcnt(8)
	s_waitcnt lgkmcnt(0)
	s_barrier
; #define PG8_STAGE(bufoff, gbase, voff) do { _Pragma("unroll") for (int _i = 0; _i < 2; ++_i) \
;         __builtin_amdgcn_global_load_lds((const unsigned*)((const char*)(gbase) + (voff)[_i]), (LAS unsigned*)(lds + (bufoff) + ldsw + _i * 8192), 16, 0, 0); } while (0)
; #define PG8_LDA(dst, b, h) do { _Pragma("unroll") for (int m = 0; m < 4; ++m) _Pragma("unroll") for (int k = 0; k < 2; ++k) dst[m][k] = *(const LAS bf16x8*)(lds + PG8_SA(b, h) + aoff + m * 2048 + k * 1024); } while (0)
; #define PG8_LDB(dst, b, h) do { _Pragma("unroll") for (int n = 0; n < 2; ++n) _Pragma("unroll") for (int k = 0; k < 2; ++k) dst[n][k] = *(const LAS bf16x8*)(lds + PG8_SB(b, h) + boff + n * 2048 + k * 1024); } while (0)
; #define PG8_MMA(ai, bj, At, Bt) do { __builtin_amdgcn_s_setprio(1); _Pragma("unroll") for (int m = 0; m < 4; ++m) _Pragma("unroll") for (int n = 0; n < 2; ++n) _Pragma("unroll") for (int k = 0; k < 2; ++k) \
;         acc[ai][bj][m][n] = __builtin_amdgcn_mfma_f32_16x16x32_bf16(Bt[n][k], At[m][k], acc[ai][bj][m][n], 0, 0, 0); __builtin_amdgcn_s_setprio(0); } while (0)
; #define PG8_WAIT_V(n) asm volatile("s_waitcnt vmcnt(" #n ")" ::: "memory")
; #define PG8_WAIT_L(n) asm volatile("s_waitcnt lgkmcnt(" #n ")" ::: "memory")
; #define PG8_BAR __builtin_amdgcn_s_barrier()
; #define PG8_SCHED __builtin_amdgcn_sched_barrier(0)
; template <int GI>
; __device__ __forceinline__ void gemm_phase(LAS unsigned char* lds, unsigned char* ws, int G, int cblk) {
;     ...
;             PG8_WAIT_V(8); PG8_WAIT_L(0); PG8_BAR; PG8_MMA(1, 0, At, B0); PG8_MMA(1, 1, At, B1); PG8_BAR; PG8_SCHED;
;             PG8_LDB(B0, 1, 0); PG8_LDB(B1, 1, 1); PG8_SCHED; PG8_LDA(At, 1, 0); PG8_STAGE(PG8_SA(0, 1), a2 + hstepA, voffA);
;             PG8_WAIT_V(8); PG8_WAIT_L(0); PG8_BAR; PG8_MMA(0, 0, At, B0); PG8_MMA(0, 1, At, B1); PG8_BAR; PG8_SCHED;
	s_setprio 1
	s_waitcnt lgkmcnt(0)
	v_mfma_f32_16x16x32_bf16 v[60:63], v[154:157], v[196:199], 0
	v_mfma_f32_16x16x32_bf16 v[56:59], v[168:171], v[196:199], 0
	v_mfma_f32_16x16x32_bf16 v[52:55], v[154:157], v[204:207], 0
	v_mfma_f32_16x16x32_bf16 v[44:47], v[168:171], v[204:207], 0
	v_mfma_f32_16x16x32_bf16 v[36:39], v[154:157], v[212:215], 0
	v_mfma_f32_16x16x32_bf16 v[28:31], v[168:171], v[212:215], 0
	v_mfma_f32_16x16x32_bf16 v[20:23], v[154:157], v[220:223], 0
	v_mfma_f32_16x16x32_bf16 v[12:15], v[168:171], v[220:223], 0
	v_mfma_f32_16x16x32_bf16 v[60:63], v[164:167], v[200:203], v[60:63]
	v_mfma_f32_16x16x32_bf16 v[56:59], v[172:175], v[200:203], v[56:59]
	v_mfma_f32_16x16x32_bf16 v[52:55], v[164:167], v[208:211], v[52:55]
	v_mfma_f32_16x16x32_bf16 v[44:47], v[172:175], v[208:211], v[44:47]
	v_mfma_f32_16x16x32_bf16 v[36:39], v[164:167], v[216:219], v[36:39]
	v_mfma_f32_16x16x32_bf16 v[28:31], v[172:175], v[216:219], v[28:31]
	v_mfma_f32_16x16x32_bf16 v[20:23], v[164:167], v[224:227], v[20:23]
	v_mfma_f32_16x16x32_bf16 v[12:15], v[172:175], v[224:227], v[12:15]
	s_setprio 0
	s_setprio 1
	v_mfma_f32_16x16x32_bf16 v[48:51], v[176:179], v[196:199], 0
	v_mfma_f32_16x16x32_bf16 v[40:43], v[184:187], v[196:199], 0
	v_mfma_f32_16x16x32_bf16 v[32:35], v[176:179], v[204:207], 0
	v_mfma_f32_16x16x32_bf16 v[24:27], v[184:187], v[204:207], 0
	v_mfma_f32_16x16x32_bf16 v[16:19], v[176:179], v[212:215], 0
	v_mfma_f32_16x16x32_bf16 v[8:11], v[184:187], v[212:215], 0
	v_mfma_f32_16x16x32_bf16 v[4:7], v[176:179], v[220:223], 0
	v_mfma_f32_16x16x32_bf16 v[0:3], v[184:187], v[220:223], 0
	v_mfma_f32_16x16x32_bf16 v[48:51], v[180:183], v[200:203], v[48:51]
	v_mfma_f32_16x16x32_bf16 v[40:43], v[192:195], v[200:203], v[40:43]
	v_mfma_f32_16x16x32_bf16 v[32:35], v[180:183], v[208:211], v[32:35]
	v_mfma_f32_16x16x32_bf16 v[24:27], v[192:195], v[208:211], v[24:27]
	v_mfma_f32_16x16x32_bf16 v[16:19], v[180:183], v[216:219], v[16:19]
	v_mfma_f32_16x16x32_bf16 v[8:11], v[192:195], v[216:219], v[8:11]
	v_mfma_f32_16x16x32_bf16 v[4:7], v[180:183], v[224:227], v[4:7]
	v_mfma_f32_16x16x32_bf16 v[0:3], v[192:195], v[224:227], v[0:3]
	s_setprio 0
	s_barrier
	s_add_i32 s34, 0, 0x18000
	v_add_u32_e32 v161, s34, v150
	s_add_i32 s58, 0, 0x1c000
	ds_read_b128 v[154:157], v161
	ds_read_b128 v[164:167], v161 offset:1024
	ds_read_b128 v[168:171], v161 offset:2048
	ds_read_b128 v[172:175], v161 offset:3072
	v_add_u32_e32 v161, s58, v150
	ds_read_b128 v[176:179], v161
	ds_read_b128 v[180:183], v161 offset:1024
	ds_read_b128 v[184:187], v161 offset:2048
	ds_read_b128 v[192:195], v161 offset:3072
	s_add_u32 s54, s54, 0x100000
	s_addc_u32 s55, s55, 0
	s_mov_b32 m0, s24
	v_lshl_add_u64 v[232:233], s[54:55], 0, v[134:135]
	ds_read_b128 v[196:199], v153 offset:32768
	ds_read_b128 v[200:203], v153 offset:33792
	ds_read_b128 v[204:207], v153 offset:34816
	ds_read_b128 v[208:211], v153 offset:35840
	ds_read_b128 v[212:215], v153 offset:36864
	ds_read_b128 v[216:219], v153 offset:37888
	ds_read_b128 v[220:223], v153 offset:38912
	ds_read_b128 v[224:227], v153 offset:39936
	global_load_lds_dwordx4 v[232:233], off
	v_lshl_add_u64 v[232:233], s[54:55], 0, v[130:131]
	s_mov_b32 m0, s25
	s_nop 0
	global_load_lds_dwordx4 v[232:233], off
	s_waitcnt vmcnt(8)
	s_waitcnt lgkmcnt(0)
	s_barrier
	s_setprio 1
	s_waitcnt lgkmcnt(0)
	v_mfma_f32_16x16x32_bf16 v[124:127], v[154:157], v[196:199], v[124:127]
	v_mfma_f32_16x16x32_bf16 v[120:123], v[168:171], v[196:199], v[120:123]
	v_mfma_f32_16x16x32_bf16 v[116:119], v[154:157], v[204:207], v[116:119]
	v_mfma_f32_16x16x32_bf16 v[108:111], v[168:171], v[204:207], v[108:111]
	v_mfma_f32_16x16x32_bf16 v[100:103], v[154:157], v[212:215], v[100:103]
	v_mfma_f32_16x16x32_bf16 v[92:95], v[168:171], v[212:215], v[92:95]
	v_mfma_f32_16x16x32_bf16 v[84:87], v[154:157], v[220:223], v[84:87]
	v_mfma_f32_16x16x32_bf16 v[76:79], v[168:171], v[220:223], v[76:79]
	v_mfma_f32_16x16x32_bf16 v[124:127], v[164:167], v[200:203], v[124:127]
	v_mfma_f32_16x16x32_bf16 v[120:123], v[172:175], v[200:203], v[120:123]
	v_mfma_f32_16x16x32_bf16 v[116:119], v[164:167], v[208:211], v[116:119]
	v_mfma_f32_16x16x32_bf16 v[108:111], v[172:175], v[208:211], v[108:111]
	v_mfma_f32_16x16x32_bf16 v[100:103], v[164:167], v[216:219], v[100:103]
	v_mfma_f32_16x16x32_bf16 v[92:95], v[172:175], v[216:219], v[92:95]
	v_mfma_f32_16x16x32_bf16 v[84:87], v[164:167], v[224:227], v[84:87]
	v_mfma_f32_16x16x32_bf16 v[76:79], v[172:175], v[224:227], v[76:79]
	s_setprio 0
	s_setprio 1
	v_mfma_f32_16x16x32_bf16 v[112:115], v[176:179], v[196:199], v[112:115]
	v_mfma_f32_16x16x32_bf16 v[104:107], v[184:187], v[196:199], v[104:107]
	v_mfma_f32_16x16x32_bf16 v[96:99], v[176:179], v[204:207], v[96:99]
	v_mfma_f32_16x16x32_bf16 v[88:91], v[184:187], v[204:207], v[88:91]
	v_mfma_f32_16x16x32_bf16 v[80:83], v[176:179], v[212:215], v[80:83]
	v_mfma_f32_16x16x32_bf16 v[72:75], v[184:187], v[212:215], v[72:75]
	v_mfma_f32_16x16x32_bf16 v[68:71], v[176:179], v[220:223], v[68:71]
	v_mfma_f32_16x16x32_bf16 v[64:67], v[184:187], v[220:223], v[64:67]
	v_mfma_f32_16x16x32_bf16 v[112:115], v[180:183], v[200:203], v[112:115]
	v_mfma_f32_16x16x32_bf16 v[104:107], v[192:195], v[200:203], v[104:107]
	v_mfma_f32_16x16x32_bf16 v[96:99], v[180:183], v[208:211], v[96:99]
	v_mfma_f32_16x16x32_bf16 v[88:91], v[192:195], v[208:211], v[88:91]
	v_mfma_f32_16x16x32_bf16 v[80:83], v[180:183], v[216:219], v[80:83]
	v_mfma_f32_16x16x32_bf16 v[72:75], v[192:195], v[216:219], v[72:75]
	v_mfma_f32_16x16x32_bf16 v[68:71], v[180:183], v[224:227], v[68:71]
	v_mfma_f32_16x16x32_bf16 v[64:67], v[192:195], v[224:227], v[64:67]
	s_setprio 0
	s_barrier
; #define PG8_STAGE(bufoff, gbase, voff) do { _Pragma("unroll") for (int _i = 0; _i < 2; ++_i) \
;         __builtin_amdgcn_global_load_lds((const unsigned*)((const char*)(gbase) + (voff)[_i]), (LAS unsigned*)(lds + (bufoff) + ldsw + _i * 8192), 16, 0, 0); } while (0)
; #define PG8_LDA(dst, b, h) do { _Pragma("unroll") for (int m = 0; m < 4; ++m) _Pragma("unroll") for (int k = 0; k < 2; ++k) dst[m][k] = *(const LAS bf16x8*)(lds + PG8_SA(b, h) + aoff + m * 2048 + k * 1024); } while (0)
; #define PG8_LDB(dst, b, h) do { _Pragma("unroll") for (int n = 0; n < 2; ++n) _Pragma("unroll") for (int k = 0; k < 2; ++k) dst[n][k] = *(const LAS bf16x8*)(lds + PG8_SB(b, h) + boff + n * 2048 + k * 1024); } while (0)
; #define PG8_MMA(ai, bj, At, Bt) do { __builtin_amdgcn_s_setprio(1); _Pragma("unroll") for (int m = 0; m < 4; ++m) _Pragma("unroll") for (int n = 0; n < 2; ++n) _Pragma("unroll") for (int k = 0; k < 2; ++k) \
;         acc[ai][bj][m][n] = __builtin_amdgcn_mfma_f32_16x16x32_bf16(Bt[n][k], At[m][k], acc[ai][bj][m][n], 0, 0, 0); __builtin_amdgcn_s_setprio(0); } while (0)
; #define PG8_WAIT_V(n) asm volatile("s_waitcnt vmcnt(" #n ")" ::: "memory")
; #define PG8_WAIT_L(n) asm volatile("s_waitcnt lgkmcnt(" #n ")" ::: "memory")
; #define PG8_BAR __builtin_amdgcn_s_barrier()
; #define PG8_SCHED __builtin_amdgcn_sched_barrier(0)
; template <int GI>
; __device__ __forceinline__ void gemm_phase(LAS unsigned char* lds, unsigned char* ws, int G, int cblk) {
;     ...
;         for (int t = 0; t < nt; t += 2) {
;             const bool last = (t == nt - 2);
;             const char* a1 = cA + (size_t)(t + 1) * kstep;
;             const char* a2 = last ? nA : cA + (size_t)(t + 2) * kstep; const char* b2 = last ? nB : cB + (size_t)(t + 2) * kstep;
;             const char* a3 = a2 + kstep; const char* b3 = b2 + kstep;
;             PG8_LDB(B0, 0, 0); PG8_LDB(B1, 0, 1); PG8_SCHED; PG8_LDA(At, 0, 0); PG8_STAGE(PG8_SA(1, 1), a1 + hstepA, voffA);
;             PG8_WAIT_V(8); PG8_WAIT_L(0); PG8_BAR; PG8_MMA(0, 0, At, B0); PG8_MMA(0, 1, At, B1); PG8_BAR; PG8_SCHED;
;     ...
;             PG8_LDA(At, 1, 1); PG8_STAGE(PG8_SB(1, 0), b3, voffB); PG8_STAGE(PG8_SB(1, 1), b3 + hstepB, voffB); PG8_STAGE(PG8_SA(1, 0), a3, voffA);
;             PG8_WAIT_V(8); PG8_WAIT_L(0); PG8_BAR; PG8_MMA(1, 0, At, B0); PG8_MMA(1, 1, At, B1); PG8_BAR; PG8_SCHED;
;         }
	s_add_i32 s34, s34, s0
	v_lshl_add_u64 v[158:159], v[158:159], 0, s[12:13]
	s_mov_b32 m0, s34
	ds_read_b128 v[196:199], v153 offset:49152
	ds_read_b128 v[200:203], v153 offset:50176
	ds_read_b128 v[204:207], v153 offset:51200
	ds_read_b128 v[208:211], v153 offset:52224
	ds_read_b128 v[212:215], v153 offset:53248
	ds_read_b128 v[216:219], v153 offset:54272
	ds_read_b128 v[220:223], v153 offset:55296
	ds_read_b128 v[224:227], v153 offset:56320
	global_load_lds_dwordx4 v[158:159], off
	s_add_i32 m0, s34, 0x2000
	s_add_u32 s52, s52, 0x80080
	v_lshl_add_u64 v[158:159], v[188:189], 0, s[12:13]
	s_addc_u32 s53, s53, 0
	s_add_i32 s34, s58, s0
	global_load_lds_dwordx4 v[158:159], off
	v_lshl_add_u64 v[158:159], s[52:53], 0, v[132:133]
	s_mov_b32 m0, s34
	s_nop 0
	global_load_lds_dwordx4 v[158:159], off
	v_lshl_add_u64 v[158:159], s[52:53], 0, v[128:129]
	s_add_i32 m0, s34, 0x2000
	s_nop 0
	global_load_lds_dwordx4 v[158:159], off
	v_lshl_add_u64 v[158:159], v[228:229], 0, s[12:13]
	s_mov_b32 m0, s33
	s_nop 0
	global_load_lds_dwordx4 v[158:159], off
	v_lshl_add_u64 v[158:159], v[230:231], 0, s[12:13]
	s_mov_b32 m0, s35
	s_nop 0
	global_load_lds_dwordx4 v[158:159], off
	s_waitcnt vmcnt(8)
	s_waitcnt lgkmcnt(0)
	s_barrier
	s_setprio 1
	s_waitcnt lgkmcnt(0)
	v_mfma_f32_16x16x32_bf16 v[60:63], v[154:157], v[196:199], v[60:63]
	v_mfma_f32_16x16x32_bf16 v[56:59], v[168:171], v[196:199], v[56:59]
	s_add_i32 s21, s21, 2
	s_add_u32 s50, s50, 0x100
	s_addc_u32 s51, s51, 0
	s_add_u32 s14, s14, 0x100
	s_addc_u32 s15, s15, 0
	v_mfma_f32_16x16x32_bf16 v[52:55], v[154:157], v[204:207], v[52:55]
	v_mfma_f32_16x16x32_bf16 v[44:47], v[168:171], v[204:207], v[44:47]
	v_mfma_f32_16x16x32_bf16 v[36:39], v[154:157], v[212:215], v[36:39]
	v_mfma_f32_16x16x32_bf16 v[28:31], v[168:171], v[212:215], v[28:31]
	v_mfma_f32_16x16x32_bf16 v[20:23], v[154:157], v[220:223], v[20:23]
	v_mfma_f32_16x16x32_bf16 v[12:15], v[168:171], v[220:223], v[12:15]
	v_mfma_f32_16x16x32_bf16 v[60:63], v[164:167], v[200:203], v[60:63]
	v_mfma_f32_16x16x32_bf16 v[56:59], v[172:175], v[200:203], v[56:59]
	v_mfma_f32_16x16x32_bf16 v[52:55], v[164:167], v[208:211], v[52:55]
	v_mfma_f32_16x16x32_bf16 v[44:47], v[172:175], v[208:211], v[44:47]
	v_mfma_f32_16x16x32_bf16 v[36:39], v[164:167], v[216:219], v[36:39]
	v_mfma_f32_16x16x32_bf16 v[28:31], v[172:175], v[216:219], v[28:31]
	v_mfma_f32_16x16x32_bf16 v[20:23], v[164:167], v[224:227], v[20:23]
	v_mfma_f32_16x16x32_bf16 v[12:15], v[172:175], v[224:227], v[12:15]
	s_setprio 0
	s_setprio 1
	v_mfma_f32_16x16x32_bf16 v[48:51], v[176:179], v[196:199], v[48:51]
	v_mfma_f32_16x16x32_bf16 v[40:43], v[184:187], v[196:199], v[40:43]
	v_mfma_f32_16x16x32_bf16 v[32:35], v[176:179], v[204:207], v[32:35]
	v_mfma_f32_16x16x32_bf16 v[24:27], v[184:187], v[204:207], v[24:27]
	v_mfma_f32_16x16x32_bf16 v[16:19], v[176:179], v[212:215], v[16:19]
	v_mfma_f32_16x16x32_bf16 v[8:11], v[184:187], v[212:215], v[8:11]
	v_mfma_f32_16x16x32_bf16 v[4:7], v[176:179], v[220:223], v[4:7]
	v_mfma_f32_16x16x32_bf16 v[0:3], v[184:187], v[220:223], v[0:3]
	v_mfma_f32_16x16x32_bf16 v[48:51], v[180:183], v[200:203], v[48:51]
	v_mfma_f32_16x16x32_bf16 v[40:43], v[192:195], v[200:203], v[40:43]
	v_mfma_f32_16x16x32_bf16 v[32:35], v[180:183], v[208:211], v[32:35]
	v_mfma_f32_16x16x32_bf16 v[24:27], v[192:195], v[208:211], v[24:27]
	v_mfma_f32_16x16x32_bf16 v[16:19], v[180:183], v[216:219], v[16:19]
	v_mfma_f32_16x16x32_bf16 v[8:11], v[192:195], v[216:219], v[8:11]
	v_mfma_f32_16x16x32_bf16 v[4:7], v[180:183], v[224:227], v[4:7]
	v_mfma_f32_16x16x32_bf16 v[0:3], v[192:195], v[224:227], v[0:3]
	s_setprio 0
	s_barrier
	s_cmp_gt_u32 s21, 5
	s_cbranch_scc0 .LBB0_416
	s_branch .Lpeel_exit_4
.LBB0_416:
	ds_read_b128 v[154:157], v151
	ds_read_b128 v[164:167], v151 offset:1024
	ds_read_b128 v[168:171], v151 offset:2048
	ds_read_b128 v[172:175], v151 offset:3072
	ds_read_b128 v[176:179], v152
	ds_read_b128 v[180:183], v152 offset:1024
	ds_read_b128 v[184:187], v152 offset:2048
	ds_read_b128 v[192:195], v152 offset:3072
	s_add_u32 s34, s50, 0xfff00080
	s_addc_u32 s52, s51, -1
	s_cmp_eq_u32 s21, 4
	s_cselect_b32 s55, s41, s52
	s_cselect_b32 s54, s40, s34
	s_cselect_b32 s53, s43, s15
	s_cselect_b32 s52, s42, s14
	v_lshl_add_u64 v[158:159], s[50:51], 0, v[138:139]
	s_add_i32 m0, s22, 0xc000
	ds_read_b128 v[196:199], v153
	ds_read_b128 v[200:203], v153 offset:1024
	ds_read_b128 v[204:207], v153 offset:2048
	ds_read_b128 v[208:211], v153 offset:3072
	ds_read_b128 v[212:215], v153 offset:4096
	ds_read_b128 v[216:219], v153 offset:5120
	ds_read_b128 v[220:223], v153 offset:6144
	ds_read_b128 v[224:227], v153 offset:7168
	global_load_lds_dwordx4 v[158:159], off
	v_lshl_add_u64 v[158:159], s[50:51], 0, v[140:141]
	s_add_i32 m0, s22, 0xe000
	s_nop 0
	global_load_lds_dwordx4 v[158:159], off
	s_waitcnt vmcnt(8)
	s_waitcnt lgkmcnt(0)
	s_barrier
; #define PG8_STAGE(bufoff, gbase, voff) do { _Pragma("unroll") for (int _i = 0; _i < 2; ++_i) \
;         __builtin_amdgcn_global_load_lds((const unsigned*)((const char*)(gbase) + (voff)[_i]), (LAS unsigned*)(lds + (bufoff) + ldsw + _i * 8192), 16, 0, 0); } while (0)
; #define PG8_LDA(dst, b, h) do { _Pragma("unroll") for (int m = 0; m < 4; ++m) _Pragma("unroll") for (int k = 0; k < 2; ++k) dst[m][k] = *(const LAS bf16x8*)(lds + PG8_SA(b, h) + aoff + m * 2048 + k * 1024); } while (0)
; #define PG8_MMA(ai, bj, At, Bt) do { __builtin_amdgcn_s_setprio(1); _Pragma("unroll") for (int m = 0; m < 4; ++m) _Pragma("unroll") for (int n = 0; n < 2; ++n) _Pragma("unroll") for (int k = 0; k < 2; ++k) \
;         acc[ai][bj][m][n] = __builtin_amdgcn_mfma_f32_16x16x32_bf16(Bt[n][k], At[m][k], acc[ai][bj][m][n], 0, 0, 0); __builtin_amdgcn_s_setprio(0); } while (0)
; #define PG8_WAIT_V(n) asm volatile("s_waitcnt vmcnt(" #n ")" ::: "memory")
; #define PG8_WAIT_L(n) asm volatile("s_waitcnt lgkmcnt(" #n ")" ::: "memory")
; #define PG8_BAR __builtin_amdgcn_s_barrier()
; #define PG8_SCHED __builtin_amdgcn_sched_barrier(0)
; template <int GI>
; __device__ __forceinline__ void gemm_phase(LAS unsigned char* lds, unsigned char* ws, int G, int cblk) {
;     ...
;             PG8_WAIT_V(8); PG8_WAIT_L(0); PG8_BAR; PG8_MMA(0, 0, At, B0); PG8_MMA(0, 1, At, B1); PG8_BAR; PG8_SCHED;
;             PG8_LDA(At, 0, 1); PG8_STAGE(PG8_SB(0, 0), b2, voffB); PG8_STAGE(PG8_SB(0, 1), b2 + hstepB, voffB); PG8_STAGE(PG8_SA(0, 0), a2, voffA);
;             PG8_WAIT_V(8); PG8_WAIT_L(0); PG8_BAR; PG8_MMA(1, 0, At, B0); PG8_MMA(1, 1, At, B1); PG8_BAR; PG8_SCHED;
	s_setprio 1
	s_waitcnt lgkmcnt(0)
	v_mfma_f32_16x16x32_bf16 v[124:127], v[154:157], v[196:199], v[124:127]
	v_mfma_f32_16x16x32_bf16 v[120:123], v[168:171], v[196:199], v[120:123]
	v_mfma_f32_16x16x32_bf16 v[116:119], v[154:157], v[204:207], v[116:119]
	v_mfma_f32_16x16x32_bf16 v[108:111], v[168:171], v[204:207], v[108:111]
	v_mfma_f32_16x16x32_bf16 v[100:103], v[154:157], v[212:215], v[100:103]
	v_mfma_f32_16x16x32_bf16 v[92:95], v[168:171], v[212:215], v[92:95]
	v_mfma_f32_16x16x32_bf16 v[84:87], v[154:157], v[220:223], v[84:87]
	v_mfma_f32_16x16x32_bf16 v[76:79], v[168:171], v[220:223], v[76:79]
	v_mfma_f32_16x16x32_bf16 v[124:127], v[164:167], v[200:203], v[124:127]
	v_mfma_f32_16x16x32_bf16 v[120:123], v[172:175], v[200:203], v[120:123]
	v_mfma_f32_16x16x32_bf16 v[116:119], v[164:167], v[208:211], v[116:119]
	v_mfma_f32_16x16x32_bf16 v[108:111], v[172:175], v[208:211], v[108:111]
	v_mfma_f32_16x16x32_bf16 v[100:103], v[164:167], v[216:219], v[100:103]
	v_mfma_f32_16x16x32_bf16 v[92:95], v[172:175], v[216:219], v[92:95]
	v_mfma_f32_16x16x32_bf16 v[84:87], v[164:167], v[224:227], v[84:87]
	v_mfma_f32_16x16x32_bf16 v[76:79], v[172:175], v[224:227], v[76:79]
	s_setprio 0
	s_setprio 1
	v_mfma_f32_16x16x32_bf16 v[112:115], v[176:179], v[196:199], v[112:115]
	v_mfma_f32_16x16x32_bf16 v[104:107], v[184:187], v[196:199], v[104:107]
	v_mfma_f32_16x16x32_bf16 v[96:99], v[176:179], v[204:207], v[96:99]
	v_mfma_f32_16x16x32_bf16 v[88:91], v[184:187], v[204:207], v[88:91]
	v_mfma_f32_16x16x32_bf16 v[80:83], v[176:179], v[212:215], v[80:83]
	v_mfma_f32_16x16x32_bf16 v[72:75], v[184:187], v[212:215], v[72:75]
	v_mfma_f32_16x16x32_bf16 v[68:71], v[176:179], v[220:223], v[68:71]
	v_mfma_f32_16x16x32_bf16 v[64:67], v[184:187], v[220:223], v[64:67]
	v_mfma_f32_16x16x32_bf16 v[112:115], v[180:183], v[200:203], v[112:115]
	v_mfma_f32_16x16x32_bf16 v[104:107], v[192:195], v[200:203], v[104:107]
	v_mfma_f32_16x16x32_bf16 v[96:99], v[180:183], v[208:211], v[96:99]
	v_mfma_f32_16x16x32_bf16 v[88:91], v[192:195], v[208:211], v[88:91]
	v_mfma_f32_16x16x32_bf16 v[80:83], v[180:183], v[216:219], v[80:83]
	v_mfma_f32_16x16x32_bf16 v[72:75], v[192:195], v[216:219], v[72:75]
	v_mfma_f32_16x16x32_bf16 v[68:71], v[180:183], v[224:227], v[68:71]
	v_mfma_f32_16x16x32_bf16 v[64:67], v[192:195], v[224:227], v[64:67]
	s_setprio 0
	s_barrier
	s_add_i32 s34, s39, s0
	v_lshl_add_u64 v[158:159], s[52:53], 0, v[132:133]
	s_mov_b32 m0, s34
	ds_read_b128 v[196:199], v153 offset:16384
	ds_read_b128 v[200:203], v153 offset:17408
	ds_read_b128 v[204:207], v153 offset:18432
	ds_read_b128 v[208:211], v153 offset:19456
	ds_read_b128 v[212:215], v153 offset:20480
	ds_read_b128 v[216:219], v153 offset:21504
	ds_read_b128 v[220:223], v153 offset:22528
	ds_read_b128 v[224:227], v153 offset:23552
	global_load_lds_dwordx4 v[158:159], off
	s_add_i32 m0, s34, 0x2000
	s_add_u32 s58, s52, 0x80000
	v_lshl_add_u64 v[188:189], s[52:53], 0, v[128:129]
	s_addc_u32 s59, s53, 0
	s_add_i32 s34, s56, s0
	global_load_lds_dwordx4 v[188:189], off
	v_lshl_add_u64 v[228:229], s[58:59], 0, v[132:133]
	s_mov_b32 m0, s34
	v_lshl_add_u64 v[230:231], s[54:55], 0, v[130:131]
	global_load_lds_dwordx4 v[228:229], off
	v_lshl_add_u64 v[228:229], s[58:59], 0, v[128:129]
	s_add_i32 m0, s34, 0x2000
	s_nop 0
	global_load_lds_dwordx4 v[228:229], off
	v_lshl_add_u64 v[228:229], s[54:55], 0, v[134:135]
	s_mov_b32 m0, s22
	s_nop 0
	global_load_lds_dwordx4 v[228:229], off
	s_mov_b32 m0, s23
	s_nop 0
	global_load_lds_dwordx4 v[230:231], off
	s_waitcnt vmcnt(8)
	s_waitcnt lgkmcnt(0)
	s_barrier
	s_setprio 1
	s_waitcnt lgkmcnt(0)
	v_mfma_f32_16x16x32_bf16 v[60:63], v[154:157], v[196:199], v[60:63]
	v_mfma_f32_16x16x32_bf16 v[56:59], v[168:171], v[196:199], v[56:59]
	v_mfma_f32_16x16x32_bf16 v[52:55], v[154:157], v[204:207], v[52:55]
	v_mfma_f32_16x16x32_bf16 v[44:47], v[168:171], v[204:207], v[44:47]
	v_mfma_f32_16x16x32_bf16 v[36:39], v[154:157], v[212:215], v[36:39]
	v_mfma_f32_16x16x32_bf16 v[28:31], v[168:171], v[212:215], v[28:31]
	v_mfma_f32_16x16x32_bf16 v[20:23], v[154:157], v[220:223], v[20:23]
	v_mfma_f32_16x16x32_bf16 v[12:15], v[168:171], v[220:223], v[12:15]
	v_mfma_f32_16x16x32_bf16 v[60:63], v[164:167], v[200:203], v[60:63]
	v_mfma_f32_16x16x32_bf16 v[56:59], v[172:175], v[200:203], v[56:59]
	v_mfma_f32_16x16x32_bf16 v[52:55], v[164:167], v[208:211], v[52:55]
	v_mfma_f32_16x16x32_bf16 v[44:47], v[172:175], v[208:211], v[44:47]
	v_mfma_f32_16x16x32_bf16 v[36:39], v[164:167], v[216:219], v[36:39]
	v_mfma_f32_16x16x32_bf16 v[28:31], v[172:175], v[216:219], v[28:31]
	v_mfma_f32_16x16x32_bf16 v[20:23], v[164:167], v[224:227], v[20:23]
	v_mfma_f32_16x16x32_bf16 v[12:15], v[172:175], v[224:227], v[12:15]
	s_setprio 0
	s_setprio 1
	v_mfma_f32_16x16x32_bf16 v[48:51], v[176:179], v[196:199], v[48:51]
	v_mfma_f32_16x16x32_bf16 v[40:43], v[184:187], v[196:199], v[40:43]
	v_mfma_f32_16x16x32_bf16 v[32:35], v[176:179], v[204:207], v[32:35]
	v_mfma_f32_16x16x32_bf16 v[24:27], v[184:187], v[204:207], v[24:27]
	v_mfma_f32_16x16x32_bf16 v[16:19], v[176:179], v[212:215], v[16:19]
	v_mfma_f32_16x16x32_bf16 v[8:11], v[184:187], v[212:215], v[8:11]
	v_mfma_f32_16x16x32_bf16 v[4:7], v[176:179], v[220:223], v[4:7]
	v_mfma_f32_16x16x32_bf16 v[0:3], v[184:187], v[220:223], v[0:3]
	v_mfma_f32_16x16x32_bf16 v[48:51], v[180:183], v[200:203], v[48:51]
	v_mfma_f32_16x16x32_bf16 v[40:43], v[192:195], v[200:203], v[40:43]
	v_mfma_f32_16x16x32_bf16 v[32:35], v[180:183], v[208:211], v[32:35]
	v_mfma_f32_16x16x32_bf16 v[24:27], v[192:195], v[208:211], v[24:27]
	v_mfma_f32_16x16x32_bf16 v[16:19], v[180:183], v[216:219], v[16:19]
	v_mfma_f32_16x16x32_bf16 v[8:11], v[192:195], v[216:219], v[8:11]
	v_mfma_f32_16x16x32_bf16 v[4:7], v[180:183], v[224:227], v[4:7]
	v_mfma_f32_16x16x32_bf16 v[0:3], v[192:195], v[224:227], v[0:3]
	s_setprio 0
	s_barrier
; #define PG8_STAGE(bufoff, gbase, voff) do { _Pragma("unroll") for (int _i = 0; _i < 2; ++_i) \
;         __builtin_amdgcn_global_load_lds((const unsigned*)((const char*)(gbase) + (voff)[_i]), (LAS unsigned*)(lds + (bufoff) + ldsw + _i * 8192), 16, 0, 0); } while (0)
; #define PG8_LDA(dst, b, h) do { _Pragma("unroll") for (int m = 0; m < 4; ++m) _Pragma("unroll") for (int k = 0; k < 2; ++k) dst[m][k] = *(const LAS bf16x8*)(lds + PG8_SA(b, h) + aoff + m * 2048 + k * 1024); } while (0)
; #define PG8_LDB(dst, b, h) do { _Pragma("unroll") for (int n = 0; n < 2; ++n) _Pragma("unroll") for (int k = 0; k < 2; ++k) dst[n][k] = *(const LAS bf16x8*)(lds + PG8_SB(b, h) + boff + n * 2048 + k * 1024); } while (0)
; #define PG8_MMA(ai, bj, At, Bt) do { __builtin_amdgcn_s_setprio(1); _Pragma("unroll") for (int m = 0; m < 4; ++m) _Pragma("unroll") for (int n = 0; n < 2; ++n) _Pragma("unroll") for (int k = 0; k < 2; ++k) \
;         acc[ai][bj][m][n] = __builtin_amdgcn_mfma_f32_16x16x32_bf16(Bt[n][k], At[m][k], acc[ai][bj][m][n], 0, 0, 0); __builtin_amdgcn_s_setprio(0); } while (0)
; #define PG8_WAIT_V(n) asm volatile("s_waitcnt vmcnt(" #n ")" ::: "memory")
; #define PG8_WAIT_L(n) asm volatile("s_waitcnt lgkmcnt(" #n ")" ::: "memory")
; #define PG8_BAR __builtin_amdgcn_s_barrier()
; #define PG8_SCHED __builtin_amdgcn_sched_barrier(0)
; template <int GI>
; __device__ __forceinline__ void gemm_phase(LAS unsigned char* lds, unsigned char* ws, int G, int cblk) {
;     ...
;             PG8_LDB(B0, 1, 0); PG8_LDB(B1, 1, 1); PG8_SCHED; PG8_LDA(At, 1, 0); PG8_STAGE(PG8_SA(0, 1), a2 + hstepA, voffA);
;             PG8_WAIT_V(8); PG8_WAIT_L(0); PG8_BAR; PG8_MMA(0, 0, At, B0); PG8_MMA(0, 1, At, B1); PG8_BAR; PG8_SCHED;
	s_add_i32 s34, 0, 0x18000
	v_add_u32_e32 v161, s34, v150
	s_add_i32 s58, 0, 0x1c000
	ds_read_b128 v[154:157], v161
	ds_read_b128 v[164:167], v161 offset:1024
	ds_read_b128 v[168:171], v161 offset:2048
	ds_read_b128 v[172:175], v161 offset:3072
	v_add_u32_e32 v161, s58, v150
	ds_read_b128 v[176:179], v161
	ds_read_b128 v[180:183], v161 offset:1024
	ds_read_b128 v[184:187], v161 offset:2048
	ds_read_b128 v[192:195], v161 offset:3072
	s_add_u32 s54, s54, 0x100000
	s_addc_u32 s55, s55, 0
	s_mov_b32 m0, s24
	v_lshl_add_u64 v[232:233], s[54:55], 0, v[134:135]
	ds_read_b128 v[196:199], v153 offset:32768
	ds_read_b128 v[200:203], v153 offset:33792
	ds_read_b128 v[204:207], v153 offset:34816
	ds_read_b128 v[208:211], v153 offset:35840
	ds_read_b128 v[212:215], v153 offset:36864
	ds_read_b128 v[216:219], v153 offset:37888
	ds_read_b128 v[220:223], v153 offset:38912
	ds_read_b128 v[224:227], v153 offset:39936
	global_load_lds_dwordx4 v[232:233], off
	v_lshl_add_u64 v[232:233], s[54:55], 0, v[130:131]
	s_mov_b32 m0, s25
	s_nop 0
	global_load_lds_dwordx4 v[232:233], off
	s_waitcnt vmcnt(8)
	s_waitcnt lgkmcnt(0)
	s_barrier
	s_setprio 1
	s_waitcnt lgkmcnt(0)
	v_mfma_f32_16x16x32_bf16 v[124:127], v[154:157], v[196:199], v[124:127]
	v_mfma_f32_16x16x32_bf16 v[120:123], v[168:171], v[196:199], v[120:123]
	v_mfma_f32_16x16x32_bf16 v[116:119], v[154:157], v[204:207], v[116:119]
	v_mfma_f32_16x16x32_bf16 v[108:111], v[168:171], v[204:207], v[108:111]
	v_mfma_f32_16x16x32_bf16 v[100:103], v[154:157], v[212:215], v[100:103]
	v_mfma_f32_16x16x32_bf16 v[92:95], v[168:171], v[212:215], v[92:95]
	v_mfma_f32_16x16x32_bf16 v[84:87], v[154:157], v[220:223], v[84:87]
	v_mfma_f32_16x16x32_bf16 v[76:79], v[168:171], v[220:223], v[76:79]
	v_mfma_f32_16x16x32_bf16 v[124:127], v[164:167], v[200:203], v[124:127]
	v_mfma_f32_16x16x32_bf16 v[120:123], v[172:175], v[200:203], v[120:123]
	v_mfma_f32_16x16x32_bf16 v[116:119], v[164:167], v[208:211], v[116:119]
	v_mfma_f32_16x16x32_bf16 v[108:111], v[172:175], v[208:211], v[108:111]
	v_mfma_f32_16x16x32_bf16 v[100:103], v[164:167], v[216:219], v[100:103]
	v_mfma_f32_16x16x32_bf16 v[92:95], v[172:175], v[216:219], v[92:95]
	v_mfma_f32_16x16x32_bf16 v[84:87], v[164:167], v[224:227], v[84:87]
	v_mfma_f32_16x16x32_bf16 v[76:79], v[172:175], v[224:227], v[76:79]
	s_setprio 0
	s_setprio 1
	v_mfma_f32_16x16x32_bf16 v[112:115], v[176:179], v[196:199], v[112:115]
	v_mfma_f32_16x16x32_bf16 v[104:107], v[184:187], v[196:199], v[104:107]
	v_mfma_f32_16x16x32_bf16 v[96:99], v[176:179], v[204:207], v[96:99]
	v_mfma_f32_16x16x32_bf16 v[88:91], v[184:187], v[204:207], v[88:91]
	v_mfma_f32_16x16x32_bf16 v[80:83], v[176:179], v[212:215], v[80:83]
	v_mfma_f32_16x16x32_bf16 v[72:75], v[184:187], v[212:215], v[72:75]
	v_mfma_f32_16x16x32_bf16 v[68:71], v[176:179], v[220:223], v[68:71]
	v_mfma_f32_16x16x32_bf16 v[64:67], v[184:187], v[220:223], v[64:67]
	v_mfma_f32_16x16x32_bf16 v[112:115], v[180:183], v[200:203], v[112:115]
	v_mfma_f32_16x16x32_bf16 v[104:107], v[192:195], v[200:203], v[104:107]
	v_mfma_f32_16x16x32_bf16 v[96:99], v[180:183], v[208:211], v[96:99]
	v_mfma_f32_16x16x32_bf16 v[88:91], v[192:195], v[208:211], v[88:91]
	v_mfma_f32_16x16x32_bf16 v[80:83], v[180:183], v[216:219], v[80:83]
	v_mfma_f32_16x16x32_bf16 v[72:75], v[192:195], v[216:219], v[72:75]
	v_mfma_f32_16x16x32_bf16 v[68:71], v[180:183], v[224:227], v[68:71]
	v_mfma_f32_16x16x32_bf16 v[64:67], v[192:195], v[224:227], v[64:67]
	s_setprio 0
	s_barrier
; #define PG8_STAGE(bufoff, gbase, voff) do { _Pragma("unroll") for (int _i = 0; _i < 2; ++_i) \
;         __builtin_amdgcn_global_load_lds((const unsigned*)((const char*)(gbase) + (voff)[_i]), (LAS unsigned*)(lds + (bufoff) + ldsw + _i * 8192), 16, 0, 0); } while (0)
; #define PG8_LDA(dst, b, h) do { _Pragma("unroll") for (int m = 0; m < 4; ++m) _Pragma("unroll") for (int k = 0; k < 2; ++k) dst[m][k] = *(const LAS bf16x8*)(lds + PG8_SA(b, h) + aoff + m * 2048 + k * 1024); } while (0)
; #define PG8_MMA(ai, bj, At, Bt) do { __builtin_amdgcn_s_setprio(1); _Pragma("unroll") for (int m = 0; m < 4; ++m) _Pragma("unroll") for (int n = 0; n < 2; ++n) _Pragma("unroll") for (int k = 0; k < 2; ++k) \
;         acc[ai][bj][m][n] = __builtin_amdgcn_mfma_f32_16x16x32_bf16(Bt[n][k], At[m][k], acc[ai][bj][m][n], 0, 0, 0); __builtin_amdgcn_s_setprio(0); } while (0)
; #define PG8_WAIT_V(n) asm volatile("s_waitcnt vmcnt(" #n ")" ::: "memory")
; #define PG8_WAIT_L(n) asm volatile("s_waitcnt lgkmcnt(" #n ")" ::: "memory")
; #define PG8_BAR __builtin_amdgcn_s_barrier()
; #define PG8_SCHED __builtin_amdgcn_sched_barrier(0)
; template <int GI>
; __device__ __forceinline__ void gemm_phase(LAS unsigned char* lds, unsigned char* ws, int G, int cblk) {
;     ...
;             PG8_LDA(At, 1, 1); PG8_STAGE(PG8_SB(1, 0), b3, voffB); PG8_STAGE(PG8_SB(1, 1), b3 + hstepB, voffB); PG8_STAGE(PG8_SA(1, 0), a3, voffA);
;             PG8_WAIT_V(8); PG8_WAIT_L(0); PG8_BAR; PG8_MMA(1, 0, At, B0); PG8_MMA(1, 1, At, B1); PG8_BAR; PG8_SCHED;
;         }
	s_add_i32 s34, s34, s0
	v_lshl_add_u64 v[158:159], v[158:159], 0, s[12:13]
	s_mov_b32 m0, s34
	ds_read_b128 v[196:199], v153 offset:49152
	ds_read_b128 v[200:203], v153 offset:50176
	ds_read_b128 v[204:207], v153 offset:51200
	ds_read_b128 v[208:211], v153 offset:52224
	ds_read_b128 v[212:215], v153 offset:53248
	ds_read_b128 v[216:219], v153 offset:54272
	ds_read_b128 v[220:223], v153 offset:55296
	ds_read_b128 v[224:227], v153 offset:56320
	global_load_lds_dwordx4 v[158:159], off
	s_add_i32 m0, s34, 0x2000
	s_add_u32 s52, s52, 0x80080
	v_lshl_add_u64 v[158:159], v[188:189], 0, s[12:13]
	s_addc_u32 s53, s53, 0
	s_add_i32 s34, s58, s0
	global_load_lds_dwordx4 v[158:159], off
	v_lshl_add_u64 v[158:159], s[52:53], 0, v[132:133]
	s_mov_b32 m0, s34
	s_nop 0
	global_load_lds_dwordx4 v[158:159], off
	v_lshl_add_u64 v[158:159], s[52:53], 0, v[128:129]
	s_add_i32 m0, s34, 0x2000
	s_nop 0
	global_load_lds_dwordx4 v[158:159], off
	v_lshl_add_u64 v[158:159], v[228:229], 0, s[12:13]
	s_mov_b32 m0, s33
	s_nop 0
	global_load_lds_dwordx4 v[158:159], off
	v_lshl_add_u64 v[158:159], v[230:231], 0, s[12:13]
	s_mov_b32 m0, s35
	s_nop 0
	global_load_lds_dwordx4 v[158:159], off
	s_waitcnt vmcnt(8)
	s_waitcnt lgkmcnt(0)
	s_barrier
	s_setprio 1
	s_waitcnt lgkmcnt(0)
	v_mfma_f32_16x16x32_bf16 v[60:63], v[154:157], v[196:199], v[60:63]
	v_mfma_f32_16x16x32_bf16 v[56:59], v[168:171], v[196:199], v[56:59]
	s_add_i32 s21, s21, 2
	s_add_u32 s50, s50, 0x100
	s_addc_u32 s51, s51, 0
	s_add_u32 s14, s14, 0x100
	s_addc_u32 s15, s15, 0
	v_mfma_f32_16x16x32_bf16 v[52:55], v[154:157], v[204:207], v[52:55]
	v_mfma_f32_16x16x32_bf16 v[44:47], v[168:171], v[204:207], v[44:47]
	v_mfma_f32_16x16x32_bf16 v[36:39], v[154:157], v[212:215], v[36:39]
	v_mfma_f32_16x16x32_bf16 v[28:31], v[168:171], v[212:215], v[28:31]
	v_mfma_f32_16x16x32_bf16 v[20:23], v[154:157], v[220:223], v[20:23]
	v_mfma_f32_16x16x32_bf16 v[12:15], v[168:171], v[220:223], v[12:15]
	v_mfma_f32_16x16x32_bf16 v[60:63], v[164:167], v[200:203], v[60:63]
	v_mfma_f32_16x16x32_bf16 v[56:59], v[172:175], v[200:203], v[56:59]
	v_mfma_f32_16x16x32_bf16 v[52:55], v[164:167], v[208:211], v[52:55]
	v_mfma_f32_16x16x32_bf16 v[44:47], v[172:175], v[208:211], v[44:47]
	v_mfma_f32_16x16x32_bf16 v[36:39], v[164:167], v[216:219], v[36:39]
	v_mfma_f32_16x16x32_bf16 v[28:31], v[172:175], v[216:219], v[28:31]
	v_mfma_f32_16x16x32_bf16 v[20:23], v[164:167], v[224:227], v[20:23]
	v_mfma_f32_16x16x32_bf16 v[12:15], v[172:175], v[224:227], v[12:15]
	s_setprio 0
	s_setprio 1
	v_mfma_f32_16x16x32_bf16 v[48:51], v[176:179], v[196:199], v[48:51]
	v_mfma_f32_16x16x32_bf16 v[40:43], v[184:187], v[196:199], v[40:43]
	v_mfma_f32_16x16x32_bf16 v[32:35], v[176:179], v[204:207], v[32:35]
	v_mfma_f32_16x16x32_bf16 v[24:27], v[184:187], v[204:207], v[24:27]
	v_mfma_f32_16x16x32_bf16 v[16:19], v[176:179], v[212:215], v[16:19]
	v_mfma_f32_16x16x32_bf16 v[8:11], v[184:187], v[212:215], v[8:11]
	v_mfma_f32_16x16x32_bf16 v[4:7], v[176:179], v[220:223], v[4:7]
	v_mfma_f32_16x16x32_bf16 v[0:3], v[184:187], v[220:223], v[0:3]
	v_mfma_f32_16x16x32_bf16 v[48:51], v[180:183], v[200:203], v[48:51]
	v_mfma_f32_16x16x32_bf16 v[40:43], v[192:195], v[200:203], v[40:43]
	v_mfma_f32_16x16x32_bf16 v[32:35], v[180:183], v[208:211], v[32:35]
	v_mfma_f32_16x16x32_bf16 v[24:27], v[192:195], v[208:211], v[24:27]
	v_mfma_f32_16x16x32_bf16 v[16:19], v[180:183], v[216:219], v[16:19]
	v_mfma_f32_16x16x32_bf16 v[8:11], v[192:195], v[216:219], v[8:11]
	v_mfma_f32_16x16x32_bf16 v[4:7], v[180:183], v[224:227], v[4:7]
	v_mfma_f32_16x16x32_bf16 v[0:3], v[192:195], v[224:227], v[0:3]
	s_setprio 0
	s_barrier
	s_cmp_gt_u32 s21, 5
	s_cbranch_scc0 .LBB0_416

; #define PG8_STAGE(bufoff, gbase, voff) do { _Pragma("unroll") for (int _i = 0; _i < 2; ++_i) \
;         __builtin_amdgcn_global_load_lds((const unsigned*)((const char*)(gbase) + (voff)[_i]), (LAS unsigned*)(lds + (bufoff) + ldsw + _i * 8192), 16, 0, 0); } while (0)
; #define PG8_LDA(dst, b, h) do { _Pragma("unroll") for (int m = 0; m < 4; ++m) _Pragma("unroll") for (int k = 0; k < 2; ++k) dst[m][k] = *(const LAS bf16x8*)(lds + PG8_SA(b, h) + aoff + m * 2048 + k * 1024); } while (0)
; #define PG8_LDB(dst, b, h) do { _Pragma("unroll") for (int n = 0; n < 2; ++n) _Pragma("unroll") for (int k = 0; k < 2; ++k) dst[n][k] = *(const LAS bf16x8*)(lds + PG8_SB(b, h) + boff + n * 2048 + k * 1024); } while (0)
; #define PG8_MMA(ai, bj, At, Bt) do { __builtin_amdgcn_s_setprio(1); _Pragma("unroll") for (int m = 0; m < 4; ++m) _Pragma("unroll") for (int n = 0; n < 2; ++n) _Pragma("unroll") for (int k = 0; k < 2; ++k) \
;         acc[ai][bj][m][n] = __builtin_amdgcn_mfma_f32_16x16x32_bf16(Bt[n][k], At[m][k], acc[ai][bj][m][n], 0, 0, 0); __builtin_amdgcn_s_setprio(0); } while (0)
; #define PG8_WAIT_V(n) asm volatile("s_waitcnt vmcnt(" #n ")" ::: "memory")
; #define PG8_WAIT_L(n) asm volatile("s_waitcnt lgkmcnt(" #n ")" ::: "memory")
; #define PG8_BAR __builtin_amdgcn_s_barrier()
; #define PG8_SCHED __builtin_amdgcn_sched_barrier(0)
; template <int GI>
; __device__ __forceinline__ void gemm_phase(LAS unsigned char* lds, unsigned char* ws, int G, int cblk) {
;     ...
;         for (int t = 0; t < nt; t += 2) {
;             const bool last = (t == nt - 2);
;             const char* a1 = cA + (size_t)(t + 1) * kstep;
;             const char* a2 = last ? nA : cA + (size_t)(t + 2) * kstep; const char* b2 = last ? nB : cB + (size_t)(t + 2) * kstep;
;             const char* a3 = a2 + kstep; const char* b3 = b2 + kstep;
;             PG8_LDB(B0, 0, 0); PG8_LDB(B1, 0, 1); PG8_SCHED; PG8_LDA(At, 0, 0); PG8_STAGE(PG8_SA(1, 1), a1 + hstepA, voffA);
;             PG8_WAIT_V(8); PG8_WAIT_L(0); PG8_BAR; PG8_MMA(0, 0, At, B0); PG8_MMA(0, 1, At, B1); PG8_BAR; PG8_SCHED;
;             PG8_LDA(At, 0, 1); PG8_STAGE(PG8_SB(0, 0), b2, voffB); PG8_STAGE(PG8_SB(0, 1), b2 + hstepB, voffB); PG8_STAGE(PG8_SA(0, 0), a2, voffA);
;             PG8_WAIT_V(8); PG8_WAIT_L(0); PG8_BAR; PG8_MMA(1, 0, At, B0); PG8_MMA(1, 1, At, B1); PG8_BAR; PG8_SCHED;
.LBB0_431:
	s_add_u32 s46, s46, 0x80080
	s_addc_u32 s47, s47, 0
	s_add_u32 s14, s48, 0x100
	s_addc_u32 s15, s49, 0
	s_mov_b32 s19, -2
	ds_read_b128 v[154:157], v151
	ds_read_b128 v[164:167], v151 offset:1024
	ds_read_b128 v[168:171], v151 offset:2048
	ds_read_b128 v[172:175], v151 offset:3072
	ds_read_b128 v[176:179], v152
	ds_read_b128 v[180:183], v152 offset:1024
	ds_read_b128 v[184:187], v152 offset:2048
	ds_read_b128 v[192:195], v152 offset:3072
	s_add_u32 s34, s46, 0xfff80080
	s_addc_u32 s48, s47, -1
	s_cmp_eq_u32 s19, 4
	s_cselect_b32 s51, s39, s48
	s_cselect_b32 s50, s38, s34
	s_cselect_b32 s49, s41, s15
	s_cselect_b32 s48, s40, s14
	v_lshl_add_u64 v[158:159], s[46:47], 0, v[138:139]
	s_add_i32 m0, s16, 0xc000
	ds_read_b128 v[196:199], v153
	ds_read_b128 v[200:203], v153 offset:1024
	ds_read_b128 v[204:207], v153 offset:2048
	ds_read_b128 v[208:211], v153 offset:3072
	ds_read_b128 v[212:215], v153 offset:4096
	ds_read_b128 v[216:219], v153 offset:5120
	ds_read_b128 v[220:223], v153 offset:6144
	ds_read_b128 v[224:227], v153 offset:7168
	global_load_lds_dwordx4 v[158:159], off
	v_lshl_add_u64 v[158:159], s[46:47], 0, v[140:141]
	s_add_i32 m0, s16, 0xe000
	s_nop 0
	global_load_lds_dwordx4 v[158:159], off
	s_waitcnt vmcnt(8)
	s_waitcnt lgkmcnt(0)
	s_barrier
	s_setprio 1
	s_waitcnt lgkmcnt(0)
	v_mfma_f32_16x16x32_bf16 v[124:127], v[154:157], v[196:199], 0
	v_mfma_f32_16x16x32_bf16 v[120:123], v[168:171], v[196:199], 0
	v_mfma_f32_16x16x32_bf16 v[116:119], v[154:157], v[204:207], 0
	v_mfma_f32_16x16x32_bf16 v[112:115], v[168:171], v[204:207], 0
	v_mfma_f32_16x16x32_bf16 v[100:103], v[154:157], v[212:215], 0
	v_mfma_f32_16x16x32_bf16 v[96:99], v[168:171], v[212:215], 0
	v_mfma_f32_16x16x32_bf16 v[84:87], v[154:157], v[220:223], 0
	v_mfma_f32_16x16x32_bf16 v[80:83], v[168:171], v[220:223], 0
	v_mfma_f32_16x16x32_bf16 v[124:127], v[164:167], v[200:203], v[124:127]
	v_mfma_f32_16x16x32_bf16 v[120:123], v[172:175], v[200:203], v[120:123]
	v_mfma_f32_16x16x32_bf16 v[116:119], v[164:167], v[208:211], v[116:119]
	v_mfma_f32_16x16x32_bf16 v[112:115], v[172:175], v[208:211], v[112:115]
	v_mfma_f32_16x16x32_bf16 v[100:103], v[164:167], v[216:219], v[100:103]
	v_mfma_f32_16x16x32_bf16 v[96:99], v[172:175], v[216:219], v[96:99]
	v_mfma_f32_16x16x32_bf16 v[84:87], v[164:167], v[224:227], v[84:87]
	v_mfma_f32_16x16x32_bf16 v[80:83], v[172:175], v[224:227], v[80:83]
	s_setprio 0
	s_setprio 1
	v_mfma_f32_16x16x32_bf16 v[108:111], v[176:179], v[196:199], 0
	v_mfma_f32_16x16x32_bf16 v[104:107], v[184:187], v[196:199], 0
	v_mfma_f32_16x16x32_bf16 v[92:95], v[176:179], v[204:207], 0
	v_mfma_f32_16x16x32_bf16 v[88:91], v[184:187], v[204:207], 0
	v_mfma_f32_16x16x32_bf16 v[76:79], v[176:179], v[212:215], 0
	v_mfma_f32_16x16x32_bf16 v[72:75], v[184:187], v[212:215], 0
	v_mfma_f32_16x16x32_bf16 v[68:71], v[176:179], v[220:223], 0
	v_mfma_f32_16x16x32_bf16 v[64:67], v[184:187], v[220:223], 0
	v_mfma_f32_16x16x32_bf16 v[108:111], v[180:183], v[200:203], v[108:111]
	v_mfma_f32_16x16x32_bf16 v[104:107], v[192:195], v[200:203], v[104:107]
	v_mfma_f32_16x16x32_bf16 v[92:95], v[180:183], v[208:211], v[92:95]
	v_mfma_f32_16x16x32_bf16 v[88:91], v[192:195], v[208:211], v[88:91]
	v_mfma_f32_16x16x32_bf16 v[76:79], v[180:183], v[216:219], v[76:79]
	v_mfma_f32_16x16x32_bf16 v[72:75], v[192:195], v[216:219], v[72:75]
	v_mfma_f32_16x16x32_bf16 v[68:71], v[180:183], v[224:227], v[68:71]
	v_mfma_f32_16x16x32_bf16 v[64:67], v[192:195], v[224:227], v[64:67]
	s_setprio 0
	s_barrier
	s_add_i32 s34, s33, s0
	v_lshl_add_u64 v[158:159], s[48:49], 0, v[132:133]
	s_mov_b32 m0, s34
	ds_read_b128 v[196:199], v153 offset:16384
	ds_read_b128 v[200:203], v153 offset:17408
	ds_read_b128 v[204:207], v153 offset:18432
	ds_read_b128 v[208:211], v153 offset:19456
	ds_read_b128 v[212:215], v153 offset:20480
	ds_read_b128 v[216:219], v153 offset:21504
	ds_read_b128 v[220:223], v153 offset:22528
	ds_read_b128 v[224:227], v153 offset:23552
	global_load_lds_dwordx4 v[158:159], off
	s_add_i32 m0, s34, 0x2000
	s_add_u32 s54, s48, 0x100000
	v_lshl_add_u64 v[188:189], s[48:49], 0, v[128:129]
	s_addc_u32 s55, s49, 0
	s_add_i32 s34, s35, s0
	global_load_lds_dwordx4 v[188:189], off
	v_lshl_add_u64 v[228:229], s[54:55], 0, v[132:133]
	s_mov_b32 m0, s34
	v_lshl_add_u64 v[230:231], s[50:51], 0, v[130:131]
	global_load_lds_dwordx4 v[228:229], off
	v_lshl_add_u64 v[228:229], s[54:55], 0, v[128:129]
	s_add_i32 m0, s34, 0x2000
	s_nop 0
	global_load_lds_dwordx4 v[228:229], off
	v_lshl_add_u64 v[228:229], s[50:51], 0, v[134:135]
	s_mov_b32 m0, s16
	s_nop 0
	global_load_lds_dwordx4 v[228:229], off
	s_mov_b32 m0, s17
	s_nop 0
	global_load_lds_dwordx4 v[230:231], off
	s_waitcnt vmcnt(8)
	s_waitcnt lgkmcnt(0)
	s_barrier
; #define PG8_STAGE(bufoff, gbase, voff) do { _Pragma("unroll") for (int _i = 0; _i < 2; ++_i) \
;         __builtin_amdgcn_global_load_lds((const unsigned*)((const char*)(gbase) + (voff)[_i]), (LAS unsigned*)(lds + (bufoff) + ldsw + _i * 8192), 16, 0, 0); } while (0)
; #define PG8_LDA(dst, b, h) do { _Pragma("unroll") for (int m = 0; m < 4; ++m) _Pragma("unroll") for (int k = 0; k < 2; ++k) dst[m][k] = *(const LAS bf16x8*)(lds + PG8_SA(b, h) + aoff + m * 2048 + k * 1024); } while (0)
; #define PG8_LDB(dst, b, h) do { _Pragma("unroll") for (int n = 0; n < 2; ++n) _Pragma("unroll") for (int k = 0; k < 2; ++k) dst[n][k] = *(const LAS bf16x8*)(lds + PG8_SB(b, h) + boff + n * 2048 + k * 1024); } while (0)
; #define PG8_MMA(ai, bj, At, Bt) do { __builtin_amdgcn_s_setprio(1); _Pragma("unroll") for (int m = 0; m < 4; ++m) _Pragma("unroll") for (int n = 0; n < 2; ++n) _Pragma("unroll") for (int k = 0; k < 2; ++k) \
;         acc[ai][bj][m][n] = __builtin_amdgcn_mfma_f32_16x16x32_bf16(Bt[n][k], At[m][k], acc[ai][bj][m][n], 0, 0, 0); __builtin_amdgcn_s_setprio(0); } while (0)
; #define PG8_WAIT_V(n) asm volatile("s_waitcnt vmcnt(" #n ")" ::: "memory")
; #define PG8_WAIT_L(n) asm volatile("s_waitcnt lgkmcnt(" #n ")" ::: "memory")
; #define PG8_BAR __builtin_amdgcn_s_barrier()
; #define PG8_SCHED __builtin_amdgcn_sched_barrier(0)
; template <int GI>
; __device__ __forceinline__ void gemm_phase(LAS unsigned char* lds, unsigned char* ws, int G, int cblk) {
;     ...
;             PG8_WAIT_V(8); PG8_WAIT_L(0); PG8_BAR; PG8_MMA(1, 0, At, B0); PG8_MMA(1, 1, At, B1); PG8_BAR; PG8_SCHED;
;             PG8_LDB(B0, 1, 0); PG8_LDB(B1, 1, 1); PG8_SCHED; PG8_LDA(At, 1, 0); PG8_STAGE(PG8_SA(0, 1), a2 + hstepA, voffA);
;             PG8_WAIT_V(8); PG8_WAIT_L(0); PG8_BAR; PG8_MMA(0, 0, At, B0); PG8_MMA(0, 1, At, B1); PG8_BAR; PG8_SCHED;
	s_setprio 1
	s_waitcnt lgkmcnt(0)
	v_mfma_f32_16x16x32_bf16 v[60:63], v[154:157], v[196:199], 0
	v_mfma_f32_16x16x32_bf16 v[56:59], v[168:171], v[196:199], 0
	v_mfma_f32_16x16x32_bf16 v[52:55], v[154:157], v[204:207], 0
	v_mfma_f32_16x16x32_bf16 v[48:51], v[168:171], v[204:207], 0
	v_mfma_f32_16x16x32_bf16 v[36:39], v[154:157], v[212:215], 0
	v_mfma_f32_16x16x32_bf16 v[32:35], v[168:171], v[212:215], 0
	v_mfma_f32_16x16x32_bf16 v[20:23], v[154:157], v[220:223], 0
	v_mfma_f32_16x16x32_bf16 v[16:19], v[168:171], v[220:223], 0
	v_mfma_f32_16x16x32_bf16 v[60:63], v[164:167], v[200:203], v[60:63]
	v_mfma_f32_16x16x32_bf16 v[56:59], v[172:175], v[200:203], v[56:59]
	v_mfma_f32_16x16x32_bf16 v[52:55], v[164:167], v[208:211], v[52:55]
	v_mfma_f32_16x16x32_bf16 v[48:51], v[172:175], v[208:211], v[48:51]
	v_mfma_f32_16x16x32_bf16 v[36:39], v[164:167], v[216:219], v[36:39]
	v_mfma_f32_16x16x32_bf16 v[32:35], v[172:175], v[216:219], v[32:35]
	v_mfma_f32_16x16x32_bf16 v[20:23], v[164:167], v[224:227], v[20:23]
	v_mfma_f32_16x16x32_bf16 v[16:19], v[172:175], v[224:227], v[16:19]
	s_setprio 0
	s_setprio 1
	v_mfma_f32_16x16x32_bf16 v[44:47], v[176:179], v[196:199], 0
	v_mfma_f32_16x16x32_bf16 v[40:43], v[184:187], v[196:199], 0
	v_mfma_f32_16x16x32_bf16 v[28:31], v[176:179], v[204:207], 0
	v_mfma_f32_16x16x32_bf16 v[24:27], v[184:187], v[204:207], 0
	v_mfma_f32_16x16x32_bf16 v[12:15], v[176:179], v[212:215], 0
	v_mfma_f32_16x16x32_bf16 v[8:11], v[184:187], v[212:215], 0
	v_mfma_f32_16x16x32_bf16 v[4:7], v[176:179], v[220:223], 0
	v_mfma_f32_16x16x32_bf16 v[0:3], v[184:187], v[220:223], 0
	v_mfma_f32_16x16x32_bf16 v[44:47], v[180:183], v[200:203], v[44:47]
	v_mfma_f32_16x16x32_bf16 v[40:43], v[192:195], v[200:203], v[40:43]
	v_mfma_f32_16x16x32_bf16 v[28:31], v[180:183], v[208:211], v[28:31]
	v_mfma_f32_16x16x32_bf16 v[24:27], v[192:195], v[208:211], v[24:27]
	v_mfma_f32_16x16x32_bf16 v[12:15], v[180:183], v[216:219], v[12:15]
	v_mfma_f32_16x16x32_bf16 v[8:11], v[192:195], v[216:219], v[8:11]
	v_mfma_f32_16x16x32_bf16 v[4:7], v[180:183], v[224:227], v[4:7]
	v_mfma_f32_16x16x32_bf16 v[0:3], v[192:195], v[224:227], v[0:3]
	s_setprio 0
	s_barrier
	s_add_i32 s34, 0, 0x18000
	v_add_u32_e32 v161, s34, v150
	s_add_i32 s53, 0, 0x1c000
	ds_read_b128 v[154:157], v161
	ds_read_b128 v[164:167], v161 offset:1024
	ds_read_b128 v[168:171], v161 offset:2048
	ds_read_b128 v[172:175], v161 offset:3072
	v_add_u32_e32 v161, s53, v150
	ds_read_b128 v[176:179], v161
	ds_read_b128 v[180:183], v161 offset:1024
	ds_read_b128 v[184:187], v161 offset:2048
	ds_read_b128 v[192:195], v161 offset:3072
	s_add_u32 s50, s50, 0x80000
	s_addc_u32 s51, s51, 0
	s_mov_b32 m0, s22
	v_lshl_add_u64 v[232:233], s[50:51], 0, v[134:135]
	ds_read_b128 v[196:199], v153 offset:32768
	ds_read_b128 v[200:203], v153 offset:33792
	ds_read_b128 v[204:207], v153 offset:34816
	ds_read_b128 v[208:211], v153 offset:35840
	ds_read_b128 v[212:215], v153 offset:36864
	ds_read_b128 v[216:219], v153 offset:37888
	ds_read_b128 v[220:223], v153 offset:38912
	ds_read_b128 v[224:227], v153 offset:39936
	global_load_lds_dwordx4 v[232:233], off
	v_lshl_add_u64 v[232:233], s[50:51], 0, v[130:131]
	s_mov_b32 m0, s23
	s_nop 0
	global_load_lds_dwordx4 v[232:233], off
	s_waitcnt vmcnt(8)
	s_waitcnt lgkmcnt(0)
	s_barrier
	s_setprio 1
	s_waitcnt lgkmcnt(0)
	v_mfma_f32_16x16x32_bf16 v[124:127], v[154:157], v[196:199], v[124:127]
	v_mfma_f32_16x16x32_bf16 v[120:123], v[168:171], v[196:199], v[120:123]
	v_mfma_f32_16x16x32_bf16 v[116:119], v[154:157], v[204:207], v[116:119]
	v_mfma_f32_16x16x32_bf16 v[112:115], v[168:171], v[204:207], v[112:115]
	v_mfma_f32_16x16x32_bf16 v[100:103], v[154:157], v[212:215], v[100:103]
	v_mfma_f32_16x16x32_bf16 v[96:99], v[168:171], v[212:215], v[96:99]
	v_mfma_f32_16x16x32_bf16 v[84:87], v[154:157], v[220:223], v[84:87]
	v_mfma_f32_16x16x32_bf16 v[80:83], v[168:171], v[220:223], v[80:83]
	v_mfma_f32_16x16x32_bf16 v[124:127], v[164:167], v[200:203], v[124:127]
	v_mfma_f32_16x16x32_bf16 v[120:123], v[172:175], v[200:203], v[120:123]
	v_mfma_f32_16x16x32_bf16 v[116:119], v[164:167], v[208:211], v[116:119]
	v_mfma_f32_16x16x32_bf16 v[112:115], v[172:175], v[208:211], v[112:115]
	v_mfma_f32_16x16x32_bf16 v[100:103], v[164:167], v[216:219], v[100:103]
	v_mfma_f32_16x16x32_bf16 v[96:99], v[172:175], v[216:219], v[96:99]
	v_mfma_f32_16x16x32_bf16 v[84:87], v[164:167], v[224:227], v[84:87]
	v_mfma_f32_16x16x32_bf16 v[80:83], v[172:175], v[224:227], v[80:83]
	s_setprio 0
	s_setprio 1
	v_mfma_f32_16x16x32_bf16 v[108:111], v[176:179], v[196:199], v[108:111]
	v_mfma_f32_16x16x32_bf16 v[104:107], v[184:187], v[196:199], v[104:107]
	v_mfma_f32_16x16x32_bf16 v[92:95], v[176:179], v[204:207], v[92:95]
	v_mfma_f32_16x16x32_bf16 v[88:91], v[184:187], v[204:207], v[88:91]
	v_mfma_f32_16x16x32_bf16 v[76:79], v[176:179], v[212:215], v[76:79]
	v_mfma_f32_16x16x32_bf16 v[72:75], v[184:187], v[212:215], v[72:75]
	v_mfma_f32_16x16x32_bf16 v[68:71], v[176:179], v[220:223], v[68:71]
	v_mfma_f32_16x16x32_bf16 v[64:67], v[184:187], v[220:223], v[64:67]
	v_mfma_f32_16x16x32_bf16 v[108:111], v[180:183], v[200:203], v[108:111]
	v_mfma_f32_16x16x32_bf16 v[104:107], v[192:195], v[200:203], v[104:107]
	v_mfma_f32_16x16x32_bf16 v[92:95], v[180:183], v[208:211], v[92:95]
	v_mfma_f32_16x16x32_bf16 v[88:91], v[192:195], v[208:211], v[88:91]
	v_mfma_f32_16x16x32_bf16 v[76:79], v[180:183], v[216:219], v[76:79]
	v_mfma_f32_16x16x32_bf16 v[72:75], v[192:195], v[216:219], v[72:75]
	v_mfma_f32_16x16x32_bf16 v[68:71], v[180:183], v[224:227], v[68:71]
	v_mfma_f32_16x16x32_bf16 v[64:67], v[192:195], v[224:227], v[64:67]
	s_setprio 0
	s_barrier
; #define PG8_STAGE(bufoff, gbase, voff) do { _Pragma("unroll") for (int _i = 0; _i < 2; ++_i) \
;         __builtin_amdgcn_global_load_lds((const unsigned*)((const char*)(gbase) + (voff)[_i]), (LAS unsigned*)(lds + (bufoff) + ldsw + _i * 8192), 16, 0, 0); } while (0)
; #define PG8_LDA(dst, b, h) do { _Pragma("unroll") for (int m = 0; m < 4; ++m) _Pragma("unroll") for (int k = 0; k < 2; ++k) dst[m][k] = *(const LAS bf16x8*)(lds + PG8_SA(b, h) + aoff + m * 2048 + k * 1024); } while (0)
; #define PG8_LDB(dst, b, h) do { _Pragma("unroll") for (int n = 0; n < 2; ++n) _Pragma("unroll") for (int k = 0; k < 2; ++k) dst[n][k] = *(const LAS bf16x8*)(lds + PG8_SB(b, h) + boff + n * 2048 + k * 1024); } while (0)
; #define PG8_MMA(ai, bj, At, Bt) do { __builtin_amdgcn_s_setprio(1); _Pragma("unroll") for (int m = 0; m < 4; ++m) _Pragma("unroll") for (int n = 0; n < 2; ++n) _Pragma("unroll") for (int k = 0; k < 2; ++k) \
;         acc[ai][bj][m][n] = __builtin_amdgcn_mfma_f32_16x16x32_bf16(Bt[n][k], At[m][k], acc[ai][bj][m][n], 0, 0, 0); __builtin_amdgcn_s_setprio(0); } while (0)
; #define PG8_WAIT_V(n) asm volatile("s_waitcnt vmcnt(" #n ")" ::: "memory")
; #define PG8_WAIT_L(n) asm volatile("s_waitcnt lgkmcnt(" #n ")" ::: "memory")
; #define PG8_BAR __builtin_amdgcn_s_barrier()
; #define PG8_SCHED __builtin_amdgcn_sched_barrier(0)
; template <int GI>
; __device__ __forceinline__ void gemm_phase(LAS unsigned char* lds, unsigned char* ws, int G, int cblk) {
;     ...
;         for (int t = 0; t < nt; t += 2) {
;             const bool last = (t == nt - 2);
;             const char* a1 = cA + (size_t)(t + 1) * kstep;
;             const char* a2 = last ? nA : cA + (size_t)(t + 2) * kstep; const char* b2 = last ? nB : cB + (size_t)(t + 2) * kstep;
;             const char* a3 = a2 + kstep; const char* b3 = b2 + kstep;
;             PG8_LDB(B0, 0, 0); PG8_LDB(B1, 0, 1); PG8_SCHED; PG8_LDA(At, 0, 0); PG8_STAGE(PG8_SA(1, 1), a1 + hstepA, voffA);
;     ...
;             PG8_LDA(At, 1, 1); PG8_STAGE(PG8_SB(1, 0), b3, voffB); PG8_STAGE(PG8_SB(1, 1), b3 + hstepB, voffB); PG8_STAGE(PG8_SA(1, 0), a3, voffA);
;             PG8_WAIT_V(8); PG8_WAIT_L(0); PG8_BAR; PG8_MMA(1, 0, At, B0); PG8_MMA(1, 1, At, B1); PG8_BAR; PG8_SCHED;
	s_add_i32 s34, s34, s0
	v_lshl_add_u64 v[158:159], v[158:159], 0, s[8:9]
	s_mov_b32 m0, s34
	ds_read_b128 v[196:199], v153 offset:49152
	ds_read_b128 v[200:203], v153 offset:50176
	ds_read_b128 v[204:207], v153 offset:51200
	ds_read_b128 v[208:211], v153 offset:52224
	ds_read_b128 v[212:215], v153 offset:53248
	ds_read_b128 v[216:219], v153 offset:54272
	ds_read_b128 v[220:223], v153 offset:55296
	ds_read_b128 v[224:227], v153 offset:56320
	global_load_lds_dwordx4 v[158:159], off
	s_add_i32 m0, s34, 0x2000
	s_add_u32 s48, s48, 0x100080
	v_lshl_add_u64 v[158:159], v[188:189], 0, s[8:9]
	s_addc_u32 s49, s49, 0
	s_add_i32 s34, s53, s0
	global_load_lds_dwordx4 v[158:159], off
	v_lshl_add_u64 v[158:159], s[48:49], 0, v[132:133]
	s_mov_b32 m0, s34
	s_nop 0
	global_load_lds_dwordx4 v[158:159], off
	v_lshl_add_u64 v[158:159], s[48:49], 0, v[128:129]
	s_add_i32 m0, s34, 0x2000
	s_nop 0
	global_load_lds_dwordx4 v[158:159], off
	v_lshl_add_u64 v[158:159], v[228:229], 0, s[8:9]
	s_mov_b32 m0, s26
	s_nop 0
	global_load_lds_dwordx4 v[158:159], off
	v_lshl_add_u64 v[158:159], v[230:231], 0, s[8:9]
	s_mov_b32 m0, s27
	s_nop 0
	global_load_lds_dwordx4 v[158:159], off
	s_waitcnt vmcnt(8)
	s_waitcnt lgkmcnt(0)
	s_barrier
	s_setprio 1
	s_waitcnt lgkmcnt(0)
	v_mfma_f32_16x16x32_bf16 v[60:63], v[154:157], v[196:199], v[60:63]
	v_mfma_f32_16x16x32_bf16 v[56:59], v[168:171], v[196:199], v[56:59]
	s_add_i32 s19, s19, 2
	s_add_u32 s46, s46, 0x100
	s_addc_u32 s47, s47, 0
	s_add_u32 s14, s14, 0x100
	s_addc_u32 s15, s15, 0
	v_mfma_f32_16x16x32_bf16 v[52:55], v[154:157], v[204:207], v[52:55]
	v_mfma_f32_16x16x32_bf16 v[48:51], v[168:171], v[204:207], v[48:51]
	v_mfma_f32_16x16x32_bf16 v[36:39], v[154:157], v[212:215], v[36:39]
	v_mfma_f32_16x16x32_bf16 v[32:35], v[168:171], v[212:215], v[32:35]
	v_mfma_f32_16x16x32_bf16 v[20:23], v[154:157], v[220:223], v[20:23]
	v_mfma_f32_16x16x32_bf16 v[16:19], v[168:171], v[220:223], v[16:19]
	v_mfma_f32_16x16x32_bf16 v[60:63], v[164:167], v[200:203], v[60:63]
	v_mfma_f32_16x16x32_bf16 v[56:59], v[172:175], v[200:203], v[56:59]
	v_mfma_f32_16x16x32_bf16 v[52:55], v[164:167], v[208:211], v[52:55]
	v_mfma_f32_16x16x32_bf16 v[48:51], v[172:175], v[208:211], v[48:51]
	v_mfma_f32_16x16x32_bf16 v[36:39], v[164:167], v[216:219], v[36:39]
	v_mfma_f32_16x16x32_bf16 v[32:35], v[172:175], v[216:219], v[32:35]
	v_mfma_f32_16x16x32_bf16 v[20:23], v[164:167], v[224:227], v[20:23]
	v_mfma_f32_16x16x32_bf16 v[16:19], v[172:175], v[224:227], v[16:19]
	s_setprio 0
	s_setprio 1
	v_mfma_f32_16x16x32_bf16 v[44:47], v[176:179], v[196:199], v[44:47]
	v_mfma_f32_16x16x32_bf16 v[40:43], v[184:187], v[196:199], v[40:43]
	v_mfma_f32_16x16x32_bf16 v[28:31], v[176:179], v[204:207], v[28:31]
	v_mfma_f32_16x16x32_bf16 v[24:27], v[184:187], v[204:207], v[24:27]
	v_mfma_f32_16x16x32_bf16 v[12:15], v[176:179], v[212:215], v[12:15]
	v_mfma_f32_16x16x32_bf16 v[8:11], v[184:187], v[212:215], v[8:11]
	v_mfma_f32_16x16x32_bf16 v[4:7], v[176:179], v[220:223], v[4:7]
	v_mfma_f32_16x16x32_bf16 v[0:3], v[184:187], v[220:223], v[0:3]
	v_mfma_f32_16x16x32_bf16 v[44:47], v[180:183], v[200:203], v[44:47]
	v_mfma_f32_16x16x32_bf16 v[40:43], v[192:195], v[200:203], v[40:43]
	v_mfma_f32_16x16x32_bf16 v[28:31], v[180:183], v[208:211], v[28:31]
	v_mfma_f32_16x16x32_bf16 v[24:27], v[192:195], v[208:211], v[24:27]
	v_mfma_f32_16x16x32_bf16 v[12:15], v[180:183], v[216:219], v[12:15]
	v_mfma_f32_16x16x32_bf16 v[8:11], v[192:195], v[216:219], v[8:11]
	v_mfma_f32_16x16x32_bf16 v[4:7], v[180:183], v[224:227], v[4:7]
	v_mfma_f32_16x16x32_bf16 v[0:3], v[192:195], v[224:227], v[0:3]
	s_setprio 0
	s_barrier
	s_cmp_gt_u32 s19, 5
	s_cbranch_scc0 .LBB0_432
	s_branch .Lpeel_exit_5
.LBB0_432:
	ds_read_b128 v[154:157], v151
	ds_read_b128 v[164:167], v151 offset:1024
	ds_read_b128 v[168:171], v151 offset:2048
	ds_read_b128 v[172:175], v151 offset:3072
	ds_read_b128 v[176:179], v152
	ds_read_b128 v[180:183], v152 offset:1024
	ds_read_b128 v[184:187], v152 offset:2048
	ds_read_b128 v[192:195], v152 offset:3072
	s_add_u32 s34, s46, 0xfff80080
	s_addc_u32 s48, s47, -1
	s_cmp_eq_u32 s19, 4
	s_cselect_b32 s51, s39, s48
	s_cselect_b32 s50, s38, s34
	s_cselect_b32 s49, s41, s15
	s_cselect_b32 s48, s40, s14
	v_lshl_add_u64 v[158:159], s[46:47], 0, v[138:139]
	s_add_i32 m0, s16, 0xc000
	ds_read_b128 v[196:199], v153
	ds_read_b128 v[200:203], v153 offset:1024
	ds_read_b128 v[204:207], v153 offset:2048
	ds_read_b128 v[208:211], v153 offset:3072
	ds_read_b128 v[212:215], v153 offset:4096
	ds_read_b128 v[216:219], v153 offset:5120
	ds_read_b128 v[220:223], v153 offset:6144
	ds_read_b128 v[224:227], v153 offset:7168
	global_load_lds_dwordx4 v[158:159], off
	v_lshl_add_u64 v[158:159], s[46:47], 0, v[140:141]
	s_add_i32 m0, s16, 0xe000
	s_nop 0
	global_load_lds_dwordx4 v[158:159], off
	s_waitcnt vmcnt(8)
	s_waitcnt lgkmcnt(0)
	s_barrier
; #define PG8_STAGE(bufoff, gbase, voff) do { _Pragma("unroll") for (int _i = 0; _i < 2; ++_i) \
;         __builtin_amdgcn_global_load_lds((const unsigned*)((const char*)(gbase) + (voff)[_i]), (LAS unsigned*)(lds + (bufoff) + ldsw + _i * 8192), 16, 0, 0); } while (0)
; #define PG8_LDA(dst, b, h) do { _Pragma("unroll") for (int m = 0; m < 4; ++m) _Pragma("unroll") for (int k = 0; k < 2; ++k) dst[m][k] = *(const LAS bf16x8*)(lds + PG8_SA(b, h) + aoff + m * 2048 + k * 1024); } while (0)
; #define PG8_LDB(dst, b, h) do { _Pragma("unroll") for (int n = 0; n < 2; ++n) _Pragma("unroll") for (int k = 0; k < 2; ++k) dst[n][k] = *(const LAS bf16x8*)(lds + PG8_SB(b, h) + boff + n * 2048 + k * 1024); } while (0)
; #define PG8_MMA(ai, bj, At, Bt) do { __builtin_amdgcn_s_setprio(1); _Pragma("unroll") for (int m = 0; m < 4; ++m) _Pragma("unroll") for (int n = 0; n < 2; ++n) _Pragma("unroll") for (int k = 0; k < 2; ++k) \
;         acc[ai][bj][m][n] = __builtin_amdgcn_mfma_f32_16x16x32_bf16(Bt[n][k], At[m][k], acc[ai][bj][m][n], 0, 0, 0); __builtin_amdgcn_s_setprio(0); } while (0)
; #define PG8_WAIT_V(n) asm volatile("s_waitcnt vmcnt(" #n ")" ::: "memory")
; #define PG8_WAIT_L(n) asm volatile("s_waitcnt lgkmcnt(" #n ")" ::: "memory")
; #define PG8_BAR __builtin_amdgcn_s_barrier()
; #define PG8_SCHED __builtin_amdgcn_sched_barrier(0)
; template <int GI>
; __device__ __forceinline__ void gemm_phase(LAS unsigned char* lds, unsigned char* ws, int G, int cblk) {
;     ...
;             PG8_LDB(B0, 0, 0); PG8_LDB(B1, 0, 1); PG8_SCHED; PG8_LDA(At, 0, 0); PG8_STAGE(PG8_SA(1, 1), a1 + hstepA, voffA);
;             PG8_WAIT_V(8); PG8_WAIT_L(0); PG8_BAR; PG8_MMA(0, 0, At, B0); PG8_MMA(0, 1, At, B1); PG8_BAR; PG8_SCHED;
;             PG8_LDA(At, 0, 1); PG8_STAGE(PG8_SB(0, 0), b2, voffB); PG8_STAGE(PG8_SB(0, 1), b2 + hstepB, voffB); PG8_STAGE(PG8_SA(0, 0), a2, voffA);
;             PG8_WAIT_V(8); PG8_WAIT_L(0); PG8_BAR; PG8_MMA(1, 0, At, B0); PG8_MMA(1, 1, At, B1); PG8_BAR; PG8_SCHED;
	s_setprio 1
	s_waitcnt lgkmcnt(0)
	v_mfma_f32_16x16x32_bf16 v[124:127], v[154:157], v[196:199], v[124:127]
	v_mfma_f32_16x16x32_bf16 v[120:123], v[168:171], v[196:199], v[120:123]
	v_mfma_f32_16x16x32_bf16 v[116:119], v[154:157], v[204:207], v[116:119]
	v_mfma_f32_16x16x32_bf16 v[112:115], v[168:171], v[204:207], v[112:115]
	v_mfma_f32_16x16x32_bf16 v[100:103], v[154:157], v[212:215], v[100:103]
	v_mfma_f32_16x16x32_bf16 v[96:99], v[168:171], v[212:215], v[96:99]
	v_mfma_f32_16x16x32_bf16 v[84:87], v[154:157], v[220:223], v[84:87]
	v_mfma_f32_16x16x32_bf16 v[80:83], v[168:171], v[220:223], v[80:83]
	v_mfma_f32_16x16x32_bf16 v[124:127], v[164:167], v[200:203], v[124:127]
	v_mfma_f32_16x16x32_bf16 v[120:123], v[172:175], v[200:203], v[120:123]
	v_mfma_f32_16x16x32_bf16 v[116:119], v[164:167], v[208:211], v[116:119]
	v_mfma_f32_16x16x32_bf16 v[112:115], v[172:175], v[208:211], v[112:115]
	v_mfma_f32_16x16x32_bf16 v[100:103], v[164:167], v[216:219], v[100:103]
	v_mfma_f32_16x16x32_bf16 v[96:99], v[172:175], v[216:219], v[96:99]
	v_mfma_f32_16x16x32_bf16 v[84:87], v[164:167], v[224:227], v[84:87]
	v_mfma_f32_16x16x32_bf16 v[80:83], v[172:175], v[224:227], v[80:83]
	s_setprio 0
	s_setprio 1
	v_mfma_f32_16x16x32_bf16 v[108:111], v[176:179], v[196:199], v[108:111]
	v_mfma_f32_16x16x32_bf16 v[104:107], v[184:187], v[196:199], v[104:107]
	v_mfma_f32_16x16x32_bf16 v[92:95], v[176:179], v[204:207], v[92:95]
	v_mfma_f32_16x16x32_bf16 v[88:91], v[184:187], v[204:207], v[88:91]
	v_mfma_f32_16x16x32_bf16 v[76:79], v[176:179], v[212:215], v[76:79]
	v_mfma_f32_16x16x32_bf16 v[72:75], v[184:187], v[212:215], v[72:75]
	v_mfma_f32_16x16x32_bf16 v[68:71], v[176:179], v[220:223], v[68:71]
	v_mfma_f32_16x16x32_bf16 v[64:67], v[184:187], v[220:223], v[64:67]
	v_mfma_f32_16x16x32_bf16 v[108:111], v[180:183], v[200:203], v[108:111]
	v_mfma_f32_16x16x32_bf16 v[104:107], v[192:195], v[200:203], v[104:107]
	v_mfma_f32_16x16x32_bf16 v[92:95], v[180:183], v[208:211], v[92:95]
	v_mfma_f32_16x16x32_bf16 v[88:91], v[192:195], v[208:211], v[88:91]
	v_mfma_f32_16x16x32_bf16 v[76:79], v[180:183], v[216:219], v[76:79]
	v_mfma_f32_16x16x32_bf16 v[72:75], v[192:195], v[216:219], v[72:75]
	v_mfma_f32_16x16x32_bf16 v[68:71], v[180:183], v[224:227], v[68:71]
	v_mfma_f32_16x16x32_bf16 v[64:67], v[192:195], v[224:227], v[64:67]
	s_setprio 0
	s_barrier
	s_add_i32 s34, s33, s0
	v_lshl_add_u64 v[158:159], s[48:49], 0, v[132:133]
	s_mov_b32 m0, s34
	ds_read_b128 v[196:199], v153 offset:16384
	ds_read_b128 v[200:203], v153 offset:17408
	ds_read_b128 v[204:207], v153 offset:18432
	ds_read_b128 v[208:211], v153 offset:19456
	ds_read_b128 v[212:215], v153 offset:20480
	ds_read_b128 v[216:219], v153 offset:21504
	ds_read_b128 v[220:223], v153 offset:22528
	ds_read_b128 v[224:227], v153 offset:23552
	global_load_lds_dwordx4 v[158:159], off
	s_add_i32 m0, s34, 0x2000
	s_add_u32 s54, s48, 0x100000
	v_lshl_add_u64 v[188:189], s[48:49], 0, v[128:129]
	s_addc_u32 s55, s49, 0
	s_add_i32 s34, s35, s0
	global_load_lds_dwordx4 v[188:189], off
	v_lshl_add_u64 v[228:229], s[54:55], 0, v[132:133]
	s_mov_b32 m0, s34
	v_lshl_add_u64 v[230:231], s[50:51], 0, v[130:131]
	global_load_lds_dwordx4 v[228:229], off
	v_lshl_add_u64 v[228:229], s[54:55], 0, v[128:129]
	s_add_i32 m0, s34, 0x2000
	s_nop 0
	global_load_lds_dwordx4 v[228:229], off
	v_lshl_add_u64 v[228:229], s[50:51], 0, v[134:135]
	s_mov_b32 m0, s16
	s_nop 0
	global_load_lds_dwordx4 v[228:229], off
	s_mov_b32 m0, s17
	s_nop 0
	global_load_lds_dwordx4 v[230:231], off
	s_waitcnt vmcnt(8)
	s_waitcnt lgkmcnt(0)
	s_barrier
	s_setprio 1
	s_waitcnt lgkmcnt(0)
	v_mfma_f32_16x16x32_bf16 v[60:63], v[154:157], v[196:199], v[60:63]
	v_mfma_f32_16x16x32_bf16 v[56:59], v[168:171], v[196:199], v[56:59]
	v_mfma_f32_16x16x32_bf16 v[52:55], v[154:157], v[204:207], v[52:55]
	v_mfma_f32_16x16x32_bf16 v[48:51], v[168:171], v[204:207], v[48:51]
	v_mfma_f32_16x16x32_bf16 v[36:39], v[154:157], v[212:215], v[36:39]
	v_mfma_f32_16x16x32_bf16 v[32:35], v[168:171], v[212:215], v[32:35]
	v_mfma_f32_16x16x32_bf16 v[20:23], v[154:157], v[220:223], v[20:23]
	v_mfma_f32_16x16x32_bf16 v[16:19], v[168:171], v[220:223], v[16:19]
	v_mfma_f32_16x16x32_bf16 v[60:63], v[164:167], v[200:203], v[60:63]
	v_mfma_f32_16x16x32_bf16 v[56:59], v[172:175], v[200:203], v[56:59]
	v_mfma_f32_16x16x32_bf16 v[52:55], v[164:167], v[208:211], v[52:55]
	v_mfma_f32_16x16x32_bf16 v[48:51], v[172:175], v[208:211], v[48:51]
	v_mfma_f32_16x16x32_bf16 v[36:39], v[164:167], v[216:219], v[36:39]
	v_mfma_f32_16x16x32_bf16 v[32:35], v[172:175], v[216:219], v[32:35]
	v_mfma_f32_16x16x32_bf16 v[20:23], v[164:167], v[224:227], v[20:23]
	v_mfma_f32_16x16x32_bf16 v[16:19], v[172:175], v[224:227], v[16:19]
	s_setprio 0
	s_setprio 1
	v_mfma_f32_16x16x32_bf16 v[44:47], v[176:179], v[196:199], v[44:47]
	v_mfma_f32_16x16x32_bf16 v[40:43], v[184:187], v[196:199], v[40:43]
	v_mfma_f32_16x16x32_bf16 v[28:31], v[176:179], v[204:207], v[28:31]
	v_mfma_f32_16x16x32_bf16 v[24:27], v[184:187], v[204:207], v[24:27]
	v_mfma_f32_16x16x32_bf16 v[12:15], v[176:179], v[212:215], v[12:15]
	v_mfma_f32_16x16x32_bf16 v[8:11], v[184:187], v[212:215], v[8:11]
	v_mfma_f32_16x16x32_bf16 v[4:7], v[176:179], v[220:223], v[4:7]
	v_mfma_f32_16x16x32_bf16 v[0:3], v[184:187], v[220:223], v[0:3]
	v_mfma_f32_16x16x32_bf16 v[44:47], v[180:183], v[200:203], v[44:47]
	v_mfma_f32_16x16x32_bf16 v[40:43], v[192:195], v[200:203], v[40:43]
	v_mfma_f32_16x16x32_bf16 v[28:31], v[180:183], v[208:211], v[28:31]
	v_mfma_f32_16x16x32_bf16 v[24:27], v[192:195], v[208:211], v[24:27]
	v_mfma_f32_16x16x32_bf16 v[12:15], v[180:183], v[216:219], v[12:15]
	v_mfma_f32_16x16x32_bf16 v[8:11], v[192:195], v[216:219], v[8:11]
	v_mfma_f32_16x16x32_bf16 v[4:7], v[180:183], v[224:227], v[4:7]
	v_mfma_f32_16x16x32_bf16 v[0:3], v[192:195], v[224:227], v[0:3]
	s_setprio 0
	s_barrier
; #define PG8_STAGE(bufoff, gbase, voff) do { _Pragma("unroll") for (int _i = 0; _i < 2; ++_i) \
;         __builtin_amdgcn_global_load_lds((const unsigned*)((const char*)(gbase) + (voff)[_i]), (LAS unsigned*)(lds + (bufoff) + ldsw + _i * 8192), 16, 0, 0); } while (0)
; #define PG8_LDA(dst, b, h) do { _Pragma("unroll") for (int m = 0; m < 4; ++m) _Pragma("unroll") for (int k = 0; k < 2; ++k) dst[m][k] = *(const LAS bf16x8*)(lds + PG8_SA(b, h) + aoff + m * 2048 + k * 1024); } while (0)
; #define PG8_LDB(dst, b, h) do { _Pragma("unroll") for (int n = 0; n < 2; ++n) _Pragma("unroll") for (int k = 0; k < 2; ++k) dst[n][k] = *(const LAS bf16x8*)(lds + PG8_SB(b, h) + boff + n * 2048 + k * 1024); } while (0)
; #define PG8_MMA(ai, bj, At, Bt) do { __builtin_amdgcn_s_setprio(1); _Pragma("unroll") for (int m = 0; m < 4; ++m) _Pragma("unroll") for (int n = 0; n < 2; ++n) _Pragma("unroll") for (int k = 0; k < 2; ++k) \
;         acc[ai][bj][m][n] = __builtin_amdgcn_mfma_f32_16x16x32_bf16(Bt[n][k], At[m][k], acc[ai][bj][m][n], 0, 0, 0); __builtin_amdgcn_s_setprio(0); } while (0)
; #define PG8_WAIT_V(n) asm volatile("s_waitcnt vmcnt(" #n ")" ::: "memory")
; #define PG8_WAIT_L(n) asm volatile("s_waitcnt lgkmcnt(" #n ")" ::: "memory")
; #define PG8_BAR __builtin_amdgcn_s_barrier()
; #define PG8_SCHED __builtin_amdgcn_sched_barrier(0)
; template <int GI>
; __device__ __forceinline__ void gemm_phase(LAS unsigned char* lds, unsigned char* ws, int G, int cblk) {
;     ...
;             PG8_LDB(B0, 1, 0); PG8_LDB(B1, 1, 1); PG8_SCHED; PG8_LDA(At, 1, 0); PG8_STAGE(PG8_SA(0, 1), a2 + hstepA, voffA);
;             PG8_WAIT_V(8); PG8_WAIT_L(0); PG8_BAR; PG8_MMA(0, 0, At, B0); PG8_MMA(0, 1, At, B1); PG8_BAR; PG8_SCHED;
	s_add_i32 s34, 0, 0x18000
	v_add_u32_e32 v161, s34, v150
	s_add_i32 s53, 0, 0x1c000
	ds_read_b128 v[154:157], v161
	ds_read_b128 v[164:167], v161 offset:1024
	ds_read_b128 v[168:171], v161 offset:2048
	ds_read_b128 v[172:175], v161 offset:3072
	v_add_u32_e32 v161, s53, v150
	ds_read_b128 v[176:179], v161
	ds_read_b128 v[180:183], v161 offset:1024
	ds_read_b128 v[184:187], v161 offset:2048
	ds_read_b128 v[192:195], v161 offset:3072
	s_add_u32 s50, s50, 0x80000
	s_addc_u32 s51, s51, 0
	s_mov_b32 m0, s22
	v_lshl_add_u64 v[232:233], s[50:51], 0, v[134:135]
	ds_read_b128 v[196:199], v153 offset:32768
	ds_read_b128 v[200:203], v153 offset:33792
	ds_read_b128 v[204:207], v153 offset:34816
	ds_read_b128 v[208:211], v153 offset:35840
	ds_read_b128 v[212:215], v153 offset:36864
	ds_read_b128 v[216:219], v153 offset:37888
	ds_read_b128 v[220:223], v153 offset:38912
	ds_read_b128 v[224:227], v153 offset:39936
	global_load_lds_dwordx4 v[232:233], off
	v_lshl_add_u64 v[232:233], s[50:51], 0, v[130:131]
	s_mov_b32 m0, s23
	s_nop 0
	global_load_lds_dwordx4 v[232:233], off
	s_waitcnt vmcnt(8)
	s_waitcnt lgkmcnt(0)
	s_barrier
	s_setprio 1
	s_waitcnt lgkmcnt(0)
	v_mfma_f32_16x16x32_bf16 v[124:127], v[154:157], v[196:199], v[124:127]
	v_mfma_f32_16x16x32_bf16 v[120:123], v[168:171], v[196:199], v[120:123]
	v_mfma_f32_16x16x32_bf16 v[116:119], v[154:157], v[204:207], v[116:119]
	v_mfma_f32_16x16x32_bf16 v[112:115], v[168:171], v[204:207], v[112:115]
	v_mfma_f32_16x16x32_bf16 v[100:103], v[154:157], v[212:215], v[100:103]
	v_mfma_f32_16x16x32_bf16 v[96:99], v[168:171], v[212:215], v[96:99]
	v_mfma_f32_16x16x32_bf16 v[84:87], v[154:157], v[220:223], v[84:87]
	v_mfma_f32_16x16x32_bf16 v[80:83], v[168:171], v[220:223], v[80:83]
	v_mfma_f32_16x16x32_bf16 v[124:127], v[164:167], v[200:203], v[124:127]
	v_mfma_f32_16x16x32_bf16 v[120:123], v[172:175], v[200:203], v[120:123]
	v_mfma_f32_16x16x32_bf16 v[116:119], v[164:167], v[208:211], v[116:119]
	v_mfma_f32_16x16x32_bf16 v[112:115], v[172:175], v[208:211], v[112:115]
	v_mfma_f32_16x16x32_bf16 v[100:103], v[164:167], v[216:219], v[100:103]
	v_mfma_f32_16x16x32_bf16 v[96:99], v[172:175], v[216:219], v[96:99]
	v_mfma_f32_16x16x32_bf16 v[84:87], v[164:167], v[224:227], v[84:87]
	v_mfma_f32_16x16x32_bf16 v[80:83], v[172:175], v[224:227], v[80:83]
	s_setprio 0
	s_setprio 1
	v_mfma_f32_16x16x32_bf16 v[108:111], v[176:179], v[196:199], v[108:111]
	v_mfma_f32_16x16x32_bf16 v[104:107], v[184:187], v[196:199], v[104:107]
	v_mfma_f32_16x16x32_bf16 v[92:95], v[176:179], v[204:207], v[92:95]
	v_mfma_f32_16x16x32_bf16 v[88:91], v[184:187], v[204:207], v[88:91]
	v_mfma_f32_16x16x32_bf16 v[76:79], v[176:179], v[212:215], v[76:79]
	v_mfma_f32_16x16x32_bf16 v[72:75], v[184:187], v[212:215], v[72:75]
	v_mfma_f32_16x16x32_bf16 v[68:71], v[176:179], v[220:223], v[68:71]
	v_mfma_f32_16x16x32_bf16 v[64:67], v[184:187], v[220:223], v[64:67]
	v_mfma_f32_16x16x32_bf16 v[108:111], v[180:183], v[200:203], v[108:111]
	v_mfma_f32_16x16x32_bf16 v[104:107], v[192:195], v[200:203], v[104:107]
	v_mfma_f32_16x16x32_bf16 v[92:95], v[180:183], v[208:211], v[92:95]
	v_mfma_f32_16x16x32_bf16 v[88:91], v[192:195], v[208:211], v[88:91]
	v_mfma_f32_16x16x32_bf16 v[76:79], v[180:183], v[216:219], v[76:79]
	v_mfma_f32_16x16x32_bf16 v[72:75], v[192:195], v[216:219], v[72:75]
	v_mfma_f32_16x16x32_bf16 v[68:71], v[180:183], v[224:227], v[68:71]
	v_mfma_f32_16x16x32_bf16 v[64:67], v[192:195], v[224:227], v[64:67]
	s_setprio 0
	s_barrier
; #define PG8_STAGE(bufoff, gbase, voff) do { _Pragma("unroll") for (int _i = 0; _i < 2; ++_i) \
;         __builtin_amdgcn_global_load_lds((const unsigned*)((const char*)(gbase) + (voff)[_i]), (LAS unsigned*)(lds + (bufoff) + ldsw + _i * 8192), 16, 0, 0); } while (0)
; #define PG8_LDA(dst, b, h) do { _Pragma("unroll") for (int m = 0; m < 4; ++m) _Pragma("unroll") for (int k = 0; k < 2; ++k) dst[m][k] = *(const LAS bf16x8*)(lds + PG8_SA(b, h) + aoff + m * 2048 + k * 1024); } while (0)
; #define PG8_MMA(ai, bj, At, Bt) do { __builtin_amdgcn_s_setprio(1); _Pragma("unroll") for (int m = 0; m < 4; ++m) _Pragma("unroll") for (int n = 0; n < 2; ++n) _Pragma("unroll") for (int k = 0; k < 2; ++k) \
;         acc[ai][bj][m][n] = __builtin_amdgcn_mfma_f32_16x16x32_bf16(Bt[n][k], At[m][k], acc[ai][bj][m][n], 0, 0, 0); __builtin_amdgcn_s_setprio(0); } while (0)
; #define PG8_WAIT_V(n) asm volatile("s_waitcnt vmcnt(" #n ")" ::: "memory")
; #define PG8_WAIT_L(n) asm volatile("s_waitcnt lgkmcnt(" #n ")" ::: "memory")
; #define PG8_BAR __builtin_amdgcn_s_barrier()
; #define PG8_SCHED __builtin_amdgcn_sched_barrier(0)
; template <int GI>
; __device__ __forceinline__ void gemm_phase(LAS unsigned char* lds, unsigned char* ws, int G, int cblk) {
;     ...
;             PG8_LDA(At, 1, 1); PG8_STAGE(PG8_SB(1, 0), b3, voffB); PG8_STAGE(PG8_SB(1, 1), b3 + hstepB, voffB); PG8_STAGE(PG8_SA(1, 0), a3, voffA);
;             PG8_WAIT_V(8); PG8_WAIT_L(0); PG8_BAR; PG8_MMA(1, 0, At, B0); PG8_MMA(1, 1, At, B1); PG8_BAR; PG8_SCHED;
;         }
	s_add_i32 s34, s34, s0
	v_lshl_add_u64 v[158:159], v[158:159], 0, s[8:9]
	s_mov_b32 m0, s34
	ds_read_b128 v[196:199], v153 offset:49152
	ds_read_b128 v[200:203], v153 offset:50176
	ds_read_b128 v[204:207], v153 offset:51200
	ds_read_b128 v[208:211], v153 offset:52224
	ds_read_b128 v[212:215], v153 offset:53248
	ds_read_b128 v[216:219], v153 offset:54272
	ds_read_b128 v[220:223], v153 offset:55296
	ds_read_b128 v[224:227], v153 offset:56320
	global_load_lds_dwordx4 v[158:159], off
	s_add_i32 m0, s34, 0x2000
	s_add_u32 s48, s48, 0x100080
	v_lshl_add_u64 v[158:159], v[188:189], 0, s[8:9]
	s_addc_u32 s49, s49, 0
	s_add_i32 s34, s53, s0
	global_load_lds_dwordx4 v[158:159], off
	v_lshl_add_u64 v[158:159], s[48:49], 0, v[132:133]
	s_mov_b32 m0, s34
	s_nop 0
	global_load_lds_dwordx4 v[158:159], off
	v_lshl_add_u64 v[158:159], s[48:49], 0, v[128:129]
	s_add_i32 m0, s34, 0x2000
	s_nop 0
	global_load_lds_dwordx4 v[158:159], off
	v_lshl_add_u64 v[158:159], v[228:229], 0, s[8:9]
	s_mov_b32 m0, s26
	s_nop 0
	global_load_lds_dwordx4 v[158:159], off
	v_lshl_add_u64 v[158:159], v[230:231], 0, s[8:9]
	s_mov_b32 m0, s27
	s_nop 0
	global_load_lds_dwordx4 v[158:159], off
	s_waitcnt vmcnt(8)
	s_waitcnt lgkmcnt(0)
	s_barrier
	s_setprio 1
	s_waitcnt lgkmcnt(0)
	v_mfma_f32_16x16x32_bf16 v[60:63], v[154:157], v[196:199], v[60:63]
	v_mfma_f32_16x16x32_bf16 v[56:59], v[168:171], v[196:199], v[56:59]
	s_add_i32 s19, s19, 2
	s_add_u32 s46, s46, 0x100
	s_addc_u32 s47, s47, 0
	s_add_u32 s14, s14, 0x100
	s_addc_u32 s15, s15, 0
	v_mfma_f32_16x16x32_bf16 v[52:55], v[154:157], v[204:207], v[52:55]
	v_mfma_f32_16x16x32_bf16 v[48:51], v[168:171], v[204:207], v[48:51]
	v_mfma_f32_16x16x32_bf16 v[36:39], v[154:157], v[212:215], v[36:39]
	v_mfma_f32_16x16x32_bf16 v[32:35], v[168:171], v[212:215], v[32:35]
	v_mfma_f32_16x16x32_bf16 v[20:23], v[154:157], v[220:223], v[20:23]
	v_mfma_f32_16x16x32_bf16 v[16:19], v[168:171], v[220:223], v[16:19]
	v_mfma_f32_16x16x32_bf16 v[60:63], v[164:167], v[200:203], v[60:63]
	v_mfma_f32_16x16x32_bf16 v[56:59], v[172:175], v[200:203], v[56:59]
	v_mfma_f32_16x16x32_bf16 v[52:55], v[164:167], v[208:211], v[52:55]
	v_mfma_f32_16x16x32_bf16 v[48:51], v[172:175], v[208:211], v[48:51]
	v_mfma_f32_16x16x32_bf16 v[36:39], v[164:167], v[216:219], v[36:39]
	v_mfma_f32_16x16x32_bf16 v[32:35], v[172:175], v[216:219], v[32:35]
	v_mfma_f32_16x16x32_bf16 v[20:23], v[164:167], v[224:227], v[20:23]
	v_mfma_f32_16x16x32_bf16 v[16:19], v[172:175], v[224:227], v[16:19]
	s_setprio 0
	s_setprio 1
	v_mfma_f32_16x16x32_bf16 v[44:47], v[176:179], v[196:199], v[44:47]
	v_mfma_f32_16x16x32_bf16 v[40:43], v[184:187], v[196:199], v[40:43]
	v_mfma_f32_16x16x32_bf16 v[28:31], v[176:179], v[204:207], v[28:31]
	v_mfma_f32_16x16x32_bf16 v[24:27], v[184:187], v[204:207], v[24:27]
	v_mfma_f32_16x16x32_bf16 v[12:15], v[176:179], v[212:215], v[12:15]
	v_mfma_f32_16x16x32_bf16 v[8:11], v[184:187], v[212:215], v[8:11]
	v_mfma_f32_16x16x32_bf16 v[4:7], v[176:179], v[220:223], v[4:7]
	v_mfma_f32_16x16x32_bf16 v[0:3], v[184:187], v[220:223], v[0:3]
	v_mfma_f32_16x16x32_bf16 v[44:47], v[180:183], v[200:203], v[44:47]
	v_mfma_f32_16x16x32_bf16 v[40:43], v[192:195], v[200:203], v[40:43]
	v_mfma_f32_16x16x32_bf16 v[28:31], v[180:183], v[208:211], v[28:31]
	v_mfma_f32_16x16x32_bf16 v[24:27], v[192:195], v[208:211], v[24:27]
	v_mfma_f32_16x16x32_bf16 v[12:15], v[180:183], v[216:219], v[12:15]
	v_mfma_f32_16x16x32_bf16 v[8:11], v[192:195], v[216:219], v[8:11]
	v_mfma_f32_16x16x32_bf16 v[4:7], v[180:183], v[224:227], v[4:7]
	v_mfma_f32_16x16x32_bf16 v[0:3], v[192:195], v[224:227], v[0:3]
	s_setprio 0
	s_barrier
	s_cmp_gt_u32 s19, 5
	s_cbranch_scc0 .LBB0_432

; #define PG8_STAGE(bufoff, gbase, voff) do { _Pragma("unroll") for (int _i = 0; _i < 2; ++_i) \
;         __builtin_amdgcn_global_load_lds((const unsigned*)((const char*)(gbase) + (voff)[_i]), (LAS unsigned*)(lds + (bufoff) + ldsw + _i * 8192), 16, 0, 0); } while (0)
; #define PG8_LDA(dst, b, h) do { _Pragma("unroll") for (int m = 0; m < 4; ++m) _Pragma("unroll") for (int k = 0; k < 2; ++k) dst[m][k] = *(const LAS bf16x8*)(lds + PG8_SA(b, h) + aoff + m * 2048 + k * 1024); } while (0)
; #define PG8_LDB(dst, b, h) do { _Pragma("unroll") for (int n = 0; n < 2; ++n) _Pragma("unroll") for (int k = 0; k < 2; ++k) dst[n][k] = *(const LAS bf16x8*)(lds + PG8_SB(b, h) + boff + n * 2048 + k * 1024); } while (0)
; #define PG8_MMA(ai, bj, At, Bt) do { __builtin_amdgcn_s_setprio(1); _Pragma("unroll") for (int m = 0; m < 4; ++m) _Pragma("unroll") for (int n = 0; n < 2; ++n) _Pragma("unroll") for (int k = 0; k < 2; ++k) \
;         acc[ai][bj][m][n] = __builtin_amdgcn_mfma_f32_16x16x32_bf16(Bt[n][k], At[m][k], acc[ai][bj][m][n], 0, 0, 0); __builtin_amdgcn_s_setprio(0); } while (0)
; #define PG8_WAIT_V(n) asm volatile("s_waitcnt vmcnt(" #n ")" ::: "memory")
; #define PG8_BAR __builtin_amdgcn_s_barrier()
; template <int GI>
; __device__ __forceinline__ void gemm_phase(LAS unsigned char* lds, unsigned char* ws, int G, int cblk) {
;     ...
;     for (;;) {
;         const bool has_next = sched_next<GI>(ws, ui + 1, G, cblk, nxt);
;         const char* nA = has_next ? nxt.A : cA; const char* nB = has_next ? nxt.B : cB;
;         for (int t = 0; t < nt; t += 2) {
;             const bool last = (t == nt - 2);
;             const char* a1 = cA + (size_t)(t + 1) * kstep;
;             const char* a2 = last ? nA : cA + (size_t)(t + 2) * kstep; const char* b2 = last ? nB : cB + (size_t)(t + 2) * kstep;
;             const char* a3 = a2 + kstep; const char* b3 = b2 + kstep;
;             PG8_LDB(B0, 0, 0); PG8_LDB(B1, 0, 1); PG8_SCHED; PG8_LDA(At, 0, 0); PG8_STAGE(PG8_SA(1, 1), a1 + hstepA, voffA);
;             PG8_WAIT_V(8); PG8_WAIT_L(0); PG8_BAR; PG8_MMA(0, 0, At, B0); PG8_MMA(0, 1, At, B1); PG8_BAR; PG8_SCHED;
;             PG8_LDA(At, 0, 1); PG8_STAGE(PG8_SB(0, 0), b2, voffB); PG8_STAGE(PG8_SB(0, 1), b2 + hstepB, voffB); PG8_STAGE(PG8_SA(0, 0), a2, voffA);
;             PG8_WAIT_V(8); PG8_WAIT_L(0); PG8_BAR; PG8_MMA(1, 0, At, B0); PG8_MMA(1, 1, At, B1); PG8_BAR; PG8_SCHED;
.LBB0_564:
	s_add_u32 s48, s48, 0x80080
	s_addc_u32 s49, s49, 0
	s_add_u32 s0, s50, 0x100
	s_addc_u32 s1, s51, 0
	s_mov_b32 s16, -2
	ds_read_b128 v[152:155], v167
	ds_read_b128 v[156:159], v167 offset:1024
	ds_read_b128 v[172:175], v167 offset:2048
	ds_read_b128 v[176:179], v167 offset:3072
	ds_read_b128 v[180:183], v168
	ds_read_b128 v[184:187], v168 offset:1024
	ds_read_b128 v[192:195], v168 offset:2048
	ds_read_b128 v[196:199], v168 offset:3072
	s_add_u32 s17, s48, 0xfff80080
	s_addc_u32 s33, s49, -1
	s_cmp_eq_u32 s16, 28
	s_cselect_b32 s53, s41, s33
	s_cselect_b32 s52, s40, s17
	s_cselect_b32 s51, s43, s1
	s_cselect_b32 s50, s42, s0
	v_lshl_add_u64 v[164:165], s[48:49], 0, v[148:149]
	s_add_i32 m0, s23, 0xc000
	ds_read_b128 v[200:203], v169
	ds_read_b128 v[204:207], v169 offset:1024
	ds_read_b128 v[208:211], v169 offset:2048
	ds_read_b128 v[212:215], v169 offset:3072
	ds_read_b128 v[216:219], v169 offset:4096
	ds_read_b128 v[220:223], v169 offset:5120
	ds_read_b128 v[224:227], v169 offset:6144
	ds_read_b128 v[228:231], v169 offset:7168
	global_load_lds_dwordx4 v[164:165], off
	v_lshl_add_u64 v[164:165], s[48:49], 0, v[150:151]
	s_add_i32 m0, s23, 0xe000
	s_nop 0
	global_load_lds_dwordx4 v[164:165], off
	s_waitcnt vmcnt(8)
	s_waitcnt lgkmcnt(0)
	s_barrier
	s_setprio 1
	s_waitcnt lgkmcnt(0)
	v_mfma_f32_16x16x32_bf16 v[124:127], v[152:155], v[200:203], 0
	v_mfma_f32_16x16x32_bf16 v[120:123], v[172:175], v[200:203], 0
	v_mfma_f32_16x16x32_bf16 v[108:111], v[152:155], v[208:211], 0
	v_mfma_f32_16x16x32_bf16 v[104:107], v[172:175], v[208:211], 0
	v_mfma_f32_16x16x32_bf16 v[92:95], v[152:155], v[216:219], 0
	v_mfma_f32_16x16x32_bf16 v[88:91], v[172:175], v[216:219], 0
	v_mfma_f32_16x16x32_bf16 v[76:79], v[152:155], v[224:227], 0
	v_mfma_f32_16x16x32_bf16 v[72:75], v[172:175], v[224:227], 0
	v_mfma_f32_16x16x32_bf16 v[124:127], v[156:159], v[204:207], v[124:127]
	v_mfma_f32_16x16x32_bf16 v[120:123], v[176:179], v[204:207], v[120:123]
	v_mfma_f32_16x16x32_bf16 v[108:111], v[156:159], v[212:215], v[108:111]
	v_mfma_f32_16x16x32_bf16 v[104:107], v[176:179], v[212:215], v[104:107]
	v_mfma_f32_16x16x32_bf16 v[92:95], v[156:159], v[220:223], v[92:95]
	v_mfma_f32_16x16x32_bf16 v[88:91], v[176:179], v[220:223], v[88:91]
	v_mfma_f32_16x16x32_bf16 v[76:79], v[156:159], v[228:231], v[76:79]
	v_mfma_f32_16x16x32_bf16 v[72:75], v[176:179], v[228:231], v[72:75]
	s_setprio 0
	s_setprio 1
	v_mfma_f32_16x16x32_bf16 v[116:119], v[180:183], v[200:203], 0
	v_mfma_f32_16x16x32_bf16 v[112:115], v[192:195], v[200:203], 0
	v_mfma_f32_16x16x32_bf16 v[100:103], v[180:183], v[208:211], 0
	v_mfma_f32_16x16x32_bf16 v[96:99], v[192:195], v[208:211], 0
	v_mfma_f32_16x16x32_bf16 v[84:87], v[180:183], v[216:219], 0
	v_mfma_f32_16x16x32_bf16 v[80:83], v[192:195], v[216:219], 0
	v_mfma_f32_16x16x32_bf16 v[68:71], v[180:183], v[224:227], 0
	v_mfma_f32_16x16x32_bf16 v[64:67], v[192:195], v[224:227], 0
	v_mfma_f32_16x16x32_bf16 v[116:119], v[184:187], v[204:207], v[116:119]
	v_mfma_f32_16x16x32_bf16 v[112:115], v[196:199], v[204:207], v[112:115]
	v_mfma_f32_16x16x32_bf16 v[100:103], v[184:187], v[212:215], v[100:103]
	v_mfma_f32_16x16x32_bf16 v[96:99], v[196:199], v[212:215], v[96:99]
	v_mfma_f32_16x16x32_bf16 v[84:87], v[184:187], v[220:223], v[84:87]
	v_mfma_f32_16x16x32_bf16 v[80:83], v[196:199], v[220:223], v[80:83]
	v_mfma_f32_16x16x32_bf16 v[68:71], v[184:187], v[228:231], v[68:71]
	v_mfma_f32_16x16x32_bf16 v[64:67], v[196:199], v[228:231], v[64:67]
	s_setprio 0
	s_barrier
	s_add_i32 s17, s60, s22
	v_lshl_add_u64 v[164:165], s[50:51], 0, v[132:133]
	s_mov_b32 m0, s17
	ds_read_b128 v[200:203], v169 offset:16384
	ds_read_b128 v[204:207], v169 offset:17408
	ds_read_b128 v[208:211], v169 offset:18432
	ds_read_b128 v[212:215], v169 offset:19456
	ds_read_b128 v[216:219], v169 offset:20480
	ds_read_b128 v[220:223], v169 offset:21504
	ds_read_b128 v[224:227], v169 offset:22528
	ds_read_b128 v[228:231], v169 offset:23552
	global_load_lds_dwordx4 v[164:165], off
	s_add_i32 m0, s17, 0x2000
	s_add_u32 s64, s50, 0x80000
	v_lshl_add_u64 v[188:189], s[50:51], 0, v[136:137]
	s_addc_u32 s65, s51, 0
	s_add_i32 s17, s61, s22
	global_load_lds_dwordx4 v[188:189], off
	v_lshl_add_u64 v[232:233], s[64:65], 0, v[132:133]
	s_mov_b32 m0, s17
	v_lshl_add_u64 v[234:235], s[52:53], 0, v[134:135]
	global_load_lds_dwordx4 v[232:233], off
	v_lshl_add_u64 v[232:233], s[64:65], 0, v[136:137]
	s_add_i32 m0, s17, 0x2000
	s_nop 0
	global_load_lds_dwordx4 v[232:233], off
	v_lshl_add_u64 v[232:233], s[52:53], 0, v[130:131]
	s_mov_b32 m0, s23
	s_nop 0
	global_load_lds_dwordx4 v[232:233], off
	s_mov_b32 m0, s24
	s_nop 0
	global_load_lds_dwordx4 v[234:235], off
	s_waitcnt vmcnt(8)
	s_waitcnt lgkmcnt(0)
	s_barrier
; #define PG8_STAGE(bufoff, gbase, voff) do { _Pragma("unroll") for (int _i = 0; _i < 2; ++_i) \
;         __builtin_amdgcn_global_load_lds((const unsigned*)((const char*)(gbase) + (voff)[_i]), (LAS unsigned*)(lds + (bufoff) + ldsw + _i * 8192), 16, 0, 0); } while (0)
; #define PG8_LDA(dst, b, h) do { _Pragma("unroll") for (int m = 0; m < 4; ++m) _Pragma("unroll") for (int k = 0; k < 2; ++k) dst[m][k] = *(const LAS bf16x8*)(lds + PG8_SA(b, h) + aoff + m * 2048 + k * 1024); } while (0)
; #define PG8_LDB(dst, b, h) do { _Pragma("unroll") for (int n = 0; n < 2; ++n) _Pragma("unroll") for (int k = 0; k < 2; ++k) dst[n][k] = *(const LAS bf16x8*)(lds + PG8_SB(b, h) + boff + n * 2048 + k * 1024); } while (0)
; #define PG8_MMA(ai, bj, At, Bt) do { __builtin_amdgcn_s_setprio(1); _Pragma("unroll") for (int m = 0; m < 4; ++m) _Pragma("unroll") for (int n = 0; n < 2; ++n) _Pragma("unroll") for (int k = 0; k < 2; ++k) \
;         acc[ai][bj][m][n] = __builtin_amdgcn_mfma_f32_16x16x32_bf16(Bt[n][k], At[m][k], acc[ai][bj][m][n], 0, 0, 0); __builtin_amdgcn_s_setprio(0); } while (0)
; #define PG8_WAIT_V(n) asm volatile("s_waitcnt vmcnt(" #n ")" ::: "memory")
; #define PG8_WAIT_L(n) asm volatile("s_waitcnt lgkmcnt(" #n ")" ::: "memory")
; #define PG8_BAR __builtin_amdgcn_s_barrier()
; #define PG8_SCHED __builtin_amdgcn_sched_barrier(0)
; template <int GI>
; __device__ __forceinline__ void gemm_phase(LAS unsigned char* lds, unsigned char* ws, int G, int cblk) {
;     ...
;             PG8_WAIT_V(8); PG8_WAIT_L(0); PG8_BAR; PG8_MMA(1, 0, At, B0); PG8_MMA(1, 1, At, B1); PG8_BAR; PG8_SCHED;
;             PG8_LDB(B0, 1, 0); PG8_LDB(B1, 1, 1); PG8_SCHED; PG8_LDA(At, 1, 0); PG8_STAGE(PG8_SA(0, 1), a2 + hstepA, voffA);
;             PG8_WAIT_V(8); PG8_WAIT_L(0); PG8_BAR; PG8_MMA(0, 0, At, B0); PG8_MMA(0, 1, At, B1); PG8_BAR; PG8_SCHED;
	s_setprio 1
	s_waitcnt lgkmcnt(0)
	v_mfma_f32_16x16x32_bf16 v[60:63], v[152:155], v[200:203], 0
	v_mfma_f32_16x16x32_bf16 v[56:59], v[172:175], v[200:203], 0
	v_mfma_f32_16x16x32_bf16 v[44:47], v[152:155], v[208:211], 0
	v_mfma_f32_16x16x32_bf16 v[40:43], v[172:175], v[208:211], 0
	v_mfma_f32_16x16x32_bf16 v[28:31], v[152:155], v[216:219], 0
	v_mfma_f32_16x16x32_bf16 v[24:27], v[172:175], v[216:219], 0
	v_mfma_f32_16x16x32_bf16 v[12:15], v[152:155], v[224:227], 0
	v_mfma_f32_16x16x32_bf16 v[8:11], v[172:175], v[224:227], 0
	v_mfma_f32_16x16x32_bf16 v[60:63], v[156:159], v[204:207], v[60:63]
	v_mfma_f32_16x16x32_bf16 v[56:59], v[176:179], v[204:207], v[56:59]
	v_mfma_f32_16x16x32_bf16 v[44:47], v[156:159], v[212:215], v[44:47]
	v_mfma_f32_16x16x32_bf16 v[40:43], v[176:179], v[212:215], v[40:43]
	v_mfma_f32_16x16x32_bf16 v[28:31], v[156:159], v[220:223], v[28:31]
	v_mfma_f32_16x16x32_bf16 v[24:27], v[176:179], v[220:223], v[24:27]
	v_mfma_f32_16x16x32_bf16 v[12:15], v[156:159], v[228:231], v[12:15]
	v_mfma_f32_16x16x32_bf16 v[8:11], v[176:179], v[228:231], v[8:11]
	s_setprio 0
	s_setprio 1
	v_mfma_f32_16x16x32_bf16 v[52:55], v[180:183], v[200:203], 0
	v_mfma_f32_16x16x32_bf16 v[48:51], v[192:195], v[200:203], 0
	v_mfma_f32_16x16x32_bf16 v[36:39], v[180:183], v[208:211], 0
	v_mfma_f32_16x16x32_bf16 v[32:35], v[192:195], v[208:211], 0
	v_mfma_f32_16x16x32_bf16 v[20:23], v[180:183], v[216:219], 0
	v_mfma_f32_16x16x32_bf16 v[16:19], v[192:195], v[216:219], 0
	v_mfma_f32_16x16x32_bf16 v[4:7], v[180:183], v[224:227], 0
	v_mfma_f32_16x16x32_bf16 v[0:3], v[192:195], v[224:227], 0
	v_mfma_f32_16x16x32_bf16 v[52:55], v[184:187], v[204:207], v[52:55]
	v_mfma_f32_16x16x32_bf16 v[48:51], v[196:199], v[204:207], v[48:51]
	v_mfma_f32_16x16x32_bf16 v[36:39], v[184:187], v[212:215], v[36:39]
	v_mfma_f32_16x16x32_bf16 v[32:35], v[196:199], v[212:215], v[32:35]
	v_mfma_f32_16x16x32_bf16 v[20:23], v[184:187], v[220:223], v[20:23]
	v_mfma_f32_16x16x32_bf16 v[16:19], v[196:199], v[220:223], v[16:19]
	v_mfma_f32_16x16x32_bf16 v[4:7], v[184:187], v[228:231], v[4:7]
	v_mfma_f32_16x16x32_bf16 v[0:3], v[196:199], v[228:231], v[0:3]
	s_setprio 0
	s_barrier
	s_add_i32 s17, 0, 0x18000
	s_add_i32 s33, 0, 0x1c000
	v_add_u32_e32 v176, s17, v161
	v_add_u32_e32 v191, s33, v161
	ds_read_b128 v[152:155], v176
	ds_read_b128 v[156:159], v176 offset:1024
	ds_read_b128 v[172:175], v176 offset:2048
	ds_read_b128 v[176:179], v176 offset:3072
	ds_read_b128 v[180:183], v191
	ds_read_b128 v[184:187], v191 offset:1024
	ds_read_b128 v[192:195], v191 offset:2048
	ds_read_b128 v[196:199], v191 offset:3072
	s_add_u32 s52, s52, 0x80000
	s_addc_u32 s53, s53, 0
	s_mov_b32 m0, s25
	v_lshl_add_u64 v[236:237], s[52:53], 0, v[130:131]
	ds_read_b128 v[200:203], v169 offset:32768
	ds_read_b128 v[204:207], v169 offset:33792
	ds_read_b128 v[208:211], v169 offset:34816
	ds_read_b128 v[212:215], v169 offset:35840
	ds_read_b128 v[216:219], v169 offset:36864
	ds_read_b128 v[220:223], v169 offset:37888
	ds_read_b128 v[224:227], v169 offset:38912
	ds_read_b128 v[228:231], v169 offset:39936
	global_load_lds_dwordx4 v[236:237], off
	v_lshl_add_u64 v[236:237], s[52:53], 0, v[134:135]
	s_mov_b32 m0, s26
	s_nop 0
	global_load_lds_dwordx4 v[236:237], off
	s_waitcnt vmcnt(8)
	s_waitcnt lgkmcnt(0)
	s_barrier
	s_setprio 1
	s_waitcnt lgkmcnt(0)
	v_mfma_f32_16x16x32_bf16 v[124:127], v[152:155], v[200:203], v[124:127]
	v_mfma_f32_16x16x32_bf16 v[120:123], v[172:175], v[200:203], v[120:123]
	v_mfma_f32_16x16x32_bf16 v[108:111], v[152:155], v[208:211], v[108:111]
	v_mfma_f32_16x16x32_bf16 v[104:107], v[172:175], v[208:211], v[104:107]
	v_mfma_f32_16x16x32_bf16 v[92:95], v[152:155], v[216:219], v[92:95]
	v_mfma_f32_16x16x32_bf16 v[88:91], v[172:175], v[216:219], v[88:91]
	v_mfma_f32_16x16x32_bf16 v[76:79], v[152:155], v[224:227], v[76:79]
	v_mfma_f32_16x16x32_bf16 v[72:75], v[172:175], v[224:227], v[72:75]
	v_mfma_f32_16x16x32_bf16 v[124:127], v[156:159], v[204:207], v[124:127]
	v_mfma_f32_16x16x32_bf16 v[120:123], v[176:179], v[204:207], v[120:123]
	v_mfma_f32_16x16x32_bf16 v[108:111], v[156:159], v[212:215], v[108:111]
	v_mfma_f32_16x16x32_bf16 v[104:107], v[176:179], v[212:215], v[104:107]
	v_mfma_f32_16x16x32_bf16 v[92:95], v[156:159], v[220:223], v[92:95]
	v_mfma_f32_16x16x32_bf16 v[88:91], v[176:179], v[220:223], v[88:91]
	v_mfma_f32_16x16x32_bf16 v[76:79], v[156:159], v[228:231], v[76:79]
	v_mfma_f32_16x16x32_bf16 v[72:75], v[176:179], v[228:231], v[72:75]
	s_setprio 0
	s_setprio 1
	v_mfma_f32_16x16x32_bf16 v[116:119], v[180:183], v[200:203], v[116:119]
	v_mfma_f32_16x16x32_bf16 v[112:115], v[192:195], v[200:203], v[112:115]
	v_mfma_f32_16x16x32_bf16 v[100:103], v[180:183], v[208:211], v[100:103]
	v_mfma_f32_16x16x32_bf16 v[96:99], v[192:195], v[208:211], v[96:99]
	v_mfma_f32_16x16x32_bf16 v[84:87], v[180:183], v[216:219], v[84:87]
	v_mfma_f32_16x16x32_bf16 v[80:83], v[192:195], v[216:219], v[80:83]
	v_mfma_f32_16x16x32_bf16 v[68:71], v[180:183], v[224:227], v[68:71]
	v_mfma_f32_16x16x32_bf16 v[64:67], v[192:195], v[224:227], v[64:67]
	v_mfma_f32_16x16x32_bf16 v[116:119], v[184:187], v[204:207], v[116:119]
	v_mfma_f32_16x16x32_bf16 v[112:115], v[196:199], v[204:207], v[112:115]
	v_mfma_f32_16x16x32_bf16 v[100:103], v[184:187], v[212:215], v[100:103]
	v_mfma_f32_16x16x32_bf16 v[96:99], v[196:199], v[212:215], v[96:99]
	v_mfma_f32_16x16x32_bf16 v[84:87], v[184:187], v[220:223], v[84:87]
	v_mfma_f32_16x16x32_bf16 v[80:83], v[196:199], v[220:223], v[80:83]
	v_mfma_f32_16x16x32_bf16 v[68:71], v[184:187], v[228:231], v[68:71]
	v_mfma_f32_16x16x32_bf16 v[64:67], v[196:199], v[228:231], v[64:67]
	s_setprio 0
	s_barrier
; #define PG8_STAGE(bufoff, gbase, voff) do { _Pragma("unroll") for (int _i = 0; _i < 2; ++_i) \
;         __builtin_amdgcn_global_load_lds((const unsigned*)((const char*)(gbase) + (voff)[_i]), (LAS unsigned*)(lds + (bufoff) + ldsw + _i * 8192), 16, 0, 0); } while (0)
; #define PG8_LDA(dst, b, h) do { _Pragma("unroll") for (int m = 0; m < 4; ++m) _Pragma("unroll") for (int k = 0; k < 2; ++k) dst[m][k] = *(const LAS bf16x8*)(lds + PG8_SA(b, h) + aoff + m * 2048 + k * 1024); } while (0)
; #define PG8_LDB(dst, b, h) do { _Pragma("unroll") for (int n = 0; n < 2; ++n) _Pragma("unroll") for (int k = 0; k < 2; ++k) dst[n][k] = *(const LAS bf16x8*)(lds + PG8_SB(b, h) + boff + n * 2048 + k * 1024); } while (0)
; #define PG8_MMA(ai, bj, At, Bt) do { __builtin_amdgcn_s_setprio(1); _Pragma("unroll") for (int m = 0; m < 4; ++m) _Pragma("unroll") for (int n = 0; n < 2; ++n) _Pragma("unroll") for (int k = 0; k < 2; ++k) \
;         acc[ai][bj][m][n] = __builtin_amdgcn_mfma_f32_16x16x32_bf16(Bt[n][k], At[m][k], acc[ai][bj][m][n], 0, 0, 0); __builtin_amdgcn_s_setprio(0); } while (0)
; #define PG8_WAIT_V(n) asm volatile("s_waitcnt vmcnt(" #n ")" ::: "memory")
; #define PG8_WAIT_L(n) asm volatile("s_waitcnt lgkmcnt(" #n ")" ::: "memory")
; #define PG8_BAR __builtin_amdgcn_s_barrier()
; #define PG8_SCHED __builtin_amdgcn_sched_barrier(0)
; template <int GI>
; __device__ __forceinline__ void gemm_phase(LAS unsigned char* lds, unsigned char* ws, int G, int cblk) {
;     ...
;         for (int t = 0; t < nt; t += 2) {
;             const bool last = (t == nt - 2);
;             const char* a1 = cA + (size_t)(t + 1) * kstep;
;             const char* a2 = last ? nA : cA + (size_t)(t + 2) * kstep; const char* b2 = last ? nB : cB + (size_t)(t + 2) * kstep;
;             const char* a3 = a2 + kstep; const char* b3 = b2 + kstep;
;             PG8_LDB(B0, 0, 0); PG8_LDB(B1, 0, 1); PG8_SCHED; PG8_LDA(At, 0, 0); PG8_STAGE(PG8_SA(1, 1), a1 + hstepA, voffA);
;     ...
;             PG8_LDA(At, 1, 1); PG8_STAGE(PG8_SB(1, 0), b3, voffB); PG8_STAGE(PG8_SB(1, 1), b3 + hstepB, voffB); PG8_STAGE(PG8_SA(1, 0), a3, voffA);
;             PG8_WAIT_V(8); PG8_WAIT_L(0); PG8_BAR; PG8_MMA(1, 0, At, B0); PG8_MMA(1, 1, At, B1); PG8_BAR; PG8_SCHED;
	s_add_i32 s17, s17, s22
	v_lshl_add_u64 v[164:165], v[164:165], 0, s[18:19]
	s_mov_b32 m0, s17
	ds_read_b128 v[200:203], v169 offset:49152
	ds_read_b128 v[204:207], v169 offset:50176
	ds_read_b128 v[208:211], v169 offset:51200
	ds_read_b128 v[212:215], v169 offset:52224
	ds_read_b128 v[216:219], v169 offset:53248
	ds_read_b128 v[220:223], v169 offset:54272
	ds_read_b128 v[224:227], v169 offset:55296
	ds_read_b128 v[228:231], v169 offset:56320
	global_load_lds_dwordx4 v[164:165], off
	s_add_i32 m0, s17, 0x2000
	s_add_u32 s50, s50, 0x80080
	v_lshl_add_u64 v[164:165], v[188:189], 0, s[18:19]
	s_addc_u32 s51, s51, 0
	s_add_i32 s17, s33, s22
	global_load_lds_dwordx4 v[164:165], off
	v_lshl_add_u64 v[164:165], s[50:51], 0, v[132:133]
	s_mov_b32 m0, s17
	s_nop 0
	global_load_lds_dwordx4 v[164:165], off
	v_lshl_add_u64 v[164:165], s[50:51], 0, v[136:137]
	s_add_i32 m0, s17, 0x2000
	s_nop 0
	global_load_lds_dwordx4 v[164:165], off
	v_lshl_add_u64 v[164:165], v[232:233], 0, s[18:19]
	s_mov_b32 m0, s35
	s_nop 0
	global_load_lds_dwordx4 v[164:165], off
	v_lshl_add_u64 v[164:165], v[234:235], 0, s[18:19]
	s_mov_b32 m0, s55
	s_nop 0
	global_load_lds_dwordx4 v[164:165], off
	s_waitcnt vmcnt(8)
	s_waitcnt lgkmcnt(0)
	s_barrier
	s_setprio 1
	s_waitcnt lgkmcnt(0)
	v_mfma_f32_16x16x32_bf16 v[60:63], v[152:155], v[200:203], v[60:63]
	v_mfma_f32_16x16x32_bf16 v[56:59], v[172:175], v[200:203], v[56:59]
	s_add_i32 s16, s16, 2
	s_add_u32 s48, s48, 0x100
	s_addc_u32 s49, s49, 0
	s_add_u32 s0, s0, 0x100
	s_addc_u32 s1, s1, 0
	v_mfma_f32_16x16x32_bf16 v[44:47], v[152:155], v[208:211], v[44:47]
	v_mfma_f32_16x16x32_bf16 v[40:43], v[172:175], v[208:211], v[40:43]
	v_mfma_f32_16x16x32_bf16 v[28:31], v[152:155], v[216:219], v[28:31]
	v_mfma_f32_16x16x32_bf16 v[24:27], v[172:175], v[216:219], v[24:27]
	v_mfma_f32_16x16x32_bf16 v[12:15], v[152:155], v[224:227], v[12:15]
	v_mfma_f32_16x16x32_bf16 v[8:11], v[172:175], v[224:227], v[8:11]
	v_mfma_f32_16x16x32_bf16 v[60:63], v[156:159], v[204:207], v[60:63]
	v_mfma_f32_16x16x32_bf16 v[56:59], v[176:179], v[204:207], v[56:59]
	v_mfma_f32_16x16x32_bf16 v[44:47], v[156:159], v[212:215], v[44:47]
	v_mfma_f32_16x16x32_bf16 v[40:43], v[176:179], v[212:215], v[40:43]
	v_mfma_f32_16x16x32_bf16 v[28:31], v[156:159], v[220:223], v[28:31]
	v_mfma_f32_16x16x32_bf16 v[24:27], v[176:179], v[220:223], v[24:27]
	v_mfma_f32_16x16x32_bf16 v[12:15], v[156:159], v[228:231], v[12:15]
	v_mfma_f32_16x16x32_bf16 v[8:11], v[176:179], v[228:231], v[8:11]
	s_setprio 0
	s_setprio 1
	v_mfma_f32_16x16x32_bf16 v[52:55], v[180:183], v[200:203], v[52:55]
	v_mfma_f32_16x16x32_bf16 v[48:51], v[192:195], v[200:203], v[48:51]
	v_mfma_f32_16x16x32_bf16 v[36:39], v[180:183], v[208:211], v[36:39]
	v_mfma_f32_16x16x32_bf16 v[32:35], v[192:195], v[208:211], v[32:35]
	v_mfma_f32_16x16x32_bf16 v[20:23], v[180:183], v[216:219], v[20:23]
	v_mfma_f32_16x16x32_bf16 v[16:19], v[192:195], v[216:219], v[16:19]
	v_mfma_f32_16x16x32_bf16 v[4:7], v[180:183], v[224:227], v[4:7]
	v_mfma_f32_16x16x32_bf16 v[0:3], v[192:195], v[224:227], v[0:3]
	v_mfma_f32_16x16x32_bf16 v[52:55], v[184:187], v[204:207], v[52:55]
	v_mfma_f32_16x16x32_bf16 v[48:51], v[196:199], v[204:207], v[48:51]
	v_mfma_f32_16x16x32_bf16 v[36:39], v[184:187], v[212:215], v[36:39]
	v_mfma_f32_16x16x32_bf16 v[32:35], v[196:199], v[212:215], v[32:35]
	v_mfma_f32_16x16x32_bf16 v[20:23], v[184:187], v[220:223], v[20:23]
	v_mfma_f32_16x16x32_bf16 v[16:19], v[196:199], v[220:223], v[16:19]
	v_mfma_f32_16x16x32_bf16 v[4:7], v[184:187], v[228:231], v[4:7]
	v_mfma_f32_16x16x32_bf16 v[0:3], v[196:199], v[228:231], v[0:3]
	s_setprio 0
	s_barrier
	s_cmp_gt_u32 s16, 29
	s_cbranch_scc0 .LBB0_565
	s_branch .Lpeel_exit_6
.LBB0_565:
	ds_read_b128 v[152:155], v167
	ds_read_b128 v[156:159], v167 offset:1024
	ds_read_b128 v[172:175], v167 offset:2048
	ds_read_b128 v[176:179], v167 offset:3072
	ds_read_b128 v[180:183], v168
	ds_read_b128 v[184:187], v168 offset:1024
	ds_read_b128 v[192:195], v168 offset:2048
	ds_read_b128 v[196:199], v168 offset:3072
	s_add_u32 s17, s48, 0xfff80080
	s_addc_u32 s33, s49, -1
	s_cmp_eq_u32 s16, 28
	s_cselect_b32 s53, s41, s33
	s_cselect_b32 s52, s40, s17
	s_cselect_b32 s51, s43, s1
	s_cselect_b32 s50, s42, s0
	v_lshl_add_u64 v[164:165], s[48:49], 0, v[148:149]
	s_add_i32 m0, s23, 0xc000
	ds_read_b128 v[200:203], v169
	ds_read_b128 v[204:207], v169 offset:1024
	ds_read_b128 v[208:211], v169 offset:2048
	ds_read_b128 v[212:215], v169 offset:3072
	ds_read_b128 v[216:219], v169 offset:4096
	ds_read_b128 v[220:223], v169 offset:5120
	ds_read_b128 v[224:227], v169 offset:6144
	ds_read_b128 v[228:231], v169 offset:7168
	global_load_lds_dwordx4 v[164:165], off
	v_lshl_add_u64 v[164:165], s[48:49], 0, v[150:151]
	s_add_i32 m0, s23, 0xe000
	s_nop 0
	global_load_lds_dwordx4 v[164:165], off
	s_waitcnt vmcnt(8)
	s_waitcnt lgkmcnt(0)
	s_barrier
; #define PG8_STAGE(bufoff, gbase, voff) do { _Pragma("unroll") for (int _i = 0; _i < 2; ++_i) \
;         __builtin_amdgcn_global_load_lds((const unsigned*)((const char*)(gbase) + (voff)[_i]), (LAS unsigned*)(lds + (bufoff) + ldsw + _i * 8192), 16, 0, 0); } while (0)
; #define PG8_LDA(dst, b, h) do { _Pragma("unroll") for (int m = 0; m < 4; ++m) _Pragma("unroll") for (int k = 0; k < 2; ++k) dst[m][k] = *(const LAS bf16x8*)(lds + PG8_SA(b, h) + aoff + m * 2048 + k * 1024); } while (0)
; #define PG8_LDB(dst, b, h) do { _Pragma("unroll") for (int n = 0; n < 2; ++n) _Pragma("unroll") for (int k = 0; k < 2; ++k) dst[n][k] = *(const LAS bf16x8*)(lds + PG8_SB(b, h) + boff + n * 2048 + k * 1024); } while (0)
; #define PG8_MMA(ai, bj, At, Bt) do { __builtin_amdgcn_s_setprio(1); _Pragma("unroll") for (int m = 0; m < 4; ++m) _Pragma("unroll") for (int n = 0; n < 2; ++n) _Pragma("unroll") for (int k = 0; k < 2; ++k) \
;         acc[ai][bj][m][n] = __builtin_amdgcn_mfma_f32_16x16x32_bf16(Bt[n][k], At[m][k], acc[ai][bj][m][n], 0, 0, 0); __builtin_amdgcn_s_setprio(0); } while (0)
; #define PG8_WAIT_V(n) asm volatile("s_waitcnt vmcnt(" #n ")" ::: "memory")
; #define PG8_WAIT_L(n) asm volatile("s_waitcnt lgkmcnt(" #n ")" ::: "memory")
; #define PG8_BAR __builtin_amdgcn_s_barrier()
; #define PG8_SCHED __builtin_amdgcn_sched_barrier(0)
; template <int GI>
; __device__ __forceinline__ void gemm_phase(LAS unsigned char* lds, unsigned char* ws, int G, int cblk) {
;     ...
;             PG8_LDB(B0, 0, 0); PG8_LDB(B1, 0, 1); PG8_SCHED; PG8_LDA(At, 0, 0); PG8_STAGE(PG8_SA(1, 1), a1 + hstepA, voffA);
;             PG8_WAIT_V(8); PG8_WAIT_L(0); PG8_BAR; PG8_MMA(0, 0, At, B0); PG8_MMA(0, 1, At, B1); PG8_BAR; PG8_SCHED;
;             PG8_LDA(At, 0, 1); PG8_STAGE(PG8_SB(0, 0), b2, voffB); PG8_STAGE(PG8_SB(0, 1), b2 + hstepB, voffB); PG8_STAGE(PG8_SA(0, 0), a2, voffA);
;             PG8_WAIT_V(8); PG8_WAIT_L(0); PG8_BAR; PG8_MMA(1, 0, At, B0); PG8_MMA(1, 1, At, B1); PG8_BAR; PG8_SCHED;
	s_setprio 1
	s_waitcnt lgkmcnt(0)
	v_mfma_f32_16x16x32_bf16 v[124:127], v[152:155], v[200:203], v[124:127]
	v_mfma_f32_16x16x32_bf16 v[120:123], v[172:175], v[200:203], v[120:123]
	v_mfma_f32_16x16x32_bf16 v[108:111], v[152:155], v[208:211], v[108:111]
	v_mfma_f32_16x16x32_bf16 v[104:107], v[172:175], v[208:211], v[104:107]
	v_mfma_f32_16x16x32_bf16 v[92:95], v[152:155], v[216:219], v[92:95]
	v_mfma_f32_16x16x32_bf16 v[88:91], v[172:175], v[216:219], v[88:91]
	v_mfma_f32_16x16x32_bf16 v[76:79], v[152:155], v[224:227], v[76:79]
	v_mfma_f32_16x16x32_bf16 v[72:75], v[172:175], v[224:227], v[72:75]
	v_mfma_f32_16x16x32_bf16 v[124:127], v[156:159], v[204:207], v[124:127]
	v_mfma_f32_16x16x32_bf16 v[120:123], v[176:179], v[204:207], v[120:123]
	v_mfma_f32_16x16x32_bf16 v[108:111], v[156:159], v[212:215], v[108:111]
	v_mfma_f32_16x16x32_bf16 v[104:107], v[176:179], v[212:215], v[104:107]
	v_mfma_f32_16x16x32_bf16 v[92:95], v[156:159], v[220:223], v[92:95]
	v_mfma_f32_16x16x32_bf16 v[88:91], v[176:179], v[220:223], v[88:91]
	v_mfma_f32_16x16x32_bf16 v[76:79], v[156:159], v[228:231], v[76:79]
	v_mfma_f32_16x16x32_bf16 v[72:75], v[176:179], v[228:231], v[72:75]
	s_setprio 0
	s_setprio 1
	v_mfma_f32_16x16x32_bf16 v[116:119], v[180:183], v[200:203], v[116:119]
	v_mfma_f32_16x16x32_bf16 v[112:115], v[192:195], v[200:203], v[112:115]
	v_mfma_f32_16x16x32_bf16 v[100:103], v[180:183], v[208:211], v[100:103]
	v_mfma_f32_16x16x32_bf16 v[96:99], v[192:195], v[208:211], v[96:99]
	v_mfma_f32_16x16x32_bf16 v[84:87], v[180:183], v[216:219], v[84:87]
	v_mfma_f32_16x16x32_bf16 v[80:83], v[192:195], v[216:219], v[80:83]
	v_mfma_f32_16x16x32_bf16 v[68:71], v[180:183], v[224:227], v[68:71]
	v_mfma_f32_16x16x32_bf16 v[64:67], v[192:195], v[224:227], v[64:67]
	v_mfma_f32_16x16x32_bf16 v[116:119], v[184:187], v[204:207], v[116:119]
	v_mfma_f32_16x16x32_bf16 v[112:115], v[196:199], v[204:207], v[112:115]
	v_mfma_f32_16x16x32_bf16 v[100:103], v[184:187], v[212:215], v[100:103]
	v_mfma_f32_16x16x32_bf16 v[96:99], v[196:199], v[212:215], v[96:99]
	v_mfma_f32_16x16x32_bf16 v[84:87], v[184:187], v[220:223], v[84:87]
	v_mfma_f32_16x16x32_bf16 v[80:83], v[196:199], v[220:223], v[80:83]
	v_mfma_f32_16x16x32_bf16 v[68:71], v[184:187], v[228:231], v[68:71]
	v_mfma_f32_16x16x32_bf16 v[64:67], v[196:199], v[228:231], v[64:67]
	s_setprio 0
	s_barrier
	s_add_i32 s17, s60, s22
	v_lshl_add_u64 v[164:165], s[50:51], 0, v[132:133]
	s_mov_b32 m0, s17
	ds_read_b128 v[200:203], v169 offset:16384
	ds_read_b128 v[204:207], v169 offset:17408
	ds_read_b128 v[208:211], v169 offset:18432
	ds_read_b128 v[212:215], v169 offset:19456
	ds_read_b128 v[216:219], v169 offset:20480
	ds_read_b128 v[220:223], v169 offset:21504
	ds_read_b128 v[224:227], v169 offset:22528
	ds_read_b128 v[228:231], v169 offset:23552
	global_load_lds_dwordx4 v[164:165], off
	s_add_i32 m0, s17, 0x2000
	s_add_u32 s64, s50, 0x80000
	v_lshl_add_u64 v[188:189], s[50:51], 0, v[136:137]
	s_addc_u32 s65, s51, 0
	s_add_i32 s17, s61, s22
	global_load_lds_dwordx4 v[188:189], off
	v_lshl_add_u64 v[232:233], s[64:65], 0, v[132:133]
	s_mov_b32 m0, s17
	v_lshl_add_u64 v[234:235], s[52:53], 0, v[134:135]
	global_load_lds_dwordx4 v[232:233], off
	v_lshl_add_u64 v[232:233], s[64:65], 0, v[136:137]
	s_add_i32 m0, s17, 0x2000
	s_nop 0
	global_load_lds_dwordx4 v[232:233], off
	v_lshl_add_u64 v[232:233], s[52:53], 0, v[130:131]
	s_mov_b32 m0, s23
	s_nop 0
	global_load_lds_dwordx4 v[232:233], off
	s_mov_b32 m0, s24
	s_nop 0
	global_load_lds_dwordx4 v[234:235], off
	s_waitcnt vmcnt(8)
	s_waitcnt lgkmcnt(0)
	s_barrier
	s_setprio 1
	s_waitcnt lgkmcnt(0)
	v_mfma_f32_16x16x32_bf16 v[60:63], v[152:155], v[200:203], v[60:63]
	v_mfma_f32_16x16x32_bf16 v[56:59], v[172:175], v[200:203], v[56:59]
	v_mfma_f32_16x16x32_bf16 v[44:47], v[152:155], v[208:211], v[44:47]
	v_mfma_f32_16x16x32_bf16 v[40:43], v[172:175], v[208:211], v[40:43]
	v_mfma_f32_16x16x32_bf16 v[28:31], v[152:155], v[216:219], v[28:31]
	v_mfma_f32_16x16x32_bf16 v[24:27], v[172:175], v[216:219], v[24:27]
	v_mfma_f32_16x16x32_bf16 v[12:15], v[152:155], v[224:227], v[12:15]
	v_mfma_f32_16x16x32_bf16 v[8:11], v[172:175], v[224:227], v[8:11]
	v_mfma_f32_16x16x32_bf16 v[60:63], v[156:159], v[204:207], v[60:63]
	v_mfma_f32_16x16x32_bf16 v[56:59], v[176:179], v[204:207], v[56:59]
	v_mfma_f32_16x16x32_bf16 v[44:47], v[156:159], v[212:215], v[44:47]
	v_mfma_f32_16x16x32_bf16 v[40:43], v[176:179], v[212:215], v[40:43]
	v_mfma_f32_16x16x32_bf16 v[28:31], v[156:159], v[220:223], v[28:31]
	v_mfma_f32_16x16x32_bf16 v[24:27], v[176:179], v[220:223], v[24:27]
	v_mfma_f32_16x16x32_bf16 v[12:15], v[156:159], v[228:231], v[12:15]
	v_mfma_f32_16x16x32_bf16 v[8:11], v[176:179], v[228:231], v[8:11]
	s_setprio 0
	s_setprio 1
	v_mfma_f32_16x16x32_bf16 v[52:55], v[180:183], v[200:203], v[52:55]
	v_mfma_f32_16x16x32_bf16 v[48:51], v[192:195], v[200:203], v[48:51]
	v_mfma_f32_16x16x32_bf16 v[36:39], v[180:183], v[208:211], v[36:39]
	v_mfma_f32_16x16x32_bf16 v[32:35], v[192:195], v[208:211], v[32:35]
	v_mfma_f32_16x16x32_bf16 v[20:23], v[180:183], v[216:219], v[20:23]
	v_mfma_f32_16x16x32_bf16 v[16:19], v[192:195], v[216:219], v[16:19]
	v_mfma_f32_16x16x32_bf16 v[4:7], v[180:183], v[224:227], v[4:7]
	v_mfma_f32_16x16x32_bf16 v[0:3], v[192:195], v[224:227], v[0:3]
	v_mfma_f32_16x16x32_bf16 v[52:55], v[184:187], v[204:207], v[52:55]
	v_mfma_f32_16x16x32_bf16 v[48:51], v[196:199], v[204:207], v[48:51]
	v_mfma_f32_16x16x32_bf16 v[36:39], v[184:187], v[212:215], v[36:39]
	v_mfma_f32_16x16x32_bf16 v[32:35], v[196:199], v[212:215], v[32:35]
	v_mfma_f32_16x16x32_bf16 v[20:23], v[184:187], v[220:223], v[20:23]
	v_mfma_f32_16x16x32_bf16 v[16:19], v[196:199], v[220:223], v[16:19]
	v_mfma_f32_16x16x32_bf16 v[4:7], v[184:187], v[228:231], v[4:7]
	v_mfma_f32_16x16x32_bf16 v[0:3], v[196:199], v[228:231], v[0:3]
	s_setprio 0
	s_barrier
; #define PG8_STAGE(bufoff, gbase, voff) do { _Pragma("unroll") for (int _i = 0; _i < 2; ++_i) \
;         __builtin_amdgcn_global_load_lds((const unsigned*)((const char*)(gbase) + (voff)[_i]), (LAS unsigned*)(lds + (bufoff) + ldsw + _i * 8192), 16, 0, 0); } while (0)
; #define PG8_LDA(dst, b, h) do { _Pragma("unroll") for (int m = 0; m < 4; ++m) _Pragma("unroll") for (int k = 0; k < 2; ++k) dst[m][k] = *(const LAS bf16x8*)(lds + PG8_SA(b, h) + aoff + m * 2048 + k * 1024); } while (0)
; #define PG8_LDB(dst, b, h) do { _Pragma("unroll") for (int n = 0; n < 2; ++n) _Pragma("unroll") for (int k = 0; k < 2; ++k) dst[n][k] = *(const LAS bf16x8*)(lds + PG8_SB(b, h) + boff + n * 2048 + k * 1024); } while (0)
; #define PG8_MMA(ai, bj, At, Bt) do { __builtin_amdgcn_s_setprio(1); _Pragma("unroll") for (int m = 0; m < 4; ++m) _Pragma("unroll") for (int n = 0; n < 2; ++n) _Pragma("unroll") for (int k = 0; k < 2; ++k) \
;         acc[ai][bj][m][n] = __builtin_amdgcn_mfma_f32_16x16x32_bf16(Bt[n][k], At[m][k], acc[ai][bj][m][n], 0, 0, 0); __builtin_amdgcn_s_setprio(0); } while (0)
; #define PG8_WAIT_V(n) asm volatile("s_waitcnt vmcnt(" #n ")" ::: "memory")
; #define PG8_WAIT_L(n) asm volatile("s_waitcnt lgkmcnt(" #n ")" ::: "memory")
; #define PG8_BAR __builtin_amdgcn_s_barrier()
; #define PG8_SCHED __builtin_amdgcn_sched_barrier(0)
; template <int GI>
; __device__ __forceinline__ void gemm_phase(LAS unsigned char* lds, unsigned char* ws, int G, int cblk) {
;     ...
;             PG8_LDB(B0, 1, 0); PG8_LDB(B1, 1, 1); PG8_SCHED; PG8_LDA(At, 1, 0); PG8_STAGE(PG8_SA(0, 1), a2 + hstepA, voffA);
;             PG8_WAIT_V(8); PG8_WAIT_L(0); PG8_BAR; PG8_MMA(0, 0, At, B0); PG8_MMA(0, 1, At, B1); PG8_BAR; PG8_SCHED;
	s_add_i32 s17, 0, 0x18000
	s_add_i32 s33, 0, 0x1c000
	v_add_u32_e32 v176, s17, v161
	v_add_u32_e32 v191, s33, v161
	ds_read_b128 v[152:155], v176
	ds_read_b128 v[156:159], v176 offset:1024
	ds_read_b128 v[172:175], v176 offset:2048
	ds_read_b128 v[176:179], v176 offset:3072
	ds_read_b128 v[180:183], v191
	ds_read_b128 v[184:187], v191 offset:1024
	ds_read_b128 v[192:195], v191 offset:2048
	ds_read_b128 v[196:199], v191 offset:3072
	s_add_u32 s52, s52, 0x80000
	s_addc_u32 s53, s53, 0
	s_mov_b32 m0, s25
	v_lshl_add_u64 v[236:237], s[52:53], 0, v[130:131]
	ds_read_b128 v[200:203], v169 offset:32768
	ds_read_b128 v[204:207], v169 offset:33792
	ds_read_b128 v[208:211], v169 offset:34816
	ds_read_b128 v[212:215], v169 offset:35840
	ds_read_b128 v[216:219], v169 offset:36864
	ds_read_b128 v[220:223], v169 offset:37888
	ds_read_b128 v[224:227], v169 offset:38912
	ds_read_b128 v[228:231], v169 offset:39936
	global_load_lds_dwordx4 v[236:237], off
	v_lshl_add_u64 v[236:237], s[52:53], 0, v[134:135]
	s_mov_b32 m0, s26
	s_nop 0
	global_load_lds_dwordx4 v[236:237], off
	s_waitcnt vmcnt(8)
	s_waitcnt lgkmcnt(0)
	s_barrier
	s_setprio 1
	s_waitcnt lgkmcnt(0)
	v_mfma_f32_16x16x32_bf16 v[124:127], v[152:155], v[200:203], v[124:127]
	v_mfma_f32_16x16x32_bf16 v[120:123], v[172:175], v[200:203], v[120:123]
	v_mfma_f32_16x16x32_bf16 v[108:111], v[152:155], v[208:211], v[108:111]
	v_mfma_f32_16x16x32_bf16 v[104:107], v[172:175], v[208:211], v[104:107]
	v_mfma_f32_16x16x32_bf16 v[92:95], v[152:155], v[216:219], v[92:95]
	v_mfma_f32_16x16x32_bf16 v[88:91], v[172:175], v[216:219], v[88:91]
	v_mfma_f32_16x16x32_bf16 v[76:79], v[152:155], v[224:227], v[76:79]
	v_mfma_f32_16x16x32_bf16 v[72:75], v[172:175], v[224:227], v[72:75]
	v_mfma_f32_16x16x32_bf16 v[124:127], v[156:159], v[204:207], v[124:127]
	v_mfma_f32_16x16x32_bf16 v[120:123], v[176:179], v[204:207], v[120:123]
	v_mfma_f32_16x16x32_bf16 v[108:111], v[156:159], v[212:215], v[108:111]
	v_mfma_f32_16x16x32_bf16 v[104:107], v[176:179], v[212:215], v[104:107]
	v_mfma_f32_16x16x32_bf16 v[92:95], v[156:159], v[220:223], v[92:95]
	v_mfma_f32_16x16x32_bf16 v[88:91], v[176:179], v[220:223], v[88:91]
	v_mfma_f32_16x16x32_bf16 v[76:79], v[156:159], v[228:231], v[76:79]
	v_mfma_f32_16x16x32_bf16 v[72:75], v[176:179], v[228:231], v[72:75]
	s_setprio 0
	s_setprio 1
	v_mfma_f32_16x16x32_bf16 v[116:119], v[180:183], v[200:203], v[116:119]
	v_mfma_f32_16x16x32_bf16 v[112:115], v[192:195], v[200:203], v[112:115]
	v_mfma_f32_16x16x32_bf16 v[100:103], v[180:183], v[208:211], v[100:103]
	v_mfma_f32_16x16x32_bf16 v[96:99], v[192:195], v[208:211], v[96:99]
	v_mfma_f32_16x16x32_bf16 v[84:87], v[180:183], v[216:219], v[84:87]
	v_mfma_f32_16x16x32_bf16 v[80:83], v[192:195], v[216:219], v[80:83]
	v_mfma_f32_16x16x32_bf16 v[68:71], v[180:183], v[224:227], v[68:71]
	v_mfma_f32_16x16x32_bf16 v[64:67], v[192:195], v[224:227], v[64:67]
	v_mfma_f32_16x16x32_bf16 v[116:119], v[184:187], v[204:207], v[116:119]
	v_mfma_f32_16x16x32_bf16 v[112:115], v[196:199], v[204:207], v[112:115]
	v_mfma_f32_16x16x32_bf16 v[100:103], v[184:187], v[212:215], v[100:103]
	v_mfma_f32_16x16x32_bf16 v[96:99], v[196:199], v[212:215], v[96:99]
	v_mfma_f32_16x16x32_bf16 v[84:87], v[184:187], v[220:223], v[84:87]
	v_mfma_f32_16x16x32_bf16 v[80:83], v[196:199], v[220:223], v[80:83]
	v_mfma_f32_16x16x32_bf16 v[68:71], v[184:187], v[228:231], v[68:71]
	v_mfma_f32_16x16x32_bf16 v[64:67], v[196:199], v[228:231], v[64:67]
	s_setprio 0
	s_barrier
; #define PG8_STAGE(bufoff, gbase, voff) do { _Pragma("unroll") for (int _i = 0; _i < 2; ++_i) \
;         __builtin_amdgcn_global_load_lds((const unsigned*)((const char*)(gbase) + (voff)[_i]), (LAS unsigned*)(lds + (bufoff) + ldsw + _i * 8192), 16, 0, 0); } while (0)
; #define PG8_LDA(dst, b, h) do { _Pragma("unroll") for (int m = 0; m < 4; ++m) _Pragma("unroll") for (int k = 0; k < 2; ++k) dst[m][k] = *(const LAS bf16x8*)(lds + PG8_SA(b, h) + aoff + m * 2048 + k * 1024); } while (0)
; #define PG8_MMA(ai, bj, At, Bt) do { __builtin_amdgcn_s_setprio(1); _Pragma("unroll") for (int m = 0; m < 4; ++m) _Pragma("unroll") for (int n = 0; n < 2; ++n) _Pragma("unroll") for (int k = 0; k < 2; ++k) \
;         acc[ai][bj][m][n] = __builtin_amdgcn_mfma_f32_16x16x32_bf16(Bt[n][k], At[m][k], acc[ai][bj][m][n], 0, 0, 0); __builtin_amdgcn_s_setprio(0); } while (0)
; #define PG8_WAIT_V(n) asm volatile("s_waitcnt vmcnt(" #n ")" ::: "memory")
; #define PG8_WAIT_L(n) asm volatile("s_waitcnt lgkmcnt(" #n ")" ::: "memory")
; #define PG8_BAR __builtin_amdgcn_s_barrier()
; #define PG8_SCHED __builtin_amdgcn_sched_barrier(0)
; template <int GI>
; __device__ __forceinline__ void gemm_phase(LAS unsigned char* lds, unsigned char* ws, int G, int cblk) {
;     ...
;             PG8_LDA(At, 1, 1); PG8_STAGE(PG8_SB(1, 0), b3, voffB); PG8_STAGE(PG8_SB(1, 1), b3 + hstepB, voffB); PG8_STAGE(PG8_SA(1, 0), a3, voffA);
;             PG8_WAIT_V(8); PG8_WAIT_L(0); PG8_BAR; PG8_MMA(1, 0, At, B0); PG8_MMA(1, 1, At, B1); PG8_BAR; PG8_SCHED;
;         }
	s_add_i32 s17, s17, s22
	v_lshl_add_u64 v[164:165], v[164:165], 0, s[18:19]
	s_mov_b32 m0, s17
	ds_read_b128 v[200:203], v169 offset:49152
	ds_read_b128 v[204:207], v169 offset:50176
	ds_read_b128 v[208:211], v169 offset:51200
	ds_read_b128 v[212:215], v169 offset:52224
	ds_read_b128 v[216:219], v169 offset:53248
	ds_read_b128 v[220:223], v169 offset:54272
	ds_read_b128 v[224:227], v169 offset:55296
	ds_read_b128 v[228:231], v169 offset:56320
	global_load_lds_dwordx4 v[164:165], off
	s_add_i32 m0, s17, 0x2000
	s_add_u32 s50, s50, 0x80080
	v_lshl_add_u64 v[164:165], v[188:189], 0, s[18:19]
	s_addc_u32 s51, s51, 0
	s_add_i32 s17, s33, s22
	global_load_lds_dwordx4 v[164:165], off
	v_lshl_add_u64 v[164:165], s[50:51], 0, v[132:133]
	s_mov_b32 m0, s17
	s_nop 0
	global_load_lds_dwordx4 v[164:165], off
	v_lshl_add_u64 v[164:165], s[50:51], 0, v[136:137]
	s_add_i32 m0, s17, 0x2000
	s_nop 0
	global_load_lds_dwordx4 v[164:165], off
	v_lshl_add_u64 v[164:165], v[232:233], 0, s[18:19]
	s_mov_b32 m0, s35
	s_nop 0
	global_load_lds_dwordx4 v[164:165], off
	v_lshl_add_u64 v[164:165], v[234:235], 0, s[18:19]
	s_mov_b32 m0, s55
	s_nop 0
	global_load_lds_dwordx4 v[164:165], off
	s_waitcnt vmcnt(8)
	s_waitcnt lgkmcnt(0)
	s_barrier
	s_setprio 1
	s_waitcnt lgkmcnt(0)
	v_mfma_f32_16x16x32_bf16 v[60:63], v[152:155], v[200:203], v[60:63]
	v_mfma_f32_16x16x32_bf16 v[56:59], v[172:175], v[200:203], v[56:59]
	s_add_i32 s16, s16, 2
	s_add_u32 s48, s48, 0x100
	s_addc_u32 s49, s49, 0
	s_add_u32 s0, s0, 0x100
	s_addc_u32 s1, s1, 0
	v_mfma_f32_16x16x32_bf16 v[44:47], v[152:155], v[208:211], v[44:47]
	v_mfma_f32_16x16x32_bf16 v[40:43], v[172:175], v[208:211], v[40:43]
	v_mfma_f32_16x16x32_bf16 v[28:31], v[152:155], v[216:219], v[28:31]
	v_mfma_f32_16x16x32_bf16 v[24:27], v[172:175], v[216:219], v[24:27]
	v_mfma_f32_16x16x32_bf16 v[12:15], v[152:155], v[224:227], v[12:15]
	v_mfma_f32_16x16x32_bf16 v[8:11], v[172:175], v[224:227], v[8:11]
	v_mfma_f32_16x16x32_bf16 v[60:63], v[156:159], v[204:207], v[60:63]
	v_mfma_f32_16x16x32_bf16 v[56:59], v[176:179], v[204:207], v[56:59]
	v_mfma_f32_16x16x32_bf16 v[44:47], v[156:159], v[212:215], v[44:47]
	v_mfma_f32_16x16x32_bf16 v[40:43], v[176:179], v[212:215], v[40:43]
	v_mfma_f32_16x16x32_bf16 v[28:31], v[156:159], v[220:223], v[28:31]
	v_mfma_f32_16x16x32_bf16 v[24:27], v[176:179], v[220:223], v[24:27]
	v_mfma_f32_16x16x32_bf16 v[12:15], v[156:159], v[228:231], v[12:15]
	v_mfma_f32_16x16x32_bf16 v[8:11], v[176:179], v[228:231], v[8:11]
	s_setprio 0
	s_setprio 1
	v_mfma_f32_16x16x32_bf16 v[52:55], v[180:183], v[200:203], v[52:55]
	v_mfma_f32_16x16x32_bf16 v[48:51], v[192:195], v[200:203], v[48:51]
	v_mfma_f32_16x16x32_bf16 v[36:39], v[180:183], v[208:211], v[36:39]
	v_mfma_f32_16x16x32_bf16 v[32:35], v[192:195], v[208:211], v[32:35]
	v_mfma_f32_16x16x32_bf16 v[20:23], v[180:183], v[216:219], v[20:23]
	v_mfma_f32_16x16x32_bf16 v[16:19], v[192:195], v[216:219], v[16:19]
	v_mfma_f32_16x16x32_bf16 v[4:7], v[180:183], v[224:227], v[4:7]
	v_mfma_f32_16x16x32_bf16 v[0:3], v[192:195], v[224:227], v[0:3]
	v_mfma_f32_16x16x32_bf16 v[52:55], v[184:187], v[204:207], v[52:55]
	v_mfma_f32_16x16x32_bf16 v[48:51], v[196:199], v[204:207], v[48:51]
	v_mfma_f32_16x16x32_bf16 v[36:39], v[184:187], v[212:215], v[36:39]
	v_mfma_f32_16x16x32_bf16 v[32:35], v[196:199], v[212:215], v[32:35]
	v_mfma_f32_16x16x32_bf16 v[20:23], v[184:187], v[220:223], v[20:23]
	v_mfma_f32_16x16x32_bf16 v[16:19], v[196:199], v[220:223], v[16:19]
	v_mfma_f32_16x16x32_bf16 v[4:7], v[184:187], v[228:231], v[4:7]
	v_mfma_f32_16x16x32_bf16 v[0:3], v[196:199], v[228:231], v[0:3]
	s_setprio 0
	s_barrier
	s_cmp_gt_u32 s16, 29
	s_cbranch_scc0 .LBB0_565

; #define PG8_STAGE(bufoff, gbase, voff) do { _Pragma("unroll") for (int _i = 0; _i < 2; ++_i) \
;         __builtin_amdgcn_global_load_lds((const unsigned*)((const char*)(gbase) + (voff)[_i]), (LAS unsigned*)(lds + (bufoff) + ldsw + _i * 8192), 16, 0, 0); } while (0)
; #define PG8_LDA(dst, b, h) do { _Pragma("unroll") for (int m = 0; m < 4; ++m) _Pragma("unroll") for (int k = 0; k < 2; ++k) dst[m][k] = *(const LAS bf16x8*)(lds + PG8_SA(b, h) + aoff + m * 2048 + k * 1024); } while (0)
; #define PG8_LDB(dst, b, h) do { _Pragma("unroll") for (int n = 0; n < 2; ++n) _Pragma("unroll") for (int k = 0; k < 2; ++k) dst[n][k] = *(const LAS bf16x8*)(lds + PG8_SB(b, h) + boff + n * 2048 + k * 1024); } while (0)
; #define PG8_MMA(ai, bj, At, Bt) do { __builtin_amdgcn_s_setprio(1); _Pragma("unroll") for (int m = 0; m < 4; ++m) _Pragma("unroll") for (int n = 0; n < 2; ++n) _Pragma("unroll") for (int k = 0; k < 2; ++k) \
;         acc[ai][bj][m][n] = __builtin_amdgcn_mfma_f32_16x16x32_bf16(Bt[n][k], At[m][k], acc[ai][bj][m][n], 0, 0, 0); __builtin_amdgcn_s_setprio(0); } while (0)
; #define PG8_WAIT_V(n) asm volatile("s_waitcnt vmcnt(" #n ")" ::: "memory")
; #define PG8_BAR __builtin_amdgcn_s_barrier()
; template <int GI>
; __device__ __forceinline__ void gemm_phase(LAS unsigned char* lds, unsigned char* ws, int G, int cblk) {
;     ...
;     for (;;) {
;         const bool has_next = sched_next<GI>(ws, ui + 1, G, cblk, nxt);
;         const char* nA = has_next ? nxt.A : cA; const char* nB = has_next ? nxt.B : cB;
;         for (int t = 0; t < nt; t += 2) {
;             const bool last = (t == nt - 2);
;             const char* a1 = cA + (size_t)(t + 1) * kstep;
;             const char* a2 = last ? nA : cA + (size_t)(t + 2) * kstep; const char* b2 = last ? nB : cB + (size_t)(t + 2) * kstep;
;             const char* a3 = a2 + kstep; const char* b3 = b2 + kstep;
;             PG8_LDB(B0, 0, 0); PG8_LDB(B1, 0, 1); PG8_SCHED; PG8_LDA(At, 0, 0); PG8_STAGE(PG8_SA(1, 1), a1 + hstepA, voffA);
;             PG8_WAIT_V(8); PG8_WAIT_L(0); PG8_BAR; PG8_MMA(0, 0, At, B0); PG8_MMA(0, 1, At, B1); PG8_BAR; PG8_SCHED;
;             PG8_LDA(At, 0, 1); PG8_STAGE(PG8_SB(0, 0), b2, voffB); PG8_STAGE(PG8_SB(0, 1), b2 + hstepB, voffB); PG8_STAGE(PG8_SA(0, 0), a2, voffA);
;             PG8_WAIT_V(8); PG8_WAIT_L(0); PG8_BAR; PG8_MMA(1, 0, At, B0); PG8_MMA(1, 1, At, B1); PG8_BAR; PG8_SCHED;
.LBB0_696:
	s_add_u32 s44, s44, 0x40080
	s_addc_u32 s45, s45, 0
	s_add_u32 s16, s46, 0x100
	s_addc_u32 s17, s47, 0
	s_mov_b32 s19, -2
	ds_read_b128 v[156:159], v153
	ds_read_b128 v[164:167], v153 offset:1024
	ds_read_b128 v[168:171], v153 offset:2048
	ds_read_b128 v[172:175], v153 offset:3072
	ds_read_b128 v[176:179], v154
	ds_read_b128 v[180:183], v154 offset:1024
	ds_read_b128 v[184:187], v154 offset:2048
	ds_read_b128 v[192:195], v154 offset:3072
	s_add_u32 s34, s44, 0xfffc0080
	s_addc_u32 s46, s45, -1
	s_cmp_eq_u32 s19, 12
	s_cselect_b32 s49, s39, s46
	s_cselect_b32 s48, s38, s34
	s_cselect_b32 s47, s41, s17
	s_cselect_b32 s46, s40, s16
	v_lshl_add_u64 v[188:189], s[44:45], 0, v[140:141]
	s_add_i32 m0, s25, 0xc000
	ds_read_b128 v[196:199], v155
	ds_read_b128 v[200:203], v155 offset:1024
	ds_read_b128 v[204:207], v155 offset:2048
	ds_read_b128 v[208:211], v155 offset:3072
	ds_read_b128 v[212:215], v155 offset:4096
	ds_read_b128 v[216:219], v155 offset:5120
	ds_read_b128 v[220:223], v155 offset:6144
	ds_read_b128 v[224:227], v155 offset:7168
	global_load_lds_dwordx4 v[188:189], off
	v_lshl_add_u64 v[188:189], s[44:45], 0, v[142:143]
	s_add_i32 m0, s25, 0xe000
	s_nop 0
	global_load_lds_dwordx4 v[188:189], off
	s_waitcnt vmcnt(8)
	s_waitcnt lgkmcnt(0)
	s_barrier
	s_setprio 1
	s_waitcnt lgkmcnt(0)
	v_mfma_f32_16x16x32_bf16 v[124:127], v[156:159], v[196:199], 0
	v_mfma_f32_16x16x32_bf16 v[120:123], v[168:171], v[196:199], 0
	v_mfma_f32_16x16x32_bf16 v[116:119], v[156:159], v[204:207], 0
	v_mfma_f32_16x16x32_bf16 v[112:115], v[168:171], v[204:207], 0
	v_mfma_f32_16x16x32_bf16 v[100:103], v[156:159], v[212:215], 0
	v_mfma_f32_16x16x32_bf16 v[96:99], v[168:171], v[212:215], 0
	v_mfma_f32_16x16x32_bf16 v[84:87], v[156:159], v[220:223], 0
	v_mfma_f32_16x16x32_bf16 v[80:83], v[168:171], v[220:223], 0
	v_mfma_f32_16x16x32_bf16 v[124:127], v[164:167], v[200:203], v[124:127]
	v_mfma_f32_16x16x32_bf16 v[120:123], v[172:175], v[200:203], v[120:123]
	v_mfma_f32_16x16x32_bf16 v[116:119], v[164:167], v[208:211], v[116:119]
	v_mfma_f32_16x16x32_bf16 v[112:115], v[172:175], v[208:211], v[112:115]
	v_mfma_f32_16x16x32_bf16 v[100:103], v[164:167], v[216:219], v[100:103]
	v_mfma_f32_16x16x32_bf16 v[96:99], v[172:175], v[216:219], v[96:99]
	v_mfma_f32_16x16x32_bf16 v[84:87], v[164:167], v[224:227], v[84:87]
	v_mfma_f32_16x16x32_bf16 v[80:83], v[172:175], v[224:227], v[80:83]
	s_setprio 0
	s_setprio 1
	v_mfma_f32_16x16x32_bf16 v[108:111], v[176:179], v[196:199], 0
	v_mfma_f32_16x16x32_bf16 v[104:107], v[184:187], v[196:199], 0
	v_mfma_f32_16x16x32_bf16 v[92:95], v[176:179], v[204:207], 0
	v_mfma_f32_16x16x32_bf16 v[88:91], v[184:187], v[204:207], 0
	v_mfma_f32_16x16x32_bf16 v[76:79], v[176:179], v[212:215], 0
	v_mfma_f32_16x16x32_bf16 v[72:75], v[184:187], v[212:215], 0
	v_mfma_f32_16x16x32_bf16 v[68:71], v[176:179], v[220:223], 0
	v_mfma_f32_16x16x32_bf16 v[64:67], v[184:187], v[220:223], 0
	v_mfma_f32_16x16x32_bf16 v[108:111], v[180:183], v[200:203], v[108:111]
	v_mfma_f32_16x16x32_bf16 v[104:107], v[192:195], v[200:203], v[104:107]
	v_mfma_f32_16x16x32_bf16 v[92:95], v[180:183], v[208:211], v[92:95]
	v_mfma_f32_16x16x32_bf16 v[88:91], v[192:195], v[208:211], v[88:91]
	v_mfma_f32_16x16x32_bf16 v[76:79], v[180:183], v[216:219], v[76:79]
	v_mfma_f32_16x16x32_bf16 v[72:75], v[192:195], v[216:219], v[72:75]
	v_mfma_f32_16x16x32_bf16 v[68:71], v[180:183], v[224:227], v[68:71]
	v_mfma_f32_16x16x32_bf16 v[64:67], v[192:195], v[224:227], v[64:67]
	s_setprio 0
	s_barrier
	s_add_i32 s34, s53, s0
	v_lshl_add_u64 v[188:189], s[46:47], 0, v[132:133]
	s_mov_b32 m0, s34
	ds_read_b128 v[196:199], v155 offset:16384
	ds_read_b128 v[200:203], v155 offset:17408
	ds_read_b128 v[204:207], v155 offset:18432
	ds_read_b128 v[208:211], v155 offset:19456
	ds_read_b128 v[212:215], v155 offset:20480
	ds_read_b128 v[216:219], v155 offset:21504
	ds_read_b128 v[220:223], v155 offset:22528
	ds_read_b128 v[224:227], v155 offset:23552
	global_load_lds_dwordx4 v[188:189], off
	s_add_i32 m0, s34, 0x2000
	s_add_u32 s58, s46, 0x40000
	v_lshl_add_u64 v[228:229], s[46:47], 0, v[136:137]
	s_addc_u32 s59, s47, 0
	s_add_i32 s34, s55, s0
	global_load_lds_dwordx4 v[228:229], off
	v_lshl_add_u64 v[230:231], s[58:59], 0, v[132:133]
	s_mov_b32 m0, s34
	v_lshl_add_u64 v[232:233], s[48:49], 0, v[134:135]
	global_load_lds_dwordx4 v[230:231], off
	v_lshl_add_u64 v[230:231], s[58:59], 0, v[136:137]
	s_add_i32 m0, s34, 0x2000
	s_nop 0
	global_load_lds_dwordx4 v[230:231], off
	v_lshl_add_u64 v[230:231], s[48:49], 0, v[130:131]
	s_mov_b32 m0, s25
	s_nop 0
	global_load_lds_dwordx4 v[230:231], off
	s_mov_b32 m0, s26
	s_nop 0
	global_load_lds_dwordx4 v[232:233], off
	s_waitcnt vmcnt(8)
	s_waitcnt lgkmcnt(0)
	s_barrier
; #define PG8_STAGE(bufoff, gbase, voff) do { _Pragma("unroll") for (int _i = 0; _i < 2; ++_i) \
;         __builtin_amdgcn_global_load_lds((const unsigned*)((const char*)(gbase) + (voff)[_i]), (LAS unsigned*)(lds + (bufoff) + ldsw + _i * 8192), 16, 0, 0); } while (0)
; #define PG8_LDA(dst, b, h) do { _Pragma("unroll") for (int m = 0; m < 4; ++m) _Pragma("unroll") for (int k = 0; k < 2; ++k) dst[m][k] = *(const LAS bf16x8*)(lds + PG8_SA(b, h) + aoff + m * 2048 + k * 1024); } while (0)
; #define PG8_LDB(dst, b, h) do { _Pragma("unroll") for (int n = 0; n < 2; ++n) _Pragma("unroll") for (int k = 0; k < 2; ++k) dst[n][k] = *(const LAS bf16x8*)(lds + PG8_SB(b, h) + boff + n * 2048 + k * 1024); } while (0)
; #define PG8_MMA(ai, bj, At, Bt) do { __builtin_amdgcn_s_setprio(1); _Pragma("unroll") for (int m = 0; m < 4; ++m) _Pragma("unroll") for (int n = 0; n < 2; ++n) _Pragma("unroll") for (int k = 0; k < 2; ++k) \
;         acc[ai][bj][m][n] = __builtin_amdgcn_mfma_f32_16x16x32_bf16(Bt[n][k], At[m][k], acc[ai][bj][m][n], 0, 0, 0); __builtin_amdgcn_s_setprio(0); } while (0)
; #define PG8_WAIT_V(n) asm volatile("s_waitcnt vmcnt(" #n ")" ::: "memory")
; #define PG8_WAIT_L(n) asm volatile("s_waitcnt lgkmcnt(" #n ")" ::: "memory")
; #define PG8_BAR __builtin_amdgcn_s_barrier()
; #define PG8_SCHED __builtin_amdgcn_sched_barrier(0)
; template <int GI>
; __device__ __forceinline__ void gemm_phase(LAS unsigned char* lds, unsigned char* ws, int G, int cblk) {
;     ...
;             PG8_WAIT_V(8); PG8_WAIT_L(0); PG8_BAR; PG8_MMA(1, 0, At, B0); PG8_MMA(1, 1, At, B1); PG8_BAR; PG8_SCHED;
;             PG8_LDB(B0, 1, 0); PG8_LDB(B1, 1, 1); PG8_SCHED; PG8_LDA(At, 1, 0); PG8_STAGE(PG8_SA(0, 1), a2 + hstepA, voffA);
;             PG8_WAIT_V(8); PG8_WAIT_L(0); PG8_BAR; PG8_MMA(0, 0, At, B0); PG8_MMA(0, 1, At, B1); PG8_BAR; PG8_SCHED;
	s_setprio 1
	s_waitcnt lgkmcnt(0)
	v_mfma_f32_16x16x32_bf16 v[60:63], v[156:159], v[196:199], 0
	v_mfma_f32_16x16x32_bf16 v[56:59], v[168:171], v[196:199], 0
	v_mfma_f32_16x16x32_bf16 v[52:55], v[156:159], v[204:207], 0
	v_mfma_f32_16x16x32_bf16 v[48:51], v[168:171], v[204:207], 0
	v_mfma_f32_16x16x32_bf16 v[36:39], v[156:159], v[212:215], 0
	v_mfma_f32_16x16x32_bf16 v[32:35], v[168:171], v[212:215], 0
	v_mfma_f32_16x16x32_bf16 v[20:23], v[156:159], v[220:223], 0
	v_mfma_f32_16x16x32_bf16 v[16:19], v[168:171], v[220:223], 0
	v_mfma_f32_16x16x32_bf16 v[60:63], v[164:167], v[200:203], v[60:63]
	v_mfma_f32_16x16x32_bf16 v[56:59], v[172:175], v[200:203], v[56:59]
	v_mfma_f32_16x16x32_bf16 v[52:55], v[164:167], v[208:211], v[52:55]
	v_mfma_f32_16x16x32_bf16 v[48:51], v[172:175], v[208:211], v[48:51]
	v_mfma_f32_16x16x32_bf16 v[36:39], v[164:167], v[216:219], v[36:39]
	v_mfma_f32_16x16x32_bf16 v[32:35], v[172:175], v[216:219], v[32:35]
	v_mfma_f32_16x16x32_bf16 v[20:23], v[164:167], v[224:227], v[20:23]
	v_mfma_f32_16x16x32_bf16 v[16:19], v[172:175], v[224:227], v[16:19]
	s_setprio 0
	s_setprio 1
	v_mfma_f32_16x16x32_bf16 v[44:47], v[176:179], v[196:199], 0
	v_mfma_f32_16x16x32_bf16 v[40:43], v[184:187], v[196:199], 0
	v_mfma_f32_16x16x32_bf16 v[28:31], v[176:179], v[204:207], 0
	v_mfma_f32_16x16x32_bf16 v[24:27], v[184:187], v[204:207], 0
	v_mfma_f32_16x16x32_bf16 v[12:15], v[176:179], v[212:215], 0
	v_mfma_f32_16x16x32_bf16 v[8:11], v[184:187], v[212:215], 0
	v_mfma_f32_16x16x32_bf16 v[4:7], v[176:179], v[220:223], 0
	v_mfma_f32_16x16x32_bf16 v[0:3], v[184:187], v[220:223], 0
	v_mfma_f32_16x16x32_bf16 v[44:47], v[180:183], v[200:203], v[44:47]
	v_mfma_f32_16x16x32_bf16 v[40:43], v[192:195], v[200:203], v[40:43]
	v_mfma_f32_16x16x32_bf16 v[28:31], v[180:183], v[208:211], v[28:31]
	v_mfma_f32_16x16x32_bf16 v[24:27], v[192:195], v[208:211], v[24:27]
	v_mfma_f32_16x16x32_bf16 v[12:15], v[180:183], v[216:219], v[12:15]
	v_mfma_f32_16x16x32_bf16 v[8:11], v[192:195], v[216:219], v[8:11]
	v_mfma_f32_16x16x32_bf16 v[4:7], v[180:183], v[224:227], v[4:7]
	v_mfma_f32_16x16x32_bf16 v[0:3], v[192:195], v[224:227], v[0:3]
	s_setprio 0
	s_barrier
	s_add_i32 s34, 0, 0x18000
	v_add_u32_e32 v161, s34, v152
	s_add_i32 s57, 0, 0x1c000
	ds_read_b128 v[156:159], v161
	ds_read_b128 v[164:167], v161 offset:1024
	ds_read_b128 v[168:171], v161 offset:2048
	ds_read_b128 v[172:175], v161 offset:3072
	v_add_u32_e32 v161, s57, v152
	ds_read_b128 v[176:179], v161
	ds_read_b128 v[180:183], v161 offset:1024
	ds_read_b128 v[184:187], v161 offset:2048
	ds_read_b128 v[192:195], v161 offset:3072
	s_add_u32 s48, s48, 0x40000
	s_addc_u32 s49, s49, 0
	s_mov_b32 m0, s27
	v_lshl_add_u64 v[234:235], s[48:49], 0, v[130:131]
	ds_read_b128 v[196:199], v155 offset:32768
	ds_read_b128 v[200:203], v155 offset:33792
	ds_read_b128 v[204:207], v155 offset:34816
	ds_read_b128 v[208:211], v155 offset:35840
	ds_read_b128 v[212:215], v155 offset:36864
	ds_read_b128 v[216:219], v155 offset:37888
	ds_read_b128 v[220:223], v155 offset:38912
	ds_read_b128 v[224:227], v155 offset:39936
	global_load_lds_dwordx4 v[234:235], off
	v_lshl_add_u64 v[234:235], s[48:49], 0, v[134:135]
	s_mov_b32 m0, s33
	s_nop 0
	global_load_lds_dwordx4 v[234:235], off
	s_waitcnt vmcnt(8)
	s_waitcnt lgkmcnt(0)
	s_barrier
	s_setprio 1
	s_waitcnt lgkmcnt(0)
	v_mfma_f32_16x16x32_bf16 v[124:127], v[156:159], v[196:199], v[124:127]
	v_mfma_f32_16x16x32_bf16 v[120:123], v[168:171], v[196:199], v[120:123]
	v_mfma_f32_16x16x32_bf16 v[116:119], v[156:159], v[204:207], v[116:119]
	v_mfma_f32_16x16x32_bf16 v[112:115], v[168:171], v[204:207], v[112:115]
	v_mfma_f32_16x16x32_bf16 v[100:103], v[156:159], v[212:215], v[100:103]
	v_mfma_f32_16x16x32_bf16 v[96:99], v[168:171], v[212:215], v[96:99]
	v_mfma_f32_16x16x32_bf16 v[84:87], v[156:159], v[220:223], v[84:87]
	v_mfma_f32_16x16x32_bf16 v[80:83], v[168:171], v[220:223], v[80:83]
	v_mfma_f32_16x16x32_bf16 v[124:127], v[164:167], v[200:203], v[124:127]
	v_mfma_f32_16x16x32_bf16 v[120:123], v[172:175], v[200:203], v[120:123]
	v_mfma_f32_16x16x32_bf16 v[116:119], v[164:167], v[208:211], v[116:119]
	v_mfma_f32_16x16x32_bf16 v[112:115], v[172:175], v[208:211], v[112:115]
	v_mfma_f32_16x16x32_bf16 v[100:103], v[164:167], v[216:219], v[100:103]
	v_mfma_f32_16x16x32_bf16 v[96:99], v[172:175], v[216:219], v[96:99]
	v_mfma_f32_16x16x32_bf16 v[84:87], v[164:167], v[224:227], v[84:87]
	v_mfma_f32_16x16x32_bf16 v[80:83], v[172:175], v[224:227], v[80:83]
	s_setprio 0
	s_setprio 1
	v_mfma_f32_16x16x32_bf16 v[108:111], v[176:179], v[196:199], v[108:111]
	v_mfma_f32_16x16x32_bf16 v[104:107], v[184:187], v[196:199], v[104:107]
	v_mfma_f32_16x16x32_bf16 v[92:95], v[176:179], v[204:207], v[92:95]
	v_mfma_f32_16x16x32_bf16 v[88:91], v[184:187], v[204:207], v[88:91]
	v_mfma_f32_16x16x32_bf16 v[76:79], v[176:179], v[212:215], v[76:79]
	v_mfma_f32_16x16x32_bf16 v[72:75], v[184:187], v[212:215], v[72:75]
	v_mfma_f32_16x16x32_bf16 v[68:71], v[176:179], v[220:223], v[68:71]
	v_mfma_f32_16x16x32_bf16 v[64:67], v[184:187], v[220:223], v[64:67]
	v_mfma_f32_16x16x32_bf16 v[108:111], v[180:183], v[200:203], v[108:111]
	v_mfma_f32_16x16x32_bf16 v[104:107], v[192:195], v[200:203], v[104:107]
	v_mfma_f32_16x16x32_bf16 v[92:95], v[180:183], v[208:211], v[92:95]
	v_mfma_f32_16x16x32_bf16 v[88:91], v[192:195], v[208:211], v[88:91]
	v_mfma_f32_16x16x32_bf16 v[76:79], v[180:183], v[216:219], v[76:79]
	v_mfma_f32_16x16x32_bf16 v[72:75], v[192:195], v[216:219], v[72:75]
	v_mfma_f32_16x16x32_bf16 v[68:71], v[180:183], v[224:227], v[68:71]
	v_mfma_f32_16x16x32_bf16 v[64:67], v[192:195], v[224:227], v[64:67]
	s_setprio 0
	s_barrier
; #define PG8_STAGE(bufoff, gbase, voff) do { _Pragma("unroll") for (int _i = 0; _i < 2; ++_i) \
;         __builtin_amdgcn_global_load_lds((const unsigned*)((const char*)(gbase) + (voff)[_i]), (LAS unsigned*)(lds + (bufoff) + ldsw + _i * 8192), 16, 0, 0); } while (0)
; #define PG8_LDA(dst, b, h) do { _Pragma("unroll") for (int m = 0; m < 4; ++m) _Pragma("unroll") for (int k = 0; k < 2; ++k) dst[m][k] = *(const LAS bf16x8*)(lds + PG8_SA(b, h) + aoff + m * 2048 + k * 1024); } while (0)
; #define PG8_LDB(dst, b, h) do { _Pragma("unroll") for (int n = 0; n < 2; ++n) _Pragma("unroll") for (int k = 0; k < 2; ++k) dst[n][k] = *(const LAS bf16x8*)(lds + PG8_SB(b, h) + boff + n * 2048 + k * 1024); } while (0)
; #define PG8_MMA(ai, bj, At, Bt) do { __builtin_amdgcn_s_setprio(1); _Pragma("unroll") for (int m = 0; m < 4; ++m) _Pragma("unroll") for (int n = 0; n < 2; ++n) _Pragma("unroll") for (int k = 0; k < 2; ++k) \
;         acc[ai][bj][m][n] = __builtin_amdgcn_mfma_f32_16x16x32_bf16(Bt[n][k], At[m][k], acc[ai][bj][m][n], 0, 0, 0); __builtin_amdgcn_s_setprio(0); } while (0)
; #define PG8_WAIT_V(n) asm volatile("s_waitcnt vmcnt(" #n ")" ::: "memory")
; #define PG8_WAIT_L(n) asm volatile("s_waitcnt lgkmcnt(" #n ")" ::: "memory")
; #define PG8_BAR __builtin_amdgcn_s_barrier()
; #define PG8_SCHED __builtin_amdgcn_sched_barrier(0)
; template <int GI>
; __device__ __forceinline__ void gemm_phase(LAS unsigned char* lds, unsigned char* ws, int G, int cblk) {
;     ...
;         for (int t = 0; t < nt; t += 2) {
;             const bool last = (t == nt - 2);
;             const char* a1 = cA + (size_t)(t + 1) * kstep;
;             const char* a2 = last ? nA : cA + (size_t)(t + 2) * kstep; const char* b2 = last ? nB : cB + (size_t)(t + 2) * kstep;
;             const char* a3 = a2 + kstep; const char* b3 = b2 + kstep;
;             PG8_LDB(B0, 0, 0); PG8_LDB(B1, 0, 1); PG8_SCHED; PG8_LDA(At, 0, 0); PG8_STAGE(PG8_SA(1, 1), a1 + hstepA, voffA);
;     ...
;             PG8_LDA(At, 1, 1); PG8_STAGE(PG8_SB(1, 0), b3, voffB); PG8_STAGE(PG8_SB(1, 1), b3 + hstepB, voffB); PG8_STAGE(PG8_SA(1, 0), a3, voffA);
;             PG8_WAIT_V(8); PG8_WAIT_L(0); PG8_BAR; PG8_MMA(1, 0, At, B0); PG8_MMA(1, 1, At, B1); PG8_BAR; PG8_SCHED;
	s_add_i32 s34, s34, s0
	v_lshl_add_u64 v[188:189], v[188:189], 0, s[12:13]
	s_mov_b32 m0, s34
	ds_read_b128 v[196:199], v155 offset:49152
	ds_read_b128 v[200:203], v155 offset:50176
	ds_read_b128 v[204:207], v155 offset:51200
	ds_read_b128 v[208:211], v155 offset:52224
	ds_read_b128 v[212:215], v155 offset:53248
	ds_read_b128 v[216:219], v155 offset:54272
	ds_read_b128 v[220:223], v155 offset:55296
	ds_read_b128 v[224:227], v155 offset:56320
	global_load_lds_dwordx4 v[188:189], off
	s_add_i32 m0, s34, 0x2000
	s_add_u32 s46, s46, 0x40080
	v_lshl_add_u64 v[188:189], v[228:229], 0, s[12:13]
	s_addc_u32 s47, s47, 0
	s_add_i32 s34, s57, s0
	global_load_lds_dwordx4 v[188:189], off
	v_lshl_add_u64 v[188:189], s[46:47], 0, v[132:133]
	s_mov_b32 m0, s34
	s_nop 0
	global_load_lds_dwordx4 v[188:189], off
	v_lshl_add_u64 v[188:189], s[46:47], 0, v[136:137]
	s_add_i32 m0, s34, 0x2000
	s_nop 0
	global_load_lds_dwordx4 v[188:189], off
	v_lshl_add_u64 v[188:189], v[230:231], 0, s[12:13]
	s_mov_b32 m0, s51
	s_nop 0
	global_load_lds_dwordx4 v[188:189], off
	v_lshl_add_u64 v[188:189], v[232:233], 0, s[12:13]
	s_mov_b32 m0, s52
	s_nop 0
	global_load_lds_dwordx4 v[188:189], off
	s_waitcnt vmcnt(8)
	s_waitcnt lgkmcnt(0)
	s_barrier
	s_setprio 1
	s_waitcnt lgkmcnt(0)
	v_mfma_f32_16x16x32_bf16 v[60:63], v[156:159], v[196:199], v[60:63]
	v_mfma_f32_16x16x32_bf16 v[56:59], v[168:171], v[196:199], v[56:59]
	s_add_i32 s19, s19, 2
	s_add_u32 s44, s44, 0x100
	s_addc_u32 s45, s45, 0
	s_add_u32 s16, s16, 0x100
	s_addc_u32 s17, s17, 0
	v_mfma_f32_16x16x32_bf16 v[52:55], v[156:159], v[204:207], v[52:55]
	v_mfma_f32_16x16x32_bf16 v[48:51], v[168:171], v[204:207], v[48:51]
	v_mfma_f32_16x16x32_bf16 v[36:39], v[156:159], v[212:215], v[36:39]
	v_mfma_f32_16x16x32_bf16 v[32:35], v[168:171], v[212:215], v[32:35]
	v_mfma_f32_16x16x32_bf16 v[20:23], v[156:159], v[220:223], v[20:23]
	v_mfma_f32_16x16x32_bf16 v[16:19], v[168:171], v[220:223], v[16:19]
	v_mfma_f32_16x16x32_bf16 v[60:63], v[164:167], v[200:203], v[60:63]
	v_mfma_f32_16x16x32_bf16 v[56:59], v[172:175], v[200:203], v[56:59]
	v_mfma_f32_16x16x32_bf16 v[52:55], v[164:167], v[208:211], v[52:55]
	v_mfma_f32_16x16x32_bf16 v[48:51], v[172:175], v[208:211], v[48:51]
	v_mfma_f32_16x16x32_bf16 v[36:39], v[164:167], v[216:219], v[36:39]
	v_mfma_f32_16x16x32_bf16 v[32:35], v[172:175], v[216:219], v[32:35]
	v_mfma_f32_16x16x32_bf16 v[20:23], v[164:167], v[224:227], v[20:23]
	v_mfma_f32_16x16x32_bf16 v[16:19], v[172:175], v[224:227], v[16:19]
	s_setprio 0
	s_setprio 1
	v_mfma_f32_16x16x32_bf16 v[44:47], v[176:179], v[196:199], v[44:47]
	v_mfma_f32_16x16x32_bf16 v[40:43], v[184:187], v[196:199], v[40:43]
	v_mfma_f32_16x16x32_bf16 v[28:31], v[176:179], v[204:207], v[28:31]
	v_mfma_f32_16x16x32_bf16 v[24:27], v[184:187], v[204:207], v[24:27]
	v_mfma_f32_16x16x32_bf16 v[12:15], v[176:179], v[212:215], v[12:15]
	v_mfma_f32_16x16x32_bf16 v[8:11], v[184:187], v[212:215], v[8:11]
	v_mfma_f32_16x16x32_bf16 v[4:7], v[176:179], v[220:223], v[4:7]
	v_mfma_f32_16x16x32_bf16 v[0:3], v[184:187], v[220:223], v[0:3]
	v_mfma_f32_16x16x32_bf16 v[44:47], v[180:183], v[200:203], v[44:47]
	v_mfma_f32_16x16x32_bf16 v[40:43], v[192:195], v[200:203], v[40:43]
	v_mfma_f32_16x16x32_bf16 v[28:31], v[180:183], v[208:211], v[28:31]
	v_mfma_f32_16x16x32_bf16 v[24:27], v[192:195], v[208:211], v[24:27]
	v_mfma_f32_16x16x32_bf16 v[12:15], v[180:183], v[216:219], v[12:15]
	v_mfma_f32_16x16x32_bf16 v[8:11], v[192:195], v[216:219], v[8:11]
	v_mfma_f32_16x16x32_bf16 v[4:7], v[180:183], v[224:227], v[4:7]
	v_mfma_f32_16x16x32_bf16 v[0:3], v[192:195], v[224:227], v[0:3]
	s_setprio 0
	s_barrier
	s_cmp_gt_u32 s19, 13
	s_cbranch_scc0 .LBB0_697
	s_branch .Lpeel_exit_7
.LBB0_697:
	ds_read_b128 v[156:159], v153
	ds_read_b128 v[164:167], v153 offset:1024
	ds_read_b128 v[168:171], v153 offset:2048
	ds_read_b128 v[172:175], v153 offset:3072
	ds_read_b128 v[176:179], v154
	ds_read_b128 v[180:183], v154 offset:1024
	ds_read_b128 v[184:187], v154 offset:2048
	ds_read_b128 v[192:195], v154 offset:3072
	s_add_u32 s34, s44, 0xfffc0080
	s_addc_u32 s46, s45, -1
	s_cmp_eq_u32 s19, 12
	s_cselect_b32 s49, s39, s46
	s_cselect_b32 s48, s38, s34
	s_cselect_b32 s47, s41, s17
	s_cselect_b32 s46, s40, s16
	v_lshl_add_u64 v[188:189], s[44:45], 0, v[140:141]
	s_add_i32 m0, s25, 0xc000
	ds_read_b128 v[196:199], v155
	ds_read_b128 v[200:203], v155 offset:1024
	ds_read_b128 v[204:207], v155 offset:2048
	ds_read_b128 v[208:211], v155 offset:3072
	ds_read_b128 v[212:215], v155 offset:4096
	ds_read_b128 v[216:219], v155 offset:5120
	ds_read_b128 v[220:223], v155 offset:6144
	ds_read_b128 v[224:227], v155 offset:7168
	global_load_lds_dwordx4 v[188:189], off
	v_lshl_add_u64 v[188:189], s[44:45], 0, v[142:143]
	s_add_i32 m0, s25, 0xe000
	s_nop 0
	global_load_lds_dwordx4 v[188:189], off
	s_waitcnt vmcnt(8)
	s_waitcnt lgkmcnt(0)
	s_barrier
; #define PG8_STAGE(bufoff, gbase, voff) do { _Pragma("unroll") for (int _i = 0; _i < 2; ++_i) \
;         __builtin_amdgcn_global_load_lds((const unsigned*)((const char*)(gbase) + (voff)[_i]), (LAS unsigned*)(lds + (bufoff) + ldsw + _i * 8192), 16, 0, 0); } while (0)
; #define PG8_LDA(dst, b, h) do { _Pragma("unroll") for (int m = 0; m < 4; ++m) _Pragma("unroll") for (int k = 0; k < 2; ++k) dst[m][k] = *(const LAS bf16x8*)(lds + PG8_SA(b, h) + aoff + m * 2048 + k * 1024); } while (0)
; #define PG8_LDB(dst, b, h) do { _Pragma("unroll") for (int n = 0; n < 2; ++n) _Pragma("unroll") for (int k = 0; k < 2; ++k) dst[n][k] = *(const LAS bf16x8*)(lds + PG8_SB(b, h) + boff + n * 2048 + k * 1024); } while (0)
; #define PG8_MMA(ai, bj, At, Bt) do { __builtin_amdgcn_s_setprio(1); _Pragma("unroll") for (int m = 0; m < 4; ++m) _Pragma("unroll") for (int n = 0; n < 2; ++n) _Pragma("unroll") for (int k = 0; k < 2; ++k) \
;         acc[ai][bj][m][n] = __builtin_amdgcn_mfma_f32_16x16x32_bf16(Bt[n][k], At[m][k], acc[ai][bj][m][n], 0, 0, 0); __builtin_amdgcn_s_setprio(0); } while (0)
; #define PG8_WAIT_V(n) asm volatile("s_waitcnt vmcnt(" #n ")" ::: "memory")
; #define PG8_WAIT_L(n) asm volatile("s_waitcnt lgkmcnt(" #n ")" ::: "memory")
; #define PG8_BAR __builtin_amdgcn_s_barrier()
; #define PG8_SCHED __builtin_amdgcn_sched_barrier(0)
; template <int GI>
; __device__ __forceinline__ void gemm_phase(LAS unsigned char* lds, unsigned char* ws, int G, int cblk) {
;     ...
;             PG8_LDB(B0, 0, 0); PG8_LDB(B1, 0, 1); PG8_SCHED; PG8_LDA(At, 0, 0); PG8_STAGE(PG8_SA(1, 1), a1 + hstepA, voffA);
;             PG8_WAIT_V(8); PG8_WAIT_L(0); PG8_BAR; PG8_MMA(0, 0, At, B0); PG8_MMA(0, 1, At, B1); PG8_BAR; PG8_SCHED;
;             PG8_LDA(At, 0, 1); PG8_STAGE(PG8_SB(0, 0), b2, voffB); PG8_STAGE(PG8_SB(0, 1), b2 + hstepB, voffB); PG8_STAGE(PG8_SA(0, 0), a2, voffA);
;             PG8_WAIT_V(8); PG8_WAIT_L(0); PG8_BAR; PG8_MMA(1, 0, At, B0); PG8_MMA(1, 1, At, B1); PG8_BAR; PG8_SCHED;
	s_setprio 1
	s_waitcnt lgkmcnt(0)
	v_mfma_f32_16x16x32_bf16 v[124:127], v[156:159], v[196:199], v[124:127]
	v_mfma_f32_16x16x32_bf16 v[120:123], v[168:171], v[196:199], v[120:123]
	v_mfma_f32_16x16x32_bf16 v[116:119], v[156:159], v[204:207], v[116:119]
	v_mfma_f32_16x16x32_bf16 v[112:115], v[168:171], v[204:207], v[112:115]
	v_mfma_f32_16x16x32_bf16 v[100:103], v[156:159], v[212:215], v[100:103]
	v_mfma_f32_16x16x32_bf16 v[96:99], v[168:171], v[212:215], v[96:99]
	v_mfma_f32_16x16x32_bf16 v[84:87], v[156:159], v[220:223], v[84:87]
	v_mfma_f32_16x16x32_bf16 v[80:83], v[168:171], v[220:223], v[80:83]
	v_mfma_f32_16x16x32_bf16 v[124:127], v[164:167], v[200:203], v[124:127]
	v_mfma_f32_16x16x32_bf16 v[120:123], v[172:175], v[200:203], v[120:123]
	v_mfma_f32_16x16x32_bf16 v[116:119], v[164:167], v[208:211], v[116:119]
	v_mfma_f32_16x16x32_bf16 v[112:115], v[172:175], v[208:211], v[112:115]
	v_mfma_f32_16x16x32_bf16 v[100:103], v[164:167], v[216:219], v[100:103]
	v_mfma_f32_16x16x32_bf16 v[96:99], v[172:175], v[216:219], v[96:99]
	v_mfma_f32_16x16x32_bf16 v[84:87], v[164:167], v[224:227], v[84:87]
	v_mfma_f32_16x16x32_bf16 v[80:83], v[172:175], v[224:227], v[80:83]
	s_setprio 0
	s_setprio 1
	v_mfma_f32_16x16x32_bf16 v[108:111], v[176:179], v[196:199], v[108:111]
	v_mfma_f32_16x16x32_bf16 v[104:107], v[184:187], v[196:199], v[104:107]
	v_mfma_f32_16x16x32_bf16 v[92:95], v[176:179], v[204:207], v[92:95]
	v_mfma_f32_16x16x32_bf16 v[88:91], v[184:187], v[204:207], v[88:91]
	v_mfma_f32_16x16x32_bf16 v[76:79], v[176:179], v[212:215], v[76:79]
	v_mfma_f32_16x16x32_bf16 v[72:75], v[184:187], v[212:215], v[72:75]
	v_mfma_f32_16x16x32_bf16 v[68:71], v[176:179], v[220:223], v[68:71]
	v_mfma_f32_16x16x32_bf16 v[64:67], v[184:187], v[220:223], v[64:67]
	v_mfma_f32_16x16x32_bf16 v[108:111], v[180:183], v[200:203], v[108:111]
	v_mfma_f32_16x16x32_bf16 v[104:107], v[192:195], v[200:203], v[104:107]
	v_mfma_f32_16x16x32_bf16 v[92:95], v[180:183], v[208:211], v[92:95]
	v_mfma_f32_16x16x32_bf16 v[88:91], v[192:195], v[208:211], v[88:91]
	v_mfma_f32_16x16x32_bf16 v[76:79], v[180:183], v[216:219], v[76:79]
	v_mfma_f32_16x16x32_bf16 v[72:75], v[192:195], v[216:219], v[72:75]
	v_mfma_f32_16x16x32_bf16 v[68:71], v[180:183], v[224:227], v[68:71]
	v_mfma_f32_16x16x32_bf16 v[64:67], v[192:195], v[224:227], v[64:67]
	s_setprio 0
	s_barrier
	s_add_i32 s34, s53, s0
	v_lshl_add_u64 v[188:189], s[46:47], 0, v[132:133]
	s_mov_b32 m0, s34
	ds_read_b128 v[196:199], v155 offset:16384
	ds_read_b128 v[200:203], v155 offset:17408
	ds_read_b128 v[204:207], v155 offset:18432
	ds_read_b128 v[208:211], v155 offset:19456
	ds_read_b128 v[212:215], v155 offset:20480
	ds_read_b128 v[216:219], v155 offset:21504
	ds_read_b128 v[220:223], v155 offset:22528
	ds_read_b128 v[224:227], v155 offset:23552
	global_load_lds_dwordx4 v[188:189], off
	s_add_i32 m0, s34, 0x2000
	s_add_u32 s58, s46, 0x40000
	v_lshl_add_u64 v[228:229], s[46:47], 0, v[136:137]
	s_addc_u32 s59, s47, 0
	s_add_i32 s34, s55, s0
	global_load_lds_dwordx4 v[228:229], off
	v_lshl_add_u64 v[230:231], s[58:59], 0, v[132:133]
	s_mov_b32 m0, s34
	v_lshl_add_u64 v[232:233], s[48:49], 0, v[134:135]
	global_load_lds_dwordx4 v[230:231], off
	v_lshl_add_u64 v[230:231], s[58:59], 0, v[136:137]
	s_add_i32 m0, s34, 0x2000
	s_nop 0
	global_load_lds_dwordx4 v[230:231], off
	v_lshl_add_u64 v[230:231], s[48:49], 0, v[130:131]
	s_mov_b32 m0, s25
	s_nop 0
	global_load_lds_dwordx4 v[230:231], off
	s_mov_b32 m0, s26
	s_nop 0
	global_load_lds_dwordx4 v[232:233], off
	s_waitcnt vmcnt(8)
	s_waitcnt lgkmcnt(0)
	s_barrier
	s_setprio 1
	s_waitcnt lgkmcnt(0)
	v_mfma_f32_16x16x32_bf16 v[60:63], v[156:159], v[196:199], v[60:63]
	v_mfma_f32_16x16x32_bf16 v[56:59], v[168:171], v[196:199], v[56:59]
	v_mfma_f32_16x16x32_bf16 v[52:55], v[156:159], v[204:207], v[52:55]
	v_mfma_f32_16x16x32_bf16 v[48:51], v[168:171], v[204:207], v[48:51]
	v_mfma_f32_16x16x32_bf16 v[36:39], v[156:159], v[212:215], v[36:39]
	v_mfma_f32_16x16x32_bf16 v[32:35], v[168:171], v[212:215], v[32:35]
	v_mfma_f32_16x16x32_bf16 v[20:23], v[156:159], v[220:223], v[20:23]
	v_mfma_f32_16x16x32_bf16 v[16:19], v[168:171], v[220:223], v[16:19]
	v_mfma_f32_16x16x32_bf16 v[60:63], v[164:167], v[200:203], v[60:63]
	v_mfma_f32_16x16x32_bf16 v[56:59], v[172:175], v[200:203], v[56:59]
	v_mfma_f32_16x16x32_bf16 v[52:55], v[164:167], v[208:211], v[52:55]
	v_mfma_f32_16x16x32_bf16 v[48:51], v[172:175], v[208:211], v[48:51]
	v_mfma_f32_16x16x32_bf16 v[36:39], v[164:167], v[216:219], v[36:39]
	v_mfma_f32_16x16x32_bf16 v[32:35], v[172:175], v[216:219], v[32:35]
	v_mfma_f32_16x16x32_bf16 v[20:23], v[164:167], v[224:227], v[20:23]
	v_mfma_f32_16x16x32_bf16 v[16:19], v[172:175], v[224:227], v[16:19]
	s_setprio 0
	s_setprio 1
	v_mfma_f32_16x16x32_bf16 v[44:47], v[176:179], v[196:199], v[44:47]
	v_mfma_f32_16x16x32_bf16 v[40:43], v[184:187], v[196:199], v[40:43]
	v_mfma_f32_16x16x32_bf16 v[28:31], v[176:179], v[204:207], v[28:31]
	v_mfma_f32_16x16x32_bf16 v[24:27], v[184:187], v[204:207], v[24:27]
	v_mfma_f32_16x16x32_bf16 v[12:15], v[176:179], v[212:215], v[12:15]
	v_mfma_f32_16x16x32_bf16 v[8:11], v[184:187], v[212:215], v[8:11]
	v_mfma_f32_16x16x32_bf16 v[4:7], v[176:179], v[220:223], v[4:7]
	v_mfma_f32_16x16x32_bf16 v[0:3], v[184:187], v[220:223], v[0:3]
	v_mfma_f32_16x16x32_bf16 v[44:47], v[180:183], v[200:203], v[44:47]
	v_mfma_f32_16x16x32_bf16 v[40:43], v[192:195], v[200:203], v[40:43]
	v_mfma_f32_16x16x32_bf16 v[28:31], v[180:183], v[208:211], v[28:31]
	v_mfma_f32_16x16x32_bf16 v[24:27], v[192:195], v[208:211], v[24:27]
	v_mfma_f32_16x16x32_bf16 v[12:15], v[180:183], v[216:219], v[12:15]
	v_mfma_f32_16x16x32_bf16 v[8:11], v[192:195], v[216:219], v[8:11]
	v_mfma_f32_16x16x32_bf16 v[4:7], v[180:183], v[224:227], v[4:7]
	v_mfma_f32_16x16x32_bf16 v[0:3], v[192:195], v[224:227], v[0:3]
	s_setprio 0
	s_barrier
; #define PG8_STAGE(bufoff, gbase, voff) do { _Pragma("unroll") for (int _i = 0; _i < 2; ++_i) \
;         __builtin_amdgcn_global_load_lds((const unsigned*)((const char*)(gbase) + (voff)[_i]), (LAS unsigned*)(lds + (bufoff) + ldsw + _i * 8192), 16, 0, 0); } while (0)
; #define PG8_LDA(dst, b, h) do { _Pragma("unroll") for (int m = 0; m < 4; ++m) _Pragma("unroll") for (int k = 0; k < 2; ++k) dst[m][k] = *(const LAS bf16x8*)(lds + PG8_SA(b, h) + aoff + m * 2048 + k * 1024); } while (0)
; #define PG8_LDB(dst, b, h) do { _Pragma("unroll") for (int n = 0; n < 2; ++n) _Pragma("unroll") for (int k = 0; k < 2; ++k) dst[n][k] = *(const LAS bf16x8*)(lds + PG8_SB(b, h) + boff + n * 2048 + k * 1024); } while (0)
; #define PG8_MMA(ai, bj, At, Bt) do { __builtin_amdgcn_s_setprio(1); _Pragma("unroll") for (int m = 0; m < 4; ++m) _Pragma("unroll") for (int n = 0; n < 2; ++n) _Pragma("unroll") for (int k = 0; k < 2; ++k) \
;         acc[ai][bj][m][n] = __builtin_amdgcn_mfma_f32_16x16x32_bf16(Bt[n][k], At[m][k], acc[ai][bj][m][n], 0, 0, 0); __builtin_amdgcn_s_setprio(0); } while (0)
; #define PG8_WAIT_V(n) asm volatile("s_waitcnt vmcnt(" #n ")" ::: "memory")
; #define PG8_WAIT_L(n) asm volatile("s_waitcnt lgkmcnt(" #n ")" ::: "memory")
; #define PG8_BAR __builtin_amdgcn_s_barrier()
; #define PG8_SCHED __builtin_amdgcn_sched_barrier(0)
; template <int GI>
; __device__ __forceinline__ void gemm_phase(LAS unsigned char* lds, unsigned char* ws, int G, int cblk) {
;     ...
;             PG8_LDB(B0, 1, 0); PG8_LDB(B1, 1, 1); PG8_SCHED; PG8_LDA(At, 1, 0); PG8_STAGE(PG8_SA(0, 1), a2 + hstepA, voffA);
;             PG8_WAIT_V(8); PG8_WAIT_L(0); PG8_BAR; PG8_MMA(0, 0, At, B0); PG8_MMA(0, 1, At, B1); PG8_BAR; PG8_SCHED;
	s_add_i32 s34, 0, 0x18000
	v_add_u32_e32 v161, s34, v152
	s_add_i32 s57, 0, 0x1c000
	ds_read_b128 v[156:159], v161
	ds_read_b128 v[164:167], v161 offset:1024
	ds_read_b128 v[168:171], v161 offset:2048
	ds_read_b128 v[172:175], v161 offset:3072
	v_add_u32_e32 v161, s57, v152
	ds_read_b128 v[176:179], v161
	ds_read_b128 v[180:183], v161 offset:1024
	ds_read_b128 v[184:187], v161 offset:2048
	ds_read_b128 v[192:195], v161 offset:3072
	s_add_u32 s48, s48, 0x40000
	s_addc_u32 s49, s49, 0
	s_mov_b32 m0, s27
	v_lshl_add_u64 v[234:235], s[48:49], 0, v[130:131]
	ds_read_b128 v[196:199], v155 offset:32768
	ds_read_b128 v[200:203], v155 offset:33792
	ds_read_b128 v[204:207], v155 offset:34816
	ds_read_b128 v[208:211], v155 offset:35840
	ds_read_b128 v[212:215], v155 offset:36864
	ds_read_b128 v[216:219], v155 offset:37888
	ds_read_b128 v[220:223], v155 offset:38912
	ds_read_b128 v[224:227], v155 offset:39936
	global_load_lds_dwordx4 v[234:235], off
	v_lshl_add_u64 v[234:235], s[48:49], 0, v[134:135]
	s_mov_b32 m0, s33
	s_nop 0
	global_load_lds_dwordx4 v[234:235], off
	s_waitcnt vmcnt(8)
	s_waitcnt lgkmcnt(0)
	s_barrier
	s_setprio 1
	s_waitcnt lgkmcnt(0)
	v_mfma_f32_16x16x32_bf16 v[124:127], v[156:159], v[196:199], v[124:127]
	v_mfma_f32_16x16x32_bf16 v[120:123], v[168:171], v[196:199], v[120:123]
	v_mfma_f32_16x16x32_bf16 v[116:119], v[156:159], v[204:207], v[116:119]
	v_mfma_f32_16x16x32_bf16 v[112:115], v[168:171], v[204:207], v[112:115]
	v_mfma_f32_16x16x32_bf16 v[100:103], v[156:159], v[212:215], v[100:103]
	v_mfma_f32_16x16x32_bf16 v[96:99], v[168:171], v[212:215], v[96:99]
	v_mfma_f32_16x16x32_bf16 v[84:87], v[156:159], v[220:223], v[84:87]
	v_mfma_f32_16x16x32_bf16 v[80:83], v[168:171], v[220:223], v[80:83]
	v_mfma_f32_16x16x32_bf16 v[124:127], v[164:167], v[200:203], v[124:127]
	v_mfma_f32_16x16x32_bf16 v[120:123], v[172:175], v[200:203], v[120:123]
	v_mfma_f32_16x16x32_bf16 v[116:119], v[164:167], v[208:211], v[116:119]
	v_mfma_f32_16x16x32_bf16 v[112:115], v[172:175], v[208:211], v[112:115]
	v_mfma_f32_16x16x32_bf16 v[100:103], v[164:167], v[216:219], v[100:103]
	v_mfma_f32_16x16x32_bf16 v[96:99], v[172:175], v[216:219], v[96:99]
	v_mfma_f32_16x16x32_bf16 v[84:87], v[164:167], v[224:227], v[84:87]
	v_mfma_f32_16x16x32_bf16 v[80:83], v[172:175], v[224:227], v[80:83]
	s_setprio 0
	s_setprio 1
	v_mfma_f32_16x16x32_bf16 v[108:111], v[176:179], v[196:199], v[108:111]
	v_mfma_f32_16x16x32_bf16 v[104:107], v[184:187], v[196:199], v[104:107]
	v_mfma_f32_16x16x32_bf16 v[92:95], v[176:179], v[204:207], v[92:95]
	v_mfma_f32_16x16x32_bf16 v[88:91], v[184:187], v[204:207], v[88:91]
	v_mfma_f32_16x16x32_bf16 v[76:79], v[176:179], v[212:215], v[76:79]
	v_mfma_f32_16x16x32_bf16 v[72:75], v[184:187], v[212:215], v[72:75]
	v_mfma_f32_16x16x32_bf16 v[68:71], v[176:179], v[220:223], v[68:71]
	v_mfma_f32_16x16x32_bf16 v[64:67], v[184:187], v[220:223], v[64:67]
	v_mfma_f32_16x16x32_bf16 v[108:111], v[180:183], v[200:203], v[108:111]
	v_mfma_f32_16x16x32_bf16 v[104:107], v[192:195], v[200:203], v[104:107]
	v_mfma_f32_16x16x32_bf16 v[92:95], v[180:183], v[208:211], v[92:95]
	v_mfma_f32_16x16x32_bf16 v[88:91], v[192:195], v[208:211], v[88:91]
	v_mfma_f32_16x16x32_bf16 v[76:79], v[180:183], v[216:219], v[76:79]
	v_mfma_f32_16x16x32_bf16 v[72:75], v[192:195], v[216:219], v[72:75]
	v_mfma_f32_16x16x32_bf16 v[68:71], v[180:183], v[224:227], v[68:71]
	v_mfma_f32_16x16x32_bf16 v[64:67], v[192:195], v[224:227], v[64:67]
	s_setprio 0
	s_barrier
; #define PG8_STAGE(bufoff, gbase, voff) do { _Pragma("unroll") for (int _i = 0; _i < 2; ++_i) \
;         __builtin_amdgcn_global_load_lds((const unsigned*)((const char*)(gbase) + (voff)[_i]), (LAS unsigned*)(lds + (bufoff) + ldsw + _i * 8192), 16, 0, 0); } while (0)
; #define PG8_LDA(dst, b, h) do { _Pragma("unroll") for (int m = 0; m < 4; ++m) _Pragma("unroll") for (int k = 0; k < 2; ++k) dst[m][k] = *(const LAS bf16x8*)(lds + PG8_SA(b, h) + aoff + m * 2048 + k * 1024); } while (0)
; #define PG8_MMA(ai, bj, At, Bt) do { __builtin_amdgcn_s_setprio(1); _Pragma("unroll") for (int m = 0; m < 4; ++m) _Pragma("unroll") for (int n = 0; n < 2; ++n) _Pragma("unroll") for (int k = 0; k < 2; ++k) \
;         acc[ai][bj][m][n] = __builtin_amdgcn_mfma_f32_16x16x32_bf16(Bt[n][k], At[m][k], acc[ai][bj][m][n], 0, 0, 0); __builtin_amdgcn_s_setprio(0); } while (0)
; #define PG8_WAIT_V(n) asm volatile("s_waitcnt vmcnt(" #n ")" ::: "memory")
; #define PG8_WAIT_L(n) asm volatile("s_waitcnt lgkmcnt(" #n ")" ::: "memory")
; #define PG8_BAR __builtin_amdgcn_s_barrier()
; #define PG8_SCHED __builtin_amdgcn_sched_barrier(0)
; template <int GI>
; __device__ __forceinline__ void gemm_phase(LAS unsigned char* lds, unsigned char* ws, int G, int cblk) {
;     ...
;             PG8_LDA(At, 1, 1); PG8_STAGE(PG8_SB(1, 0), b3, voffB); PG8_STAGE(PG8_SB(1, 1), b3 + hstepB, voffB); PG8_STAGE(PG8_SA(1, 0), a3, voffA);
;             PG8_WAIT_V(8); PG8_WAIT_L(0); PG8_BAR; PG8_MMA(1, 0, At, B0); PG8_MMA(1, 1, At, B1); PG8_BAR; PG8_SCHED;
;         }
	s_add_i32 s34, s34, s0
	v_lshl_add_u64 v[188:189], v[188:189], 0, s[12:13]
	s_mov_b32 m0, s34
	ds_read_b128 v[196:199], v155 offset:49152
	ds_read_b128 v[200:203], v155 offset:50176
	ds_read_b128 v[204:207], v155 offset:51200
	ds_read_b128 v[208:211], v155 offset:52224
	ds_read_b128 v[212:215], v155 offset:53248
	ds_read_b128 v[216:219], v155 offset:54272
	ds_read_b128 v[220:223], v155 offset:55296
	ds_read_b128 v[224:227], v155 offset:56320
	global_load_lds_dwordx4 v[188:189], off
	s_add_i32 m0, s34, 0x2000
	s_add_u32 s46, s46, 0x40080
	v_lshl_add_u64 v[188:189], v[228:229], 0, s[12:13]
	s_addc_u32 s47, s47, 0
	s_add_i32 s34, s57, s0
	global_load_lds_dwordx4 v[188:189], off
	v_lshl_add_u64 v[188:189], s[46:47], 0, v[132:133]
	s_mov_b32 m0, s34
	s_nop 0
	global_load_lds_dwordx4 v[188:189], off
	v_lshl_add_u64 v[188:189], s[46:47], 0, v[136:137]
	s_add_i32 m0, s34, 0x2000
	s_nop 0
	global_load_lds_dwordx4 v[188:189], off
	v_lshl_add_u64 v[188:189], v[230:231], 0, s[12:13]
	s_mov_b32 m0, s51
	s_nop 0
	global_load_lds_dwordx4 v[188:189], off
	v_lshl_add_u64 v[188:189], v[232:233], 0, s[12:13]
	s_mov_b32 m0, s52
	s_nop 0
	global_load_lds_dwordx4 v[188:189], off
	s_waitcnt vmcnt(8)
	s_waitcnt lgkmcnt(0)
	s_barrier
	s_setprio 1
	s_waitcnt lgkmcnt(0)
	v_mfma_f32_16x16x32_bf16 v[60:63], v[156:159], v[196:199], v[60:63]
	v_mfma_f32_16x16x32_bf16 v[56:59], v[168:171], v[196:199], v[56:59]
	s_add_i32 s19, s19, 2
	s_add_u32 s44, s44, 0x100
	s_addc_u32 s45, s45, 0
	s_add_u32 s16, s16, 0x100
	s_addc_u32 s17, s17, 0
	v_mfma_f32_16x16x32_bf16 v[52:55], v[156:159], v[204:207], v[52:55]
	v_mfma_f32_16x16x32_bf16 v[48:51], v[168:171], v[204:207], v[48:51]
	v_mfma_f32_16x16x32_bf16 v[36:39], v[156:159], v[212:215], v[36:39]
	v_mfma_f32_16x16x32_bf16 v[32:35], v[168:171], v[212:215], v[32:35]
	v_mfma_f32_16x16x32_bf16 v[20:23], v[156:159], v[220:223], v[20:23]
	v_mfma_f32_16x16x32_bf16 v[16:19], v[168:171], v[220:223], v[16:19]
	v_mfma_f32_16x16x32_bf16 v[60:63], v[164:167], v[200:203], v[60:63]
	v_mfma_f32_16x16x32_bf16 v[56:59], v[172:175], v[200:203], v[56:59]
	v_mfma_f32_16x16x32_bf16 v[52:55], v[164:167], v[208:211], v[52:55]
	v_mfma_f32_16x16x32_bf16 v[48:51], v[172:175], v[208:211], v[48:51]
	v_mfma_f32_16x16x32_bf16 v[36:39], v[164:167], v[216:219], v[36:39]
	v_mfma_f32_16x16x32_bf16 v[32:35], v[172:175], v[216:219], v[32:35]
	v_mfma_f32_16x16x32_bf16 v[20:23], v[164:167], v[224:227], v[20:23]
	v_mfma_f32_16x16x32_bf16 v[16:19], v[172:175], v[224:227], v[16:19]
	s_setprio 0
	s_setprio 1
	v_mfma_f32_16x16x32_bf16 v[44:47], v[176:179], v[196:199], v[44:47]
	v_mfma_f32_16x16x32_bf16 v[40:43], v[184:187], v[196:199], v[40:43]
	v_mfma_f32_16x16x32_bf16 v[28:31], v[176:179], v[204:207], v[28:31]
	v_mfma_f32_16x16x32_bf16 v[24:27], v[184:187], v[204:207], v[24:27]
	v_mfma_f32_16x16x32_bf16 v[12:15], v[176:179], v[212:215], v[12:15]
	v_mfma_f32_16x16x32_bf16 v[8:11], v[184:187], v[212:215], v[8:11]
	v_mfma_f32_16x16x32_bf16 v[4:7], v[176:179], v[220:223], v[4:7]
	v_mfma_f32_16x16x32_bf16 v[0:3], v[184:187], v[220:223], v[0:3]
	v_mfma_f32_16x16x32_bf16 v[44:47], v[180:183], v[200:203], v[44:47]
	v_mfma_f32_16x16x32_bf16 v[40:43], v[192:195], v[200:203], v[40:43]
	v_mfma_f32_16x16x32_bf16 v[28:31], v[180:183], v[208:211], v[28:31]
	v_mfma_f32_16x16x32_bf16 v[24:27], v[192:195], v[208:211], v[24:27]
	v_mfma_f32_16x16x32_bf16 v[12:15], v[180:183], v[216:219], v[12:15]
	v_mfma_f32_16x16x32_bf16 v[8:11], v[192:195], v[216:219], v[8:11]
	v_mfma_f32_16x16x32_bf16 v[4:7], v[180:183], v[224:227], v[4:7]
	v_mfma_f32_16x16x32_bf16 v[0:3], v[192:195], v[224:227], v[0:3]
	s_setprio 0
	s_barrier
	s_cmp_gt_u32 s19, 13
	s_cbranch_scc0 .LBB0_697

; #define PG8_STAGE(bufoff, gbase, voff) do { _Pragma("unroll") for (int _i = 0; _i < 2; ++_i) \
;         __builtin_amdgcn_global_load_lds((const unsigned*)((const char*)(gbase) + (voff)[_i]), (LAS unsigned*)(lds + (bufoff) + ldsw + _i * 8192), 16, 0, 0); } while (0)
; #define PG8_LDA(dst, b, h) do { _Pragma("unroll") for (int m = 0; m < 4; ++m) _Pragma("unroll") for (int k = 0; k < 2; ++k) dst[m][k] = *(const LAS bf16x8*)(lds + PG8_SA(b, h) + aoff + m * 2048 + k * 1024); } while (0)
; #define PG8_LDB(dst, b, h) do { _Pragma("unroll") for (int n = 0; n < 2; ++n) _Pragma("unroll") for (int k = 0; k < 2; ++k) dst[n][k] = *(const LAS bf16x8*)(lds + PG8_SB(b, h) + boff + n * 2048 + k * 1024); } while (0)
; #define PG8_MMA(ai, bj, At, Bt) do { __builtin_amdgcn_s_setprio(1); _Pragma("unroll") for (int m = 0; m < 4; ++m) _Pragma("unroll") for (int n = 0; n < 2; ++n) _Pragma("unroll") for (int k = 0; k < 2; ++k) \
;         acc[ai][bj][m][n] = __builtin_amdgcn_mfma_f32_16x16x32_bf16(Bt[n][k], At[m][k], acc[ai][bj][m][n], 0, 0, 0); __builtin_amdgcn_s_setprio(0); } while (0)
; #define PG8_WAIT_V(n) asm volatile("s_waitcnt vmcnt(" #n ")" ::: "memory")
; #define PG8_BAR __builtin_amdgcn_s_barrier()
; template <int GI>
; __device__ __forceinline__ void gemm_phase(LAS unsigned char* lds, unsigned char* ws, int G, int cblk) {
;     ...
;     for (;;) {
;         const bool has_next = sched_next<GI>(ws, ui + 1, G, cblk, nxt);
;         const char* nA = has_next ? nxt.A : cA; const char* nB = has_next ? nxt.B : cB;
;         for (int t = 0; t < nt; t += 2) {
;             const bool last = (t == nt - 2);
;             const char* a1 = cA + (size_t)(t + 1) * kstep;
;             const char* a2 = last ? nA : cA + (size_t)(t + 2) * kstep; const char* b2 = last ? nB : cB + (size_t)(t + 2) * kstep;
;             const char* a3 = a2 + kstep; const char* b3 = b2 + kstep;
;             PG8_LDB(B0, 0, 0); PG8_LDB(B1, 0, 1); PG8_SCHED; PG8_LDA(At, 0, 0); PG8_STAGE(PG8_SA(1, 1), a1 + hstepA, voffA);
;             PG8_WAIT_V(8); PG8_WAIT_L(0); PG8_BAR; PG8_MMA(0, 0, At, B0); PG8_MMA(0, 1, At, B1); PG8_BAR; PG8_SCHED;
;             PG8_LDA(At, 0, 1); PG8_STAGE(PG8_SB(0, 0), b2, voffB); PG8_STAGE(PG8_SB(0, 1), b2 + hstepB, voffB); PG8_STAGE(PG8_SA(0, 0), a2, voffA);
;             PG8_WAIT_V(8); PG8_WAIT_L(0); PG8_BAR; PG8_MMA(1, 0, At, B0); PG8_MMA(1, 1, At, B1); PG8_BAR; PG8_SCHED;
.LBB0_819:
	s_add_u32 s40, s40, 0x80080
	s_addc_u32 s41, s41, 0
	s_add_u32 s0, s42, 0x100
	s_addc_u32 s1, s43, 0
	s_mov_b32 s17, -2
	ds_read_b128 v[156:159], v153
	ds_read_b128 v[164:167], v153 offset:1024
	ds_read_b128 v[168:171], v153 offset:2048
	ds_read_b128 v[172:175], v153 offset:3072
	ds_read_b128 v[176:179], v154
	ds_read_b128 v[180:183], v154 offset:1024
	ds_read_b128 v[184:187], v154 offset:2048
	ds_read_b128 v[192:195], v154 offset:3072
	s_add_u32 s24, s40, 0xfff80080
	s_addc_u32 s25, s41, -1
	s_cmp_eq_u32 s17, 28
	s_cselect_b32 s45, s19, s25
	s_cselect_b32 s44, s18, s24
	s_cselect_b32 s43, s21, s1
	s_cselect_b32 s42, s20, s0
	v_lshl_add_u64 v[188:189], s[40:41], 0, v[140:141]
	s_add_i32 m0, s49, 0xc000
	ds_read_b128 v[196:199], v155
	ds_read_b128 v[200:203], v155 offset:1024
	ds_read_b128 v[204:207], v155 offset:2048
	ds_read_b128 v[208:211], v155 offset:3072
	ds_read_b128 v[212:215], v155 offset:4096
	ds_read_b128 v[216:219], v155 offset:5120
	ds_read_b128 v[220:223], v155 offset:6144
	ds_read_b128 v[224:227], v155 offset:7168
	global_load_lds_dwordx4 v[188:189], off
	v_lshl_add_u64 v[188:189], s[40:41], 0, v[142:143]
	s_add_i32 m0, s49, 0xe000
	s_nop 0
	global_load_lds_dwordx4 v[188:189], off
	s_waitcnt vmcnt(8)
	s_waitcnt lgkmcnt(0)
	s_barrier
	s_setprio 1
	s_waitcnt lgkmcnt(0)
	v_mfma_f32_16x16x32_bf16 v[124:127], v[156:159], v[196:199], 0
	v_mfma_f32_16x16x32_bf16 v[120:123], v[168:171], v[196:199], 0
	v_mfma_f32_16x16x32_bf16 v[108:111], v[156:159], v[204:207], 0
	v_mfma_f32_16x16x32_bf16 v[104:107], v[168:171], v[204:207], 0
	v_mfma_f32_16x16x32_bf16 v[92:95], v[156:159], v[212:215], 0
	v_mfma_f32_16x16x32_bf16 v[88:91], v[168:171], v[212:215], 0
	v_mfma_f32_16x16x32_bf16 v[76:79], v[156:159], v[220:223], 0
	v_mfma_f32_16x16x32_bf16 v[72:75], v[168:171], v[220:223], 0
	v_mfma_f32_16x16x32_bf16 v[124:127], v[164:167], v[200:203], v[124:127]
	v_mfma_f32_16x16x32_bf16 v[120:123], v[172:175], v[200:203], v[120:123]
	v_mfma_f32_16x16x32_bf16 v[108:111], v[164:167], v[208:211], v[108:111]
	v_mfma_f32_16x16x32_bf16 v[104:107], v[172:175], v[208:211], v[104:107]
	v_mfma_f32_16x16x32_bf16 v[92:95], v[164:167], v[216:219], v[92:95]
	v_mfma_f32_16x16x32_bf16 v[88:91], v[172:175], v[216:219], v[88:91]
	v_mfma_f32_16x16x32_bf16 v[76:79], v[164:167], v[224:227], v[76:79]
	v_mfma_f32_16x16x32_bf16 v[72:75], v[172:175], v[224:227], v[72:75]
	s_setprio 0
	s_setprio 1
	v_mfma_f32_16x16x32_bf16 v[116:119], v[176:179], v[196:199], 0
	v_mfma_f32_16x16x32_bf16 v[112:115], v[184:187], v[196:199], 0
	v_mfma_f32_16x16x32_bf16 v[100:103], v[176:179], v[204:207], 0
	v_mfma_f32_16x16x32_bf16 v[96:99], v[184:187], v[204:207], 0
	v_mfma_f32_16x16x32_bf16 v[84:87], v[176:179], v[212:215], 0
	v_mfma_f32_16x16x32_bf16 v[80:83], v[184:187], v[212:215], 0
	v_mfma_f32_16x16x32_bf16 v[68:71], v[176:179], v[220:223], 0
	v_mfma_f32_16x16x32_bf16 v[64:67], v[184:187], v[220:223], 0
	v_mfma_f32_16x16x32_bf16 v[116:119], v[180:183], v[200:203], v[116:119]
	v_mfma_f32_16x16x32_bf16 v[112:115], v[192:195], v[200:203], v[112:115]
	v_mfma_f32_16x16x32_bf16 v[100:103], v[180:183], v[208:211], v[100:103]
	v_mfma_f32_16x16x32_bf16 v[96:99], v[192:195], v[208:211], v[96:99]
	v_mfma_f32_16x16x32_bf16 v[84:87], v[180:183], v[216:219], v[84:87]
	v_mfma_f32_16x16x32_bf16 v[80:83], v[192:195], v[216:219], v[80:83]
	v_mfma_f32_16x16x32_bf16 v[68:71], v[180:183], v[224:227], v[68:71]
	v_mfma_f32_16x16x32_bf16 v[64:67], v[192:195], v[224:227], v[64:67]
	s_setprio 0
	s_barrier
	s_add_i32 s24, s56, s26
	v_lshl_add_u64 v[188:189], s[42:43], 0, v[134:135]
	s_mov_b32 m0, s24
	ds_read_b128 v[196:199], v155 offset:16384
	ds_read_b128 v[200:203], v155 offset:17408
	ds_read_b128 v[204:207], v155 offset:18432
	ds_read_b128 v[208:211], v155 offset:19456
	ds_read_b128 v[212:215], v155 offset:20480
	ds_read_b128 v[216:219], v155 offset:21504
	ds_read_b128 v[220:223], v155 offset:22528
	ds_read_b128 v[224:227], v155 offset:23552
	global_load_lds_dwordx4 v[188:189], off
	s_add_i32 m0, s24, 0x2000
	s_add_u32 s24, s42, 0x80000
	v_lshl_add_u64 v[228:229], s[42:43], 0, v[130:131]
	s_addc_u32 s25, s43, 0
	s_add_i32 s33, s57, s26
	global_load_lds_dwordx4 v[228:229], off
	v_lshl_add_u64 v[230:231], s[24:25], 0, v[134:135]
	s_mov_b32 m0, s33
	v_lshl_add_u64 v[232:233], s[44:45], 0, v[132:133]
	global_load_lds_dwordx4 v[230:231], off
	v_lshl_add_u64 v[230:231], s[24:25], 0, v[130:131]
	s_add_i32 m0, s33, 0x2000
	s_nop 0
	global_load_lds_dwordx4 v[230:231], off
	v_lshl_add_u64 v[230:231], s[44:45], 0, v[136:137]
	s_mov_b32 m0, s49
	s_nop 0
	global_load_lds_dwordx4 v[230:231], off
	s_mov_b32 m0, s50
	s_nop 0
	global_load_lds_dwordx4 v[232:233], off
	s_waitcnt vmcnt(8)
	s_waitcnt lgkmcnt(0)
	s_barrier
; #define PG8_STAGE(bufoff, gbase, voff) do { _Pragma("unroll") for (int _i = 0; _i < 2; ++_i) \
;         __builtin_amdgcn_global_load_lds((const unsigned*)((const char*)(gbase) + (voff)[_i]), (LAS unsigned*)(lds + (bufoff) + ldsw + _i * 8192), 16, 0, 0); } while (0)
; #define PG8_LDA(dst, b, h) do { _Pragma("unroll") for (int m = 0; m < 4; ++m) _Pragma("unroll") for (int k = 0; k < 2; ++k) dst[m][k] = *(const LAS bf16x8*)(lds + PG8_SA(b, h) + aoff + m * 2048 + k * 1024); } while (0)
; #define PG8_LDB(dst, b, h) do { _Pragma("unroll") for (int n = 0; n < 2; ++n) _Pragma("unroll") for (int k = 0; k < 2; ++k) dst[n][k] = *(const LAS bf16x8*)(lds + PG8_SB(b, h) + boff + n * 2048 + k * 1024); } while (0)
; #define PG8_MMA(ai, bj, At, Bt) do { __builtin_amdgcn_s_setprio(1); _Pragma("unroll") for (int m = 0; m < 4; ++m) _Pragma("unroll") for (int n = 0; n < 2; ++n) _Pragma("unroll") for (int k = 0; k < 2; ++k) \
;         acc[ai][bj][m][n] = __builtin_amdgcn_mfma_f32_16x16x32_bf16(Bt[n][k], At[m][k], acc[ai][bj][m][n], 0, 0, 0); __builtin_amdgcn_s_setprio(0); } while (0)
; #define PG8_WAIT_V(n) asm volatile("s_waitcnt vmcnt(" #n ")" ::: "memory")
; #define PG8_WAIT_L(n) asm volatile("s_waitcnt lgkmcnt(" #n ")" ::: "memory")
; #define PG8_BAR __builtin_amdgcn_s_barrier()
; #define PG8_SCHED __builtin_amdgcn_sched_barrier(0)
; template <int GI>
; __device__ __forceinline__ void gemm_phase(LAS unsigned char* lds, unsigned char* ws, int G, int cblk) {
;     ...
;             PG8_WAIT_V(8); PG8_WAIT_L(0); PG8_BAR; PG8_MMA(1, 0, At, B0); PG8_MMA(1, 1, At, B1); PG8_BAR; PG8_SCHED;
;             PG8_LDB(B0, 1, 0); PG8_LDB(B1, 1, 1); PG8_SCHED; PG8_LDA(At, 1, 0); PG8_STAGE(PG8_SA(0, 1), a2 + hstepA, voffA);
;             PG8_WAIT_V(8); PG8_WAIT_L(0); PG8_BAR; PG8_MMA(0, 0, At, B0); PG8_MMA(0, 1, At, B1); PG8_BAR; PG8_SCHED;
	s_setprio 1
	s_waitcnt lgkmcnt(0)
	v_mfma_f32_16x16x32_bf16 v[60:63], v[156:159], v[196:199], 0
	v_mfma_f32_16x16x32_bf16 v[56:59], v[168:171], v[196:199], 0
	v_mfma_f32_16x16x32_bf16 v[44:47], v[156:159], v[204:207], 0
	v_mfma_f32_16x16x32_bf16 v[40:43], v[168:171], v[204:207], 0
	v_mfma_f32_16x16x32_bf16 v[28:31], v[156:159], v[212:215], 0
	v_mfma_f32_16x16x32_bf16 v[24:27], v[168:171], v[212:215], 0
	v_mfma_f32_16x16x32_bf16 v[12:15], v[156:159], v[220:223], 0
	v_mfma_f32_16x16x32_bf16 v[8:11], v[168:171], v[220:223], 0
	v_mfma_f32_16x16x32_bf16 v[60:63], v[164:167], v[200:203], v[60:63]
	v_mfma_f32_16x16x32_bf16 v[56:59], v[172:175], v[200:203], v[56:59]
	v_mfma_f32_16x16x32_bf16 v[44:47], v[164:167], v[208:211], v[44:47]
	v_mfma_f32_16x16x32_bf16 v[40:43], v[172:175], v[208:211], v[40:43]
	v_mfma_f32_16x16x32_bf16 v[28:31], v[164:167], v[216:219], v[28:31]
	v_mfma_f32_16x16x32_bf16 v[24:27], v[172:175], v[216:219], v[24:27]
	v_mfma_f32_16x16x32_bf16 v[12:15], v[164:167], v[224:227], v[12:15]
	v_mfma_f32_16x16x32_bf16 v[8:11], v[172:175], v[224:227], v[8:11]
	s_setprio 0
	s_setprio 1
	v_mfma_f32_16x16x32_bf16 v[52:55], v[176:179], v[196:199], 0
	v_mfma_f32_16x16x32_bf16 v[48:51], v[184:187], v[196:199], 0
	v_mfma_f32_16x16x32_bf16 v[36:39], v[176:179], v[204:207], 0
	v_mfma_f32_16x16x32_bf16 v[32:35], v[184:187], v[204:207], 0
	v_mfma_f32_16x16x32_bf16 v[20:23], v[176:179], v[212:215], 0
	v_mfma_f32_16x16x32_bf16 v[16:19], v[184:187], v[212:215], 0
	v_mfma_f32_16x16x32_bf16 v[4:7], v[176:179], v[220:223], 0
	v_mfma_f32_16x16x32_bf16 v[0:3], v[184:187], v[220:223], 0
	v_mfma_f32_16x16x32_bf16 v[52:55], v[180:183], v[200:203], v[52:55]
	v_mfma_f32_16x16x32_bf16 v[48:51], v[192:195], v[200:203], v[48:51]
	v_mfma_f32_16x16x32_bf16 v[36:39], v[180:183], v[208:211], v[36:39]
	v_mfma_f32_16x16x32_bf16 v[32:35], v[192:195], v[208:211], v[32:35]
	v_mfma_f32_16x16x32_bf16 v[20:23], v[180:183], v[216:219], v[20:23]
	v_mfma_f32_16x16x32_bf16 v[16:19], v[192:195], v[216:219], v[16:19]
	v_mfma_f32_16x16x32_bf16 v[4:7], v[180:183], v[224:227], v[4:7]
	v_mfma_f32_16x16x32_bf16 v[0:3], v[192:195], v[224:227], v[0:3]
	s_setprio 0
	s_barrier
	s_add_i32 s33, 0, 0x18000
	v_add_u32_e32 v161, s33, v152
	s_add_i32 s34, 0, 0x1c000
	ds_read_b128 v[156:159], v161
	ds_read_b128 v[164:167], v161 offset:1024
	ds_read_b128 v[168:171], v161 offset:2048
	ds_read_b128 v[172:175], v161 offset:3072
	v_add_u32_e32 v161, s34, v152
	ds_read_b128 v[176:179], v161
	ds_read_b128 v[180:183], v161 offset:1024
	ds_read_b128 v[184:187], v161 offset:2048
	ds_read_b128 v[192:195], v161 offset:3072
	s_add_u32 s24, s44, 0x80000
	s_addc_u32 s25, s45, 0
	s_mov_b32 m0, s51
	v_lshl_add_u64 v[234:235], s[24:25], 0, v[136:137]
	ds_read_b128 v[196:199], v155 offset:32768
	ds_read_b128 v[200:203], v155 offset:33792
	ds_read_b128 v[204:207], v155 offset:34816
	ds_read_b128 v[208:211], v155 offset:35840
	ds_read_b128 v[212:215], v155 offset:36864
	ds_read_b128 v[216:219], v155 offset:37888
	ds_read_b128 v[220:223], v155 offset:38912
	ds_read_b128 v[224:227], v155 offset:39936
	global_load_lds_dwordx4 v[234:235], off
	v_lshl_add_u64 v[234:235], s[24:25], 0, v[132:133]
	s_mov_b32 m0, s52
	s_nop 0
	global_load_lds_dwordx4 v[234:235], off
	s_waitcnt vmcnt(8)
	s_waitcnt lgkmcnt(0)
	s_barrier
	s_setprio 1
	s_waitcnt lgkmcnt(0)
	v_mfma_f32_16x16x32_bf16 v[124:127], v[156:159], v[196:199], v[124:127]
	v_mfma_f32_16x16x32_bf16 v[120:123], v[168:171], v[196:199], v[120:123]
	v_mfma_f32_16x16x32_bf16 v[108:111], v[156:159], v[204:207], v[108:111]
	v_mfma_f32_16x16x32_bf16 v[104:107], v[168:171], v[204:207], v[104:107]
	v_mfma_f32_16x16x32_bf16 v[92:95], v[156:159], v[212:215], v[92:95]
	v_mfma_f32_16x16x32_bf16 v[88:91], v[168:171], v[212:215], v[88:91]
	v_mfma_f32_16x16x32_bf16 v[76:79], v[156:159], v[220:223], v[76:79]
	v_mfma_f32_16x16x32_bf16 v[72:75], v[168:171], v[220:223], v[72:75]
	v_mfma_f32_16x16x32_bf16 v[124:127], v[164:167], v[200:203], v[124:127]
	v_mfma_f32_16x16x32_bf16 v[120:123], v[172:175], v[200:203], v[120:123]
	v_mfma_f32_16x16x32_bf16 v[108:111], v[164:167], v[208:211], v[108:111]
	v_mfma_f32_16x16x32_bf16 v[104:107], v[172:175], v[208:211], v[104:107]
	v_mfma_f32_16x16x32_bf16 v[92:95], v[164:167], v[216:219], v[92:95]
	v_mfma_f32_16x16x32_bf16 v[88:91], v[172:175], v[216:219], v[88:91]
	v_mfma_f32_16x16x32_bf16 v[76:79], v[164:167], v[224:227], v[76:79]
	v_mfma_f32_16x16x32_bf16 v[72:75], v[172:175], v[224:227], v[72:75]
	s_setprio 0
	s_setprio 1
	v_mfma_f32_16x16x32_bf16 v[116:119], v[176:179], v[196:199], v[116:119]
	v_mfma_f32_16x16x32_bf16 v[112:115], v[184:187], v[196:199], v[112:115]
	v_mfma_f32_16x16x32_bf16 v[100:103], v[176:179], v[204:207], v[100:103]
	v_mfma_f32_16x16x32_bf16 v[96:99], v[184:187], v[204:207], v[96:99]
	v_mfma_f32_16x16x32_bf16 v[84:87], v[176:179], v[212:215], v[84:87]
	v_mfma_f32_16x16x32_bf16 v[80:83], v[184:187], v[212:215], v[80:83]
	v_mfma_f32_16x16x32_bf16 v[68:71], v[176:179], v[220:223], v[68:71]
	v_mfma_f32_16x16x32_bf16 v[64:67], v[184:187], v[220:223], v[64:67]
	v_mfma_f32_16x16x32_bf16 v[116:119], v[180:183], v[200:203], v[116:119]
	v_mfma_f32_16x16x32_bf16 v[112:115], v[192:195], v[200:203], v[112:115]
	v_mfma_f32_16x16x32_bf16 v[100:103], v[180:183], v[208:211], v[100:103]
	v_mfma_f32_16x16x32_bf16 v[96:99], v[192:195], v[208:211], v[96:99]
	v_mfma_f32_16x16x32_bf16 v[84:87], v[180:183], v[216:219], v[84:87]
	v_mfma_f32_16x16x32_bf16 v[80:83], v[192:195], v[216:219], v[80:83]
	v_mfma_f32_16x16x32_bf16 v[68:71], v[180:183], v[224:227], v[68:71]
	v_mfma_f32_16x16x32_bf16 v[64:67], v[192:195], v[224:227], v[64:67]
	s_setprio 0
	s_barrier
; #define PG8_STAGE(bufoff, gbase, voff) do { _Pragma("unroll") for (int _i = 0; _i < 2; ++_i) \
;         __builtin_amdgcn_global_load_lds((const unsigned*)((const char*)(gbase) + (voff)[_i]), (LAS unsigned*)(lds + (bufoff) + ldsw + _i * 8192), 16, 0, 0); } while (0)
; #define PG8_LDA(dst, b, h) do { _Pragma("unroll") for (int m = 0; m < 4; ++m) _Pragma("unroll") for (int k = 0; k < 2; ++k) dst[m][k] = *(const LAS bf16x8*)(lds + PG8_SA(b, h) + aoff + m * 2048 + k * 1024); } while (0)
; #define PG8_LDB(dst, b, h) do { _Pragma("unroll") for (int n = 0; n < 2; ++n) _Pragma("unroll") for (int k = 0; k < 2; ++k) dst[n][k] = *(const LAS bf16x8*)(lds + PG8_SB(b, h) + boff + n * 2048 + k * 1024); } while (0)
; #define PG8_MMA(ai, bj, At, Bt) do { __builtin_amdgcn_s_setprio(1); _Pragma("unroll") for (int m = 0; m < 4; ++m) _Pragma("unroll") for (int n = 0; n < 2; ++n) _Pragma("unroll") for (int k = 0; k < 2; ++k) \
;         acc[ai][bj][m][n] = __builtin_amdgcn_mfma_f32_16x16x32_bf16(Bt[n][k], At[m][k], acc[ai][bj][m][n], 0, 0, 0); __builtin_amdgcn_s_setprio(0); } while (0)
; #define PG8_WAIT_V(n) asm volatile("s_waitcnt vmcnt(" #n ")" ::: "memory")
; #define PG8_WAIT_L(n) asm volatile("s_waitcnt lgkmcnt(" #n ")" ::: "memory")
; #define PG8_BAR __builtin_amdgcn_s_barrier()
; #define PG8_SCHED __builtin_amdgcn_sched_barrier(0)
; template <int GI>
; __device__ __forceinline__ void gemm_phase(LAS unsigned char* lds, unsigned char* ws, int G, int cblk) {
;     ...
;         for (int t = 0; t < nt; t += 2) {
;             const bool last = (t == nt - 2);
;             const char* a1 = cA + (size_t)(t + 1) * kstep;
;             const char* a2 = last ? nA : cA + (size_t)(t + 2) * kstep; const char* b2 = last ? nB : cB + (size_t)(t + 2) * kstep;
;             const char* a3 = a2 + kstep; const char* b3 = b2 + kstep;
;             PG8_LDB(B0, 0, 0); PG8_LDB(B1, 0, 1); PG8_SCHED; PG8_LDA(At, 0, 0); PG8_STAGE(PG8_SA(1, 1), a1 + hstepA, voffA);
;     ...
;             PG8_LDA(At, 1, 1); PG8_STAGE(PG8_SB(1, 0), b3, voffB); PG8_STAGE(PG8_SB(1, 1), b3 + hstepB, voffB); PG8_STAGE(PG8_SA(1, 0), a3, voffA);
;             PG8_WAIT_V(8); PG8_WAIT_L(0); PG8_BAR; PG8_MMA(1, 0, At, B0); PG8_MMA(1, 1, At, B1); PG8_BAR; PG8_SCHED;
	s_add_i32 s24, s33, s26
	v_lshl_add_u64 v[188:189], v[188:189], 0, s[12:13]
	s_mov_b32 m0, s24
	ds_read_b128 v[196:199], v155 offset:49152
	ds_read_b128 v[200:203], v155 offset:50176
	ds_read_b128 v[204:207], v155 offset:51200
	ds_read_b128 v[208:211], v155 offset:52224
	ds_read_b128 v[212:215], v155 offset:53248
	ds_read_b128 v[216:219], v155 offset:54272
	ds_read_b128 v[220:223], v155 offset:55296
	ds_read_b128 v[224:227], v155 offset:56320
	global_load_lds_dwordx4 v[188:189], off
	s_add_i32 m0, s24, 0x2000
	s_add_u32 s24, s42, 0x80080
	v_lshl_add_u64 v[188:189], v[228:229], 0, s[12:13]
	s_addc_u32 s25, s43, 0
	s_add_i32 s33, s34, s26
	global_load_lds_dwordx4 v[188:189], off
	v_lshl_add_u64 v[188:189], s[24:25], 0, v[134:135]
	s_mov_b32 m0, s33
	s_nop 0
	global_load_lds_dwordx4 v[188:189], off
	v_lshl_add_u64 v[188:189], s[24:25], 0, v[130:131]
	s_add_i32 m0, s33, 0x2000
	s_nop 0
	global_load_lds_dwordx4 v[188:189], off
	v_lshl_add_u64 v[188:189], v[230:231], 0, s[12:13]
	s_mov_b32 m0, s53
	s_nop 0
	global_load_lds_dwordx4 v[188:189], off
	v_lshl_add_u64 v[188:189], v[232:233], 0, s[12:13]
	s_mov_b32 m0, s55
	s_nop 0
	global_load_lds_dwordx4 v[188:189], off
	s_waitcnt vmcnt(8)
	s_waitcnt lgkmcnt(0)
	s_barrier
	s_setprio 1
	s_waitcnt lgkmcnt(0)
	v_mfma_f32_16x16x32_bf16 v[60:63], v[156:159], v[196:199], v[60:63]
	v_mfma_f32_16x16x32_bf16 v[56:59], v[168:171], v[196:199], v[56:59]
	s_add_i32 s17, s17, 2
	s_add_u32 s40, s40, 0x100
	s_addc_u32 s41, s41, 0
	s_add_u32 s0, s0, 0x100
	s_addc_u32 s1, s1, 0
	v_mfma_f32_16x16x32_bf16 v[44:47], v[156:159], v[204:207], v[44:47]
	v_mfma_f32_16x16x32_bf16 v[40:43], v[168:171], v[204:207], v[40:43]
	v_mfma_f32_16x16x32_bf16 v[28:31], v[156:159], v[212:215], v[28:31]
	v_mfma_f32_16x16x32_bf16 v[24:27], v[168:171], v[212:215], v[24:27]
	v_mfma_f32_16x16x32_bf16 v[12:15], v[156:159], v[220:223], v[12:15]
	v_mfma_f32_16x16x32_bf16 v[8:11], v[168:171], v[220:223], v[8:11]
	v_mfma_f32_16x16x32_bf16 v[60:63], v[164:167], v[200:203], v[60:63]
	v_mfma_f32_16x16x32_bf16 v[56:59], v[172:175], v[200:203], v[56:59]
	v_mfma_f32_16x16x32_bf16 v[44:47], v[164:167], v[208:211], v[44:47]
	v_mfma_f32_16x16x32_bf16 v[40:43], v[172:175], v[208:211], v[40:43]
	v_mfma_f32_16x16x32_bf16 v[28:31], v[164:167], v[216:219], v[28:31]
	v_mfma_f32_16x16x32_bf16 v[24:27], v[172:175], v[216:219], v[24:27]
	v_mfma_f32_16x16x32_bf16 v[12:15], v[164:167], v[224:227], v[12:15]
	v_mfma_f32_16x16x32_bf16 v[8:11], v[172:175], v[224:227], v[8:11]
	s_setprio 0
	s_setprio 1
	v_mfma_f32_16x16x32_bf16 v[52:55], v[176:179], v[196:199], v[52:55]
	v_mfma_f32_16x16x32_bf16 v[48:51], v[184:187], v[196:199], v[48:51]
	v_mfma_f32_16x16x32_bf16 v[36:39], v[176:179], v[204:207], v[36:39]
	v_mfma_f32_16x16x32_bf16 v[32:35], v[184:187], v[204:207], v[32:35]
	v_mfma_f32_16x16x32_bf16 v[20:23], v[176:179], v[212:215], v[20:23]
	v_mfma_f32_16x16x32_bf16 v[16:19], v[184:187], v[212:215], v[16:19]
	v_mfma_f32_16x16x32_bf16 v[4:7], v[176:179], v[220:223], v[4:7]
	v_mfma_f32_16x16x32_bf16 v[0:3], v[184:187], v[220:223], v[0:3]
	v_mfma_f32_16x16x32_bf16 v[52:55], v[180:183], v[200:203], v[52:55]
	v_mfma_f32_16x16x32_bf16 v[48:51], v[192:195], v[200:203], v[48:51]
	v_mfma_f32_16x16x32_bf16 v[36:39], v[180:183], v[208:211], v[36:39]
	v_mfma_f32_16x16x32_bf16 v[32:35], v[192:195], v[208:211], v[32:35]
	v_mfma_f32_16x16x32_bf16 v[20:23], v[180:183], v[216:219], v[20:23]
	v_mfma_f32_16x16x32_bf16 v[16:19], v[192:195], v[216:219], v[16:19]
	v_mfma_f32_16x16x32_bf16 v[4:7], v[180:183], v[224:227], v[4:7]
	v_mfma_f32_16x16x32_bf16 v[0:3], v[192:195], v[224:227], v[0:3]
	s_setprio 0
	s_barrier
	s_cmp_gt_u32 s17, 29
	s_cbranch_scc0 .LBB0_820
	s_branch .Lpeel_exit_8
.LBB0_820:
	ds_read_b128 v[156:159], v153
	ds_read_b128 v[164:167], v153 offset:1024
	ds_read_b128 v[168:171], v153 offset:2048
	ds_read_b128 v[172:175], v153 offset:3072
	ds_read_b128 v[176:179], v154
	ds_read_b128 v[180:183], v154 offset:1024
	ds_read_b128 v[184:187], v154 offset:2048
	ds_read_b128 v[192:195], v154 offset:3072
	s_add_u32 s24, s40, 0xfff80080
	s_addc_u32 s25, s41, -1
	s_cmp_eq_u32 s17, 28
	s_cselect_b32 s45, s19, s25
	s_cselect_b32 s44, s18, s24
	s_cselect_b32 s43, s21, s1
	s_cselect_b32 s42, s20, s0
	v_lshl_add_u64 v[188:189], s[40:41], 0, v[140:141]
	s_add_i32 m0, s49, 0xc000
	ds_read_b128 v[196:199], v155
	ds_read_b128 v[200:203], v155 offset:1024
	ds_read_b128 v[204:207], v155 offset:2048
	ds_read_b128 v[208:211], v155 offset:3072
	ds_read_b128 v[212:215], v155 offset:4096
	ds_read_b128 v[216:219], v155 offset:5120
	ds_read_b128 v[220:223], v155 offset:6144
	ds_read_b128 v[224:227], v155 offset:7168
	global_load_lds_dwordx4 v[188:189], off
	v_lshl_add_u64 v[188:189], s[40:41], 0, v[142:143]
	s_add_i32 m0, s49, 0xe000
	s_nop 0
	global_load_lds_dwordx4 v[188:189], off
	s_waitcnt vmcnt(8)
	s_waitcnt lgkmcnt(0)
	s_barrier
; #define PG8_STAGE(bufoff, gbase, voff) do { _Pragma("unroll") for (int _i = 0; _i < 2; ++_i) \
;         __builtin_amdgcn_global_load_lds((const unsigned*)((const char*)(gbase) + (voff)[_i]), (LAS unsigned*)(lds + (bufoff) + ldsw + _i * 8192), 16, 0, 0); } while (0)
; #define PG8_LDA(dst, b, h) do { _Pragma("unroll") for (int m = 0; m < 4; ++m) _Pragma("unroll") for (int k = 0; k < 2; ++k) dst[m][k] = *(const LAS bf16x8*)(lds + PG8_SA(b, h) + aoff + m * 2048 + k * 1024); } while (0)
; #define PG8_LDB(dst, b, h) do { _Pragma("unroll") for (int n = 0; n < 2; ++n) _Pragma("unroll") for (int k = 0; k < 2; ++k) dst[n][k] = *(const LAS bf16x8*)(lds + PG8_SB(b, h) + boff + n * 2048 + k * 1024); } while (0)
; #define PG8_MMA(ai, bj, At, Bt) do { __builtin_amdgcn_s_setprio(1); _Pragma("unroll") for (int m = 0; m < 4; ++m) _Pragma("unroll") for (int n = 0; n < 2; ++n) _Pragma("unroll") for (int k = 0; k < 2; ++k) \
;         acc[ai][bj][m][n] = __builtin_amdgcn_mfma_f32_16x16x32_bf16(Bt[n][k], At[m][k], acc[ai][bj][m][n], 0, 0, 0); __builtin_amdgcn_s_setprio(0); } while (0)
; #define PG8_WAIT_V(n) asm volatile("s_waitcnt vmcnt(" #n ")" ::: "memory")
; #define PG8_WAIT_L(n) asm volatile("s_waitcnt lgkmcnt(" #n ")" ::: "memory")
; #define PG8_BAR __builtin_amdgcn_s_barrier()
; #define PG8_SCHED __builtin_amdgcn_sched_barrier(0)
; template <int GI>
; __device__ __forceinline__ void gemm_phase(LAS unsigned char* lds, unsigned char* ws, int G, int cblk) {
;     ...
;             PG8_LDB(B0, 0, 0); PG8_LDB(B1, 0, 1); PG8_SCHED; PG8_LDA(At, 0, 0); PG8_STAGE(PG8_SA(1, 1), a1 + hstepA, voffA);
;             PG8_WAIT_V(8); PG8_WAIT_L(0); PG8_BAR; PG8_MMA(0, 0, At, B0); PG8_MMA(0, 1, At, B1); PG8_BAR; PG8_SCHED;
;             PG8_LDA(At, 0, 1); PG8_STAGE(PG8_SB(0, 0), b2, voffB); PG8_STAGE(PG8_SB(0, 1), b2 + hstepB, voffB); PG8_STAGE(PG8_SA(0, 0), a2, voffA);
;             PG8_WAIT_V(8); PG8_WAIT_L(0); PG8_BAR; PG8_MMA(1, 0, At, B0); PG8_MMA(1, 1, At, B1); PG8_BAR; PG8_SCHED;
	s_setprio 1
	s_waitcnt lgkmcnt(0)
	v_mfma_f32_16x16x32_bf16 v[124:127], v[156:159], v[196:199], v[124:127]
	v_mfma_f32_16x16x32_bf16 v[120:123], v[168:171], v[196:199], v[120:123]
	v_mfma_f32_16x16x32_bf16 v[108:111], v[156:159], v[204:207], v[108:111]
	v_mfma_f32_16x16x32_bf16 v[104:107], v[168:171], v[204:207], v[104:107]
	v_mfma_f32_16x16x32_bf16 v[92:95], v[156:159], v[212:215], v[92:95]
	v_mfma_f32_16x16x32_bf16 v[88:91], v[168:171], v[212:215], v[88:91]
	v_mfma_f32_16x16x32_bf16 v[76:79], v[156:159], v[220:223], v[76:79]
	v_mfma_f32_16x16x32_bf16 v[72:75], v[168:171], v[220:223], v[72:75]
	v_mfma_f32_16x16x32_bf16 v[124:127], v[164:167], v[200:203], v[124:127]
	v_mfma_f32_16x16x32_bf16 v[120:123], v[172:175], v[200:203], v[120:123]
	v_mfma_f32_16x16x32_bf16 v[108:111], v[164:167], v[208:211], v[108:111]
	v_mfma_f32_16x16x32_bf16 v[104:107], v[172:175], v[208:211], v[104:107]
	v_mfma_f32_16x16x32_bf16 v[92:95], v[164:167], v[216:219], v[92:95]
	v_mfma_f32_16x16x32_bf16 v[88:91], v[172:175], v[216:219], v[88:91]
	v_mfma_f32_16x16x32_bf16 v[76:79], v[164:167], v[224:227], v[76:79]
	v_mfma_f32_16x16x32_bf16 v[72:75], v[172:175], v[224:227], v[72:75]
	s_setprio 0
	s_setprio 1
	v_mfma_f32_16x16x32_bf16 v[116:119], v[176:179], v[196:199], v[116:119]
	v_mfma_f32_16x16x32_bf16 v[112:115], v[184:187], v[196:199], v[112:115]
	v_mfma_f32_16x16x32_bf16 v[100:103], v[176:179], v[204:207], v[100:103]
	v_mfma_f32_16x16x32_bf16 v[96:99], v[184:187], v[204:207], v[96:99]
	v_mfma_f32_16x16x32_bf16 v[84:87], v[176:179], v[212:215], v[84:87]
	v_mfma_f32_16x16x32_bf16 v[80:83], v[184:187], v[212:215], v[80:83]
	v_mfma_f32_16x16x32_bf16 v[68:71], v[176:179], v[220:223], v[68:71]
	v_mfma_f32_16x16x32_bf16 v[64:67], v[184:187], v[220:223], v[64:67]
	v_mfma_f32_16x16x32_bf16 v[116:119], v[180:183], v[200:203], v[116:119]
	v_mfma_f32_16x16x32_bf16 v[112:115], v[192:195], v[200:203], v[112:115]
	v_mfma_f32_16x16x32_bf16 v[100:103], v[180:183], v[208:211], v[100:103]
	v_mfma_f32_16x16x32_bf16 v[96:99], v[192:195], v[208:211], v[96:99]
	v_mfma_f32_16x16x32_bf16 v[84:87], v[180:183], v[216:219], v[84:87]
	v_mfma_f32_16x16x32_bf16 v[80:83], v[192:195], v[216:219], v[80:83]
	v_mfma_f32_16x16x32_bf16 v[68:71], v[180:183], v[224:227], v[68:71]
	v_mfma_f32_16x16x32_bf16 v[64:67], v[192:195], v[224:227], v[64:67]
	s_setprio 0
	s_barrier
	s_add_i32 s24, s56, s26
	v_lshl_add_u64 v[188:189], s[42:43], 0, v[134:135]
	s_mov_b32 m0, s24
	ds_read_b128 v[196:199], v155 offset:16384
	ds_read_b128 v[200:203], v155 offset:17408
	ds_read_b128 v[204:207], v155 offset:18432
	ds_read_b128 v[208:211], v155 offset:19456
	ds_read_b128 v[212:215], v155 offset:20480
	ds_read_b128 v[216:219], v155 offset:21504
	ds_read_b128 v[220:223], v155 offset:22528
	ds_read_b128 v[224:227], v155 offset:23552
	global_load_lds_dwordx4 v[188:189], off
	s_add_i32 m0, s24, 0x2000
	s_add_u32 s24, s42, 0x80000
	v_lshl_add_u64 v[228:229], s[42:43], 0, v[130:131]
	s_addc_u32 s25, s43, 0
	s_add_i32 s33, s57, s26
	global_load_lds_dwordx4 v[228:229], off
	v_lshl_add_u64 v[230:231], s[24:25], 0, v[134:135]
	s_mov_b32 m0, s33
	v_lshl_add_u64 v[232:233], s[44:45], 0, v[132:133]
	global_load_lds_dwordx4 v[230:231], off
	v_lshl_add_u64 v[230:231], s[24:25], 0, v[130:131]
	s_add_i32 m0, s33, 0x2000
	s_nop 0
	global_load_lds_dwordx4 v[230:231], off
	v_lshl_add_u64 v[230:231], s[44:45], 0, v[136:137]
	s_mov_b32 m0, s49
	s_nop 0
	global_load_lds_dwordx4 v[230:231], off
	s_mov_b32 m0, s50
	s_nop 0
	global_load_lds_dwordx4 v[232:233], off
	s_waitcnt vmcnt(8)
	s_waitcnt lgkmcnt(0)
	s_barrier
	s_setprio 1
	s_waitcnt lgkmcnt(0)
	v_mfma_f32_16x16x32_bf16 v[60:63], v[156:159], v[196:199], v[60:63]
	v_mfma_f32_16x16x32_bf16 v[56:59], v[168:171], v[196:199], v[56:59]
	v_mfma_f32_16x16x32_bf16 v[44:47], v[156:159], v[204:207], v[44:47]
	v_mfma_f32_16x16x32_bf16 v[40:43], v[168:171], v[204:207], v[40:43]
	v_mfma_f32_16x16x32_bf16 v[28:31], v[156:159], v[212:215], v[28:31]
	v_mfma_f32_16x16x32_bf16 v[24:27], v[168:171], v[212:215], v[24:27]
	v_mfma_f32_16x16x32_bf16 v[12:15], v[156:159], v[220:223], v[12:15]
	v_mfma_f32_16x16x32_bf16 v[8:11], v[168:171], v[220:223], v[8:11]
	v_mfma_f32_16x16x32_bf16 v[60:63], v[164:167], v[200:203], v[60:63]
	v_mfma_f32_16x16x32_bf16 v[56:59], v[172:175], v[200:203], v[56:59]
	v_mfma_f32_16x16x32_bf16 v[44:47], v[164:167], v[208:211], v[44:47]
	v_mfma_f32_16x16x32_bf16 v[40:43], v[172:175], v[208:211], v[40:43]
	v_mfma_f32_16x16x32_bf16 v[28:31], v[164:167], v[216:219], v[28:31]
	v_mfma_f32_16x16x32_bf16 v[24:27], v[172:175], v[216:219], v[24:27]
	v_mfma_f32_16x16x32_bf16 v[12:15], v[164:167], v[224:227], v[12:15]
	v_mfma_f32_16x16x32_bf16 v[8:11], v[172:175], v[224:227], v[8:11]
	s_setprio 0
	s_setprio 1
	v_mfma_f32_16x16x32_bf16 v[52:55], v[176:179], v[196:199], v[52:55]
	v_mfma_f32_16x16x32_bf16 v[48:51], v[184:187], v[196:199], v[48:51]
	v_mfma_f32_16x16x32_bf16 v[36:39], v[176:179], v[204:207], v[36:39]
	v_mfma_f32_16x16x32_bf16 v[32:35], v[184:187], v[204:207], v[32:35]
	v_mfma_f32_16x16x32_bf16 v[20:23], v[176:179], v[212:215], v[20:23]
	v_mfma_f32_16x16x32_bf16 v[16:19], v[184:187], v[212:215], v[16:19]
	v_mfma_f32_16x16x32_bf16 v[4:7], v[176:179], v[220:223], v[4:7]
	v_mfma_f32_16x16x32_bf16 v[0:3], v[184:187], v[220:223], v[0:3]
	v_mfma_f32_16x16x32_bf16 v[52:55], v[180:183], v[200:203], v[52:55]
	v_mfma_f32_16x16x32_bf16 v[48:51], v[192:195], v[200:203], v[48:51]
	v_mfma_f32_16x16x32_bf16 v[36:39], v[180:183], v[208:211], v[36:39]
	v_mfma_f32_16x16x32_bf16 v[32:35], v[192:195], v[208:211], v[32:35]
	v_mfma_f32_16x16x32_bf16 v[20:23], v[180:183], v[216:219], v[20:23]
	v_mfma_f32_16x16x32_bf16 v[16:19], v[192:195], v[216:219], v[16:19]
	v_mfma_f32_16x16x32_bf16 v[4:7], v[180:183], v[224:227], v[4:7]
	v_mfma_f32_16x16x32_bf16 v[0:3], v[192:195], v[224:227], v[0:3]
	s_setprio 0
	s_barrier
; #define PG8_STAGE(bufoff, gbase, voff) do { _Pragma("unroll") for (int _i = 0; _i < 2; ++_i) \
;         __builtin_amdgcn_global_load_lds((const unsigned*)((const char*)(gbase) + (voff)[_i]), (LAS unsigned*)(lds + (bufoff) + ldsw + _i * 8192), 16, 0, 0); } while (0)
; #define PG8_LDA(dst, b, h) do { _Pragma("unroll") for (int m = 0; m < 4; ++m) _Pragma("unroll") for (int k = 0; k < 2; ++k) dst[m][k] = *(const LAS bf16x8*)(lds + PG8_SA(b, h) + aoff + m * 2048 + k * 1024); } while (0)
; #define PG8_LDB(dst, b, h) do { _Pragma("unroll") for (int n = 0; n < 2; ++n) _Pragma("unroll") for (int k = 0; k < 2; ++k) dst[n][k] = *(const LAS bf16x8*)(lds + PG8_SB(b, h) + boff + n * 2048 + k * 1024); } while (0)
; #define PG8_MMA(ai, bj, At, Bt) do { __builtin_amdgcn_s_setprio(1); _Pragma("unroll") for (int m = 0; m < 4; ++m) _Pragma("unroll") for (int n = 0; n < 2; ++n) _Pragma("unroll") for (int k = 0; k < 2; ++k) \
;         acc[ai][bj][m][n] = __builtin_amdgcn_mfma_f32_16x16x32_bf16(Bt[n][k], At[m][k], acc[ai][bj][m][n], 0, 0, 0); __builtin_amdgcn_s_setprio(0); } while (0)
; #define PG8_WAIT_V(n) asm volatile("s_waitcnt vmcnt(" #n ")" ::: "memory")
; #define PG8_WAIT_L(n) asm volatile("s_waitcnt lgkmcnt(" #n ")" ::: "memory")
; #define PG8_BAR __builtin_amdgcn_s_barrier()
; #define PG8_SCHED __builtin_amdgcn_sched_barrier(0)
; template <int GI>
; __device__ __forceinline__ void gemm_phase(LAS unsigned char* lds, unsigned char* ws, int G, int cblk) {
;     ...
;             PG8_LDB(B0, 1, 0); PG8_LDB(B1, 1, 1); PG8_SCHED; PG8_LDA(At, 1, 0); PG8_STAGE(PG8_SA(0, 1), a2 + hstepA, voffA);
;             PG8_WAIT_V(8); PG8_WAIT_L(0); PG8_BAR; PG8_MMA(0, 0, At, B0); PG8_MMA(0, 1, At, B1); PG8_BAR; PG8_SCHED;
	s_add_i32 s33, 0, 0x18000
	v_add_u32_e32 v161, s33, v152
	s_add_i32 s34, 0, 0x1c000
	ds_read_b128 v[156:159], v161
	ds_read_b128 v[164:167], v161 offset:1024
	ds_read_b128 v[168:171], v161 offset:2048
	ds_read_b128 v[172:175], v161 offset:3072
	v_add_u32_e32 v161, s34, v152
	ds_read_b128 v[176:179], v161
	ds_read_b128 v[180:183], v161 offset:1024
	ds_read_b128 v[184:187], v161 offset:2048
	ds_read_b128 v[192:195], v161 offset:3072
	s_add_u32 s24, s44, 0x80000
	s_addc_u32 s25, s45, 0
	s_mov_b32 m0, s51
	v_lshl_add_u64 v[234:235], s[24:25], 0, v[136:137]
	ds_read_b128 v[196:199], v155 offset:32768
	ds_read_b128 v[200:203], v155 offset:33792
	ds_read_b128 v[204:207], v155 offset:34816
	ds_read_b128 v[208:211], v155 offset:35840
	ds_read_b128 v[212:215], v155 offset:36864
	ds_read_b128 v[216:219], v155 offset:37888
	ds_read_b128 v[220:223], v155 offset:38912
	ds_read_b128 v[224:227], v155 offset:39936
	global_load_lds_dwordx4 v[234:235], off
	v_lshl_add_u64 v[234:235], s[24:25], 0, v[132:133]
	s_mov_b32 m0, s52
	s_nop 0
	global_load_lds_dwordx4 v[234:235], off
	s_waitcnt vmcnt(8)
	s_waitcnt lgkmcnt(0)
	s_barrier
	s_setprio 1
	s_waitcnt lgkmcnt(0)
	v_mfma_f32_16x16x32_bf16 v[124:127], v[156:159], v[196:199], v[124:127]
	v_mfma_f32_16x16x32_bf16 v[120:123], v[168:171], v[196:199], v[120:123]
	v_mfma_f32_16x16x32_bf16 v[108:111], v[156:159], v[204:207], v[108:111]
	v_mfma_f32_16x16x32_bf16 v[104:107], v[168:171], v[204:207], v[104:107]
	v_mfma_f32_16x16x32_bf16 v[92:95], v[156:159], v[212:215], v[92:95]
	v_mfma_f32_16x16x32_bf16 v[88:91], v[168:171], v[212:215], v[88:91]
	v_mfma_f32_16x16x32_bf16 v[76:79], v[156:159], v[220:223], v[76:79]
	v_mfma_f32_16x16x32_bf16 v[72:75], v[168:171], v[220:223], v[72:75]
	v_mfma_f32_16x16x32_bf16 v[124:127], v[164:167], v[200:203], v[124:127]
	v_mfma_f32_16x16x32_bf16 v[120:123], v[172:175], v[200:203], v[120:123]
	v_mfma_f32_16x16x32_bf16 v[108:111], v[164:167], v[208:211], v[108:111]
	v_mfma_f32_16x16x32_bf16 v[104:107], v[172:175], v[208:211], v[104:107]
	v_mfma_f32_16x16x32_bf16 v[92:95], v[164:167], v[216:219], v[92:95]
	v_mfma_f32_16x16x32_bf16 v[88:91], v[172:175], v[216:219], v[88:91]
	v_mfma_f32_16x16x32_bf16 v[76:79], v[164:167], v[224:227], v[76:79]
	v_mfma_f32_16x16x32_bf16 v[72:75], v[172:175], v[224:227], v[72:75]
	s_setprio 0
	s_setprio 1
	v_mfma_f32_16x16x32_bf16 v[116:119], v[176:179], v[196:199], v[116:119]
	v_mfma_f32_16x16x32_bf16 v[112:115], v[184:187], v[196:199], v[112:115]
	v_mfma_f32_16x16x32_bf16 v[100:103], v[176:179], v[204:207], v[100:103]
	v_mfma_f32_16x16x32_bf16 v[96:99], v[184:187], v[204:207], v[96:99]
	v_mfma_f32_16x16x32_bf16 v[84:87], v[176:179], v[212:215], v[84:87]
	v_mfma_f32_16x16x32_bf16 v[80:83], v[184:187], v[212:215], v[80:83]
	v_mfma_f32_16x16x32_bf16 v[68:71], v[176:179], v[220:223], v[68:71]
	v_mfma_f32_16x16x32_bf16 v[64:67], v[184:187], v[220:223], v[64:67]
	v_mfma_f32_16x16x32_bf16 v[116:119], v[180:183], v[200:203], v[116:119]
	v_mfma_f32_16x16x32_bf16 v[112:115], v[192:195], v[200:203], v[112:115]
	v_mfma_f32_16x16x32_bf16 v[100:103], v[180:183], v[208:211], v[100:103]
	v_mfma_f32_16x16x32_bf16 v[96:99], v[192:195], v[208:211], v[96:99]
	v_mfma_f32_16x16x32_bf16 v[84:87], v[180:183], v[216:219], v[84:87]
	v_mfma_f32_16x16x32_bf16 v[80:83], v[192:195], v[216:219], v[80:83]
	v_mfma_f32_16x16x32_bf16 v[68:71], v[180:183], v[224:227], v[68:71]
	v_mfma_f32_16x16x32_bf16 v[64:67], v[192:195], v[224:227], v[64:67]
	s_setprio 0
	s_barrier
; #define PG8_STAGE(bufoff, gbase, voff) do { _Pragma("unroll") for (int _i = 0; _i < 2; ++_i) \
;         __builtin_amdgcn_global_load_lds((const unsigned*)((const char*)(gbase) + (voff)[_i]), (LAS unsigned*)(lds + (bufoff) + ldsw + _i * 8192), 16, 0, 0); } while (0)
; #define PG8_LDA(dst, b, h) do { _Pragma("unroll") for (int m = 0; m < 4; ++m) _Pragma("unroll") for (int k = 0; k < 2; ++k) dst[m][k] = *(const LAS bf16x8*)(lds + PG8_SA(b, h) + aoff + m * 2048 + k * 1024); } while (0)
; #define PG8_MMA(ai, bj, At, Bt) do { __builtin_amdgcn_s_setprio(1); _Pragma("unroll") for (int m = 0; m < 4; ++m) _Pragma("unroll") for (int n = 0; n < 2; ++n) _Pragma("unroll") for (int k = 0; k < 2; ++k) \
;         acc[ai][bj][m][n] = __builtin_amdgcn_mfma_f32_16x16x32_bf16(Bt[n][k], At[m][k], acc[ai][bj][m][n], 0, 0, 0); __builtin_amdgcn_s_setprio(0); } while (0)
; #define PG8_WAIT_V(n) asm volatile("s_waitcnt vmcnt(" #n ")" ::: "memory")
; #define PG8_WAIT_L(n) asm volatile("s_waitcnt lgkmcnt(" #n ")" ::: "memory")
; #define PG8_BAR __builtin_amdgcn_s_barrier()
; #define PG8_SCHED __builtin_amdgcn_sched_barrier(0)
; template <int GI>
; __device__ __forceinline__ void gemm_phase(LAS unsigned char* lds, unsigned char* ws, int G, int cblk) {
;     ...
;             PG8_LDA(At, 1, 1); PG8_STAGE(PG8_SB(1, 0), b3, voffB); PG8_STAGE(PG8_SB(1, 1), b3 + hstepB, voffB); PG8_STAGE(PG8_SA(1, 0), a3, voffA);
;             PG8_WAIT_V(8); PG8_WAIT_L(0); PG8_BAR; PG8_MMA(1, 0, At, B0); PG8_MMA(1, 1, At, B1); PG8_BAR; PG8_SCHED;
;         }
	s_add_i32 s24, s33, s26
	v_lshl_add_u64 v[188:189], v[188:189], 0, s[12:13]
	s_mov_b32 m0, s24
	ds_read_b128 v[196:199], v155 offset:49152
	ds_read_b128 v[200:203], v155 offset:50176
	ds_read_b128 v[204:207], v155 offset:51200
	ds_read_b128 v[208:211], v155 offset:52224
	ds_read_b128 v[212:215], v155 offset:53248
	ds_read_b128 v[216:219], v155 offset:54272
	ds_read_b128 v[220:223], v155 offset:55296
	ds_read_b128 v[224:227], v155 offset:56320
	global_load_lds_dwordx4 v[188:189], off
	s_add_i32 m0, s24, 0x2000
	s_add_u32 s24, s42, 0x80080
	v_lshl_add_u64 v[188:189], v[228:229], 0, s[12:13]
	s_addc_u32 s25, s43, 0
	s_add_i32 s33, s34, s26
	global_load_lds_dwordx4 v[188:189], off
	v_lshl_add_u64 v[188:189], s[24:25], 0, v[134:135]
	s_mov_b32 m0, s33
	s_nop 0
	global_load_lds_dwordx4 v[188:189], off
	v_lshl_add_u64 v[188:189], s[24:25], 0, v[130:131]
	s_add_i32 m0, s33, 0x2000
	s_nop 0
	global_load_lds_dwordx4 v[188:189], off
	v_lshl_add_u64 v[188:189], v[230:231], 0, s[12:13]
	s_mov_b32 m0, s53
	s_nop 0
	global_load_lds_dwordx4 v[188:189], off
	v_lshl_add_u64 v[188:189], v[232:233], 0, s[12:13]
	s_mov_b32 m0, s55
	s_nop 0
	global_load_lds_dwordx4 v[188:189], off
	s_waitcnt vmcnt(8)
	s_waitcnt lgkmcnt(0)
	s_barrier
	s_setprio 1
	s_waitcnt lgkmcnt(0)
	v_mfma_f32_16x16x32_bf16 v[60:63], v[156:159], v[196:199], v[60:63]
	v_mfma_f32_16x16x32_bf16 v[56:59], v[168:171], v[196:199], v[56:59]
	s_add_i32 s17, s17, 2
	s_add_u32 s40, s40, 0x100
	s_addc_u32 s41, s41, 0
	s_add_u32 s0, s0, 0x100
	s_addc_u32 s1, s1, 0
	v_mfma_f32_16x16x32_bf16 v[44:47], v[156:159], v[204:207], v[44:47]
	v_mfma_f32_16x16x32_bf16 v[40:43], v[168:171], v[204:207], v[40:43]
	v_mfma_f32_16x16x32_bf16 v[28:31], v[156:159], v[212:215], v[28:31]
	v_mfma_f32_16x16x32_bf16 v[24:27], v[168:171], v[212:215], v[24:27]
	v_mfma_f32_16x16x32_bf16 v[12:15], v[156:159], v[220:223], v[12:15]
	v_mfma_f32_16x16x32_bf16 v[8:11], v[168:171], v[220:223], v[8:11]
	v_mfma_f32_16x16x32_bf16 v[60:63], v[164:167], v[200:203], v[60:63]
	v_mfma_f32_16x16x32_bf16 v[56:59], v[172:175], v[200:203], v[56:59]
	v_mfma_f32_16x16x32_bf16 v[44:47], v[164:167], v[208:211], v[44:47]
	v_mfma_f32_16x16x32_bf16 v[40:43], v[172:175], v[208:211], v[40:43]
	v_mfma_f32_16x16x32_bf16 v[28:31], v[164:167], v[216:219], v[28:31]
	v_mfma_f32_16x16x32_bf16 v[24:27], v[172:175], v[216:219], v[24:27]
	v_mfma_f32_16x16x32_bf16 v[12:15], v[164:167], v[224:227], v[12:15]
	v_mfma_f32_16x16x32_bf16 v[8:11], v[172:175], v[224:227], v[8:11]
	s_setprio 0
	s_setprio 1
	v_mfma_f32_16x16x32_bf16 v[52:55], v[176:179], v[196:199], v[52:55]
	v_mfma_f32_16x16x32_bf16 v[48:51], v[184:187], v[196:199], v[48:51]
	v_mfma_f32_16x16x32_bf16 v[36:39], v[176:179], v[204:207], v[36:39]
	v_mfma_f32_16x16x32_bf16 v[32:35], v[184:187], v[204:207], v[32:35]
	v_mfma_f32_16x16x32_bf16 v[20:23], v[176:179], v[212:215], v[20:23]
	v_mfma_f32_16x16x32_bf16 v[16:19], v[184:187], v[212:215], v[16:19]
	v_mfma_f32_16x16x32_bf16 v[4:7], v[176:179], v[220:223], v[4:7]
	v_mfma_f32_16x16x32_bf16 v[0:3], v[184:187], v[220:223], v[0:3]
	v_mfma_f32_16x16x32_bf16 v[52:55], v[180:183], v[200:203], v[52:55]
	v_mfma_f32_16x16x32_bf16 v[48:51], v[192:195], v[200:203], v[48:51]
	v_mfma_f32_16x16x32_bf16 v[36:39], v[180:183], v[208:211], v[36:39]
	v_mfma_f32_16x16x32_bf16 v[32:35], v[192:195], v[208:211], v[32:35]
	v_mfma_f32_16x16x32_bf16 v[20:23], v[180:183], v[216:219], v[20:23]
	v_mfma_f32_16x16x32_bf16 v[16:19], v[192:195], v[216:219], v[16:19]
	v_mfma_f32_16x16x32_bf16 v[4:7], v[180:183], v[224:227], v[4:7]
	v_mfma_f32_16x16x32_bf16 v[0:3], v[192:195], v[224:227], v[0:3]
	s_setprio 0
	s_barrier
	s_cmp_gt_u32 s17, 29
	s_cbranch_scc0 .LBB0_820

; #define PG8_STAGE(bufoff, gbase, voff) do { _Pragma("unroll") for (int _i = 0; _i < 2; ++_i) \
;         __builtin_amdgcn_global_load_lds((const unsigned*)((const char*)(gbase) + (voff)[_i]), (LAS unsigned*)(lds + (bufoff) + ldsw + _i * 8192), 16, 0, 0); } while (0)
; #define PG8_LDA(dst, b, h) do { _Pragma("unroll") for (int m = 0; m < 4; ++m) _Pragma("unroll") for (int k = 0; k < 2; ++k) dst[m][k] = *(const LAS bf16x8*)(lds + PG8_SA(b, h) + aoff + m * 2048 + k * 1024); } while (0)
; #define PG8_LDB(dst, b, h) do { _Pragma("unroll") for (int n = 0; n < 2; ++n) _Pragma("unroll") for (int k = 0; k < 2; ++k) dst[n][k] = *(const LAS bf16x8*)(lds + PG8_SB(b, h) + boff + n * 2048 + k * 1024); } while (0)
; #define PG8_MMA(ai, bj, At, Bt) do { __builtin_amdgcn_s_setprio(1); _Pragma("unroll") for (int m = 0; m < 4; ++m) _Pragma("unroll") for (int n = 0; n < 2; ++n) _Pragma("unroll") for (int k = 0; k < 2; ++k) \
;         acc[ai][bj][m][n] = __builtin_amdgcn_mfma_f32_16x16x32_bf16(Bt[n][k], At[m][k], acc[ai][bj][m][n], 0, 0, 0); __builtin_amdgcn_s_setprio(0); } while (0)
; #define PG8_WAIT_V(n) asm volatile("s_waitcnt vmcnt(" #n ")" ::: "memory")
; #define PG8_BAR __builtin_amdgcn_s_barrier()
; template <int GI>
; __device__ __forceinline__ void gemm_phase(LAS unsigned char* lds, unsigned char* ws, int G, int cblk) {
;     ...
;     for (;;) {
;         const bool has_next = sched_next<GI>(ws, ui + 1, G, cblk, nxt);
;         const char* nA = has_next ? nxt.A : cA; const char* nB = has_next ? nxt.B : cB;
;         for (int t = 0; t < nt; t += 2) {
;             const bool last = (t == nt - 2);
;             const char* a1 = cA + (size_t)(t + 1) * kstep;
;             const char* a2 = last ? nA : cA + (size_t)(t + 2) * kstep; const char* b2 = last ? nB : cB + (size_t)(t + 2) * kstep;
;             const char* a3 = a2 + kstep; const char* b3 = b2 + kstep;
;             PG8_LDB(B0, 0, 0); PG8_LDB(B1, 0, 1); PG8_SCHED; PG8_LDA(At, 0, 0); PG8_STAGE(PG8_SA(1, 1), a1 + hstepA, voffA);
;             PG8_WAIT_V(8); PG8_WAIT_L(0); PG8_BAR; PG8_MMA(0, 0, At, B0); PG8_MMA(0, 1, At, B1); PG8_BAR; PG8_SCHED;
;             PG8_LDA(At, 0, 1); PG8_STAGE(PG8_SB(0, 0), b2, voffB); PG8_STAGE(PG8_SB(0, 1), b2 + hstepB, voffB); PG8_STAGE(PG8_SA(0, 0), a2, voffA);
;             PG8_WAIT_V(8); PG8_WAIT_L(0); PG8_BAR; PG8_MMA(1, 0, At, B0); PG8_MMA(1, 1, At, B1); PG8_BAR; PG8_SCHED;
.LBB0_895:
	s_add_u32 s15, s40, 0x100
	s_addc_u32 s53, s41, 0
	s_mov_b32 s54, -2
	ds_read_b128 v[156:159], v153
	ds_read_b128 v[164:167], v153 offset:1024
	ds_read_b128 v[168:171], v153 offset:2048
	ds_read_b128 v[172:175], v153 offset:3072
	ds_read_b128 v[176:179], v154
	ds_read_b128 v[180:183], v154 offset:1024
	ds_read_b128 v[184:187], v154 offset:2048
	ds_read_b128 v[192:195], v154 offset:3072
	s_add_u32 s40, s38, 0x100
	s_addc_u32 s41, s39, 0
	s_cmpk_eq_i32 s54, 0x54
	s_cselect_b32 s45, s21, s41
	s_cselect_b32 s44, s20, s40
	s_cselect_b32 s43, s23, s53
	s_cselect_b32 s42, s22, s15
	v_lshl_add_u64 v[188:189], s[38:39], 0, v[140:141]
	s_add_i32 m0, s24, 0xc000
	ds_read_b128 v[196:199], v155
	ds_read_b128 v[200:203], v155 offset:1024
	ds_read_b128 v[204:207], v155 offset:2048
	ds_read_b128 v[208:211], v155 offset:3072
	ds_read_b128 v[212:215], v155 offset:4096
	ds_read_b128 v[216:219], v155 offset:5120
	ds_read_b128 v[220:223], v155 offset:6144
	ds_read_b128 v[224:227], v155 offset:7168
	global_load_lds_dwordx4 v[188:189], off
	v_lshl_add_u64 v[188:189], s[38:39], 0, v[142:143]
	s_add_i32 m0, s24, 0xe000
	s_nop 0
	global_load_lds_dwordx4 v[188:189], off
	s_waitcnt vmcnt(8)
	s_waitcnt lgkmcnt(0)
	s_barrier
	s_setprio 1
	s_waitcnt lgkmcnt(0)
	v_mfma_f32_16x16x32_bf16 v[124:127], v[156:159], v[196:199], 0
	v_mfma_f32_16x16x32_bf16 v[120:123], v[168:171], v[196:199], 0
	v_mfma_f32_16x16x32_bf16 v[116:119], v[156:159], v[204:207], 0
	v_mfma_f32_16x16x32_bf16 v[112:115], v[168:171], v[204:207], 0
	v_mfma_f32_16x16x32_bf16 v[100:103], v[156:159], v[212:215], 0
	v_mfma_f32_16x16x32_bf16 v[96:99], v[168:171], v[212:215], 0
	v_mfma_f32_16x16x32_bf16 v[84:87], v[156:159], v[220:223], 0
	v_mfma_f32_16x16x32_bf16 v[80:83], v[168:171], v[220:223], 0
	v_mfma_f32_16x16x32_bf16 v[124:127], v[164:167], v[200:203], v[124:127]
	v_mfma_f32_16x16x32_bf16 v[120:123], v[172:175], v[200:203], v[120:123]
	v_mfma_f32_16x16x32_bf16 v[116:119], v[164:167], v[208:211], v[116:119]
	v_mfma_f32_16x16x32_bf16 v[112:115], v[172:175], v[208:211], v[112:115]
	v_mfma_f32_16x16x32_bf16 v[100:103], v[164:167], v[216:219], v[100:103]
	v_mfma_f32_16x16x32_bf16 v[96:99], v[172:175], v[216:219], v[96:99]
	v_mfma_f32_16x16x32_bf16 v[84:87], v[164:167], v[224:227], v[84:87]
	v_mfma_f32_16x16x32_bf16 v[80:83], v[172:175], v[224:227], v[80:83]
	s_setprio 0
	s_setprio 1
	v_mfma_f32_16x16x32_bf16 v[108:111], v[176:179], v[196:199], 0
	v_mfma_f32_16x16x32_bf16 v[104:107], v[184:187], v[196:199], 0
	v_mfma_f32_16x16x32_bf16 v[92:95], v[176:179], v[204:207], 0
	v_mfma_f32_16x16x32_bf16 v[88:91], v[184:187], v[204:207], 0
	v_mfma_f32_16x16x32_bf16 v[76:79], v[176:179], v[212:215], 0
	v_mfma_f32_16x16x32_bf16 v[72:75], v[184:187], v[212:215], 0
	v_mfma_f32_16x16x32_bf16 v[68:71], v[176:179], v[220:223], 0
	v_mfma_f32_16x16x32_bf16 v[64:67], v[184:187], v[220:223], 0
	v_mfma_f32_16x16x32_bf16 v[108:111], v[180:183], v[200:203], v[108:111]
	v_mfma_f32_16x16x32_bf16 v[104:107], v[192:195], v[200:203], v[104:107]
	v_mfma_f32_16x16x32_bf16 v[92:95], v[180:183], v[208:211], v[92:95]
	v_mfma_f32_16x16x32_bf16 v[88:91], v[192:195], v[208:211], v[88:91]
	v_mfma_f32_16x16x32_bf16 v[76:79], v[180:183], v[216:219], v[76:79]
	v_mfma_f32_16x16x32_bf16 v[72:75], v[192:195], v[216:219], v[72:75]
	v_mfma_f32_16x16x32_bf16 v[68:71], v[180:183], v[224:227], v[68:71]
	v_mfma_f32_16x16x32_bf16 v[64:67], v[192:195], v[224:227], v[64:67]
	s_setprio 0
	s_barrier
	s_add_i32 s34, s50, s0
	v_lshl_add_u64 v[188:189], s[42:43], 0, v[132:133]
	s_mov_b32 m0, s34
	ds_read_b128 v[196:199], v155 offset:16384
	ds_read_b128 v[200:203], v155 offset:17408
	ds_read_b128 v[204:207], v155 offset:18432
	ds_read_b128 v[208:211], v155 offset:19456
	ds_read_b128 v[212:215], v155 offset:20480
	ds_read_b128 v[216:219], v155 offset:21504
	ds_read_b128 v[220:223], v155 offset:22528
	ds_read_b128 v[224:227], v155 offset:23552
	global_load_lds_dwordx4 v[188:189], off
	s_add_i32 m0, s34, 0x2000
	s_add_u32 s38, s42, 0x160000
	v_lshl_add_u64 v[228:229], s[42:43], 0, v[136:137]
	s_addc_u32 s39, s43, 0
	s_add_i32 s34, s51, s0
	global_load_lds_dwordx4 v[228:229], off
	v_lshl_add_u64 v[230:231], s[38:39], 0, v[132:133]
	s_mov_b32 m0, s34
	v_lshl_add_u64 v[232:233], s[44:45], 0, v[134:135]
	global_load_lds_dwordx4 v[230:231], off
	v_lshl_add_u64 v[230:231], s[38:39], 0, v[136:137]
	s_add_i32 m0, s34, 0x2000
	s_nop 0
	global_load_lds_dwordx4 v[230:231], off
	v_lshl_add_u64 v[230:231], s[44:45], 0, v[130:131]
	s_mov_b32 m0, s24
	s_nop 0
	global_load_lds_dwordx4 v[230:231], off
	s_mov_b32 m0, s25
	s_nop 0
	global_load_lds_dwordx4 v[232:233], off
	s_waitcnt vmcnt(8)
	s_waitcnt lgkmcnt(0)
	s_barrier
; #define PG8_STAGE(bufoff, gbase, voff) do { _Pragma("unroll") for (int _i = 0; _i < 2; ++_i) \
;         __builtin_amdgcn_global_load_lds((const unsigned*)((const char*)(gbase) + (voff)[_i]), (LAS unsigned*)(lds + (bufoff) + ldsw + _i * 8192), 16, 0, 0); } while (0)
; #define PG8_LDA(dst, b, h) do { _Pragma("unroll") for (int m = 0; m < 4; ++m) _Pragma("unroll") for (int k = 0; k < 2; ++k) dst[m][k] = *(const LAS bf16x8*)(lds + PG8_SA(b, h) + aoff + m * 2048 + k * 1024); } while (0)
; #define PG8_LDB(dst, b, h) do { _Pragma("unroll") for (int n = 0; n < 2; ++n) _Pragma("unroll") for (int k = 0; k < 2; ++k) dst[n][k] = *(const LAS bf16x8*)(lds + PG8_SB(b, h) + boff + n * 2048 + k * 1024); } while (0)
; #define PG8_MMA(ai, bj, At, Bt) do { __builtin_amdgcn_s_setprio(1); _Pragma("unroll") for (int m = 0; m < 4; ++m) _Pragma("unroll") for (int n = 0; n < 2; ++n) _Pragma("unroll") for (int k = 0; k < 2; ++k) \
;         acc[ai][bj][m][n] = __builtin_amdgcn_mfma_f32_16x16x32_bf16(Bt[n][k], At[m][k], acc[ai][bj][m][n], 0, 0, 0); __builtin_amdgcn_s_setprio(0); } while (0)
; #define PG8_WAIT_V(n) asm volatile("s_waitcnt vmcnt(" #n ")" ::: "memory")
; #define PG8_WAIT_L(n) asm volatile("s_waitcnt lgkmcnt(" #n ")" ::: "memory")
; #define PG8_BAR __builtin_amdgcn_s_barrier()
; #define PG8_SCHED __builtin_amdgcn_sched_barrier(0)
; template <int GI>
; __device__ __forceinline__ void gemm_phase(LAS unsigned char* lds, unsigned char* ws, int G, int cblk) {
;     ...
;             PG8_WAIT_V(8); PG8_WAIT_L(0); PG8_BAR; PG8_MMA(1, 0, At, B0); PG8_MMA(1, 1, At, B1); PG8_BAR; PG8_SCHED;
;             PG8_LDB(B0, 1, 0); PG8_LDB(B1, 1, 1); PG8_SCHED; PG8_LDA(At, 1, 0); PG8_STAGE(PG8_SA(0, 1), a2 + hstepA, voffA);
;             PG8_WAIT_V(8); PG8_WAIT_L(0); PG8_BAR; PG8_MMA(0, 0, At, B0); PG8_MMA(0, 1, At, B1); PG8_BAR; PG8_SCHED;
	s_setprio 1
	s_waitcnt lgkmcnt(0)
	v_mfma_f32_16x16x32_bf16 v[60:63], v[156:159], v[196:199], 0
	v_mfma_f32_16x16x32_bf16 v[56:59], v[168:171], v[196:199], 0
	v_mfma_f32_16x16x32_bf16 v[52:55], v[156:159], v[204:207], 0
	v_mfma_f32_16x16x32_bf16 v[48:51], v[168:171], v[204:207], 0
	v_mfma_f32_16x16x32_bf16 v[36:39], v[156:159], v[212:215], 0
	v_mfma_f32_16x16x32_bf16 v[32:35], v[168:171], v[212:215], 0
	v_mfma_f32_16x16x32_bf16 v[20:23], v[156:159], v[220:223], 0
	v_mfma_f32_16x16x32_bf16 v[16:19], v[168:171], v[220:223], 0
	v_mfma_f32_16x16x32_bf16 v[60:63], v[164:167], v[200:203], v[60:63]
	v_mfma_f32_16x16x32_bf16 v[56:59], v[172:175], v[200:203], v[56:59]
	v_mfma_f32_16x16x32_bf16 v[52:55], v[164:167], v[208:211], v[52:55]
	v_mfma_f32_16x16x32_bf16 v[48:51], v[172:175], v[208:211], v[48:51]
	v_mfma_f32_16x16x32_bf16 v[36:39], v[164:167], v[216:219], v[36:39]
	v_mfma_f32_16x16x32_bf16 v[32:35], v[172:175], v[216:219], v[32:35]
	v_mfma_f32_16x16x32_bf16 v[20:23], v[164:167], v[224:227], v[20:23]
	v_mfma_f32_16x16x32_bf16 v[16:19], v[172:175], v[224:227], v[16:19]
	s_setprio 0
	s_setprio 1
	v_mfma_f32_16x16x32_bf16 v[44:47], v[176:179], v[196:199], 0
	v_mfma_f32_16x16x32_bf16 v[40:43], v[184:187], v[196:199], 0
	v_mfma_f32_16x16x32_bf16 v[28:31], v[176:179], v[204:207], 0
	v_mfma_f32_16x16x32_bf16 v[24:27], v[184:187], v[204:207], 0
	v_mfma_f32_16x16x32_bf16 v[12:15], v[176:179], v[212:215], 0
	v_mfma_f32_16x16x32_bf16 v[8:11], v[184:187], v[212:215], 0
	v_mfma_f32_16x16x32_bf16 v[4:7], v[176:179], v[220:223], 0
	v_mfma_f32_16x16x32_bf16 v[0:3], v[184:187], v[220:223], 0
	v_mfma_f32_16x16x32_bf16 v[44:47], v[180:183], v[200:203], v[44:47]
	v_mfma_f32_16x16x32_bf16 v[40:43], v[192:195], v[200:203], v[40:43]
	v_mfma_f32_16x16x32_bf16 v[28:31], v[180:183], v[208:211], v[28:31]
	v_mfma_f32_16x16x32_bf16 v[24:27], v[192:195], v[208:211], v[24:27]
	v_mfma_f32_16x16x32_bf16 v[12:15], v[180:183], v[216:219], v[12:15]
	v_mfma_f32_16x16x32_bf16 v[8:11], v[192:195], v[216:219], v[8:11]
	v_mfma_f32_16x16x32_bf16 v[4:7], v[180:183], v[224:227], v[4:7]
	v_mfma_f32_16x16x32_bf16 v[0:3], v[192:195], v[224:227], v[0:3]
	s_setprio 0
	s_barrier
	s_add_i32 s34, 0, 0x18000
	v_add_u32_e32 v161, s34, v152
	s_add_i32 s55, 0, 0x1c000
	ds_read_b128 v[156:159], v161
	ds_read_b128 v[164:167], v161 offset:1024
	ds_read_b128 v[168:171], v161 offset:2048
	ds_read_b128 v[172:175], v161 offset:3072
	v_add_u32_e32 v161, s55, v152
	ds_read_b128 v[176:179], v161
	ds_read_b128 v[180:183], v161 offset:1024
	ds_read_b128 v[184:187], v161 offset:2048
	ds_read_b128 v[192:195], v161 offset:3072
	s_add_u32 s38, s44, 0x160000
	s_addc_u32 s39, s45, 0
	s_mov_b32 m0, s26
	v_lshl_add_u64 v[234:235], s[38:39], 0, v[130:131]
	ds_read_b128 v[196:199], v155 offset:32768
	ds_read_b128 v[200:203], v155 offset:33792
	ds_read_b128 v[204:207], v155 offset:34816
	ds_read_b128 v[208:211], v155 offset:35840
	ds_read_b128 v[212:215], v155 offset:36864
	ds_read_b128 v[216:219], v155 offset:37888
	ds_read_b128 v[220:223], v155 offset:38912
	ds_read_b128 v[224:227], v155 offset:39936
	global_load_lds_dwordx4 v[234:235], off
	v_lshl_add_u64 v[234:235], s[38:39], 0, v[134:135]
	s_mov_b32 m0, s27
	s_nop 0
	global_load_lds_dwordx4 v[234:235], off
	s_waitcnt vmcnt(8)
	s_waitcnt lgkmcnt(0)
	s_barrier
	s_setprio 1
	s_waitcnt lgkmcnt(0)
	v_mfma_f32_16x16x32_bf16 v[124:127], v[156:159], v[196:199], v[124:127]
	v_mfma_f32_16x16x32_bf16 v[120:123], v[168:171], v[196:199], v[120:123]
	v_mfma_f32_16x16x32_bf16 v[116:119], v[156:159], v[204:207], v[116:119]
	v_mfma_f32_16x16x32_bf16 v[112:115], v[168:171], v[204:207], v[112:115]
	v_mfma_f32_16x16x32_bf16 v[100:103], v[156:159], v[212:215], v[100:103]
	v_mfma_f32_16x16x32_bf16 v[96:99], v[168:171], v[212:215], v[96:99]
	v_mfma_f32_16x16x32_bf16 v[84:87], v[156:159], v[220:223], v[84:87]
	v_mfma_f32_16x16x32_bf16 v[80:83], v[168:171], v[220:223], v[80:83]
	v_mfma_f32_16x16x32_bf16 v[124:127], v[164:167], v[200:203], v[124:127]
	v_mfma_f32_16x16x32_bf16 v[120:123], v[172:175], v[200:203], v[120:123]
	v_mfma_f32_16x16x32_bf16 v[116:119], v[164:167], v[208:211], v[116:119]
	v_mfma_f32_16x16x32_bf16 v[112:115], v[172:175], v[208:211], v[112:115]
	v_mfma_f32_16x16x32_bf16 v[100:103], v[164:167], v[216:219], v[100:103]
	v_mfma_f32_16x16x32_bf16 v[96:99], v[172:175], v[216:219], v[96:99]
	v_mfma_f32_16x16x32_bf16 v[84:87], v[164:167], v[224:227], v[84:87]
	v_mfma_f32_16x16x32_bf16 v[80:83], v[172:175], v[224:227], v[80:83]
	s_setprio 0
	s_setprio 1
	v_mfma_f32_16x16x32_bf16 v[108:111], v[176:179], v[196:199], v[108:111]
	v_mfma_f32_16x16x32_bf16 v[104:107], v[184:187], v[196:199], v[104:107]
	v_mfma_f32_16x16x32_bf16 v[92:95], v[176:179], v[204:207], v[92:95]
	v_mfma_f32_16x16x32_bf16 v[88:91], v[184:187], v[204:207], v[88:91]
	v_mfma_f32_16x16x32_bf16 v[76:79], v[176:179], v[212:215], v[76:79]
	v_mfma_f32_16x16x32_bf16 v[72:75], v[184:187], v[212:215], v[72:75]
	v_mfma_f32_16x16x32_bf16 v[68:71], v[176:179], v[220:223], v[68:71]
	v_mfma_f32_16x16x32_bf16 v[64:67], v[184:187], v[220:223], v[64:67]
	v_mfma_f32_16x16x32_bf16 v[108:111], v[180:183], v[200:203], v[108:111]
	v_mfma_f32_16x16x32_bf16 v[104:107], v[192:195], v[200:203], v[104:107]
	v_mfma_f32_16x16x32_bf16 v[92:95], v[180:183], v[208:211], v[92:95]
	v_mfma_f32_16x16x32_bf16 v[88:91], v[192:195], v[208:211], v[88:91]
	v_mfma_f32_16x16x32_bf16 v[76:79], v[180:183], v[216:219], v[76:79]
	v_mfma_f32_16x16x32_bf16 v[72:75], v[192:195], v[216:219], v[72:75]
	v_mfma_f32_16x16x32_bf16 v[68:71], v[180:183], v[224:227], v[68:71]
	v_mfma_f32_16x16x32_bf16 v[64:67], v[192:195], v[224:227], v[64:67]
	s_setprio 0
	s_barrier
; #define PG8_STAGE(bufoff, gbase, voff) do { _Pragma("unroll") for (int _i = 0; _i < 2; ++_i) \
;         __builtin_amdgcn_global_load_lds((const unsigned*)((const char*)(gbase) + (voff)[_i]), (LAS unsigned*)(lds + (bufoff) + ldsw + _i * 8192), 16, 0, 0); } while (0)
; #define PG8_LDA(dst, b, h) do { _Pragma("unroll") for (int m = 0; m < 4; ++m) _Pragma("unroll") for (int k = 0; k < 2; ++k) dst[m][k] = *(const LAS bf16x8*)(lds + PG8_SA(b, h) + aoff + m * 2048 + k * 1024); } while (0)
; #define PG8_LDB(dst, b, h) do { _Pragma("unroll") for (int n = 0; n < 2; ++n) _Pragma("unroll") for (int k = 0; k < 2; ++k) dst[n][k] = *(const LAS bf16x8*)(lds + PG8_SB(b, h) + boff + n * 2048 + k * 1024); } while (0)
; #define PG8_WAIT_V(n) asm volatile("s_waitcnt vmcnt(" #n ")" ::: "memory")
; #define PG8_WAIT_L(n) asm volatile("s_waitcnt lgkmcnt(" #n ")" ::: "memory")
; template <int GI>
; __device__ __forceinline__ void gemm_phase(LAS unsigned char* lds, unsigned char* ws, int G, int cblk) {
;     ...
;         for (int t = 0; t < nt; t += 2) {
;             const bool last = (t == nt - 2);
;             const char* a1 = cA + (size_t)(t + 1) * kstep;
;             const char* a2 = last ? nA : cA + (size_t)(t + 2) * kstep; const char* b2 = last ? nB : cB + (size_t)(t + 2) * kstep;
;             const char* a3 = a2 + kstep; const char* b3 = b2 + kstep;
;             PG8_LDB(B0, 0, 0); PG8_LDB(B1, 0, 1); PG8_SCHED; PG8_LDA(At, 0, 0); PG8_STAGE(PG8_SA(1, 1), a1 + hstepA, voffA);
;             PG8_WAIT_V(8); PG8_WAIT_L(0); PG8_BAR; PG8_MMA(0, 0, At, B0); PG8_MMA(0, 1, At, B1); PG8_BAR; PG8_SCHED;
;             PG8_LDA(At, 0, 1); PG8_STAGE(PG8_SB(0, 0), b2, voffB); PG8_STAGE(PG8_SB(0, 1), b2 + hstepB, voffB); PG8_STAGE(PG8_SA(0, 0), a2, voffA);
;             PG8_WAIT_V(8); PG8_WAIT_L(0); PG8_BAR; PG8_MMA(1, 0, At, B0); PG8_MMA(1, 1, At, B1); PG8_BAR; PG8_SCHED;
;             PG8_LDB(B0, 1, 0); PG8_LDB(B1, 1, 1); PG8_SCHED; PG8_LDA(At, 1, 0); PG8_STAGE(PG8_SA(0, 1), a2 + hstepA, voffA);
;             PG8_WAIT_V(8); PG8_WAIT_L(0); PG8_BAR; PG8_MMA(0, 0, At, B0); PG8_MMA(0, 1, At, B1); PG8_BAR; PG8_SCHED;
;             PG8_LDA(At, 1, 1); PG8_STAGE(PG8_SB(1, 0), b3, voffB); PG8_STAGE(PG8_SB(1, 1), b3 + hstepB, voffB); PG8_STAGE(PG8_SA(1, 0), a3, voffA);
;             PG8_WAIT_V(8); PG8_WAIT_L(0); PG8_BAR; PG8_MMA(1, 0, At, B0); PG8_MMA(1, 1, At, B1); PG8_BAR; PG8_SCHED;
	s_add_i32 s34, s34, s0
	v_lshl_add_u64 v[188:189], v[188:189], 0, s[10:11]
	s_mov_b32 m0, s34
	ds_read_b128 v[196:199], v155 offset:49152
	ds_read_b128 v[200:203], v155 offset:50176
	ds_read_b128 v[204:207], v155 offset:51200
	ds_read_b128 v[208:211], v155 offset:52224
	ds_read_b128 v[212:215], v155 offset:53248
	ds_read_b128 v[216:219], v155 offset:54272
	ds_read_b128 v[220:223], v155 offset:55296
	ds_read_b128 v[224:227], v155 offset:56320
	global_load_lds_dwordx4 v[188:189], off
	s_add_i32 m0, s34, 0x2000
	s_add_u32 s38, s42, 0x160080
	v_lshl_add_u64 v[188:189], v[228:229], 0, s[10:11]
	s_addc_u32 s39, s43, 0
	s_add_i32 s34, s55, s0
	global_load_lds_dwordx4 v[188:189], off
	v_lshl_add_u64 v[188:189], s[38:39], 0, v[132:133]
	s_mov_b32 m0, s34
	s_nop 0
	global_load_lds_dwordx4 v[188:189], off
	v_lshl_add_u64 v[188:189], s[38:39], 0, v[136:137]
	s_add_i32 m0, s34, 0x2000
	s_nop 0
	global_load_lds_dwordx4 v[188:189], off
	v_lshl_add_u64 v[188:189], v[230:231], 0, s[10:11]
	s_mov_b32 m0, s48
	s_nop 0
	global_load_lds_dwordx4 v[188:189], off
	v_lshl_add_u64 v[188:189], v[232:233], 0, s[10:11]
	s_mov_b32 m0, s49
	s_nop 0
	global_load_lds_dwordx4 v[188:189], off
	s_waitcnt vmcnt(8)
	s_waitcnt lgkmcnt(0)
	s_barrier
	s_setprio 1
	s_waitcnt lgkmcnt(0)
	v_mfma_f32_16x16x32_bf16 v[60:63], v[156:159], v[196:199], v[60:63]
	v_mfma_f32_16x16x32_bf16 v[56:59], v[168:171], v[196:199], v[56:59]
	s_add_i32 s54, s54, 2
	s_add_u32 s15, s15, 0x100
	s_addc_u32 s53, s53, 0
	s_mov_b64 s[38:39], s[40:41]
	v_mfma_f32_16x16x32_bf16 v[52:55], v[156:159], v[204:207], v[52:55]
	v_mfma_f32_16x16x32_bf16 v[48:51], v[168:171], v[204:207], v[48:51]
	v_mfma_f32_16x16x32_bf16 v[36:39], v[156:159], v[212:215], v[36:39]
	v_mfma_f32_16x16x32_bf16 v[32:35], v[168:171], v[212:215], v[32:35]
	v_mfma_f32_16x16x32_bf16 v[20:23], v[156:159], v[220:223], v[20:23]
	v_mfma_f32_16x16x32_bf16 v[16:19], v[168:171], v[220:223], v[16:19]
	v_mfma_f32_16x16x32_bf16 v[60:63], v[164:167], v[200:203], v[60:63]
	v_mfma_f32_16x16x32_bf16 v[56:59], v[172:175], v[200:203], v[56:59]
	v_mfma_f32_16x16x32_bf16 v[52:55], v[164:167], v[208:211], v[52:55]
	v_mfma_f32_16x16x32_bf16 v[48:51], v[172:175], v[208:211], v[48:51]
	v_mfma_f32_16x16x32_bf16 v[36:39], v[164:167], v[216:219], v[36:39]
	v_mfma_f32_16x16x32_bf16 v[32:35], v[172:175], v[216:219], v[32:35]
	v_mfma_f32_16x16x32_bf16 v[20:23], v[164:167], v[224:227], v[20:23]
	v_mfma_f32_16x16x32_bf16 v[16:19], v[172:175], v[224:227], v[16:19]
	s_setprio 0
	s_setprio 1
	v_mfma_f32_16x16x32_bf16 v[44:47], v[176:179], v[196:199], v[44:47]
	v_mfma_f32_16x16x32_bf16 v[40:43], v[184:187], v[196:199], v[40:43]
	v_mfma_f32_16x16x32_bf16 v[28:31], v[176:179], v[204:207], v[28:31]
	v_mfma_f32_16x16x32_bf16 v[24:27], v[184:187], v[204:207], v[24:27]
	v_mfma_f32_16x16x32_bf16 v[12:15], v[176:179], v[212:215], v[12:15]
	v_mfma_f32_16x16x32_bf16 v[8:11], v[184:187], v[212:215], v[8:11]
	v_mfma_f32_16x16x32_bf16 v[4:7], v[176:179], v[220:223], v[4:7]
	v_mfma_f32_16x16x32_bf16 v[0:3], v[184:187], v[220:223], v[0:3]
	v_mfma_f32_16x16x32_bf16 v[44:47], v[180:183], v[200:203], v[44:47]
	v_mfma_f32_16x16x32_bf16 v[40:43], v[192:195], v[200:203], v[40:43]
	v_mfma_f32_16x16x32_bf16 v[28:31], v[180:183], v[208:211], v[28:31]
	v_mfma_f32_16x16x32_bf16 v[24:27], v[192:195], v[208:211], v[24:27]
	v_mfma_f32_16x16x32_bf16 v[12:15], v[180:183], v[216:219], v[12:15]
	v_mfma_f32_16x16x32_bf16 v[8:11], v[192:195], v[216:219], v[8:11]
	v_mfma_f32_16x16x32_bf16 v[4:7], v[180:183], v[224:227], v[4:7]
	v_mfma_f32_16x16x32_bf16 v[0:3], v[192:195], v[224:227], v[0:3]
	s_setprio 0
	s_barrier
	s_cmpk_gt_u32 s54, 0x55
	s_cbranch_scc0 .LBB0_896
	s_branch .Lpeel_exit_9
.LBB0_896:
	ds_read_b128 v[156:159], v153
	ds_read_b128 v[164:167], v153 offset:1024
	ds_read_b128 v[168:171], v153 offset:2048
	ds_read_b128 v[172:175], v153 offset:3072
	ds_read_b128 v[176:179], v154
	ds_read_b128 v[180:183], v154 offset:1024
	ds_read_b128 v[184:187], v154 offset:2048
	ds_read_b128 v[192:195], v154 offset:3072
	s_add_u32 s40, s38, 0x100
	s_addc_u32 s41, s39, 0
	s_cmpk_eq_i32 s54, 0x54
	s_cselect_b32 s45, s21, s41
	s_cselect_b32 s44, s20, s40
	s_cselect_b32 s43, s23, s53
	s_cselect_b32 s42, s22, s15
	v_lshl_add_u64 v[188:189], s[38:39], 0, v[140:141]
	s_add_i32 m0, s24, 0xc000
	ds_read_b128 v[196:199], v155
	ds_read_b128 v[200:203], v155 offset:1024
	ds_read_b128 v[204:207], v155 offset:2048
	ds_read_b128 v[208:211], v155 offset:3072
	ds_read_b128 v[212:215], v155 offset:4096
	ds_read_b128 v[216:219], v155 offset:5120
	ds_read_b128 v[220:223], v155 offset:6144
	ds_read_b128 v[224:227], v155 offset:7168
	global_load_lds_dwordx4 v[188:189], off
	v_lshl_add_u64 v[188:189], s[38:39], 0, v[142:143]
	s_add_i32 m0, s24, 0xe000
	s_nop 0
	global_load_lds_dwordx4 v[188:189], off
	s_waitcnt vmcnt(8)
	s_waitcnt lgkmcnt(0)
	s_barrier
; #define PG8_STAGE(bufoff, gbase, voff) do { _Pragma("unroll") for (int _i = 0; _i < 2; ++_i) \
;         __builtin_amdgcn_global_load_lds((const unsigned*)((const char*)(gbase) + (voff)[_i]), (LAS unsigned*)(lds + (bufoff) + ldsw + _i * 8192), 16, 0, 0); } while (0)
; #define PG8_LDA(dst, b, h) do { _Pragma("unroll") for (int m = 0; m < 4; ++m) _Pragma("unroll") for (int k = 0; k < 2; ++k) dst[m][k] = *(const LAS bf16x8*)(lds + PG8_SA(b, h) + aoff + m * 2048 + k * 1024); } while (0)
; #define PG8_MMA(ai, bj, At, Bt) do { __builtin_amdgcn_s_setprio(1); _Pragma("unroll") for (int m = 0; m < 4; ++m) _Pragma("unroll") for (int n = 0; n < 2; ++n) _Pragma("unroll") for (int k = 0; k < 2; ++k) \
;         acc[ai][bj][m][n] = __builtin_amdgcn_mfma_f32_16x16x32_bf16(Bt[n][k], At[m][k], acc[ai][bj][m][n], 0, 0, 0); __builtin_amdgcn_s_setprio(0); } while (0)
; #define PG8_WAIT_V(n) asm volatile("s_waitcnt vmcnt(" #n ")" ::: "memory")
; #define PG8_WAIT_L(n) asm volatile("s_waitcnt lgkmcnt(" #n ")" ::: "memory")
; #define PG8_BAR __builtin_amdgcn_s_barrier()
; #define PG8_SCHED __builtin_amdgcn_sched_barrier(0)
; template <int GI>
; __device__ __forceinline__ void gemm_phase(LAS unsigned char* lds, unsigned char* ws, int G, int cblk) {
;     ...
;             PG8_WAIT_V(8); PG8_WAIT_L(0); PG8_BAR; PG8_MMA(0, 0, At, B0); PG8_MMA(0, 1, At, B1); PG8_BAR; PG8_SCHED;
;             PG8_LDA(At, 0, 1); PG8_STAGE(PG8_SB(0, 0), b2, voffB); PG8_STAGE(PG8_SB(0, 1), b2 + hstepB, voffB); PG8_STAGE(PG8_SA(0, 0), a2, voffA);
;             PG8_WAIT_V(8); PG8_WAIT_L(0); PG8_BAR; PG8_MMA(1, 0, At, B0); PG8_MMA(1, 1, At, B1); PG8_BAR; PG8_SCHED;
	s_setprio 1
	s_waitcnt lgkmcnt(0)
	v_mfma_f32_16x16x32_bf16 v[124:127], v[156:159], v[196:199], v[124:127]
	v_mfma_f32_16x16x32_bf16 v[120:123], v[168:171], v[196:199], v[120:123]
	v_mfma_f32_16x16x32_bf16 v[116:119], v[156:159], v[204:207], v[116:119]
	v_mfma_f32_16x16x32_bf16 v[112:115], v[168:171], v[204:207], v[112:115]
	v_mfma_f32_16x16x32_bf16 v[100:103], v[156:159], v[212:215], v[100:103]
	v_mfma_f32_16x16x32_bf16 v[96:99], v[168:171], v[212:215], v[96:99]
	v_mfma_f32_16x16x32_bf16 v[84:87], v[156:159], v[220:223], v[84:87]
	v_mfma_f32_16x16x32_bf16 v[80:83], v[168:171], v[220:223], v[80:83]
	v_mfma_f32_16x16x32_bf16 v[124:127], v[164:167], v[200:203], v[124:127]
	v_mfma_f32_16x16x32_bf16 v[120:123], v[172:175], v[200:203], v[120:123]
	v_mfma_f32_16x16x32_bf16 v[116:119], v[164:167], v[208:211], v[116:119]
	v_mfma_f32_16x16x32_bf16 v[112:115], v[172:175], v[208:211], v[112:115]
	v_mfma_f32_16x16x32_bf16 v[100:103], v[164:167], v[216:219], v[100:103]
	v_mfma_f32_16x16x32_bf16 v[96:99], v[172:175], v[216:219], v[96:99]
	v_mfma_f32_16x16x32_bf16 v[84:87], v[164:167], v[224:227], v[84:87]
	v_mfma_f32_16x16x32_bf16 v[80:83], v[172:175], v[224:227], v[80:83]
	s_setprio 0
	s_setprio 1
	v_mfma_f32_16x16x32_bf16 v[108:111], v[176:179], v[196:199], v[108:111]
	v_mfma_f32_16x16x32_bf16 v[104:107], v[184:187], v[196:199], v[104:107]
	v_mfma_f32_16x16x32_bf16 v[92:95], v[176:179], v[204:207], v[92:95]
	v_mfma_f32_16x16x32_bf16 v[88:91], v[184:187], v[204:207], v[88:91]
	v_mfma_f32_16x16x32_bf16 v[76:79], v[176:179], v[212:215], v[76:79]
	v_mfma_f32_16x16x32_bf16 v[72:75], v[184:187], v[212:215], v[72:75]
	v_mfma_f32_16x16x32_bf16 v[68:71], v[176:179], v[220:223], v[68:71]
	v_mfma_f32_16x16x32_bf16 v[64:67], v[184:187], v[220:223], v[64:67]
	v_mfma_f32_16x16x32_bf16 v[108:111], v[180:183], v[200:203], v[108:111]
	v_mfma_f32_16x16x32_bf16 v[104:107], v[192:195], v[200:203], v[104:107]
	v_mfma_f32_16x16x32_bf16 v[92:95], v[180:183], v[208:211], v[92:95]
	v_mfma_f32_16x16x32_bf16 v[88:91], v[192:195], v[208:211], v[88:91]
	v_mfma_f32_16x16x32_bf16 v[76:79], v[180:183], v[216:219], v[76:79]
	v_mfma_f32_16x16x32_bf16 v[72:75], v[192:195], v[216:219], v[72:75]
	v_mfma_f32_16x16x32_bf16 v[68:71], v[180:183], v[224:227], v[68:71]
	v_mfma_f32_16x16x32_bf16 v[64:67], v[192:195], v[224:227], v[64:67]
	s_setprio 0
	s_barrier
	s_add_i32 s34, s50, s0
	v_lshl_add_u64 v[188:189], s[42:43], 0, v[132:133]
	s_mov_b32 m0, s34
	ds_read_b128 v[196:199], v155 offset:16384
	ds_read_b128 v[200:203], v155 offset:17408
	ds_read_b128 v[204:207], v155 offset:18432
	ds_read_b128 v[208:211], v155 offset:19456
	ds_read_b128 v[212:215], v155 offset:20480
	ds_read_b128 v[216:219], v155 offset:21504
	ds_read_b128 v[220:223], v155 offset:22528
	ds_read_b128 v[224:227], v155 offset:23552
	global_load_lds_dwordx4 v[188:189], off
	s_add_i32 m0, s34, 0x2000
	s_add_u32 s38, s42, 0x160000
	v_lshl_add_u64 v[228:229], s[42:43], 0, v[136:137]
	s_addc_u32 s39, s43, 0
	s_add_i32 s34, s51, s0
	global_load_lds_dwordx4 v[228:229], off
	v_lshl_add_u64 v[230:231], s[38:39], 0, v[132:133]
	s_mov_b32 m0, s34
	v_lshl_add_u64 v[232:233], s[44:45], 0, v[134:135]
	global_load_lds_dwordx4 v[230:231], off
	v_lshl_add_u64 v[230:231], s[38:39], 0, v[136:137]
	s_add_i32 m0, s34, 0x2000
	s_nop 0
	global_load_lds_dwordx4 v[230:231], off
	v_lshl_add_u64 v[230:231], s[44:45], 0, v[130:131]
	s_mov_b32 m0, s24
	s_nop 0
	global_load_lds_dwordx4 v[230:231], off
	s_mov_b32 m0, s25
	s_nop 0
	global_load_lds_dwordx4 v[232:233], off
	s_waitcnt vmcnt(8)
	s_waitcnt lgkmcnt(0)
	s_barrier
	s_setprio 1
	s_waitcnt lgkmcnt(0)
	v_mfma_f32_16x16x32_bf16 v[60:63], v[156:159], v[196:199], v[60:63]
	v_mfma_f32_16x16x32_bf16 v[56:59], v[168:171], v[196:199], v[56:59]
	v_mfma_f32_16x16x32_bf16 v[52:55], v[156:159], v[204:207], v[52:55]
	v_mfma_f32_16x16x32_bf16 v[48:51], v[168:171], v[204:207], v[48:51]
	v_mfma_f32_16x16x32_bf16 v[36:39], v[156:159], v[212:215], v[36:39]
	v_mfma_f32_16x16x32_bf16 v[32:35], v[168:171], v[212:215], v[32:35]
	v_mfma_f32_16x16x32_bf16 v[20:23], v[156:159], v[220:223], v[20:23]
	v_mfma_f32_16x16x32_bf16 v[16:19], v[168:171], v[220:223], v[16:19]
	v_mfma_f32_16x16x32_bf16 v[60:63], v[164:167], v[200:203], v[60:63]
	v_mfma_f32_16x16x32_bf16 v[56:59], v[172:175], v[200:203], v[56:59]
	v_mfma_f32_16x16x32_bf16 v[52:55], v[164:167], v[208:211], v[52:55]
	v_mfma_f32_16x16x32_bf16 v[48:51], v[172:175], v[208:211], v[48:51]
	v_mfma_f32_16x16x32_bf16 v[36:39], v[164:167], v[216:219], v[36:39]
	v_mfma_f32_16x16x32_bf16 v[32:35], v[172:175], v[216:219], v[32:35]
	v_mfma_f32_16x16x32_bf16 v[20:23], v[164:167], v[224:227], v[20:23]
	v_mfma_f32_16x16x32_bf16 v[16:19], v[172:175], v[224:227], v[16:19]
	s_setprio 0
	s_setprio 1
	v_mfma_f32_16x16x32_bf16 v[44:47], v[176:179], v[196:199], v[44:47]
	v_mfma_f32_16x16x32_bf16 v[40:43], v[184:187], v[196:199], v[40:43]
	v_mfma_f32_16x16x32_bf16 v[28:31], v[176:179], v[204:207], v[28:31]
	v_mfma_f32_16x16x32_bf16 v[24:27], v[184:187], v[204:207], v[24:27]
	v_mfma_f32_16x16x32_bf16 v[12:15], v[176:179], v[212:215], v[12:15]
	v_mfma_f32_16x16x32_bf16 v[8:11], v[184:187], v[212:215], v[8:11]
	v_mfma_f32_16x16x32_bf16 v[4:7], v[176:179], v[220:223], v[4:7]
	v_mfma_f32_16x16x32_bf16 v[0:3], v[184:187], v[220:223], v[0:3]
	v_mfma_f32_16x16x32_bf16 v[44:47], v[180:183], v[200:203], v[44:47]
	v_mfma_f32_16x16x32_bf16 v[40:43], v[192:195], v[200:203], v[40:43]
	v_mfma_f32_16x16x32_bf16 v[28:31], v[180:183], v[208:211], v[28:31]
	v_mfma_f32_16x16x32_bf16 v[24:27], v[192:195], v[208:211], v[24:27]
	v_mfma_f32_16x16x32_bf16 v[12:15], v[180:183], v[216:219], v[12:15]
	v_mfma_f32_16x16x32_bf16 v[8:11], v[192:195], v[216:219], v[8:11]
	v_mfma_f32_16x16x32_bf16 v[4:7], v[180:183], v[224:227], v[4:7]
	v_mfma_f32_16x16x32_bf16 v[0:3], v[192:195], v[224:227], v[0:3]
	s_setprio 0
	s_barrier
; #define PG8_STAGE(bufoff, gbase, voff) do { _Pragma("unroll") for (int _i = 0; _i < 2; ++_i) \
;         __builtin_amdgcn_global_load_lds((const unsigned*)((const char*)(gbase) + (voff)[_i]), (LAS unsigned*)(lds + (bufoff) + ldsw + _i * 8192), 16, 0, 0); } while (0)
; #define PG8_LDA(dst, b, h) do { _Pragma("unroll") for (int m = 0; m < 4; ++m) _Pragma("unroll") for (int k = 0; k < 2; ++k) dst[m][k] = *(const LAS bf16x8*)(lds + PG8_SA(b, h) + aoff + m * 2048 + k * 1024); } while (0)
; #define PG8_LDB(dst, b, h) do { _Pragma("unroll") for (int n = 0; n < 2; ++n) _Pragma("unroll") for (int k = 0; k < 2; ++k) dst[n][k] = *(const LAS bf16x8*)(lds + PG8_SB(b, h) + boff + n * 2048 + k * 1024); } while (0)
; #define PG8_MMA(ai, bj, At, Bt) do { __builtin_amdgcn_s_setprio(1); _Pragma("unroll") for (int m = 0; m < 4; ++m) _Pragma("unroll") for (int n = 0; n < 2; ++n) _Pragma("unroll") for (int k = 0; k < 2; ++k) \
;         acc[ai][bj][m][n] = __builtin_amdgcn_mfma_f32_16x16x32_bf16(Bt[n][k], At[m][k], acc[ai][bj][m][n], 0, 0, 0); __builtin_amdgcn_s_setprio(0); } while (0)
; #define PG8_WAIT_V(n) asm volatile("s_waitcnt vmcnt(" #n ")" ::: "memory")
; #define PG8_WAIT_L(n) asm volatile("s_waitcnt lgkmcnt(" #n ")" ::: "memory")
; #define PG8_BAR __builtin_amdgcn_s_barrier()
; #define PG8_SCHED __builtin_amdgcn_sched_barrier(0)
; template <int GI>
; __device__ __forceinline__ void gemm_phase(LAS unsigned char* lds, unsigned char* ws, int G, int cblk) {
;     ...
;             PG8_LDB(B0, 1, 0); PG8_LDB(B1, 1, 1); PG8_SCHED; PG8_LDA(At, 1, 0); PG8_STAGE(PG8_SA(0, 1), a2 + hstepA, voffA);
;             PG8_WAIT_V(8); PG8_WAIT_L(0); PG8_BAR; PG8_MMA(0, 0, At, B0); PG8_MMA(0, 1, At, B1); PG8_BAR; PG8_SCHED;
	s_add_i32 s34, 0, 0x18000
	v_add_u32_e32 v161, s34, v152
	s_add_i32 s55, 0, 0x1c000
	ds_read_b128 v[156:159], v161
	ds_read_b128 v[164:167], v161 offset:1024
	ds_read_b128 v[168:171], v161 offset:2048
	ds_read_b128 v[172:175], v161 offset:3072
	v_add_u32_e32 v161, s55, v152
	ds_read_b128 v[176:179], v161
	ds_read_b128 v[180:183], v161 offset:1024
	ds_read_b128 v[184:187], v161 offset:2048
	ds_read_b128 v[192:195], v161 offset:3072
	s_add_u32 s38, s44, 0x160000
	s_addc_u32 s39, s45, 0
	s_mov_b32 m0, s26
	v_lshl_add_u64 v[234:235], s[38:39], 0, v[130:131]
	ds_read_b128 v[196:199], v155 offset:32768
	ds_read_b128 v[200:203], v155 offset:33792
	ds_read_b128 v[204:207], v155 offset:34816
	ds_read_b128 v[208:211], v155 offset:35840
	ds_read_b128 v[212:215], v155 offset:36864
	ds_read_b128 v[216:219], v155 offset:37888
	ds_read_b128 v[220:223], v155 offset:38912
	ds_read_b128 v[224:227], v155 offset:39936
	global_load_lds_dwordx4 v[234:235], off
	v_lshl_add_u64 v[234:235], s[38:39], 0, v[134:135]
	s_mov_b32 m0, s27
	s_nop 0
	global_load_lds_dwordx4 v[234:235], off
	s_waitcnt vmcnt(8)
	s_waitcnt lgkmcnt(0)
	s_barrier
	s_setprio 1
	s_waitcnt lgkmcnt(0)
	v_mfma_f32_16x16x32_bf16 v[124:127], v[156:159], v[196:199], v[124:127]
	v_mfma_f32_16x16x32_bf16 v[120:123], v[168:171], v[196:199], v[120:123]
	v_mfma_f32_16x16x32_bf16 v[116:119], v[156:159], v[204:207], v[116:119]
	v_mfma_f32_16x16x32_bf16 v[112:115], v[168:171], v[204:207], v[112:115]
	v_mfma_f32_16x16x32_bf16 v[100:103], v[156:159], v[212:215], v[100:103]
	v_mfma_f32_16x16x32_bf16 v[96:99], v[168:171], v[212:215], v[96:99]
	v_mfma_f32_16x16x32_bf16 v[84:87], v[156:159], v[220:223], v[84:87]
	v_mfma_f32_16x16x32_bf16 v[80:83], v[168:171], v[220:223], v[80:83]
	v_mfma_f32_16x16x32_bf16 v[124:127], v[164:167], v[200:203], v[124:127]
	v_mfma_f32_16x16x32_bf16 v[120:123], v[172:175], v[200:203], v[120:123]
	v_mfma_f32_16x16x32_bf16 v[116:119], v[164:167], v[208:211], v[116:119]
	v_mfma_f32_16x16x32_bf16 v[112:115], v[172:175], v[208:211], v[112:115]
	v_mfma_f32_16x16x32_bf16 v[100:103], v[164:167], v[216:219], v[100:103]
	v_mfma_f32_16x16x32_bf16 v[96:99], v[172:175], v[216:219], v[96:99]
	v_mfma_f32_16x16x32_bf16 v[84:87], v[164:167], v[224:227], v[84:87]
	v_mfma_f32_16x16x32_bf16 v[80:83], v[172:175], v[224:227], v[80:83]
	s_setprio 0
	s_setprio 1
	v_mfma_f32_16x16x32_bf16 v[108:111], v[176:179], v[196:199], v[108:111]
	v_mfma_f32_16x16x32_bf16 v[104:107], v[184:187], v[196:199], v[104:107]
	v_mfma_f32_16x16x32_bf16 v[92:95], v[176:179], v[204:207], v[92:95]
	v_mfma_f32_16x16x32_bf16 v[88:91], v[184:187], v[204:207], v[88:91]
	v_mfma_f32_16x16x32_bf16 v[76:79], v[176:179], v[212:215], v[76:79]
	v_mfma_f32_16x16x32_bf16 v[72:75], v[184:187], v[212:215], v[72:75]
	v_mfma_f32_16x16x32_bf16 v[68:71], v[176:179], v[220:223], v[68:71]
	v_mfma_f32_16x16x32_bf16 v[64:67], v[184:187], v[220:223], v[64:67]
	v_mfma_f32_16x16x32_bf16 v[108:111], v[180:183], v[200:203], v[108:111]
	v_mfma_f32_16x16x32_bf16 v[104:107], v[192:195], v[200:203], v[104:107]
	v_mfma_f32_16x16x32_bf16 v[92:95], v[180:183], v[208:211], v[92:95]
	v_mfma_f32_16x16x32_bf16 v[88:91], v[192:195], v[208:211], v[88:91]
	v_mfma_f32_16x16x32_bf16 v[76:79], v[180:183], v[216:219], v[76:79]
	v_mfma_f32_16x16x32_bf16 v[72:75], v[192:195], v[216:219], v[72:75]
	v_mfma_f32_16x16x32_bf16 v[68:71], v[180:183], v[224:227], v[68:71]
	v_mfma_f32_16x16x32_bf16 v[64:67], v[192:195], v[224:227], v[64:67]
	s_setprio 0
	s_barrier
; #define PG8_STAGE(bufoff, gbase, voff) do { _Pragma("unroll") for (int _i = 0; _i < 2; ++_i) \
;         __builtin_amdgcn_global_load_lds((const unsigned*)((const char*)(gbase) + (voff)[_i]), (LAS unsigned*)(lds + (bufoff) + ldsw + _i * 8192), 16, 0, 0); } while (0)
; #define PG8_LDA(dst, b, h) do { _Pragma("unroll") for (int m = 0; m < 4; ++m) _Pragma("unroll") for (int k = 0; k < 2; ++k) dst[m][k] = *(const LAS bf16x8*)(lds + PG8_SA(b, h) + aoff + m * 2048 + k * 1024); } while (0)
; #define PG8_MMA(ai, bj, At, Bt) do { __builtin_amdgcn_s_setprio(1); _Pragma("unroll") for (int m = 0; m < 4; ++m) _Pragma("unroll") for (int n = 0; n < 2; ++n) _Pragma("unroll") for (int k = 0; k < 2; ++k) \
;         acc[ai][bj][m][n] = __builtin_amdgcn_mfma_f32_16x16x32_bf16(Bt[n][k], At[m][k], acc[ai][bj][m][n], 0, 0, 0); __builtin_amdgcn_s_setprio(0); } while (0)
; #define PG8_WAIT_V(n) asm volatile("s_waitcnt vmcnt(" #n ")" ::: "memory")
; #define PG8_WAIT_L(n) asm volatile("s_waitcnt lgkmcnt(" #n ")" ::: "memory")
; #define PG8_BAR __builtin_amdgcn_s_barrier()
; #define PG8_SCHED __builtin_amdgcn_sched_barrier(0)
; template <int GI>
; __device__ __forceinline__ void gemm_phase(LAS unsigned char* lds, unsigned char* ws, int G, int cblk) {
;     ...
;             PG8_LDA(At, 1, 1); PG8_STAGE(PG8_SB(1, 0), b3, voffB); PG8_STAGE(PG8_SB(1, 1), b3 + hstepB, voffB); PG8_STAGE(PG8_SA(1, 0), a3, voffA);
;             PG8_WAIT_V(8); PG8_WAIT_L(0); PG8_BAR; PG8_MMA(1, 0, At, B0); PG8_MMA(1, 1, At, B1); PG8_BAR; PG8_SCHED;
;         }
	s_add_i32 s34, s34, s0
	v_lshl_add_u64 v[188:189], v[188:189], 0, s[10:11]
	s_mov_b32 m0, s34
	ds_read_b128 v[196:199], v155 offset:49152
	ds_read_b128 v[200:203], v155 offset:50176
	ds_read_b128 v[204:207], v155 offset:51200
	ds_read_b128 v[208:211], v155 offset:52224
	ds_read_b128 v[212:215], v155 offset:53248
	ds_read_b128 v[216:219], v155 offset:54272
	ds_read_b128 v[220:223], v155 offset:55296
	ds_read_b128 v[224:227], v155 offset:56320
	global_load_lds_dwordx4 v[188:189], off
	s_add_i32 m0, s34, 0x2000
	s_add_u32 s38, s42, 0x160080
	v_lshl_add_u64 v[188:189], v[228:229], 0, s[10:11]
	s_addc_u32 s39, s43, 0
	s_add_i32 s34, s55, s0
	global_load_lds_dwordx4 v[188:189], off
	v_lshl_add_u64 v[188:189], s[38:39], 0, v[132:133]
	s_mov_b32 m0, s34
	s_nop 0
	global_load_lds_dwordx4 v[188:189], off
	v_lshl_add_u64 v[188:189], s[38:39], 0, v[136:137]
	s_add_i32 m0, s34, 0x2000
	s_nop 0
	global_load_lds_dwordx4 v[188:189], off
	v_lshl_add_u64 v[188:189], v[230:231], 0, s[10:11]
	s_mov_b32 m0, s48
	s_nop 0
	global_load_lds_dwordx4 v[188:189], off
	v_lshl_add_u64 v[188:189], v[232:233], 0, s[10:11]
	s_mov_b32 m0, s49
	s_nop 0
	global_load_lds_dwordx4 v[188:189], off
	s_waitcnt vmcnt(8)
	s_waitcnt lgkmcnt(0)
	s_barrier
	s_setprio 1
	s_waitcnt lgkmcnt(0)
	v_mfma_f32_16x16x32_bf16 v[60:63], v[156:159], v[196:199], v[60:63]
	v_mfma_f32_16x16x32_bf16 v[56:59], v[168:171], v[196:199], v[56:59]
	s_add_i32 s54, s54, 2
	s_add_u32 s15, s15, 0x100
	s_addc_u32 s53, s53, 0
	s_mov_b64 s[38:39], s[40:41]
	v_mfma_f32_16x16x32_bf16 v[52:55], v[156:159], v[204:207], v[52:55]
	v_mfma_f32_16x16x32_bf16 v[48:51], v[168:171], v[204:207], v[48:51]
	v_mfma_f32_16x16x32_bf16 v[36:39], v[156:159], v[212:215], v[36:39]
	v_mfma_f32_16x16x32_bf16 v[32:35], v[168:171], v[212:215], v[32:35]
	v_mfma_f32_16x16x32_bf16 v[20:23], v[156:159], v[220:223], v[20:23]
	v_mfma_f32_16x16x32_bf16 v[16:19], v[168:171], v[220:223], v[16:19]
	v_mfma_f32_16x16x32_bf16 v[60:63], v[164:167], v[200:203], v[60:63]
	v_mfma_f32_16x16x32_bf16 v[56:59], v[172:175], v[200:203], v[56:59]
	v_mfma_f32_16x16x32_bf16 v[52:55], v[164:167], v[208:211], v[52:55]
	v_mfma_f32_16x16x32_bf16 v[48:51], v[172:175], v[208:211], v[48:51]
	v_mfma_f32_16x16x32_bf16 v[36:39], v[164:167], v[216:219], v[36:39]
	v_mfma_f32_16x16x32_bf16 v[32:35], v[172:175], v[216:219], v[32:35]
	v_mfma_f32_16x16x32_bf16 v[20:23], v[164:167], v[224:227], v[20:23]
	v_mfma_f32_16x16x32_bf16 v[16:19], v[172:175], v[224:227], v[16:19]
	s_setprio 0
	s_setprio 1
	v_mfma_f32_16x16x32_bf16 v[44:47], v[176:179], v[196:199], v[44:47]
	v_mfma_f32_16x16x32_bf16 v[40:43], v[184:187], v[196:199], v[40:43]
	v_mfma_f32_16x16x32_bf16 v[28:31], v[176:179], v[204:207], v[28:31]
	v_mfma_f32_16x16x32_bf16 v[24:27], v[184:187], v[204:207], v[24:27]
	v_mfma_f32_16x16x32_bf16 v[12:15], v[176:179], v[212:215], v[12:15]
	v_mfma_f32_16x16x32_bf16 v[8:11], v[184:187], v[212:215], v[8:11]
	v_mfma_f32_16x16x32_bf16 v[4:7], v[176:179], v[220:223], v[4:7]
	v_mfma_f32_16x16x32_bf16 v[0:3], v[184:187], v[220:223], v[0:3]
	v_mfma_f32_16x16x32_bf16 v[44:47], v[180:183], v[200:203], v[44:47]
	v_mfma_f32_16x16x32_bf16 v[40:43], v[192:195], v[200:203], v[40:43]
	v_mfma_f32_16x16x32_bf16 v[28:31], v[180:183], v[208:211], v[28:31]
	v_mfma_f32_16x16x32_bf16 v[24:27], v[192:195], v[208:211], v[24:27]
	v_mfma_f32_16x16x32_bf16 v[12:15], v[180:183], v[216:219], v[12:15]
	v_mfma_f32_16x16x32_bf16 v[8:11], v[192:195], v[216:219], v[8:11]
	v_mfma_f32_16x16x32_bf16 v[4:7], v[180:183], v[224:227], v[4:7]
	v_mfma_f32_16x16x32_bf16 v[0:3], v[192:195], v[224:227], v[0:3]
	s_setprio 0
	s_barrier
	s_cmpk_gt_u32 s54, 0x55
	s_cbranch_scc0 .LBB0_896
